# critical-path trims: PEER header loads issued above the stage A/B barrier, epilogue loads without draining the v ring, accumulators zeroed under the v prologue loads
# speedup vs baseline: 1.0012x; 1.0012x over previous
; #define LAS __attribute__((address_space(3)))
; __device__ __forceinline__ unsigned f2key(float f) { const unsigned u = __float_as_uint(f); return (u & 0x80000000u) ? ~u : (u | 0x80000000u); }
; __device__ __forceinline__ void peer_tile(const Args& A, LAS unsigned char* lds, int tile) {
;     int tid_o = threadIdx.x; asm volatile("" : "+v"(tid_o)); const int tid = tid_o, lane = tid & 63, w = tid >> 6, g = lane >> 4, l15 = lane & 15;
;     const bf16_t* QRY = (const bf16_t*)(A.ws + WS_QRY);
;     const bf16_t* KEYS = (const bf16_t*)(A.ws + WS_KEYS);
;     const bf16_t* ACT = (const bf16_t*)(A.ws + WS_ACT);
;     const float* MOD = (const float*)(A.ws + WS_MOD);
;     LAS unsigned* idx = (LAS unsigned*)(lds + PE_IDX) + (w * 64 + lane) * 33;
;     LAS u32x2* SEL = (LAS u32x2*)(lds + PE_SEL);
;     {
;         const int tg = w & 3, hg = w >> 2, tl = 16 * tg + l15;
;         const size_t m = (size_t)tile * 64 + tl;
;         unsigned LA[4][2][16];
; #pragma unroll
;         for (int hh = 0; hh < 4; ++hh) {
;             const int h = 4 * hg + hh;
; #pragma unroll
;             for (int p = 0; p < 2; ++p) {
;                 const int hp = 2 * h + p;
;                 unsigned k0[16], k1[16];
;                 { const bf16_t* sp = QRY + m * 2048 + hp * 128 + 32 * g;
;                   const u32x4 s0 = *(const u32x4*)sp, s1 = *(const u32x4*)(sp + 8), s2 = *(const u32x4*)(sp + 16), s3 = *(const u32x4*)(sp + 24);
;                   const unsigned sw[16] = {s0.x, s0.y, s0.z, s0.w, s1.x, s1.y, s1.z, s1.w, s2.x, s2.y, s2.z, s2.w, s3.x, s3.y, s3.z, s3.w};
; #pragma unroll
;                   for (int i = 0; i < 16; ++i) {
;                       const float lo = (float)__builtin_bit_cast(_Float16, (unsigned short)(sw[i] & 0xffffu)), hi = (float)__builtin_bit_cast(_Float16, (unsigned short)(sw[i] >> 16));
;                       const unsigned klo = (f2key(lo) & ~127u) | (unsigned)(127 - (32 * g + 2 * i)), khi = (f2key(hi) & ~127u) | (unsigned)(127 - (32 * g + 2 * i + 1));
;                       if (i < 8) { k0[2 * i] = klo; k0[2 * i + 1] = khi; } else { k1[2 * (i - 8)] = klo; k1[2 * (i - 8) + 1] = khi; } } }
;                 sort16_desc(k0); sort16_desc(k1); merge16(k0, k1);
.LBB0_699:
	v_mov_b32_e32 v19, v214
	s_ashr_i32 s3, s2, 31
	v_ashrrev_i32_e32 v7, 6, v19
	v_and_b32_e32 v0, 15, v19
	v_lshlrev_b32_e32 v1, 4, v7
	v_and_or_b32 v13, v1, 48, v0
	s_lshl_b64 s[28:29], s[2:3], 6
	v_or_b32_e32 v0, s28, v13
	v_mov_b32_e32 v1, s29
	v_bfe_u32 v221, v19, 4, 2
	v_ashrrev_i32_e32 v11, 8, v19
	v_lshlrev_b64 v[0:1], 12, v[0:1]
	v_lshlrev_b32_e32 v2, 10, v11
	v_lshl_add_u64 v[0:1], s[54:55], 0, v[0:1]
	v_lshlrev_b32_e32 v112, 6, v221
	v_lshl_add_u64 v[0:1], v[0:1], 0, v[112:113]
	v_ashrrev_i32_e32 v3, 31, v2
	v_lshl_add_u64 v[4:5], v[2:3], 1, v[0:1]
	global_load_dwordx4 v[20:23], v[4:5], off
	global_load_dwordx4 v[24:27], v[4:5], off offset:16
	global_load_dwordx4 v[0:3], v[4:5], off offset:48
	global_load_dwordx4 v[28:31], v[4:5], off offset:32
	v_lshlrev_b32_e32 v15, 5, v221
	v_or_b32_e32 v8, 8, v15
	v_or_b32_e32 v14, 2, v15
	v_or_b32_e32 v12, 4, v15
	v_or_b32_e32 v10, 6, v15
	v_and_b32_e32 v9, 63, v19
	v_cmp_gt_u32_e64 s[0:1], 16, v9
	v_cmp_gt_u32_e64 s[4:5], 32, v9
	v_mul_lo_u32 v6, v19, s17
	s_mov_b32 s3, 8
	s_waitcnt vmcnt(3)
	v_cvt_f32_f16_sdwa v17, v20 dst_sel:DWORD dst_unused:UNUSED_PAD src0_sel:WORD_1
	v_cvt_f32_f16_e32 v16, v20
	v_cvt_f32_f16_sdwa v20, v21 dst_sel:DWORD dst_unused:UNUSED_PAD src0_sel:WORD_1
	v_cvt_f32_f16_e32 v18, v21
	v_cvt_f32_f16_e32 v21, v22
	v_cvt_f32_f16_sdwa v22, v22 dst_sel:DWORD dst_unused:UNUSED_PAD src0_sel:WORD_1
	v_not_b32_e32 v34, v17
	v_or_b32_e32 v35, 0x80000000, v17
	v_cmp_gt_i32_e32 vcc, 0, v17
	v_not_b32_e32 v36, v16
	v_or_b32_e32 v37, 0x80000000, v16
	v_cndmask_b32_e32 v17, v35, v34, vcc
	v_cmp_gt_i32_e32 vcc, 0, v16
	v_cvt_f32_f16_e32 v32, v23
	v_cvt_f32_f16_sdwa v23, v23 dst_sel:DWORD dst_unused:UNUSED_PAD src0_sel:WORD_1
	v_not_b32_e32 v38, v20
	v_or_b32_e32 v39, 0x80000000, v20
	v_cndmask_b32_e32 v16, v37, v36, vcc
	v_cmp_gt_i32_e32 vcc, 0, v20
	v_not_b32_e32 v40, v18
	v_or_b32_e32 v41, 0x80000000, v18
	v_cndmask_b32_e32 v20, v39, v38, vcc
	v_cmp_gt_i32_e32 vcc, 0, v18
	s_waitcnt vmcnt(2)
	v_cvt_f32_f16_e32 v33, v24
	v_cvt_f32_f16_sdwa v24, v24 dst_sel:DWORD dst_unused:UNUSED_PAD src0_sel:WORD_1
	v_not_b32_e32 v42, v22
	v_or_b32_e32 v43, 0x80000000, v22
	v_cndmask_b32_e32 v18, v41, v40, vcc
	v_cmp_gt_i32_e32 vcc, 0, v22
	v_not_b32_e32 v44, v21
	v_or_b32_e32 v45, 0x80000000, v21
	v_cndmask_b32_e32 v22, v43, v42, vcc
	v_cmp_gt_i32_e32 vcc, 0, v21
	v_not_b32_e32 v46, v23
	v_or_b32_e32 v47, 0x80000000, v23
	v_cndmask_b32_e32 v21, v45, v44, vcc
	v_cmp_gt_i32_e32 vcc, 0, v23
	v_not_b32_e32 v48, v32
	v_or_b32_e32 v49, 0x80000000, v32
	v_cndmask_b32_e32 v23, v47, v46, vcc
	v_cmp_gt_i32_e32 vcc, 0, v32
	v_and_b32_e32 v16, 0xffffff80, v16
	v_not_b32_e32 v50, v24
	v_or_b32_e32 v51, 0x80000000, v24
	v_cndmask_b32_e32 v32, v49, v48, vcc
	v_sub_u32_e32 v16, v16, v15
	v_cmp_gt_i32_e32 vcc, 0, v24
	v_add_u32_e32 v35, 0x7f, v16
	v_and_b32_e32 v17, 0xffffff80, v17
	v_cndmask_b32_e32 v16, v51, v50, vcc
	v_and_b32_e32 v16, 0xffffff80, v16
	v_sub_u32_e32 v17, v17, v15
	v_sub_u32_e32 v16, v16, v8
	v_add_u32_e32 v34, 0x7e, v17
	v_add_u32_e32 v41, 0x7e, v16
	v_not_b32_e32 v16, v33
	v_or_b32_e32 v17, 0x80000000, v33
	v_cmp_gt_i32_e32 vcc, 0, v33
	v_and_b32_e32 v20, 0xffffff80, v20
	v_and_b32_e32 v18, 0xffffff80, v18
	v_cndmask_b32_e32 v16, v17, v16, vcc
	v_cvt_f32_f16_sdwa v17, v25 dst_sel:DWORD dst_unused:UNUSED_PAD src0_sel:WORD_1
	v_and_b32_e32 v21, 0xffffff80, v21
	v_sub_u32_e32 v20, v20, v14
	v_sub_u32_e32 v18, v18, v14
	v_sub_u32_e32 v21, v21, v12
	v_add_u32_e32 v36, 0x7e, v20
	v_add_u32_e32 v37, 0x7f, v18
	v_add_u32_e32 v39, 0x7f, v21
	v_and_b32_e32 v16, 0xffffff80, v16
	v_cvt_f32_f16_e32 v18, v25
	v_not_b32_e32 v20, v17
	v_or_b32_e32 v21, 0x80000000, v17
	v_cmp_gt_i32_e32 vcc, 0, v17
	v_sub_u32_e32 v16, v16, v8
	v_add_u32_e32 v33, 0x7f, v16
	v_cndmask_b32_e32 v17, v21, v20, vcc
	v_or_b32_e32 v16, 10, v15
	v_and_b32_e32 v17, 0xffffff80, v17
	v_sub_u32_e32 v17, v17, v16
	v_add_u32_e32 v42, 0x7e, v17
	v_not_b32_e32 v17, v18
	v_or_b32_e32 v20, 0x80000000, v18
	v_cmp_gt_i32_e32 vcc, 0, v18
	v_cvt_f32_f16_sdwa v18, v26 dst_sel:DWORD dst_unused:UNUSED_PAD src0_sel:WORD_1
	v_and_b32_e32 v22, 0xffffff80, v22
	v_sub_u32_e32 v22, v22, v12
	v_cndmask_b32_e32 v17, v20, v17, vcc
	v_add_u32_e32 v38, 0x7e, v22
	v_and_b32_e32 v17, 0xffffff80, v17
	v_cvt_f32_f16_e32 v20, v26
	v_not_b32_e32 v21, v18
	v_or_b32_e32 v22, 0x80000000, v18
	v_cmp_gt_i32_e32 vcc, 0, v18
	v_sub_u32_e32 v17, v17, v16
	v_add_u32_e32 v43, 0x7f, v17
	v_cndmask_b32_e32 v18, v22, v21, vcc
	v_or_b32_e32 v17, 12, v15
	v_and_b32_e32 v18, 0xffffff80, v18
	v_sub_u32_e32 v18, v18, v17
	v_add_u32_e32 v44, 0x7e, v18
	v_not_b32_e32 v18, v20
	v_or_b32_e32 v21, 0x80000000, v20
	v_cmp_gt_i32_e32 vcc, 0, v20
	v_cvt_f32_f16_sdwa v20, v27 dst_sel:DWORD dst_unused:UNUSED_PAD src0_sel:WORD_1
	v_and_b32_e32 v23, 0xffffff80, v23
	v_sub_u32_e32 v23, v23, v10
	v_cndmask_b32_e32 v18, v21, v18, vcc
	v_add_u32_e32 v40, 0x7e, v23
	v_and_b32_e32 v18, 0xffffff80, v18
	v_cvt_f32_f16_e32 v21, v27
	v_not_b32_e32 v22, v20
	v_or_b32_e32 v23, 0x80000000, v20
	v_cmp_gt_i32_e32 vcc, 0, v20
	v_sub_u32_e32 v18, v18, v17
	v_add_u32_e32 v45, 0x7f, v18
	v_cndmask_b32_e32 v20, v23, v22, vcc
	v_or_b32_e32 v18, 14, v15
	v_and_b32_e32 v20, 0xffffff80, v20
	v_sub_u32_e32 v20, v20, v18
	v_add_u32_e32 v27, 0x7e, v20
	v_not_b32_e32 v20, v21
	v_or_b32_e32 v22, 0x80000000, v21
	v_cmp_gt_i32_e32 vcc, 0, v21
	s_waitcnt vmcnt(0)
; __device__ __forceinline__ unsigned f2key(float f) { const unsigned u = __float_as_uint(f); return (u & 0x80000000u) ? ~u : (u | 0x80000000u); }
; #define CE_DESC(a, b) do { const unsigned _mx = (a) > (b) ? (a) : (b), _mn = (a) > (b) ? (b) : (a); (a) = _mx; (b) = _mn; } while (0)
; __device__ __forceinline__ void sort16_desc(unsigned (&k)[16]) {
; #pragma unroll
;     for (int size = 2; size <= 16; size <<= 1)
; #pragma unroll
;         for (int stride = size >> 1; stride > 0; stride >>= 1)
; #pragma unroll
;             for (int i = 0; i < 16; ++i) { const int j = i ^ stride;
;                 if (j > i) { if ((i & size) == 0) CE_DESC(k[i], k[j]); else CE_DESC(k[j], k[i]); } }
; }
; __device__ __forceinline__ void peer_tile(const Args& A, LAS unsigned char* lds, int tile) {
;     ...
;                   for (int i = 0; i < 16; ++i) {
;                       const float lo = (float)__builtin_bit_cast(_Float16, (unsigned short)(sw[i] & 0xffffu)), hi = (float)__builtin_bit_cast(_Float16, (unsigned short)(sw[i] >> 16));
;                       const unsigned klo = (f2key(lo) & ~127u) | (unsigned)(127 - (32 * g + 2 * i)), khi = (f2key(hi) & ~127u) | (unsigned)(127 - (32 * g + 2 * i + 1));
;                       if (i < 8) { k0[2 * i] = klo; k0[2 * i + 1] = khi; } else { k1[2 * (i - 8)] = klo; k1[2 * (i - 8) + 1] = khi; } } }
	v_cvt_f32_f16_sdwa v21, v28 dst_sel:DWORD dst_unused:UNUSED_PAD src0_sel:WORD_1
	v_and_b32_e32 v32, 0xffffff80, v32
	v_cndmask_b32_e32 v20, v22, v20, vcc
	v_and_b32_e32 v20, 0xffffff80, v20
	v_cvt_f32_f16_e32 v22, v28
	v_not_b32_e32 v23, v21
	v_or_b32_e32 v24, 0x80000000, v21
	v_cmp_gt_i32_e32 vcc, 0, v21
	v_sub_u32_e32 v20, v20, v18
	v_add_u32_e32 v46, 0x7f, v20
	v_cndmask_b32_e32 v21, v24, v23, vcc
	v_or_b32_e32 v20, 16, v15
	v_and_b32_e32 v21, 0xffffff80, v21
	v_sub_u32_e32 v21, v21, v20
	v_add_u32_e32 v47, 0x7e, v21
	v_not_b32_e32 v21, v22
	v_or_b32_e32 v23, 0x80000000, v22
	v_cmp_gt_i32_e32 vcc, 0, v22
	v_cvt_f32_f16_sdwa v22, v29 dst_sel:DWORD dst_unused:UNUSED_PAD src0_sel:WORD_1
	v_sub_u32_e32 v32, v32, v10
	v_cndmask_b32_e32 v21, v23, v21, vcc
	v_and_b32_e32 v21, 0xffffff80, v21
	v_cvt_f32_f16_e32 v23, v29
	v_not_b32_e32 v24, v22
	v_or_b32_e32 v25, 0x80000000, v22
	v_cmp_gt_i32_e32 vcc, 0, v22
	v_sub_u32_e32 v21, v21, v20
	v_add_u32_e32 v48, 0x7f, v21
	v_cndmask_b32_e32 v22, v25, v24, vcc
	v_or_b32_e32 v21, 18, v15
	v_and_b32_e32 v22, 0xffffff80, v22
	v_sub_u32_e32 v22, v22, v21
	v_add_u32_e32 v29, 0x7e, v22
	v_not_b32_e32 v22, v23
	v_or_b32_e32 v24, 0x80000000, v23
	v_cmp_gt_i32_e32 vcc, 0, v23
	v_cvt_f32_f16_sdwa v23, v30 dst_sel:DWORD dst_unused:UNUSED_PAD src0_sel:WORD_1
	v_add_u32_e32 v32, 0x7f, v32
	v_cndmask_b32_e32 v22, v24, v22, vcc
	v_and_b32_e32 v22, 0xffffff80, v22
	v_cvt_f32_f16_e32 v24, v30
	v_not_b32_e32 v25, v23
	v_or_b32_e32 v26, 0x80000000, v23
	v_cmp_gt_i32_e32 vcc, 0, v23
	v_sub_u32_e32 v22, v22, v21
	v_add_u32_e32 v49, 0x7f, v22
	v_cndmask_b32_e32 v23, v26, v25, vcc
	v_or_b32_e32 v22, 20, v15
	v_and_b32_e32 v23, 0xffffff80, v23
	v_sub_u32_e32 v23, v23, v22
	v_add_u32_e32 v30, 0x7e, v23
	v_not_b32_e32 v23, v24
	v_or_b32_e32 v25, 0x80000000, v24
	v_cmp_gt_i32_e32 vcc, 0, v24
	v_cvt_f32_f16_sdwa v24, v31 dst_sel:DWORD dst_unused:UNUSED_PAD src0_sel:WORD_1
	v_max_u32_e32 v64, v48, v47
	v_cndmask_b32_e32 v23, v25, v23, vcc
	v_and_b32_e32 v23, 0xffffff80, v23
	v_cvt_f32_f16_e32 v25, v31
	v_not_b32_e32 v26, v24
	v_or_b32_e32 v28, 0x80000000, v24
	v_cmp_gt_i32_e32 vcc, 0, v24
	v_sub_u32_e32 v23, v23, v22
	v_add_u32_e32 v50, 0x7f, v23
	v_cndmask_b32_e32 v24, v28, v26, vcc
	v_or_b32_e32 v23, 22, v15
	v_and_b32_e32 v24, 0xffffff80, v24
	v_sub_u32_e32 v24, v24, v23
	v_add_u32_e32 v31, 0x7e, v24
	v_not_b32_e32 v24, v25
	v_or_b32_e32 v26, 0x80000000, v25
	v_cmp_gt_i32_e32 vcc, 0, v25
	v_cvt_f32_f16_sdwa v25, v0 dst_sel:DWORD dst_unused:UNUSED_PAD src0_sel:WORD_1
	v_cvt_f32_f16_e32 v0, v0
	v_cndmask_b32_e32 v24, v26, v24, vcc
	v_and_b32_e32 v24, 0xffffff80, v24
	v_not_b32_e32 v26, v25
	v_or_b32_e32 v28, 0x80000000, v25
	v_cmp_gt_i32_e32 vcc, 0, v25
	v_sub_u32_e32 v24, v24, v23
	v_add_u32_e32 v51, 0x7f, v24
	v_cndmask_b32_e32 v25, v28, v26, vcc
	v_or_b32_e32 v24, 24, v15
	v_and_b32_e32 v25, 0xffffff80, v25
	v_sub_u32_e32 v25, v25, v24
	v_add_u32_e32 v52, 0x7e, v25
	v_not_b32_e32 v25, v0
	v_or_b32_e32 v26, 0x80000000, v0
	v_cmp_gt_i32_e32 vcc, 0, v0
	v_min_u32_e32 v47, v48, v47
	v_max_u32_e32 v48, v29, v49
	v_cndmask_b32_e32 v0, v26, v25, vcc
	v_cvt_f32_f16_sdwa v26, v1 dst_sel:DWORD dst_unused:UNUSED_PAD src0_sel:WORD_1
	v_cvt_f32_f16_e32 v1, v1
	v_or_b32_e32 v25, 26, v15
	v_and_b32_e32 v0, 0xffffff80, v0
	v_not_b32_e32 v28, v26
	v_or_b32_e32 v53, 0x80000000, v26
	v_cmp_gt_i32_e32 vcc, 0, v26
	v_sub_u32_e32 v0, v0, v24
	v_add_u32_e32 v0, 0x7f, v0
	v_cndmask_b32_e32 v26, v53, v28, vcc
	v_and_b32_e32 v26, 0xffffff80, v26
	v_sub_u32_e32 v26, v26, v25
	v_add_u32_e32 v53, 0x7e, v26
	v_not_b32_e32 v26, v1
	v_or_b32_e32 v28, 0x80000000, v1
	v_cmp_gt_i32_e32 vcc, 0, v1
	v_min_u32_e32 v29, v29, v49
	v_max_u32_e32 v49, v50, v30
	v_cndmask_b32_e32 v1, v28, v26, vcc
	v_cvt_f32_f16_sdwa v28, v2 dst_sel:DWORD dst_unused:UNUSED_PAD src0_sel:WORD_1
	v_cvt_f32_f16_e32 v2, v2
	v_or_b32_e32 v26, 28, v15
	v_and_b32_e32 v1, 0xffffff80, v1
	v_not_b32_e32 v54, v28
	v_or_b32_e32 v55, 0x80000000, v28
	v_cmp_gt_i32_e32 vcc, 0, v28
	v_sub_u32_e32 v1, v1, v25
	v_add_u32_e32 v1, 0x7f, v1
	v_cndmask_b32_e32 v28, v55, v54, vcc
	v_and_b32_e32 v28, 0xffffff80, v28
	v_sub_u32_e32 v28, v28, v26
	v_add_u32_e32 v54, 0x7e, v28
	v_not_b32_e32 v28, v2
	v_or_b32_e32 v55, 0x80000000, v2
	v_cmp_gt_i32_e32 vcc, 0, v2
	v_min_u32_e32 v30, v50, v30
	v_max_u32_e32 v50, v31, v51
	v_cndmask_b32_e32 v2, v55, v28, vcc
	v_cvt_f32_f16_e32 v55, v3
	v_cvt_f32_f16_sdwa v3, v3 dst_sel:DWORD dst_unused:UNUSED_PAD src0_sel:WORD_1
	v_and_b32_e32 v2, 0xffffff80, v2
	v_or_b32_e32 v28, 30, v15
	v_not_b32_e32 v56, v55
	v_or_b32_e32 v57, 0x80000000, v55
	v_cmp_gt_i32_e32 vcc, 0, v55
	v_sub_u32_e32 v2, v2, v26
	v_add_u32_e32 v2, 0x7f, v2
	v_cndmask_b32_e32 v55, v57, v56, vcc
	v_not_b32_e32 v56, v3
	v_or_b32_e32 v57, 0x80000000, v3
	v_cmp_gt_i32_e32 vcc, 0, v3
	v_and_b32_e32 v55, 0xffffff80, v55
	v_sub_u32_e32 v55, v55, v28
	v_cndmask_b32_e32 v3, v57, v56, vcc
	v_and_b32_e32 v3, 0xffffff80, v3
	v_sub_u32_e32 v3, v3, v28
	v_add_u32_e32 v55, 0x7f, v55
	v_add_u32_e32 v3, 0x7e, v3
	v_max_u32_e32 v56, v35, v34
	v_min_u32_e32 v34, v35, v34
	v_max_u32_e32 v35, v36, v37
	v_min_u32_e32 v36, v36, v37
	v_max_u32_e32 v37, v39, v38
	v_min_u32_e32 v38, v39, v38
	v_max_u32_e32 v39, v40, v32
	v_min_u32_e32 v32, v40, v32
	v_max_u32_e32 v40, v33, v41
	v_min_u32_e32 v33, v33, v41
	v_max_u32_e32 v41, v42, v43
	v_min_u32_e32 v42, v42, v43
	v_max_u32_e32 v43, v45, v44
	v_min_u32_e32 v44, v45, v44
	v_max_u32_e32 v45, v27, v46
	v_min_u32_e32 v27, v27, v46
	v_min_u32_e32 v31, v31, v51
	v_max_u32_e32 v51, v0, v52
	v_min_u32_e32 v0, v0, v52
	v_max_u32_e32 v52, v53, v1
	v_min_u32_e32 v1, v53, v1
	v_max_u32_e32 v53, v2, v54
; #define CE_DESC(a, b) do { const unsigned _mx = (a) > (b) ? (a) : (b), _mn = (a) > (b) ? (b) : (a); (a) = _mx; (b) = _mn; } while (0)
; __device__ __forceinline__ void sort16_desc(unsigned (&k)[16]) {
; #pragma unroll
;     for (int size = 2; size <= 16; size <<= 1)
; #pragma unroll
;         for (int stride = size >> 1; stride > 0; stride >>= 1)
; #pragma unroll
;             for (int i = 0; i < 16; ++i) { const int j = i ^ stride;
;                 if (j > i) { if ((i & size) == 0) CE_DESC(k[i], k[j]); else CE_DESC(k[j], k[i]); } }
; }
	v_min_u32_e32 v2, v2, v54
	v_max_u32_e32 v54, v3, v55
	v_min_u32_e32 v3, v3, v55
	v_max_u32_e32 v46, v56, v36
	v_min_u32_e32 v36, v56, v36
	v_max_u32_e32 v56, v34, v35
	v_min_u32_e32 v34, v34, v35
	v_max_u32_e32 v35, v32, v37
	v_min_u32_e32 v32, v32, v37
	v_max_u32_e32 v37, v39, v38
	v_min_u32_e32 v38, v39, v38
	v_max_u32_e32 v39, v40, v42
	v_min_u32_e32 v40, v40, v42
	v_max_u32_e32 v42, v33, v41
	v_min_u32_e32 v33, v33, v41
	v_max_u32_e32 v41, v27, v43
	v_min_u32_e32 v27, v27, v43
	v_max_u32_e32 v43, v45, v44
	v_min_u32_e32 v44, v45, v44
	v_max_u32_e32 v55, v64, v29
	v_min_u32_e32 v29, v64, v29
	v_max_u32_e32 v64, v47, v48
	v_min_u32_e32 v47, v47, v48
	v_max_u32_e32 v48, v31, v49
	v_min_u32_e32 v31, v31, v49
	v_max_u32_e32 v49, v50, v30
	v_min_u32_e32 v30, v50, v30
	v_max_u32_e32 v50, v51, v1
	v_min_u32_e32 v1, v51, v1
	v_max_u32_e32 v51, v0, v52
	v_min_u32_e32 v0, v0, v52
	v_max_u32_e32 v52, v3, v53
	v_min_u32_e32 v3, v3, v53
	v_max_u32_e32 v53, v54, v2
	v_min_u32_e32 v2, v54, v2
	v_max_u32_e32 v45, v46, v56
	v_min_u32_e32 v46, v46, v56
	v_max_u32_e32 v56, v36, v34
	v_min_u32_e32 v34, v36, v34
	v_max_u32_e32 v36, v38, v32
	v_min_u32_e32 v32, v38, v32
	v_max_u32_e32 v38, v37, v35
	v_min_u32_e32 v35, v37, v35
	v_max_u32_e32 v37, v39, v42
	v_min_u32_e32 v39, v39, v42
	v_max_u32_e32 v42, v40, v33
	v_min_u32_e32 v33, v40, v33
	v_max_u32_e32 v40, v44, v27
	v_min_u32_e32 v27, v44, v27
	v_max_u32_e32 v44, v43, v41
	v_min_u32_e32 v41, v43, v41
	v_max_u32_e32 v54, v55, v64
	v_min_u32_e32 v55, v55, v64
	v_max_u32_e32 v64, v29, v47
	v_min_u32_e32 v29, v29, v47
	v_max_u32_e32 v47, v30, v31
	v_min_u32_e32 v30, v30, v31
	v_max_u32_e32 v31, v49, v48
	v_min_u32_e32 v48, v49, v48
	v_max_u32_e32 v49, v50, v51
	v_min_u32_e32 v50, v50, v51
	v_max_u32_e32 v51, v1, v0
	v_min_u32_e32 v0, v1, v0
	v_max_u32_e32 v1, v2, v3
	v_min_u32_e32 v2, v2, v3
	v_max_u32_e32 v3, v53, v52
	v_min_u32_e32 v52, v53, v52
	v_max_u32_e32 v43, v45, v32
	v_min_u32_e32 v32, v45, v32
	v_max_u32_e32 v45, v46, v36
	v_min_u32_e32 v36, v46, v36
	v_max_u32_e32 v46, v56, v35
	v_min_u32_e32 v35, v56, v35
	v_max_u32_e32 v56, v34, v38
	v_min_u32_e32 v34, v34, v38
	v_max_u32_e32 v38, v27, v37
	v_min_u32_e32 v27, v27, v37
	v_max_u32_e32 v37, v40, v39
	v_min_u32_e32 v39, v40, v39
	v_max_u32_e32 v40, v41, v42
	v_min_u32_e32 v41, v41, v42
	v_max_u32_e32 v42, v44, v33
	v_min_u32_e32 v33, v44, v33
	v_max_u32_e32 v53, v54, v30
	v_min_u32_e32 v30, v54, v30
	v_max_u32_e32 v54, v55, v47
	v_min_u32_e32 v47, v55, v47
	v_max_u32_e32 v55, v64, v48
	v_min_u32_e32 v48, v64, v48
	v_max_u32_e32 v64, v29, v31
	v_min_u32_e32 v29, v29, v31
	v_max_u32_e32 v31, v2, v49
	v_min_u32_e32 v2, v2, v49
	v_max_u32_e32 v49, v1, v50
	v_min_u32_e32 v1, v1, v50
	v_max_u32_e32 v50, v52, v51
	v_min_u32_e32 v51, v52, v51
	v_max_u32_e32 v52, v3, v0
	v_min_u32_e32 v0, v3, v0
	v_max_u32_e32 v44, v43, v46
	v_min_u32_e32 v43, v43, v46
	v_max_u32_e32 v46, v45, v56
	v_min_u32_e32 v45, v45, v56
	v_max_u32_e32 v56, v32, v35
	v_min_u32_e32 v32, v32, v35
	v_max_u32_e32 v35, v36, v34
	v_min_u32_e32 v34, v36, v34
	v_max_u32_e32 v36, v41, v27
	v_min_u32_e32 v27, v41, v27
	v_max_u32_e32 v41, v33, v39
	v_min_u32_e32 v33, v33, v39
	v_max_u32_e32 v39, v40, v38
	v_min_u32_e32 v38, v40, v38
	v_max_u32_e32 v40, v42, v37
	v_min_u32_e32 v37, v42, v37
	v_max_u32_e32 v3, v53, v55
	v_min_u32_e32 v53, v53, v55
	v_max_u32_e32 v55, v54, v64
	v_min_u32_e32 v54, v54, v64
	v_max_u32_e32 v64, v30, v48
	v_min_u32_e32 v30, v30, v48
	v_max_u32_e32 v48, v47, v29
	v_min_u32_e32 v29, v47, v29
	v_max_u32_e32 v47, v51, v2
	v_min_u32_e32 v2, v51, v2
	v_max_u32_e32 v51, v0, v1
	v_min_u32_e32 v0, v0, v1
	v_max_u32_e32 v1, v50, v31
	v_min_u32_e32 v31, v50, v31
	v_max_u32_e32 v50, v52, v49
	v_min_u32_e32 v49, v52, v49
	v_max_u32_e32 v42, v44, v46
	v_min_u32_e32 v44, v44, v46
	v_max_u32_e32 v46, v43, v45
	v_min_u32_e32 v43, v43, v45
	v_max_u32_e32 v45, v56, v35
	v_min_u32_e32 v35, v56, v35
	v_max_u32_e32 v56, v32, v34
	v_min_u32_e32 v32, v32, v34
	v_max_u32_e32 v34, v33, v27
	v_min_u32_e32 v27, v33, v27
	v_max_u32_e32 v33, v41, v36
	v_min_u32_e32 v36, v41, v36
	v_max_u32_e32 v41, v37, v38
	v_min_u32_e32 v37, v37, v38
	v_max_u32_e32 v38, v40, v39
	v_min_u32_e32 v39, v40, v39
	v_max_u32_e32 v52, v3, v55
	v_min_u32_e32 v3, v3, v55
	v_max_u32_e32 v55, v53, v54
	v_min_u32_e32 v53, v53, v54
	v_max_u32_e32 v54, v64, v48
	v_min_u32_e32 v48, v64, v48
	v_max_u32_e32 v64, v30, v29
	v_min_u32_e32 v29, v30, v29
	v_max_u32_e32 v30, v0, v2
	v_min_u32_e32 v0, v0, v2
	v_max_u32_e32 v2, v51, v47
	v_min_u32_e32 v47, v51, v47
	v_max_u32_e32 v51, v49, v31
	v_min_u32_e32 v31, v49, v31
	v_max_u32_e32 v49, v50, v1
	v_min_u32_e32 v1, v50, v1
	v_max_u32_e32 v40, v42, v27
	v_min_u32_e32 v27, v42, v27
	v_max_u32_e32 v42, v44, v34
	v_min_u32_e32 v34, v44, v34
	v_max_u32_e32 v44, v46, v36
	v_min_u32_e32 v36, v46, v36
	v_max_u32_e32 v46, v43, v33
	v_min_u32_e32 v33, v43, v33
	v_max_u32_e32 v43, v45, v37
	v_min_u32_e32 v37, v45, v37
	v_max_u32_e32 v45, v35, v41
	v_min_u32_e32 v35, v35, v41
	v_max_u32_e32 v41, v56, v39
	v_min_u32_e32 v39, v56, v39
	v_max_u32_e32 v56, v32, v38
	v_min_u32_e32 v32, v32, v38
	v_max_u32_e32 v50, v52, v0
	v_min_u32_e32 v0, v52, v0
	v_max_u32_e32 v52, v3, v30
	v_min_u32_e32 v3, v3, v30
	v_max_u32_e32 v30, v55, v47
	v_min_u32_e32 v47, v55, v47
	v_max_u32_e32 v55, v53, v2
	v_min_u32_e32 v2, v53, v2
	v_max_u32_e32 v53, v54, v31
	v_min_u32_e32 v31, v54, v31
	v_max_u32_e32 v54, v48, v51
	v_min_u32_e32 v48, v48, v51
	v_max_u32_e32 v51, v64, v1
	v_min_u32_e32 v1, v64, v1
	v_max_u32_e32 v64, v29, v49
	v_min_u32_e32 v29, v29, v49
	v_max_u32_e32 v38, v40, v43
	v_min_u32_e32 v40, v40, v43
; #define CE_DESC(a, b) do { const unsigned _mx = (a) > (b) ? (a) : (b), _mn = (a) > (b) ? (b) : (a); (a) = _mx; (b) = _mn; } while (0)
; __device__ __forceinline__ void merge16(unsigned (&a)[16], const unsigned (&b)[16]) {
; #pragma unroll
;     for (int i = 0; i < 16; ++i) a[i] = a[i] > b[15 - i] ? a[i] : b[15 - i];
; #pragma unroll
;     for (int stride = 8; stride > 0; stride >>= 1)
; #pragma unroll
;         for (int i = 0; i < 16; ++i) { const int j = i ^ stride; if (j > i) CE_DESC(a[i], a[j]); }
; }
; __device__ __forceinline__ void peer_tile(const Args& A, LAS unsigned char* lds, int tile) {
;     ...
;                 for (int msk = 16; msk <= 32; msk <<= 1) {
; #pragma unroll
;                     for (int i = 0; i < 16; ++i) k1[i] = (unsigned)__shfl_xor((int)k0[i], msk);
;                     merge16(k0, k1); }
	v_max_u32_e32 v43, v42, v45
	v_min_u32_e32 v42, v42, v45
	v_max_u32_e32 v45, v44, v41
	v_min_u32_e32 v41, v44, v41
	v_max_u32_e32 v44, v46, v56
	v_min_u32_e32 v46, v46, v56
	v_max_u32_e32 v56, v27, v37
	v_min_u32_e32 v27, v27, v37
	v_max_u32_e32 v37, v34, v35
	v_min_u32_e32 v34, v34, v35
	v_max_u32_e32 v35, v36, v39
	v_min_u32_e32 v36, v36, v39
	v_max_u32_e32 v39, v33, v32
	v_min_u32_e32 v32, v33, v32
	v_max_u32_e32 v49, v50, v53
	v_min_u32_e32 v50, v50, v53
	v_max_u32_e32 v53, v52, v54
	v_min_u32_e32 v52, v52, v54
	v_max_u32_e32 v54, v30, v51
	v_min_u32_e32 v30, v30, v51
	v_max_u32_e32 v51, v55, v64
	v_min_u32_e32 v55, v55, v64
	v_max_u32_e32 v64, v0, v31
	v_min_u32_e32 v0, v0, v31
	v_max_u32_e32 v31, v3, v48
	v_min_u32_e32 v3, v3, v48
	v_max_u32_e32 v48, v47, v1
	v_min_u32_e32 v1, v47, v1
	v_max_u32_e32 v47, v2, v29
	v_min_u32_e32 v2, v2, v29
	v_max_u32_e32 v33, v38, v45
	v_min_u32_e32 v38, v38, v45
	v_max_u32_e32 v45, v43, v44
	v_min_u32_e32 v43, v43, v44
	v_max_u32_e32 v44, v40, v41
	v_min_u32_e32 v40, v40, v41
	v_max_u32_e32 v41, v42, v46
	v_min_u32_e32 v42, v42, v46
	v_max_u32_e32 v46, v56, v35
	v_min_u32_e32 v35, v56, v35
	v_max_u32_e32 v56, v37, v39
	v_min_u32_e32 v37, v37, v39
	v_max_u32_e32 v39, v27, v36
	v_min_u32_e32 v27, v27, v36
	v_max_u32_e32 v36, v34, v32
	v_min_u32_e32 v32, v34, v32
	v_max_u32_e32 v29, v49, v54
	v_min_u32_e32 v49, v49, v54
	v_max_u32_e32 v54, v53, v51
	v_min_u32_e32 v51, v53, v51
	v_max_u32_e32 v53, v50, v30
	v_min_u32_e32 v30, v50, v30
	v_max_u32_e32 v50, v52, v55
	v_min_u32_e32 v52, v52, v55
	v_max_u32_e32 v55, v64, v48
	v_min_u32_e32 v48, v64, v48
	v_max_u32_e32 v64, v31, v47
	v_min_u32_e32 v31, v31, v47
	v_max_u32_e32 v47, v0, v1
	v_min_u32_e32 v0, v0, v1
	v_max_u32_e32 v1, v3, v2
	v_min_u32_e32 v2, v3, v2
	v_min_u32_e32 v34, v33, v45
	v_min_u32_e32 v57, v38, v43
	v_min_u32_e32 v58, v44, v41
	v_min_u32_e32 v59, v40, v42
	v_min_u32_e32 v60, v46, v56
	v_min_u32_e32 v61, v35, v37
	v_min_u32_e32 v62, v39, v36
	v_min_u32_e32 v63, v27, v32
	v_min_u32_e32 v3, v29, v54
	v_min_u32_e32 v65, v49, v51
	v_min_u32_e32 v66, v53, v50
	v_min_u32_e32 v67, v30, v52
	v_min_u32_e32 v68, v55, v64
	v_min_u32_e32 v69, v48, v31
	v_min_u32_e32 v70, v47, v1
	v_min_u32_e32 v71, v0, v2
	v_max3_u32 v33, v33, v45, v71
	v_max3_u32 v0, v34, v0, v2
	v_max3_u32 v2, v38, v43, v70
	v_max3_u32 v1, v57, v47, v1
	v_max3_u32 v34, v44, v41, v69
	v_max3_u32 v31, v58, v48, v31
	v_max3_u32 v38, v40, v42, v68
	v_max3_u32 v40, v59, v55, v64
	v_max3_u32 v41, v46, v56, v67
	v_max3_u32 v30, v60, v30, v52
	v_max3_u32 v35, v35, v37, v66
	v_max3_u32 v37, v61, v53, v50
	v_max3_u32 v36, v39, v36, v65
	v_max3_u32 v39, v62, v49, v51
	v_max3_u32 v3, v27, v32, v3
	v_max3_u32 v27, v63, v29, v54
	v_max_u32_e32 v29, v33, v41
	v_min_u32_e32 v32, v33, v41
	v_max_u32_e32 v33, v0, v30
	v_min_u32_e32 v0, v0, v30
	v_max_u32_e32 v30, v2, v35
	v_min_u32_e32 v2, v2, v35
	v_max_u32_e32 v35, v1, v37
	v_min_u32_e32 v1, v1, v37
	v_max_u32_e32 v37, v34, v36
	v_min_u32_e32 v34, v34, v36
	v_max_u32_e32 v36, v31, v39
	v_min_u32_e32 v31, v31, v39
	v_max_u32_e32 v39, v38, v3
	v_min_u32_e32 v3, v38, v3
	v_max_u32_e32 v38, v40, v27
	v_min_u32_e32 v27, v40, v27
	v_max_u32_e32 v40, v29, v37
	v_min_u32_e32 v29, v29, v37
	v_max_u32_e32 v37, v33, v36
	v_min_u32_e32 v33, v33, v36
	v_max_u32_e32 v36, v30, v39
	v_min_u32_e32 v30, v30, v39
	v_max_u32_e32 v39, v35, v38
	v_min_u32_e32 v35, v35, v38
	v_max_u32_e32 v38, v32, v34
	v_min_u32_e32 v32, v32, v34
	v_max_u32_e32 v34, v0, v31
	v_min_u32_e32 v0, v0, v31
	v_max_u32_e32 v31, v2, v3
	v_min_u32_e32 v2, v2, v3
	v_max_u32_e32 v3, v1, v27
	v_min_u32_e32 v1, v1, v27
	v_max_u32_e32 v27, v40, v36
	v_min_u32_e32 v36, v40, v36
	v_max_u32_e32 v40, v37, v39
	v_min_u32_e32 v37, v37, v39
	v_max_u32_e32 v39, v29, v30
	v_min_u32_e32 v29, v29, v30
	v_max_u32_e32 v30, v33, v35
	v_min_u32_e32 v33, v33, v35
	v_max_u32_e32 v35, v38, v31
	v_min_u32_e32 v31, v38, v31
	v_max_u32_e32 v38, v34, v3
	v_min_u32_e32 v3, v34, v3
	v_max_u32_e32 v34, v32, v2
	v_min_u32_e32 v2, v32, v2
	v_max_u32_e32 v32, v0, v1
	v_min_u32_e32 v0, v0, v1
	v_cmp_lt_i32_e32 vcc, v217, v216
	v_max_u32_e32 v41, v36, v37
	v_min_u32_e32 v36, v36, v37
	v_max_u32_e32 v37, v39, v30
	v_min_u32_e32 v30, v39, v30
	v_max_u32_e32 v39, v29, v33
	v_min_u32_e32 v29, v29, v33
	v_max_u32_e32 v33, v35, v38
	v_min_u32_e32 v35, v35, v38
	v_max_u32_e32 v38, v31, v3
	v_min_u32_e32 v3, v31, v3
	v_max_u32_e32 v31, v34, v32
	v_min_u32_e32 v32, v34, v32
	v_max_u32_e32 v34, v2, v0
	v_min_u32_e32 v0, v2, v0
	v_cndmask_b32_e32 v2, v215, v217, vcc
	v_max_u32_e32 v1, v27, v40
	v_min_u32_e32 v40, v27, v40
	v_lshlrev_b32_e32 v27, 2, v2
	ds_bpermute_b32 v2, v27, v1
	ds_bpermute_b32 v42, v27, v40
	ds_bpermute_b32 v43, v27, v41
	ds_bpermute_b32 v44, v27, v36
	ds_bpermute_b32 v45, v27, v37
	ds_bpermute_b32 v46, v27, v30
	ds_bpermute_b32 v47, v27, v39
	ds_bpermute_b32 v48, v27, v29
	ds_bpermute_b32 v49, v27, v33
	ds_bpermute_b32 v50, v27, v35
	ds_bpermute_b32 v51, v27, v38
	ds_bpermute_b32 v52, v27, v0
	ds_bpermute_b32 v53, v27, v34
	ds_bpermute_b32 v54, v27, v32
	ds_bpermute_b32 v55, v27, v31
	ds_bpermute_b32 v56, v27, v3
	s_waitcnt lgkmcnt(4)
	v_max_u32_e32 v1, v1, v52
	s_waitcnt lgkmcnt(3)
	v_max_u32_e32 v40, v40, v53
	s_waitcnt lgkmcnt(2)
	v_max_u32_e32 v41, v41, v54
	s_waitcnt lgkmcnt(1)
	v_max_u32_e32 v36, v36, v55
	s_waitcnt lgkmcnt(0)
; __device__ __forceinline__ void peer_tile(const Args& A, LAS unsigned char* lds, int tile) {
;     ...
;                 { const bf16_t* sp = QRY + m * 2048 + hp * 128 + 32 * g;
;                   const u32x4 s0 = *(const u32x4*)sp, s1 = *(const u32x4*)(sp + 8), s2 = *(const u32x4*)(sp + 16), s3 = *(const u32x4*)(sp + 24);
;     ...
;                 for (int msk = 16; msk <= 32; msk <<= 1) {
; #pragma unroll
;                     for (int i = 0; i < 16; ++i) k1[i] = (unsigned)__shfl_xor((int)k0[i], msk);
;                     merge16(k0, k1); }
; #pragma unroll
;                 for (int i = 0; i < 16; ++i) LA[hh][p][i] = k0[i];
	v_max_u32_e32 v37, v37, v56
	v_max_u32_e32 v30, v30, v51
	v_max_u32_e32 v39, v39, v50
	v_max_u32_e32 v29, v29, v49
	v_max_u32_e32 v33, v33, v48
	v_max_u32_e32 v35, v35, v47
	v_max_u32_e32 v38, v38, v46
	v_max_u32_e32 v3, v3, v45
	v_max_u32_e32 v31, v31, v44
	v_max_u32_e32 v32, v32, v43
	v_max_u32_e32 v34, v34, v42
	v_max_u32_e32 v0, v0, v2
	v_max_u32_e32 v2, v1, v33
	v_min_u32_e32 v1, v1, v33
	v_max_u32_e32 v33, v40, v35
	v_min_u32_e32 v35, v40, v35
	v_max_u32_e32 v40, v41, v38
	v_min_u32_e32 v38, v41, v38
	v_max_u32_e32 v41, v36, v3
	v_min_u32_e32 v3, v36, v3
	v_max_u32_e32 v36, v37, v31
	v_min_u32_e32 v31, v37, v31
	v_max_u32_e32 v37, v30, v32
	v_min_u32_e32 v30, v30, v32
	v_max_u32_e32 v32, v39, v34
	v_min_u32_e32 v34, v39, v34
	v_max_u32_e32 v39, v29, v0
	v_min_u32_e32 v0, v29, v0
	v_max_u32_e32 v29, v2, v36
	v_min_u32_e32 v2, v2, v36
	v_max_u32_e32 v36, v33, v37
	v_min_u32_e32 v33, v33, v37
	v_max_u32_e32 v37, v40, v32
	v_min_u32_e32 v32, v40, v32
	v_max_u32_e32 v40, v41, v39
	v_min_u32_e32 v39, v41, v39
	v_max_u32_e32 v41, v1, v31
	v_min_u32_e32 v1, v1, v31
	v_max_u32_e32 v31, v35, v30
	v_min_u32_e32 v30, v35, v30
	v_max_u32_e32 v35, v38, v34
	v_min_u32_e32 v34, v38, v34
	v_max_u32_e32 v38, v3, v0
	v_min_u32_e32 v0, v3, v0
	v_max_u32_e32 v3, v29, v37
	v_min_u32_e32 v29, v29, v37
	v_max_u32_e32 v37, v36, v40
	v_min_u32_e32 v36, v36, v40
	v_max_u32_e32 v40, v2, v32
	v_min_u32_e32 v2, v2, v32
	v_max_u32_e32 v32, v33, v39
	v_min_u32_e32 v33, v33, v39
	v_max_u32_e32 v39, v41, v35
	v_min_u32_e32 v35, v41, v35
	v_max_u32_e32 v41, v31, v38
	v_min_u32_e32 v31, v31, v38
	v_max_u32_e32 v38, v1, v34
	v_min_u32_e32 v1, v1, v34
	v_max_u32_e32 v34, v30, v0
	v_min_u32_e32 v0, v30, v0
	v_cmp_lt_i32_e32 vcc, v218, v216
	v_max_u32_e32 v42, v40, v32
	v_min_u32_e32 v32, v40, v32
	v_max_u32_e32 v40, v2, v33
	v_min_u32_e32 v2, v2, v33
	v_max_u32_e32 v33, v39, v41
	v_min_u32_e32 v39, v39, v41
	v_max_u32_e32 v41, v35, v31
	v_min_u32_e32 v31, v35, v31
	v_max_u32_e32 v35, v38, v34
	v_min_u32_e32 v34, v38, v34
	v_max_u32_e32 v38, v1, v0
	v_min_u32_e32 v0, v1, v0
	v_cndmask_b32_e32 v1, v215, v218, vcc
	v_max_u32_e32 v30, v3, v37
	v_min_u32_e32 v3, v3, v37
	v_max_u32_e32 v37, v29, v36
	v_min_u32_e32 v36, v29, v36
	v_lshlrev_b32_e32 v29, 2, v1
	ds_bpermute_b32 v46, v29, v0
	ds_bpermute_b32 v1, v29, v30
	ds_bpermute_b32 v43, v29, v3
	ds_bpermute_b32 v44, v29, v37
	ds_bpermute_b32 v45, v29, v36
	s_waitcnt lgkmcnt(4)
	v_max_u32_e32 v30, v30, v46
	global_load_dwordx4 v[46:49], v[4:5], off offset:272
	global_load_dwordx4 v[50:53], v[4:5], off offset:256
	ds_bpermute_b32 v54, v29, v42
	ds_bpermute_b32 v55, v29, v32
	ds_bpermute_b32 v56, v29, v40
	ds_bpermute_b32 v57, v29, v2
	ds_bpermute_b32 v58, v29, v33
	ds_bpermute_b32 v59, v29, v39
	ds_bpermute_b32 v60, v29, v41
	ds_bpermute_b32 v61, v29, v31
	ds_bpermute_b32 v62, v29, v35
	ds_bpermute_b32 v63, v29, v38
	ds_bpermute_b32 v64, v29, v34
	s_waitcnt lgkmcnt(4)
	v_max_u32_e32 v32, v32, v60
	s_waitcnt lgkmcnt(3)
	v_max_u32_e32 v42, v42, v61
	s_waitcnt lgkmcnt(2)
	v_max_u32_e32 v36, v36, v62
	s_waitcnt lgkmcnt(1)
	v_max_u32_e32 v3, v3, v63
	s_waitcnt lgkmcnt(0)
	v_max_u32_e32 v37, v37, v64
	v_max_u32_e32 v40, v40, v59
	v_max_u32_e32 v2, v2, v58
	v_max_u32_e32 v33, v33, v57
	v_max_u32_e32 v39, v39, v56
	v_max_u32_e32 v41, v41, v55
	v_max_u32_e32 v31, v31, v54
	v_max_u32_e32 v35, v35, v45
	v_max_u32_e32 v34, v34, v44
	v_max_u32_e32 v38, v38, v43
	v_max_u32_e32 v0, v0, v1
	v_max_u32_e32 v1, v30, v33
	v_min_u32_e32 v30, v30, v33
	v_max_u32_e32 v33, v3, v39
	v_min_u32_e32 v3, v3, v39
	v_max_u32_e32 v39, v37, v41
	v_min_u32_e32 v37, v37, v41
	v_max_u32_e32 v41, v36, v31
	v_min_u32_e32 v31, v36, v31
	v_max_u32_e32 v36, v42, v35
	v_min_u32_e32 v35, v42, v35
	v_max_u32_e32 v42, v32, v34
	v_min_u32_e32 v32, v32, v34
	v_max_u32_e32 v34, v40, v38
	v_min_u32_e32 v38, v40, v38
	v_max_u32_e32 v40, v2, v0
	v_min_u32_e32 v0, v2, v0
	v_max_u32_e32 v2, v1, v36
	v_min_u32_e32 v1, v1, v36
	v_max_u32_e32 v36, v33, v42
	v_min_u32_e32 v33, v33, v42
	v_max_u32_e32 v42, v39, v34
	v_min_u32_e32 v34, v39, v34
	v_max_u32_e32 v39, v41, v40
	v_min_u32_e32 v40, v41, v40
	v_max_u32_e32 v41, v30, v35
	v_min_u32_e32 v30, v30, v35
	v_max_u32_e32 v35, v3, v32
	v_min_u32_e32 v3, v3, v32
	v_max_u32_e32 v32, v37, v38
	v_min_u32_e32 v37, v37, v38
	v_max_u32_e32 v38, v31, v0
	v_min_u32_e32 v0, v31, v0
	v_max_u32_e32 v31, v2, v42
	v_min_u32_e32 v2, v2, v42
	v_max_u32_e32 v42, v36, v39
	v_min_u32_e32 v36, v36, v39
	v_max_u32_e32 v39, v1, v34
	v_min_u32_e32 v1, v1, v34
	v_max_u32_e32 v34, v33, v40
	v_min_u32_e32 v33, v33, v40
	v_max_u32_e32 v54, v41, v32
	v_min_u32_e32 v32, v41, v32
	v_max_u32_e32 v55, v35, v38
	v_min_u32_e32 v56, v35, v38
	v_max_u32_e32 v57, v30, v37
	v_min_u32_e32 v30, v30, v37
	v_max_u32_e32 v58, v3, v0
	v_min_u32_e32 v0, v3, v0
	v_max_u32_e32 v45, v31, v42
	v_min_u32_e32 v44, v31, v42
	v_max_u32_e32 v43, v2, v36
	v_min_u32_e32 v42, v2, v36
	v_max_u32_e32 v41, v39, v34
	v_min_u32_e32 v40, v39, v34
	v_max_u32_e32 v39, v1, v33
	v_min_u32_e32 v38, v1, v33
	v_max_u32_e32 v37, v54, v55
	v_min_u32_e32 v36, v54, v55
	v_max_u32_e32 v35, v32, v56
	v_min_u32_e32 v34, v32, v56
	v_max_u32_e32 v33, v57, v58
	v_min_u32_e32 v32, v57, v58
	v_max_u32_e32 v31, v30, v0
	v_min_u32_e32 v30, v30, v0
	global_load_dwordx4 v[0:3], v[4:5], off offset:304
	global_load_dwordx4 v[54:57], v[4:5], off offset:288
	s_waitcnt vmcnt(2)
; __device__ __forceinline__ unsigned f2key(float f) { const unsigned u = __float_as_uint(f); return (u & 0x80000000u) ? ~u : (u | 0x80000000u); }
; __device__ __forceinline__ void peer_tile(const Args& A, LAS unsigned char* lds, int tile) {
;     ...
;                   for (int i = 0; i < 16; ++i) {
;                       const float lo = (float)__builtin_bit_cast(_Float16, (unsigned short)(sw[i] & 0xffffu)), hi = (float)__builtin_bit_cast(_Float16, (unsigned short)(sw[i] >> 16));
;                       const unsigned klo = (f2key(lo) & ~127u) | (unsigned)(127 - (32 * g + 2 * i)), khi = (f2key(hi) & ~127u) | (unsigned)(127 - (32 * g + 2 * i + 1));
;                       if (i < 8) { k0[2 * i] = klo; k0[2 * i + 1] = khi; } else { k1[2 * (i - 8)] = klo; k1[2 * (i - 8) + 1] = khi; } } }
	v_cvt_f32_f16_sdwa v58, v50 dst_sel:DWORD dst_unused:UNUSED_PAD src0_sel:WORD_1
	v_cvt_f32_f16_e32 v50, v50
	v_not_b32_e32 v59, v58
	v_or_b32_e32 v60, 0x80000000, v58
	v_cmp_gt_i32_e32 vcc, 0, v58
	s_nop 1
	v_cndmask_b32_e32 v58, v60, v59, vcc
	v_not_b32_e32 v59, v50
	v_or_b32_e32 v60, 0x80000000, v50
	v_cmp_gt_i32_e32 vcc, 0, v50
	v_and_b32_e32 v58, 0xffffff80, v58
	v_sub_u32_e32 v58, v58, v15
	v_cndmask_b32_e32 v50, v60, v59, vcc
	v_cvt_f32_f16_sdwa v59, v51 dst_sel:DWORD dst_unused:UNUSED_PAD src0_sel:WORD_1
	v_cvt_f32_f16_e32 v51, v51
	v_and_b32_e32 v50, 0xffffff80, v50
	v_sub_u32_e32 v50, v50, v15
	v_not_b32_e32 v60, v59
	v_or_b32_e32 v61, 0x80000000, v59
	v_cmp_gt_i32_e32 vcc, 0, v59
	v_add_u32_e32 v58, 0x7e, v58
	v_add_u32_e32 v50, 0x7f, v50
	v_cndmask_b32_e32 v59, v61, v60, vcc
	v_not_b32_e32 v60, v51
	v_or_b32_e32 v61, 0x80000000, v51
	v_cmp_gt_i32_e32 vcc, 0, v51
	v_and_b32_e32 v59, 0xffffff80, v59
	v_sub_u32_e32 v59, v59, v14
	v_cndmask_b32_e32 v51, v61, v60, vcc
	v_cvt_f32_f16_sdwa v60, v52 dst_sel:DWORD dst_unused:UNUSED_PAD src0_sel:WORD_1
	v_cvt_f32_f16_e32 v52, v52
	v_and_b32_e32 v51, 0xffffff80, v51
	v_sub_u32_e32 v51, v51, v14
	v_not_b32_e32 v61, v60
	v_or_b32_e32 v62, 0x80000000, v60
	v_cmp_gt_i32_e32 vcc, 0, v60
	v_add_u32_e32 v59, 0x7e, v59
	v_add_u32_e32 v51, 0x7f, v51
	v_cndmask_b32_e32 v60, v62, v61, vcc
	v_not_b32_e32 v61, v52
	v_or_b32_e32 v62, 0x80000000, v52
	v_cmp_gt_i32_e32 vcc, 0, v52
	v_and_b32_e32 v60, 0xffffff80, v60
	v_sub_u32_e32 v60, v60, v12
	v_cndmask_b32_e32 v52, v62, v61, vcc
	v_cvt_f32_f16_sdwa v61, v53 dst_sel:DWORD dst_unused:UNUSED_PAD src0_sel:WORD_1
	v_cvt_f32_f16_e32 v53, v53
	v_and_b32_e32 v52, 0xffffff80, v52
	v_sub_u32_e32 v52, v52, v12
	v_not_b32_e32 v62, v61
	v_or_b32_e32 v63, 0x80000000, v61
	v_cmp_gt_i32_e32 vcc, 0, v61
	v_add_u32_e32 v60, 0x7e, v60
	v_add_u32_e32 v52, 0x7f, v52
	v_cndmask_b32_e32 v61, v63, v62, vcc
	v_not_b32_e32 v62, v53
	v_or_b32_e32 v63, 0x80000000, v53
	v_cmp_gt_i32_e32 vcc, 0, v53
	v_and_b32_e32 v61, 0xffffff80, v61
	v_sub_u32_e32 v61, v61, v10
	v_cndmask_b32_e32 v53, v63, v62, vcc
	v_cvt_f32_f16_sdwa v62, v46 dst_sel:DWORD dst_unused:UNUSED_PAD src0_sel:WORD_1
	v_cvt_f32_f16_e32 v46, v46
	v_and_b32_e32 v53, 0xffffff80, v53
	v_sub_u32_e32 v53, v53, v10
	v_not_b32_e32 v63, v62
	v_or_b32_e32 v64, 0x80000000, v62
	v_cmp_gt_i32_e32 vcc, 0, v62
	v_add_u32_e32 v61, 0x7e, v61
	v_add_u32_e32 v53, 0x7f, v53
	v_cndmask_b32_e32 v62, v64, v63, vcc
	v_not_b32_e32 v63, v46
	v_or_b32_e32 v64, 0x80000000, v46
	v_cmp_gt_i32_e32 vcc, 0, v46
	v_and_b32_e32 v62, 0xffffff80, v62
	v_sub_u32_e32 v62, v62, v8
	v_cndmask_b32_e32 v46, v64, v63, vcc
	v_cvt_f32_f16_sdwa v63, v47 dst_sel:DWORD dst_unused:UNUSED_PAD src0_sel:WORD_1
	v_cvt_f32_f16_e32 v47, v47
	v_and_b32_e32 v46, 0xffffff80, v46
	v_sub_u32_e32 v46, v46, v8
	v_not_b32_e32 v64, v63
	v_or_b32_e32 v65, 0x80000000, v63
	v_cmp_gt_i32_e32 vcc, 0, v63
	v_add_u32_e32 v62, 0x7e, v62
	v_add_u32_e32 v46, 0x7f, v46
	v_cndmask_b32_e32 v63, v65, v64, vcc
	v_not_b32_e32 v64, v47
	v_or_b32_e32 v65, 0x80000000, v47
	v_cmp_gt_i32_e32 vcc, 0, v47
	v_and_b32_e32 v63, 0xffffff80, v63
	v_sub_u32_e32 v63, v63, v16
	v_cndmask_b32_e32 v47, v65, v64, vcc
	v_cvt_f32_f16_sdwa v64, v48 dst_sel:DWORD dst_unused:UNUSED_PAD src0_sel:WORD_1
	v_cvt_f32_f16_e32 v48, v48
	v_and_b32_e32 v47, 0xffffff80, v47
	v_sub_u32_e32 v47, v47, v16
	v_not_b32_e32 v65, v64
	v_or_b32_e32 v66, 0x80000000, v64
	v_cmp_gt_i32_e32 vcc, 0, v64
	v_add_u32_e32 v63, 0x7e, v63
	v_add_u32_e32 v47, 0x7f, v47
	v_cndmask_b32_e32 v64, v66, v65, vcc
	v_not_b32_e32 v65, v48
	v_or_b32_e32 v66, 0x80000000, v48
	v_cmp_gt_i32_e32 vcc, 0, v48
	v_and_b32_e32 v64, 0xffffff80, v64
	v_sub_u32_e32 v64, v64, v17
	v_cndmask_b32_e32 v48, v66, v65, vcc
	v_cvt_f32_f16_sdwa v65, v49 dst_sel:DWORD dst_unused:UNUSED_PAD src0_sel:WORD_1
	v_cvt_f32_f16_e32 v49, v49
	v_and_b32_e32 v48, 0xffffff80, v48
	v_sub_u32_e32 v48, v48, v17
	v_not_b32_e32 v66, v65
	v_or_b32_e32 v67, 0x80000000, v65
	v_cmp_gt_i32_e32 vcc, 0, v65
	v_add_u32_e32 v64, 0x7e, v64
	v_add_u32_e32 v48, 0x7f, v48
	v_cndmask_b32_e32 v65, v67, v66, vcc
	v_not_b32_e32 v66, v49
	v_or_b32_e32 v67, 0x80000000, v49
	v_cmp_gt_i32_e32 vcc, 0, v49
	v_and_b32_e32 v65, 0xffffff80, v65
	v_sub_u32_e32 v65, v65, v18
	v_cndmask_b32_e32 v49, v67, v66, vcc
	s_waitcnt vmcnt(0)
; __device__ __forceinline__ unsigned f2key(float f) { const unsigned u = __float_as_uint(f); return (u & 0x80000000u) ? ~u : (u | 0x80000000u); }
; #define CE_DESC(a, b) do { const unsigned _mx = (a) > (b) ? (a) : (b), _mn = (a) > (b) ? (b) : (a); (a) = _mx; (b) = _mn; } while (0)
; __device__ __forceinline__ void sort16_desc(unsigned (&k)[16]) {
; #pragma unroll
;     for (int size = 2; size <= 16; size <<= 1)
; #pragma unroll
;         for (int stride = size >> 1; stride > 0; stride >>= 1)
; #pragma unroll
;             for (int i = 0; i < 16; ++i) { const int j = i ^ stride;
;                 if (j > i) { if ((i & size) == 0) CE_DESC(k[i], k[j]); else CE_DESC(k[j], k[i]); } }
; }
; __device__ __forceinline__ void peer_tile(const Args& A, LAS unsigned char* lds, int tile) {
;     ...
;                   for (int i = 0; i < 16; ++i) {
;                       const float lo = (float)__builtin_bit_cast(_Float16, (unsigned short)(sw[i] & 0xffffu)), hi = (float)__builtin_bit_cast(_Float16, (unsigned short)(sw[i] >> 16));
;                       const unsigned klo = (f2key(lo) & ~127u) | (unsigned)(127 - (32 * g + 2 * i)), khi = (f2key(hi) & ~127u) | (unsigned)(127 - (32 * g + 2 * i + 1));
;                       if (i < 8) { k0[2 * i] = klo; k0[2 * i + 1] = khi; } else { k1[2 * (i - 8)] = klo; k1[2 * (i - 8) + 1] = khi; } } }
	v_cvt_f32_f16_sdwa v66, v54 dst_sel:DWORD dst_unused:UNUSED_PAD src0_sel:WORD_1
	v_cvt_f32_f16_e32 v54, v54
	v_and_b32_e32 v49, 0xffffff80, v49
	v_sub_u32_e32 v49, v49, v18
	v_not_b32_e32 v67, v66
	v_or_b32_e32 v68, 0x80000000, v66
	v_cmp_gt_i32_e32 vcc, 0, v66
	v_add_u32_e32 v65, 0x7e, v65
	v_add_u32_e32 v49, 0x7f, v49
	v_cndmask_b32_e32 v66, v68, v67, vcc
	v_not_b32_e32 v67, v54
	v_or_b32_e32 v68, 0x80000000, v54
	v_cmp_gt_i32_e32 vcc, 0, v54
	v_and_b32_e32 v66, 0xffffff80, v66
	v_sub_u32_e32 v66, v66, v20
	v_cndmask_b32_e32 v54, v68, v67, vcc
	v_cvt_f32_f16_sdwa v67, v55 dst_sel:DWORD dst_unused:UNUSED_PAD src0_sel:WORD_1
	v_cvt_f32_f16_e32 v55, v55
	v_and_b32_e32 v54, 0xffffff80, v54
	v_sub_u32_e32 v54, v54, v20
	v_not_b32_e32 v68, v67
	v_or_b32_e32 v69, 0x80000000, v67
	v_cmp_gt_i32_e32 vcc, 0, v67
	v_add_u32_e32 v66, 0x7e, v66
	v_add_u32_e32 v54, 0x7f, v54
	v_cndmask_b32_e32 v67, v69, v68, vcc
	v_not_b32_e32 v68, v55
	v_or_b32_e32 v69, 0x80000000, v55
	v_cmp_gt_i32_e32 vcc, 0, v55
	v_and_b32_e32 v67, 0xffffff80, v67
	v_sub_u32_e32 v67, v67, v21
	v_cndmask_b32_e32 v55, v69, v68, vcc
	v_cvt_f32_f16_sdwa v68, v56 dst_sel:DWORD dst_unused:UNUSED_PAD src0_sel:WORD_1
	v_cvt_f32_f16_e32 v56, v56
	v_and_b32_e32 v55, 0xffffff80, v55
	v_sub_u32_e32 v55, v55, v21
	v_not_b32_e32 v69, v68
	v_or_b32_e32 v70, 0x80000000, v68
	v_cmp_gt_i32_e32 vcc, 0, v68
	v_add_u32_e32 v67, 0x7e, v67
	v_add_u32_e32 v55, 0x7f, v55
	v_cndmask_b32_e32 v68, v70, v69, vcc
	v_not_b32_e32 v69, v56
	v_or_b32_e32 v70, 0x80000000, v56
	v_cmp_gt_i32_e32 vcc, 0, v56
	v_and_b32_e32 v68, 0xffffff80, v68
	v_sub_u32_e32 v68, v68, v22
	v_cndmask_b32_e32 v56, v70, v69, vcc
	v_cvt_f32_f16_sdwa v69, v57 dst_sel:DWORD dst_unused:UNUSED_PAD src0_sel:WORD_1
	v_cvt_f32_f16_e32 v57, v57
	v_and_b32_e32 v56, 0xffffff80, v56
	v_sub_u32_e32 v56, v56, v22
	v_not_b32_e32 v70, v69
	v_or_b32_e32 v71, 0x80000000, v69
	v_cmp_gt_i32_e32 vcc, 0, v69
	v_add_u32_e32 v68, 0x7e, v68
	v_add_u32_e32 v56, 0x7f, v56
	v_cndmask_b32_e32 v69, v71, v70, vcc
	v_not_b32_e32 v70, v57
	v_or_b32_e32 v71, 0x80000000, v57
	v_cmp_gt_i32_e32 vcc, 0, v57
	v_and_b32_e32 v69, 0xffffff80, v69
	v_sub_u32_e32 v69, v69, v23
	v_cndmask_b32_e32 v57, v71, v70, vcc
	v_cvt_f32_f16_sdwa v70, v0 dst_sel:DWORD dst_unused:UNUSED_PAD src0_sel:WORD_1
	v_cvt_f32_f16_e32 v0, v0
	v_and_b32_e32 v57, 0xffffff80, v57
	v_sub_u32_e32 v57, v57, v23
	v_not_b32_e32 v71, v70
	v_or_b32_e32 v72, 0x80000000, v70
	v_cmp_gt_i32_e32 vcc, 0, v70
	v_add_u32_e32 v69, 0x7e, v69
	v_add_u32_e32 v57, 0x7f, v57
	v_cndmask_b32_e32 v70, v72, v71, vcc
	v_not_b32_e32 v71, v0
	v_or_b32_e32 v72, 0x80000000, v0
	v_cmp_gt_i32_e32 vcc, 0, v0
	v_and_b32_e32 v70, 0xffffff80, v70
	v_sub_u32_e32 v70, v70, v24
	v_cndmask_b32_e32 v0, v72, v71, vcc
	v_cvt_f32_f16_sdwa v71, v1 dst_sel:DWORD dst_unused:UNUSED_PAD src0_sel:WORD_1
	v_cvt_f32_f16_e32 v1, v1
	v_and_b32_e32 v0, 0xffffff80, v0
	v_sub_u32_e32 v0, v0, v24
	v_not_b32_e32 v72, v71
	v_or_b32_e32 v73, 0x80000000, v71
	v_cmp_gt_i32_e32 vcc, 0, v71
	v_add_u32_e32 v70, 0x7e, v70
	v_add_u32_e32 v0, 0x7f, v0
	v_cndmask_b32_e32 v71, v73, v72, vcc
	v_not_b32_e32 v72, v1
	v_or_b32_e32 v73, 0x80000000, v1
	v_cmp_gt_i32_e32 vcc, 0, v1
	v_and_b32_e32 v71, 0xffffff80, v71
	v_sub_u32_e32 v71, v71, v25
	v_cndmask_b32_e32 v1, v73, v72, vcc
	v_cvt_f32_f16_sdwa v72, v2 dst_sel:DWORD dst_unused:UNUSED_PAD src0_sel:WORD_1
	v_cvt_f32_f16_e32 v2, v2
	v_and_b32_e32 v1, 0xffffff80, v1
	v_sub_u32_e32 v1, v1, v25
	v_not_b32_e32 v73, v72
	v_or_b32_e32 v74, 0x80000000, v72
	v_cmp_gt_i32_e32 vcc, 0, v72
	v_add_u32_e32 v71, 0x7e, v71
	v_add_u32_e32 v1, 0x7f, v1
	v_cndmask_b32_e32 v72, v74, v73, vcc
	v_not_b32_e32 v73, v2
	v_or_b32_e32 v74, 0x80000000, v2
	v_cmp_gt_i32_e32 vcc, 0, v2
	v_and_b32_e32 v72, 0xffffff80, v72
	v_sub_u32_e32 v72, v72, v26
	v_cndmask_b32_e32 v2, v74, v73, vcc
	v_cvt_f32_f16_sdwa v73, v3 dst_sel:DWORD dst_unused:UNUSED_PAD src0_sel:WORD_1
	v_cvt_f32_f16_e32 v3, v3
	v_and_b32_e32 v2, 0xffffff80, v2
	v_sub_u32_e32 v2, v2, v26
	v_not_b32_e32 v74, v73
	v_or_b32_e32 v75, 0x80000000, v73
	v_cmp_gt_i32_e32 vcc, 0, v73
	v_add_u32_e32 v72, 0x7e, v72
	v_add_u32_e32 v2, 0x7f, v2
	v_cndmask_b32_e32 v73, v75, v74, vcc
	v_not_b32_e32 v74, v3
	v_or_b32_e32 v75, 0x80000000, v3
	v_cmp_gt_i32_e32 vcc, 0, v3
	v_and_b32_e32 v73, 0xffffff80, v73
	v_sub_u32_e32 v73, v73, v28
	v_cndmask_b32_e32 v3, v75, v74, vcc
	v_and_b32_e32 v3, 0xffffff80, v3
	v_sub_u32_e32 v3, v3, v28
	v_add_u32_e32 v73, 0x7e, v73
	v_add_u32_e32 v3, 0x7f, v3
	v_max_u32_e32 v74, v50, v58
	v_min_u32_e32 v50, v50, v58
	v_max_u32_e32 v58, v59, v51
	v_min_u32_e32 v51, v59, v51
	v_max_u32_e32 v59, v52, v60
	v_min_u32_e32 v52, v52, v60
	v_max_u32_e32 v60, v61, v53
	v_min_u32_e32 v53, v61, v53
	v_max_u32_e32 v61, v46, v62
	v_min_u32_e32 v46, v46, v62
	v_max_u32_e32 v62, v63, v47
	v_min_u32_e32 v47, v63, v47
	v_max_u32_e32 v63, v48, v64
	v_min_u32_e32 v48, v48, v64
	v_max_u32_e32 v64, v65, v49
	v_min_u32_e32 v49, v65, v49
	v_max_u32_e32 v82, v54, v66
	v_min_u32_e32 v54, v54, v66
	v_max_u32_e32 v66, v67, v55
	v_min_u32_e32 v55, v67, v55
	v_max_u32_e32 v67, v56, v68
	v_min_u32_e32 v56, v56, v68
	v_max_u32_e32 v68, v69, v57
	v_min_u32_e32 v57, v69, v57
	v_max_u32_e32 v69, v0, v70
	v_min_u32_e32 v0, v0, v70
	v_max_u32_e32 v70, v71, v1
	v_min_u32_e32 v1, v71, v1
	v_max_u32_e32 v71, v2, v72
	v_min_u32_e32 v2, v2, v72
	v_max_u32_e32 v72, v73, v3
	v_min_u32_e32 v3, v73, v3
	v_max_u32_e32 v65, v74, v51
	v_min_u32_e32 v51, v74, v51
	v_max_u32_e32 v74, v50, v58
	v_min_u32_e32 v50, v50, v58
	v_max_u32_e32 v58, v53, v59
	v_min_u32_e32 v53, v53, v59
	v_max_u32_e32 v59, v60, v52
	v_min_u32_e32 v52, v60, v52
; #define CE_DESC(a, b) do { const unsigned _mx = (a) > (b) ? (a) : (b), _mn = (a) > (b) ? (b) : (a); (a) = _mx; (b) = _mn; } while (0)
; __device__ __forceinline__ void sort16_desc(unsigned (&k)[16]) {
; #pragma unroll
;     for (int size = 2; size <= 16; size <<= 1)
; #pragma unroll
;         for (int stride = size >> 1; stride > 0; stride >>= 1)
; #pragma unroll
;             for (int i = 0; i < 16; ++i) { const int j = i ^ stride;
;                 if (j > i) { if ((i & size) == 0) CE_DESC(k[i], k[j]); else CE_DESC(k[j], k[i]); } }
; }
	v_max_u32_e32 v60, v61, v47
	v_min_u32_e32 v47, v61, v47
	v_max_u32_e32 v61, v46, v62
	v_min_u32_e32 v46, v46, v62
	v_max_u32_e32 v62, v49, v63
	v_min_u32_e32 v49, v49, v63
	v_max_u32_e32 v63, v64, v48
	v_min_u32_e32 v48, v64, v48
	v_max_u32_e32 v73, v82, v55
	v_min_u32_e32 v55, v82, v55
	v_max_u32_e32 v82, v54, v66
	v_min_u32_e32 v54, v54, v66
	v_max_u32_e32 v66, v57, v67
	v_min_u32_e32 v57, v57, v67
	v_max_u32_e32 v67, v68, v56
	v_min_u32_e32 v56, v68, v56
	v_max_u32_e32 v68, v69, v1
	v_min_u32_e32 v1, v69, v1
	v_max_u32_e32 v69, v0, v70
	v_min_u32_e32 v0, v0, v70
	v_max_u32_e32 v70, v3, v71
	v_min_u32_e32 v3, v3, v71
	v_max_u32_e32 v71, v72, v2
	v_min_u32_e32 v2, v72, v2
	v_max_u32_e32 v64, v65, v74
	v_min_u32_e32 v65, v65, v74
	v_max_u32_e32 v74, v51, v50
	v_min_u32_e32 v50, v51, v50
	v_max_u32_e32 v51, v52, v53
	v_min_u32_e32 v52, v52, v53
	v_max_u32_e32 v53, v59, v58
	v_min_u32_e32 v58, v59, v58
	v_max_u32_e32 v59, v60, v61
	v_min_u32_e32 v60, v60, v61
	v_max_u32_e32 v61, v47, v46
	v_min_u32_e32 v46, v47, v46
	v_max_u32_e32 v47, v48, v49
	v_min_u32_e32 v48, v48, v49
	v_max_u32_e32 v49, v63, v62
	v_min_u32_e32 v62, v63, v62
	v_max_u32_e32 v72, v73, v82
	v_min_u32_e32 v73, v73, v82
	v_max_u32_e32 v82, v55, v54
	v_min_u32_e32 v54, v55, v54
	v_max_u32_e32 v55, v56, v57
	v_min_u32_e32 v56, v56, v57
	v_max_u32_e32 v57, v67, v66
	v_min_u32_e32 v66, v67, v66
	v_max_u32_e32 v67, v68, v69
	v_min_u32_e32 v68, v68, v69
	v_max_u32_e32 v69, v1, v0
	v_min_u32_e32 v0, v1, v0
	v_max_u32_e32 v1, v2, v3
	v_min_u32_e32 v2, v2, v3
	v_max_u32_e32 v3, v71, v70
	v_min_u32_e32 v70, v71, v70
	v_max_u32_e32 v63, v64, v52
	v_min_u32_e32 v52, v64, v52
	v_max_u32_e32 v64, v65, v51
	v_min_u32_e32 v51, v65, v51
	v_max_u32_e32 v65, v74, v58
	v_min_u32_e32 v58, v74, v58
	v_max_u32_e32 v74, v50, v53
	v_min_u32_e32 v50, v50, v53
	v_max_u32_e32 v53, v48, v59
	v_min_u32_e32 v48, v48, v59
	v_max_u32_e32 v59, v47, v60
	v_min_u32_e32 v47, v47, v60
	v_max_u32_e32 v60, v62, v61
	v_min_u32_e32 v61, v62, v61
	v_max_u32_e32 v62, v49, v46
	v_min_u32_e32 v46, v49, v46
	v_max_u32_e32 v71, v72, v56
	v_min_u32_e32 v56, v72, v56
	v_max_u32_e32 v72, v73, v55
	v_min_u32_e32 v55, v73, v55
	v_max_u32_e32 v73, v82, v66
	v_min_u32_e32 v66, v82, v66
	v_max_u32_e32 v82, v54, v57
	v_min_u32_e32 v54, v54, v57
	v_max_u32_e32 v57, v2, v67
	v_min_u32_e32 v2, v2, v67
	v_max_u32_e32 v67, v1, v68
	v_min_u32_e32 v1, v1, v68
	v_max_u32_e32 v68, v70, v69
	v_min_u32_e32 v69, v70, v69
	v_max_u32_e32 v70, v3, v0
	v_min_u32_e32 v0, v3, v0
	v_max_u32_e32 v49, v63, v65
	v_min_u32_e32 v63, v63, v65
	v_max_u32_e32 v65, v64, v74
	v_min_u32_e32 v64, v64, v74
	v_max_u32_e32 v74, v52, v58
	v_min_u32_e32 v52, v52, v58
	v_max_u32_e32 v58, v51, v50
	v_min_u32_e32 v50, v51, v50
	v_max_u32_e32 v51, v61, v48
	v_min_u32_e32 v48, v61, v48
	v_max_u32_e32 v61, v46, v47
	v_min_u32_e32 v46, v46, v47
	v_max_u32_e32 v47, v60, v53
	v_min_u32_e32 v53, v60, v53
	v_max_u32_e32 v60, v62, v59
	v_min_u32_e32 v59, v62, v59
	v_max_u32_e32 v3, v71, v73
	v_min_u32_e32 v71, v71, v73
	v_max_u32_e32 v73, v72, v82
	v_min_u32_e32 v72, v72, v82
	v_max_u32_e32 v82, v56, v66
	v_min_u32_e32 v56, v56, v66
	v_max_u32_e32 v66, v55, v54
	v_min_u32_e32 v54, v55, v54
	v_max_u32_e32 v55, v69, v2
	v_min_u32_e32 v2, v69, v2
	v_max_u32_e32 v69, v0, v1
	v_min_u32_e32 v0, v0, v1
	v_max_u32_e32 v1, v68, v57
	v_min_u32_e32 v57, v68, v57
	v_max_u32_e32 v68, v70, v67
	v_min_u32_e32 v67, v70, v67
	v_max_u32_e32 v62, v49, v65
	v_min_u32_e32 v49, v49, v65
	v_max_u32_e32 v65, v63, v64
	v_min_u32_e32 v63, v63, v64
	v_max_u32_e32 v64, v74, v58
	v_min_u32_e32 v58, v74, v58
	v_max_u32_e32 v74, v52, v50
	v_min_u32_e32 v50, v52, v50
	v_max_u32_e32 v52, v46, v48
	v_min_u32_e32 v46, v46, v48
	v_max_u32_e32 v48, v61, v51
	v_min_u32_e32 v51, v61, v51
	v_max_u32_e32 v61, v59, v53
	v_min_u32_e32 v53, v59, v53
	v_max_u32_e32 v59, v60, v47
	v_min_u32_e32 v47, v60, v47
	v_max_u32_e32 v70, v3, v73
	v_min_u32_e32 v3, v3, v73
	v_max_u32_e32 v73, v71, v72
	v_min_u32_e32 v71, v71, v72
	v_max_u32_e32 v72, v82, v66
	v_min_u32_e32 v66, v82, v66
	v_max_u32_e32 v82, v56, v54
	v_min_u32_e32 v54, v56, v54
	v_max_u32_e32 v56, v0, v2
	v_min_u32_e32 v0, v0, v2
	v_max_u32_e32 v2, v69, v55
	v_min_u32_e32 v55, v69, v55
	v_max_u32_e32 v69, v67, v57
	v_min_u32_e32 v57, v67, v57
	v_max_u32_e32 v67, v68, v1
	v_min_u32_e32 v1, v68, v1
	v_max_u32_e32 v60, v62, v46
	v_min_u32_e32 v46, v62, v46
	v_max_u32_e32 v62, v49, v52
	v_min_u32_e32 v49, v49, v52
	v_max_u32_e32 v52, v65, v51
	v_min_u32_e32 v51, v65, v51
	v_max_u32_e32 v65, v63, v48
	v_min_u32_e32 v48, v63, v48
	v_max_u32_e32 v63, v64, v53
	v_min_u32_e32 v53, v64, v53
	v_max_u32_e32 v64, v58, v61
	v_min_u32_e32 v58, v58, v61
	v_max_u32_e32 v61, v74, v47
	v_min_u32_e32 v47, v74, v47
	v_max_u32_e32 v74, v50, v59
	v_min_u32_e32 v50, v50, v59
	v_max_u32_e32 v68, v70, v0
	v_min_u32_e32 v0, v70, v0
	v_max_u32_e32 v70, v3, v56
	v_min_u32_e32 v3, v3, v56
	v_max_u32_e32 v56, v73, v55
	v_min_u32_e32 v55, v73, v55
	v_max_u32_e32 v73, v71, v2
	v_min_u32_e32 v2, v71, v2
	v_max_u32_e32 v71, v72, v57
	v_min_u32_e32 v57, v72, v57
	v_max_u32_e32 v72, v66, v69
	v_min_u32_e32 v66, v66, v69
	v_max_u32_e32 v69, v82, v1
	v_min_u32_e32 v1, v82, v1
	v_max_u32_e32 v82, v54, v67
	v_min_u32_e32 v54, v54, v67
	v_max_u32_e32 v59, v60, v63
	v_min_u32_e32 v60, v60, v63
	v_max_u32_e32 v63, v62, v64
	v_min_u32_e32 v62, v62, v64
	v_max_u32_e32 v64, v52, v61
	v_min_u32_e32 v52, v52, v61
	v_max_u32_e32 v61, v65, v74
	v_min_u32_e32 v65, v65, v74
	v_max_u32_e32 v74, v46, v53
	v_min_u32_e32 v46, v46, v53
	v_max_u32_e32 v53, v49, v58
	v_min_u32_e32 v49, v49, v58
	v_max_u32_e32 v58, v51, v47
; #define CE_DESC(a, b) do { const unsigned _mx = (a) > (b) ? (a) : (b), _mn = (a) > (b) ? (b) : (a); (a) = _mx; (b) = _mn; } while (0)
; __device__ __forceinline__ void merge16(unsigned (&a)[16], const unsigned (&b)[16]) {
; #pragma unroll
;     for (int i = 0; i < 16; ++i) a[i] = a[i] > b[15 - i] ? a[i] : b[15 - i];
; #pragma unroll
;     for (int stride = 8; stride > 0; stride >>= 1)
; #pragma unroll
;         for (int i = 0; i < 16; ++i) { const int j = i ^ stride; if (j > i) CE_DESC(a[i], a[j]); }
; }
; __device__ __forceinline__ void peer_tile(const Args& A, LAS unsigned char* lds, int tile) {
;     ...
;                 for (int msk = 16; msk <= 32; msk <<= 1) {
; #pragma unroll
;                     for (int i = 0; i < 16; ++i) k1[i] = (unsigned)__shfl_xor((int)k0[i], msk);
;                     merge16(k0, k1); }
	v_min_u32_e32 v47, v51, v47
	v_max_u32_e32 v51, v48, v50
	v_min_u32_e32 v48, v48, v50
	v_max_u32_e32 v67, v68, v71
	v_min_u32_e32 v68, v68, v71
	v_max_u32_e32 v71, v70, v72
	v_min_u32_e32 v70, v70, v72
	v_max_u32_e32 v72, v56, v69
	v_min_u32_e32 v56, v56, v69
	v_max_u32_e32 v69, v73, v82
	v_min_u32_e32 v73, v73, v82
	v_max_u32_e32 v82, v0, v57
	v_min_u32_e32 v0, v0, v57
	v_max_u32_e32 v57, v3, v66
	v_min_u32_e32 v3, v3, v66
	v_max_u32_e32 v66, v55, v1
	v_min_u32_e32 v1, v55, v1
	v_max_u32_e32 v55, v2, v54
	v_min_u32_e32 v2, v2, v54
	v_max_u32_e32 v50, v59, v64
	v_min_u32_e32 v59, v59, v64
	v_max_u32_e32 v64, v63, v61
	v_min_u32_e32 v61, v63, v61
	v_max_u32_e32 v63, v60, v52
	v_min_u32_e32 v52, v60, v52
	v_max_u32_e32 v60, v62, v65
	v_min_u32_e32 v62, v62, v65
	v_max_u32_e32 v65, v74, v58
	v_min_u32_e32 v58, v74, v58
	v_max_u32_e32 v74, v53, v51
	v_min_u32_e32 v51, v53, v51
	v_max_u32_e32 v53, v46, v47
	v_min_u32_e32 v46, v46, v47
	v_max_u32_e32 v47, v49, v48
	v_min_u32_e32 v48, v49, v48
	v_max_u32_e32 v54, v67, v72
	v_min_u32_e32 v67, v67, v72
	v_max_u32_e32 v72, v71, v69
	v_min_u32_e32 v69, v71, v69
	v_max_u32_e32 v71, v68, v56
	v_min_u32_e32 v56, v68, v56
	v_max_u32_e32 v68, v70, v73
	v_min_u32_e32 v70, v70, v73
	v_max_u32_e32 v73, v82, v66
	v_min_u32_e32 v66, v82, v66
	v_max_u32_e32 v82, v57, v55
	v_min_u32_e32 v55, v57, v55
	v_max_u32_e32 v57, v0, v1
	v_min_u32_e32 v0, v0, v1
	v_max_u32_e32 v1, v3, v2
	v_min_u32_e32 v2, v3, v2
	v_min_u32_e32 v49, v50, v64
	v_min_u32_e32 v75, v59, v61
	v_min_u32_e32 v76, v63, v60
	v_min_u32_e32 v77, v52, v62
	v_min_u32_e32 v78, v65, v74
	v_min_u32_e32 v79, v58, v51
	v_min_u32_e32 v80, v53, v47
	v_min_u32_e32 v81, v46, v48
	v_min_u32_e32 v3, v54, v72
	v_min_u32_e32 v83, v67, v69
	v_min_u32_e32 v84, v71, v68
	v_min_u32_e32 v85, v56, v70
	v_min_u32_e32 v86, v73, v82
	v_min_u32_e32 v87, v66, v55
	v_min_u32_e32 v88, v57, v1
	v_min_u32_e32 v89, v0, v2
	v_max3_u32 v50, v50, v64, v89
	v_max3_u32 v0, v49, v0, v2
	v_max3_u32 v2, v59, v61, v88
	v_max3_u32 v1, v75, v57, v1
	v_max3_u32 v49, v63, v60, v87
	v_max3_u32 v55, v76, v66, v55
	v_max3_u32 v52, v52, v62, v86
	v_max3_u32 v57, v77, v73, v82
	v_max3_u32 v59, v65, v74, v85
	v_max3_u32 v56, v78, v56, v70
	v_max3_u32 v51, v58, v51, v84
	v_max3_u32 v58, v79, v71, v68
	v_max3_u32 v47, v53, v47, v83
	v_max3_u32 v53, v80, v67, v69
	v_max3_u32 v3, v46, v48, v3
	v_max3_u32 v46, v81, v54, v72
	v_max_u32_e32 v48, v50, v59
	v_min_u32_e32 v50, v50, v59
	v_max_u32_e32 v54, v0, v56
	v_min_u32_e32 v0, v0, v56
	v_max_u32_e32 v56, v2, v51
	v_min_u32_e32 v2, v2, v51
	v_max_u32_e32 v51, v1, v58
	v_min_u32_e32 v1, v1, v58
	v_max_u32_e32 v58, v49, v47
	v_min_u32_e32 v47, v49, v47
	v_max_u32_e32 v49, v55, v53
	v_min_u32_e32 v53, v55, v53
	v_max_u32_e32 v55, v52, v3
	v_min_u32_e32 v3, v52, v3
	v_max_u32_e32 v52, v57, v46
	v_min_u32_e32 v46, v57, v46
	v_max_u32_e32 v57, v48, v58
	v_min_u32_e32 v48, v48, v58
	v_max_u32_e32 v58, v54, v49
	v_min_u32_e32 v49, v54, v49
	v_max_u32_e32 v54, v56, v55
	v_min_u32_e32 v55, v56, v55
	v_max_u32_e32 v56, v51, v52
	v_min_u32_e32 v51, v51, v52
	v_max_u32_e32 v52, v50, v47
	v_min_u32_e32 v47, v50, v47
	v_max_u32_e32 v50, v0, v53
	v_min_u32_e32 v0, v0, v53
	v_max_u32_e32 v53, v2, v3
	v_min_u32_e32 v2, v2, v3
	v_max_u32_e32 v3, v1, v46
	v_min_u32_e32 v1, v1, v46
	v_max_u32_e32 v46, v57, v54
	v_min_u32_e32 v54, v57, v54
	v_max_u32_e32 v57, v58, v56
	v_min_u32_e32 v56, v58, v56
	v_max_u32_e32 v58, v48, v55
	v_min_u32_e32 v48, v48, v55
	v_max_u32_e32 v55, v49, v51
	v_min_u32_e32 v49, v49, v51
	v_max_u32_e32 v51, v52, v53
	v_min_u32_e32 v52, v52, v53
	v_max_u32_e32 v53, v50, v3
	v_min_u32_e32 v3, v50, v3
	v_max_u32_e32 v50, v47, v2
	v_min_u32_e32 v2, v47, v2
	v_max_u32_e32 v47, v0, v1
	v_min_u32_e32 v0, v0, v1
	v_max_u32_e32 v1, v46, v57
	v_min_u32_e32 v46, v46, v57
	v_max_u32_e32 v57, v54, v56
	v_min_u32_e32 v54, v54, v56
	v_max_u32_e32 v56, v58, v55
	v_min_u32_e32 v55, v58, v55
	v_max_u32_e32 v58, v48, v49
	v_min_u32_e32 v48, v48, v49
	v_max_u32_e32 v49, v51, v53
	v_min_u32_e32 v51, v51, v53
	v_max_u32_e32 v53, v52, v3
	v_min_u32_e32 v3, v52, v3
	v_max_u32_e32 v52, v50, v47
	v_min_u32_e32 v47, v50, v47
	v_max_u32_e32 v50, v2, v0
	v_min_u32_e32 v0, v2, v0
	ds_bpermute_b32 v2, v27, v1
	ds_bpermute_b32 v59, v27, v46
	ds_bpermute_b32 v60, v27, v57
	ds_bpermute_b32 v61, v27, v54
	ds_bpermute_b32 v62, v27, v56
	ds_bpermute_b32 v63, v27, v55
	ds_bpermute_b32 v64, v27, v58
	ds_bpermute_b32 v65, v27, v48
	ds_bpermute_b32 v66, v27, v49
	ds_bpermute_b32 v67, v27, v51
	ds_bpermute_b32 v68, v27, v53
	ds_bpermute_b32 v69, v27, v0
	ds_bpermute_b32 v70, v27, v50
	ds_bpermute_b32 v71, v27, v47
	ds_bpermute_b32 v72, v27, v52
	ds_bpermute_b32 v73, v27, v3
	s_waitcnt lgkmcnt(4)
	v_max_u32_e32 v1, v1, v69
	s_waitcnt lgkmcnt(3)
	v_max_u32_e32 v46, v46, v70
	s_waitcnt lgkmcnt(2)
	v_max_u32_e32 v57, v57, v71
	s_waitcnt lgkmcnt(1)
	v_max_u32_e32 v54, v54, v72
	s_waitcnt lgkmcnt(0)
; __device__ __forceinline__ void peer_tile(const Args& A, LAS unsigned char* lds, int tile) {
;     ...
;                 { const bf16_t* sp = QRY + m * 2048 + hp * 128 + 32 * g;
;                   const u32x4 s0 = *(const u32x4*)sp, s1 = *(const u32x4*)(sp + 8), s2 = *(const u32x4*)(sp + 16), s3 = *(const u32x4*)(sp + 24);
;     ...
;                 for (int msk = 16; msk <= 32; msk <<= 1) {
; #pragma unroll
;                     for (int i = 0; i < 16; ++i) k1[i] = (unsigned)__shfl_xor((int)k0[i], msk);
;                     merge16(k0, k1); }
; #pragma unroll
;                 for (int i = 0; i < 16; ++i) LA[hh][p][i] = k0[i];
	v_max_u32_e32 v56, v56, v73
	v_max_u32_e32 v55, v55, v68
	v_max_u32_e32 v58, v58, v67
	v_max_u32_e32 v48, v48, v66
	v_max_u32_e32 v49, v49, v65
	v_max_u32_e32 v51, v51, v64
	v_max_u32_e32 v53, v53, v63
	v_max_u32_e32 v3, v3, v62
	v_max_u32_e32 v52, v52, v61
	v_max_u32_e32 v47, v47, v60
	v_max_u32_e32 v50, v50, v59
	v_max_u32_e32 v0, v0, v2
	v_max_u32_e32 v2, v1, v49
	v_min_u32_e32 v1, v1, v49
	v_max_u32_e32 v49, v46, v51
	v_min_u32_e32 v46, v46, v51
	v_max_u32_e32 v51, v57, v53
	v_min_u32_e32 v53, v57, v53
	v_max_u32_e32 v57, v54, v3
	v_min_u32_e32 v3, v54, v3
	v_max_u32_e32 v54, v56, v52
	v_min_u32_e32 v52, v56, v52
	v_max_u32_e32 v56, v55, v47
	v_min_u32_e32 v47, v55, v47
	v_max_u32_e32 v55, v58, v50
	v_min_u32_e32 v50, v58, v50
	v_max_u32_e32 v58, v48, v0
	v_min_u32_e32 v0, v48, v0
	v_max_u32_e32 v48, v2, v54
	v_min_u32_e32 v2, v2, v54
	v_max_u32_e32 v54, v49, v56
	v_min_u32_e32 v49, v49, v56
	v_max_u32_e32 v56, v51, v55
	v_min_u32_e32 v51, v51, v55
	v_max_u32_e32 v55, v57, v58
	v_min_u32_e32 v57, v57, v58
	v_max_u32_e32 v58, v1, v52
	v_min_u32_e32 v1, v1, v52
	v_max_u32_e32 v52, v46, v47
	v_min_u32_e32 v46, v46, v47
	v_max_u32_e32 v47, v53, v50
	v_min_u32_e32 v50, v53, v50
	v_max_u32_e32 v53, v3, v0
	v_min_u32_e32 v0, v3, v0
	v_max_u32_e32 v3, v48, v56
	v_min_u32_e32 v48, v48, v56
	v_max_u32_e32 v56, v54, v55
	v_min_u32_e32 v54, v54, v55
	v_max_u32_e32 v55, v2, v51
	v_min_u32_e32 v2, v2, v51
	v_max_u32_e32 v51, v49, v57
	v_min_u32_e32 v49, v49, v57
	v_max_u32_e32 v57, v58, v47
	v_min_u32_e32 v47, v58, v47
	v_max_u32_e32 v58, v52, v53
	v_min_u32_e32 v52, v52, v53
	v_max_u32_e32 v53, v1, v50
	v_min_u32_e32 v1, v1, v50
	v_max_u32_e32 v50, v46, v0
	v_min_u32_e32 v0, v46, v0
	v_max_u32_e32 v46, v3, v56
	v_min_u32_e32 v3, v3, v56
	v_max_u32_e32 v56, v48, v54
	v_min_u32_e32 v48, v48, v54
	v_max_u32_e32 v54, v55, v51
	v_min_u32_e32 v51, v55, v51
	v_max_u32_e32 v55, v2, v49
	v_min_u32_e32 v2, v2, v49
	v_max_u32_e32 v49, v57, v58
	v_min_u32_e32 v57, v57, v58
	v_max_u32_e32 v58, v47, v52
	v_min_u32_e32 v47, v47, v52
	v_max_u32_e32 v52, v53, v50
	v_min_u32_e32 v50, v53, v50
	v_max_u32_e32 v53, v1, v0
	v_min_u32_e32 v0, v1, v0
	ds_bpermute_b32 v62, v29, v0
	ds_bpermute_b32 v1, v29, v46
	ds_bpermute_b32 v59, v29, v3
	ds_bpermute_b32 v60, v29, v56
	ds_bpermute_b32 v61, v29, v48
	s_waitcnt lgkmcnt(4)
	v_max_u32_e32 v46, v46, v62
	global_load_dwordx4 v[62:65], v[4:5], off offset:528
	global_load_dwordx4 v[66:69], v[4:5], off offset:512
	ds_bpermute_b32 v70, v29, v54
	ds_bpermute_b32 v71, v29, v51
	ds_bpermute_b32 v72, v29, v55
	ds_bpermute_b32 v73, v29, v2
	ds_bpermute_b32 v74, v29, v49
	ds_bpermute_b32 v75, v29, v57
	ds_bpermute_b32 v76, v29, v58
	ds_bpermute_b32 v77, v29, v47
	ds_bpermute_b32 v78, v29, v52
	ds_bpermute_b32 v79, v29, v53
	ds_bpermute_b32 v80, v29, v50
	s_waitcnt lgkmcnt(4)
	v_max_u32_e32 v51, v51, v76
	s_waitcnt lgkmcnt(3)
	v_max_u32_e32 v54, v54, v77
	s_waitcnt lgkmcnt(2)
	v_max_u32_e32 v48, v48, v78
	s_waitcnt lgkmcnt(1)
	v_max_u32_e32 v3, v3, v79
	s_waitcnt lgkmcnt(0)
	v_max_u32_e32 v56, v56, v80
	v_max_u32_e32 v55, v55, v75
	v_max_u32_e32 v2, v2, v74
	v_max_u32_e32 v49, v49, v73
	v_max_u32_e32 v57, v57, v72
	v_max_u32_e32 v58, v58, v71
	v_max_u32_e32 v47, v47, v70
	v_max_u32_e32 v52, v52, v61
	v_max_u32_e32 v50, v50, v60
	v_max_u32_e32 v53, v53, v59
	v_max_u32_e32 v0, v0, v1
	v_max_u32_e32 v1, v46, v49
	v_min_u32_e32 v46, v46, v49
	v_max_u32_e32 v49, v3, v57
	v_min_u32_e32 v3, v3, v57
	v_max_u32_e32 v57, v56, v58
	v_min_u32_e32 v56, v56, v58
	v_max_u32_e32 v58, v48, v47
	v_min_u32_e32 v47, v48, v47
	v_max_u32_e32 v48, v54, v52
	v_min_u32_e32 v52, v54, v52
	v_max_u32_e32 v54, v51, v50
	v_min_u32_e32 v50, v51, v50
	v_max_u32_e32 v51, v55, v53
	v_min_u32_e32 v53, v55, v53
	v_max_u32_e32 v55, v2, v0
	v_min_u32_e32 v0, v2, v0
	v_max_u32_e32 v2, v1, v48
	v_min_u32_e32 v1, v1, v48
	v_max_u32_e32 v48, v49, v54
	v_min_u32_e32 v49, v49, v54
	v_max_u32_e32 v54, v57, v51
	v_min_u32_e32 v51, v57, v51
	v_max_u32_e32 v57, v58, v55
	v_min_u32_e32 v55, v58, v55
	v_max_u32_e32 v58, v46, v52
	v_min_u32_e32 v46, v46, v52
	v_max_u32_e32 v52, v3, v50
	v_min_u32_e32 v3, v3, v50
	v_max_u32_e32 v50, v56, v53
	v_min_u32_e32 v53, v56, v53
	v_max_u32_e32 v56, v47, v0
	v_min_u32_e32 v0, v47, v0
	v_max_u32_e32 v47, v2, v54
	v_min_u32_e32 v2, v2, v54
	v_max_u32_e32 v54, v48, v57
	v_min_u32_e32 v48, v48, v57
	v_max_u32_e32 v70, v1, v51
	v_min_u32_e32 v1, v1, v51
	v_max_u32_e32 v51, v49, v55
	v_min_u32_e32 v49, v49, v55
	v_max_u32_e32 v71, v58, v50
	v_min_u32_e32 v50, v58, v50
	v_max_u32_e32 v72, v52, v56
	v_min_u32_e32 v73, v52, v56
	v_max_u32_e32 v74, v46, v53
	v_min_u32_e32 v46, v46, v53
	v_max_u32_e32 v75, v3, v0
	v_min_u32_e32 v0, v3, v0
	v_max_u32_e32 v61, v47, v54
	v_min_u32_e32 v60, v47, v54
	v_max_u32_e32 v59, v2, v48
	v_min_u32_e32 v58, v2, v48
	v_max_u32_e32 v57, v70, v51
	v_min_u32_e32 v56, v70, v51
	v_max_u32_e32 v55, v1, v49
	v_min_u32_e32 v54, v1, v49
	v_max_u32_e32 v53, v71, v72
	v_min_u32_e32 v52, v71, v72
	v_max_u32_e32 v51, v50, v73
	v_min_u32_e32 v50, v50, v73
	v_max_u32_e32 v47, v46, v0
	v_min_u32_e32 v46, v46, v0
	global_load_dwordx4 v[0:3], v[4:5], off offset:560
	global_load_dwordx4 v[70:73], v[4:5], off offset:544
	v_max_u32_e32 v49, v74, v75
	v_min_u32_e32 v48, v74, v75
	s_waitcnt vmcnt(2)
; __device__ __forceinline__ unsigned f2key(float f) { const unsigned u = __float_as_uint(f); return (u & 0x80000000u) ? ~u : (u | 0x80000000u); }
; __device__ __forceinline__ void peer_tile(const Args& A, LAS unsigned char* lds, int tile) {
;     ...
;                   for (int i = 0; i < 16; ++i) {
;                       const float lo = (float)__builtin_bit_cast(_Float16, (unsigned short)(sw[i] & 0xffffu)), hi = (float)__builtin_bit_cast(_Float16, (unsigned short)(sw[i] >> 16));
;                       const unsigned klo = (f2key(lo) & ~127u) | (unsigned)(127 - (32 * g + 2 * i)), khi = (f2key(hi) & ~127u) | (unsigned)(127 - (32 * g + 2 * i + 1));
;                       if (i < 8) { k0[2 * i] = klo; k0[2 * i + 1] = khi; } else { k1[2 * (i - 8)] = klo; k1[2 * (i - 8) + 1] = khi; } } }
	v_cvt_f32_f16_sdwa v74, v66 dst_sel:DWORD dst_unused:UNUSED_PAD src0_sel:WORD_1
	v_cvt_f32_f16_e32 v66, v66
	v_not_b32_e32 v75, v74
	v_or_b32_e32 v76, 0x80000000, v74
	v_cmp_gt_i32_e32 vcc, 0, v74
	s_nop 1
	v_cndmask_b32_e32 v74, v76, v75, vcc
	v_not_b32_e32 v75, v66
	v_or_b32_e32 v76, 0x80000000, v66
	v_cmp_gt_i32_e32 vcc, 0, v66
	v_and_b32_e32 v74, 0xffffff80, v74
	v_sub_u32_e32 v74, v74, v15
	v_cndmask_b32_e32 v66, v76, v75, vcc
	v_cvt_f32_f16_sdwa v75, v67 dst_sel:DWORD dst_unused:UNUSED_PAD src0_sel:WORD_1
	v_cvt_f32_f16_e32 v67, v67
	v_and_b32_e32 v66, 0xffffff80, v66
	v_sub_u32_e32 v66, v66, v15
	v_not_b32_e32 v76, v75
	v_or_b32_e32 v77, 0x80000000, v75
	v_cmp_gt_i32_e32 vcc, 0, v75
	v_add_u32_e32 v74, 0x7e, v74
	v_add_u32_e32 v66, 0x7f, v66
	v_cndmask_b32_e32 v75, v77, v76, vcc
	v_not_b32_e32 v76, v67
	v_or_b32_e32 v77, 0x80000000, v67
	v_cmp_gt_i32_e32 vcc, 0, v67
	v_and_b32_e32 v75, 0xffffff80, v75
	v_sub_u32_e32 v75, v75, v14
	v_cndmask_b32_e32 v67, v77, v76, vcc
	v_cvt_f32_f16_sdwa v76, v68 dst_sel:DWORD dst_unused:UNUSED_PAD src0_sel:WORD_1
	v_cvt_f32_f16_e32 v68, v68
	v_and_b32_e32 v67, 0xffffff80, v67
	v_sub_u32_e32 v67, v67, v14
	v_not_b32_e32 v77, v76
	v_or_b32_e32 v78, 0x80000000, v76
	v_cmp_gt_i32_e32 vcc, 0, v76
	v_add_u32_e32 v75, 0x7e, v75
	v_add_u32_e32 v67, 0x7f, v67
	v_cndmask_b32_e32 v76, v78, v77, vcc
	v_not_b32_e32 v77, v68
	v_or_b32_e32 v78, 0x80000000, v68
	v_cmp_gt_i32_e32 vcc, 0, v68
	v_and_b32_e32 v76, 0xffffff80, v76
	v_sub_u32_e32 v76, v76, v12
	v_cndmask_b32_e32 v68, v78, v77, vcc
	v_cvt_f32_f16_sdwa v77, v69 dst_sel:DWORD dst_unused:UNUSED_PAD src0_sel:WORD_1
	v_cvt_f32_f16_e32 v69, v69
	v_and_b32_e32 v68, 0xffffff80, v68
	v_sub_u32_e32 v68, v68, v12
	v_not_b32_e32 v78, v77
	v_or_b32_e32 v79, 0x80000000, v77
	v_cmp_gt_i32_e32 vcc, 0, v77
	v_add_u32_e32 v76, 0x7e, v76
	v_add_u32_e32 v68, 0x7f, v68
	v_cndmask_b32_e32 v77, v79, v78, vcc
	v_not_b32_e32 v78, v69
	v_or_b32_e32 v79, 0x80000000, v69
	v_cmp_gt_i32_e32 vcc, 0, v69
	v_and_b32_e32 v77, 0xffffff80, v77
	v_sub_u32_e32 v77, v77, v10
	v_cndmask_b32_e32 v69, v79, v78, vcc
	v_cvt_f32_f16_sdwa v78, v62 dst_sel:DWORD dst_unused:UNUSED_PAD src0_sel:WORD_1
	v_cvt_f32_f16_e32 v62, v62
	v_and_b32_e32 v69, 0xffffff80, v69
	v_sub_u32_e32 v69, v69, v10
	v_not_b32_e32 v79, v78
	v_or_b32_e32 v80, 0x80000000, v78
	v_cmp_gt_i32_e32 vcc, 0, v78
	v_add_u32_e32 v77, 0x7e, v77
	v_add_u32_e32 v69, 0x7f, v69
	v_cndmask_b32_e32 v78, v80, v79, vcc
	v_not_b32_e32 v79, v62
	v_or_b32_e32 v80, 0x80000000, v62
	v_cmp_gt_i32_e32 vcc, 0, v62
	v_and_b32_e32 v78, 0xffffff80, v78
	v_sub_u32_e32 v78, v78, v8
	v_cndmask_b32_e32 v62, v80, v79, vcc
	v_cvt_f32_f16_sdwa v79, v63 dst_sel:DWORD dst_unused:UNUSED_PAD src0_sel:WORD_1
	v_cvt_f32_f16_e32 v63, v63
	v_and_b32_e32 v62, 0xffffff80, v62
	v_sub_u32_e32 v62, v62, v8
	v_not_b32_e32 v80, v79
	v_or_b32_e32 v81, 0x80000000, v79
	v_cmp_gt_i32_e32 vcc, 0, v79
	v_add_u32_e32 v78, 0x7e, v78
	v_add_u32_e32 v62, 0x7f, v62
	v_cndmask_b32_e32 v79, v81, v80, vcc
	v_not_b32_e32 v80, v63
	v_or_b32_e32 v81, 0x80000000, v63
	v_cmp_gt_i32_e32 vcc, 0, v63
	v_and_b32_e32 v79, 0xffffff80, v79
	v_sub_u32_e32 v79, v79, v16
	v_cndmask_b32_e32 v63, v81, v80, vcc
	v_cvt_f32_f16_sdwa v80, v64 dst_sel:DWORD dst_unused:UNUSED_PAD src0_sel:WORD_1
	v_cvt_f32_f16_e32 v64, v64
	v_and_b32_e32 v63, 0xffffff80, v63
	v_sub_u32_e32 v63, v63, v16
	v_not_b32_e32 v81, v80
	v_or_b32_e32 v82, 0x80000000, v80
	v_cmp_gt_i32_e32 vcc, 0, v80
	v_add_u32_e32 v79, 0x7e, v79
	v_add_u32_e32 v63, 0x7f, v63
	v_cndmask_b32_e32 v80, v82, v81, vcc
	v_not_b32_e32 v81, v64
	v_or_b32_e32 v82, 0x80000000, v64
	v_cmp_gt_i32_e32 vcc, 0, v64
	v_and_b32_e32 v80, 0xffffff80, v80
	v_sub_u32_e32 v80, v80, v17
	v_cndmask_b32_e32 v64, v82, v81, vcc
	v_cvt_f32_f16_sdwa v81, v65 dst_sel:DWORD dst_unused:UNUSED_PAD src0_sel:WORD_1
	v_cvt_f32_f16_e32 v65, v65
	v_and_b32_e32 v64, 0xffffff80, v64
	v_sub_u32_e32 v64, v64, v17
	v_not_b32_e32 v82, v81
	v_or_b32_e32 v83, 0x80000000, v81
	v_cmp_gt_i32_e32 vcc, 0, v81
	v_add_u32_e32 v80, 0x7e, v80
	v_add_u32_e32 v64, 0x7f, v64
	v_cndmask_b32_e32 v81, v83, v82, vcc
	v_not_b32_e32 v82, v65
	v_or_b32_e32 v83, 0x80000000, v65
	v_cmp_gt_i32_e32 vcc, 0, v65
	v_and_b32_e32 v81, 0xffffff80, v81
	v_sub_u32_e32 v81, v81, v18
	v_cndmask_b32_e32 v65, v83, v82, vcc
	s_waitcnt vmcnt(0)
; __device__ __forceinline__ unsigned f2key(float f) { const unsigned u = __float_as_uint(f); return (u & 0x80000000u) ? ~u : (u | 0x80000000u); }
; #define CE_DESC(a, b) do { const unsigned _mx = (a) > (b) ? (a) : (b), _mn = (a) > (b) ? (b) : (a); (a) = _mx; (b) = _mn; } while (0)
; __device__ __forceinline__ void sort16_desc(unsigned (&k)[16]) {
; #pragma unroll
;     for (int size = 2; size <= 16; size <<= 1)
; #pragma unroll
;         for (int stride = size >> 1; stride > 0; stride >>= 1)
; #pragma unroll
;             for (int i = 0; i < 16; ++i) { const int j = i ^ stride;
;                 if (j > i) { if ((i & size) == 0) CE_DESC(k[i], k[j]); else CE_DESC(k[j], k[i]); } }
; }
; __device__ __forceinline__ void peer_tile(const Args& A, LAS unsigned char* lds, int tile) {
;     ...
;                   for (int i = 0; i < 16; ++i) {
;                       const float lo = (float)__builtin_bit_cast(_Float16, (unsigned short)(sw[i] & 0xffffu)), hi = (float)__builtin_bit_cast(_Float16, (unsigned short)(sw[i] >> 16));
;                       const unsigned klo = (f2key(lo) & ~127u) | (unsigned)(127 - (32 * g + 2 * i)), khi = (f2key(hi) & ~127u) | (unsigned)(127 - (32 * g + 2 * i + 1));
;                       if (i < 8) { k0[2 * i] = klo; k0[2 * i + 1] = khi; } else { k1[2 * (i - 8)] = klo; k1[2 * (i - 8) + 1] = khi; } } }
	v_cvt_f32_f16_sdwa v82, v70 dst_sel:DWORD dst_unused:UNUSED_PAD src0_sel:WORD_1
	v_cvt_f32_f16_e32 v70, v70
	v_and_b32_e32 v65, 0xffffff80, v65
	v_sub_u32_e32 v65, v65, v18
	v_not_b32_e32 v83, v82
	v_or_b32_e32 v84, 0x80000000, v82
	v_cmp_gt_i32_e32 vcc, 0, v82
	v_add_u32_e32 v81, 0x7e, v81
	v_add_u32_e32 v65, 0x7f, v65
	v_cndmask_b32_e32 v82, v84, v83, vcc
	v_not_b32_e32 v83, v70
	v_or_b32_e32 v84, 0x80000000, v70
	v_cmp_gt_i32_e32 vcc, 0, v70
	v_and_b32_e32 v82, 0xffffff80, v82
	v_sub_u32_e32 v82, v82, v20
	v_cndmask_b32_e32 v70, v84, v83, vcc
	v_cvt_f32_f16_sdwa v83, v71 dst_sel:DWORD dst_unused:UNUSED_PAD src0_sel:WORD_1
	v_cvt_f32_f16_e32 v71, v71
	v_and_b32_e32 v70, 0xffffff80, v70
	v_sub_u32_e32 v70, v70, v20
	v_not_b32_e32 v84, v83
	v_or_b32_e32 v85, 0x80000000, v83
	v_cmp_gt_i32_e32 vcc, 0, v83
	v_add_u32_e32 v82, 0x7e, v82
	v_add_u32_e32 v70, 0x7f, v70
	v_cndmask_b32_e32 v83, v85, v84, vcc
	v_not_b32_e32 v84, v71
	v_or_b32_e32 v85, 0x80000000, v71
	v_cmp_gt_i32_e32 vcc, 0, v71
	v_and_b32_e32 v83, 0xffffff80, v83
	v_sub_u32_e32 v83, v83, v21
	v_cndmask_b32_e32 v71, v85, v84, vcc
	v_cvt_f32_f16_sdwa v84, v72 dst_sel:DWORD dst_unused:UNUSED_PAD src0_sel:WORD_1
	v_cvt_f32_f16_e32 v72, v72
	v_and_b32_e32 v71, 0xffffff80, v71
	v_sub_u32_e32 v71, v71, v21
	v_not_b32_e32 v85, v84
	v_or_b32_e32 v86, 0x80000000, v84
	v_cmp_gt_i32_e32 vcc, 0, v84
	v_add_u32_e32 v83, 0x7e, v83
	v_add_u32_e32 v71, 0x7f, v71
	v_cndmask_b32_e32 v84, v86, v85, vcc
	v_not_b32_e32 v85, v72
	v_or_b32_e32 v86, 0x80000000, v72
	v_cmp_gt_i32_e32 vcc, 0, v72
	v_and_b32_e32 v84, 0xffffff80, v84
	v_sub_u32_e32 v84, v84, v22
	v_cndmask_b32_e32 v72, v86, v85, vcc
	v_cvt_f32_f16_sdwa v85, v73 dst_sel:DWORD dst_unused:UNUSED_PAD src0_sel:WORD_1
	v_cvt_f32_f16_e32 v73, v73
	v_and_b32_e32 v72, 0xffffff80, v72
	v_sub_u32_e32 v72, v72, v22
	v_not_b32_e32 v86, v85
	v_or_b32_e32 v87, 0x80000000, v85
	v_cmp_gt_i32_e32 vcc, 0, v85
	v_add_u32_e32 v84, 0x7e, v84
	v_add_u32_e32 v72, 0x7f, v72
	v_cndmask_b32_e32 v85, v87, v86, vcc
	v_not_b32_e32 v86, v73
	v_or_b32_e32 v87, 0x80000000, v73
	v_cmp_gt_i32_e32 vcc, 0, v73
	v_and_b32_e32 v85, 0xffffff80, v85
	v_sub_u32_e32 v85, v85, v23
	v_cndmask_b32_e32 v73, v87, v86, vcc
	v_cvt_f32_f16_sdwa v86, v0 dst_sel:DWORD dst_unused:UNUSED_PAD src0_sel:WORD_1
	v_cvt_f32_f16_e32 v0, v0
	v_and_b32_e32 v73, 0xffffff80, v73
	v_sub_u32_e32 v73, v73, v23
	v_not_b32_e32 v87, v86
	v_or_b32_e32 v88, 0x80000000, v86
	v_cmp_gt_i32_e32 vcc, 0, v86
	v_add_u32_e32 v85, 0x7e, v85
	v_add_u32_e32 v73, 0x7f, v73
	v_cndmask_b32_e32 v86, v88, v87, vcc
	v_not_b32_e32 v87, v0
	v_or_b32_e32 v88, 0x80000000, v0
	v_cmp_gt_i32_e32 vcc, 0, v0
	v_and_b32_e32 v86, 0xffffff80, v86
	v_sub_u32_e32 v86, v86, v24
	v_cndmask_b32_e32 v0, v88, v87, vcc
	v_cvt_f32_f16_sdwa v87, v1 dst_sel:DWORD dst_unused:UNUSED_PAD src0_sel:WORD_1
	v_cvt_f32_f16_e32 v1, v1
	v_and_b32_e32 v0, 0xffffff80, v0
	v_sub_u32_e32 v0, v0, v24
	v_not_b32_e32 v88, v87
	v_or_b32_e32 v89, 0x80000000, v87
	v_cmp_gt_i32_e32 vcc, 0, v87
	v_add_u32_e32 v86, 0x7e, v86
	v_add_u32_e32 v0, 0x7f, v0
	v_cndmask_b32_e32 v87, v89, v88, vcc
	v_not_b32_e32 v88, v1
	v_or_b32_e32 v89, 0x80000000, v1
	v_cmp_gt_i32_e32 vcc, 0, v1
	v_and_b32_e32 v87, 0xffffff80, v87
	v_sub_u32_e32 v87, v87, v25
	v_cndmask_b32_e32 v1, v89, v88, vcc
	v_cvt_f32_f16_sdwa v88, v2 dst_sel:DWORD dst_unused:UNUSED_PAD src0_sel:WORD_1
	v_cvt_f32_f16_e32 v2, v2
	v_and_b32_e32 v1, 0xffffff80, v1
	v_sub_u32_e32 v1, v1, v25
	v_not_b32_e32 v89, v88
	v_or_b32_e32 v90, 0x80000000, v88
	v_cmp_gt_i32_e32 vcc, 0, v88
	v_add_u32_e32 v87, 0x7e, v87
	v_add_u32_e32 v1, 0x7f, v1
	v_cndmask_b32_e32 v88, v90, v89, vcc
	v_not_b32_e32 v89, v2
	v_or_b32_e32 v90, 0x80000000, v2
	v_cmp_gt_i32_e32 vcc, 0, v2
	v_and_b32_e32 v88, 0xffffff80, v88
	v_sub_u32_e32 v88, v88, v26
	v_cndmask_b32_e32 v2, v90, v89, vcc
	v_cvt_f32_f16_sdwa v89, v3 dst_sel:DWORD dst_unused:UNUSED_PAD src0_sel:WORD_1
	v_cvt_f32_f16_e32 v3, v3
	v_and_b32_e32 v2, 0xffffff80, v2
	v_sub_u32_e32 v2, v2, v26
	v_not_b32_e32 v90, v89
	v_or_b32_e32 v91, 0x80000000, v89
	v_cmp_gt_i32_e32 vcc, 0, v89
	v_add_u32_e32 v88, 0x7e, v88
	v_add_u32_e32 v2, 0x7f, v2
	v_cndmask_b32_e32 v89, v91, v90, vcc
	v_not_b32_e32 v90, v3
	v_or_b32_e32 v91, 0x80000000, v3
	v_cmp_gt_i32_e32 vcc, 0, v3
	v_and_b32_e32 v89, 0xffffff80, v89
	v_sub_u32_e32 v89, v89, v28
	v_cndmask_b32_e32 v3, v91, v90, vcc
	v_and_b32_e32 v3, 0xffffff80, v3
	v_sub_u32_e32 v3, v3, v28
	v_add_u32_e32 v89, 0x7e, v89
	v_add_u32_e32 v3, 0x7f, v3
	v_max_u32_e32 v90, v66, v74
	v_min_u32_e32 v66, v66, v74
	v_max_u32_e32 v74, v75, v67
	v_min_u32_e32 v67, v75, v67
	v_max_u32_e32 v75, v68, v76
	v_min_u32_e32 v68, v68, v76
	v_max_u32_e32 v76, v77, v69
	v_min_u32_e32 v69, v77, v69
	v_max_u32_e32 v77, v62, v78
	v_min_u32_e32 v62, v62, v78
	v_max_u32_e32 v78, v79, v63
	v_min_u32_e32 v63, v79, v63
	v_max_u32_e32 v79, v64, v80
	v_min_u32_e32 v64, v64, v80
	v_max_u32_e32 v80, v81, v65
	v_min_u32_e32 v65, v81, v65
	v_max_u32_e32 v98, v70, v82
	v_min_u32_e32 v70, v70, v82
	v_max_u32_e32 v82, v83, v71
	v_min_u32_e32 v71, v83, v71
	v_max_u32_e32 v83, v72, v84
	v_min_u32_e32 v72, v72, v84
	v_max_u32_e32 v84, v85, v73
	v_min_u32_e32 v73, v85, v73
	v_max_u32_e32 v85, v0, v86
	v_min_u32_e32 v0, v0, v86
	v_max_u32_e32 v86, v87, v1
	v_min_u32_e32 v1, v87, v1
	v_max_u32_e32 v87, v2, v88
	v_min_u32_e32 v2, v2, v88
	v_max_u32_e32 v88, v89, v3
	v_min_u32_e32 v3, v89, v3
	v_max_u32_e32 v81, v90, v67
	v_min_u32_e32 v67, v90, v67
	v_max_u32_e32 v90, v66, v74
	v_min_u32_e32 v66, v66, v74
	v_max_u32_e32 v74, v69, v75
	v_min_u32_e32 v69, v69, v75
	v_max_u32_e32 v75, v76, v68
	v_min_u32_e32 v68, v76, v68
; #define CE_DESC(a, b) do { const unsigned _mx = (a) > (b) ? (a) : (b), _mn = (a) > (b) ? (b) : (a); (a) = _mx; (b) = _mn; } while (0)
; __device__ __forceinline__ void sort16_desc(unsigned (&k)[16]) {
; #pragma unroll
;     for (int size = 2; size <= 16; size <<= 1)
; #pragma unroll
;         for (int stride = size >> 1; stride > 0; stride >>= 1)
; #pragma unroll
;             for (int i = 0; i < 16; ++i) { const int j = i ^ stride;
;                 if (j > i) { if ((i & size) == 0) CE_DESC(k[i], k[j]); else CE_DESC(k[j], k[i]); } }
; }
	v_max_u32_e32 v76, v77, v63
	v_min_u32_e32 v63, v77, v63
	v_max_u32_e32 v77, v62, v78
	v_min_u32_e32 v62, v62, v78
	v_max_u32_e32 v78, v65, v79
	v_min_u32_e32 v65, v65, v79
	v_max_u32_e32 v79, v80, v64
	v_min_u32_e32 v64, v80, v64
	v_max_u32_e32 v89, v98, v71
	v_min_u32_e32 v71, v98, v71
	v_max_u32_e32 v98, v70, v82
	v_min_u32_e32 v70, v70, v82
	v_max_u32_e32 v82, v73, v83
	v_min_u32_e32 v73, v73, v83
	v_max_u32_e32 v83, v84, v72
	v_min_u32_e32 v72, v84, v72
	v_max_u32_e32 v84, v85, v1
	v_min_u32_e32 v1, v85, v1
	v_max_u32_e32 v85, v0, v86
	v_min_u32_e32 v0, v0, v86
	v_max_u32_e32 v86, v3, v87
	v_min_u32_e32 v3, v3, v87
	v_max_u32_e32 v87, v88, v2
	v_min_u32_e32 v2, v88, v2
	v_max_u32_e32 v80, v81, v90
	v_min_u32_e32 v81, v81, v90
	v_max_u32_e32 v90, v67, v66
	v_min_u32_e32 v66, v67, v66
	v_max_u32_e32 v67, v68, v69
	v_min_u32_e32 v68, v68, v69
	v_max_u32_e32 v69, v75, v74
	v_min_u32_e32 v74, v75, v74
	v_max_u32_e32 v75, v76, v77
	v_min_u32_e32 v76, v76, v77
	v_max_u32_e32 v77, v63, v62
	v_min_u32_e32 v62, v63, v62
	v_max_u32_e32 v63, v64, v65
	v_min_u32_e32 v64, v64, v65
	v_max_u32_e32 v65, v79, v78
	v_min_u32_e32 v78, v79, v78
	v_max_u32_e32 v88, v89, v98
	v_min_u32_e32 v89, v89, v98
	v_max_u32_e32 v98, v71, v70
	v_min_u32_e32 v70, v71, v70
	v_max_u32_e32 v71, v72, v73
	v_min_u32_e32 v72, v72, v73
	v_max_u32_e32 v73, v83, v82
	v_min_u32_e32 v82, v83, v82
	v_max_u32_e32 v83, v84, v85
	v_min_u32_e32 v84, v84, v85
	v_max_u32_e32 v85, v1, v0
	v_min_u32_e32 v0, v1, v0
	v_max_u32_e32 v1, v2, v3
	v_min_u32_e32 v2, v2, v3
	v_max_u32_e32 v3, v87, v86
	v_min_u32_e32 v86, v87, v86
	v_max_u32_e32 v79, v80, v68
	v_min_u32_e32 v68, v80, v68
	v_max_u32_e32 v80, v81, v67
	v_min_u32_e32 v67, v81, v67
	v_max_u32_e32 v81, v90, v74
	v_min_u32_e32 v74, v90, v74
	v_max_u32_e32 v90, v66, v69
	v_min_u32_e32 v66, v66, v69
	v_max_u32_e32 v69, v64, v75
	v_min_u32_e32 v64, v64, v75
	v_max_u32_e32 v75, v63, v76
	v_min_u32_e32 v63, v63, v76
	v_max_u32_e32 v76, v78, v77
	v_min_u32_e32 v77, v78, v77
	v_max_u32_e32 v78, v65, v62
	v_min_u32_e32 v62, v65, v62
	v_max_u32_e32 v87, v88, v72
	v_min_u32_e32 v72, v88, v72
	v_max_u32_e32 v88, v89, v71
	v_min_u32_e32 v71, v89, v71
	v_max_u32_e32 v89, v98, v82
	v_min_u32_e32 v82, v98, v82
	v_max_u32_e32 v98, v70, v73
	v_min_u32_e32 v70, v70, v73
	v_max_u32_e32 v73, v2, v83
	v_min_u32_e32 v2, v2, v83
	v_max_u32_e32 v83, v1, v84
	v_min_u32_e32 v1, v1, v84
	v_max_u32_e32 v84, v86, v85
	v_min_u32_e32 v85, v86, v85
	v_max_u32_e32 v86, v3, v0
	v_min_u32_e32 v0, v3, v0
	v_max_u32_e32 v65, v79, v81
	v_min_u32_e32 v79, v79, v81
	v_max_u32_e32 v81, v80, v90
	v_min_u32_e32 v80, v80, v90
	v_max_u32_e32 v90, v68, v74
	v_min_u32_e32 v68, v68, v74
	v_max_u32_e32 v74, v67, v66
	v_min_u32_e32 v66, v67, v66
	v_max_u32_e32 v67, v77, v64
	v_min_u32_e32 v64, v77, v64
	v_max_u32_e32 v77, v62, v63
	v_min_u32_e32 v62, v62, v63
	v_max_u32_e32 v63, v76, v69
	v_min_u32_e32 v69, v76, v69
	v_max_u32_e32 v76, v78, v75
	v_min_u32_e32 v75, v78, v75
	v_max_u32_e32 v3, v87, v89
	v_min_u32_e32 v87, v87, v89
	v_max_u32_e32 v89, v88, v98
	v_min_u32_e32 v88, v88, v98
	v_max_u32_e32 v98, v72, v82
	v_min_u32_e32 v72, v72, v82
	v_max_u32_e32 v82, v71, v70
	v_min_u32_e32 v70, v71, v70
	v_max_u32_e32 v71, v85, v2
	v_min_u32_e32 v2, v85, v2
	v_max_u32_e32 v85, v0, v1
	v_min_u32_e32 v0, v0, v1
	v_max_u32_e32 v1, v84, v73
	v_min_u32_e32 v73, v84, v73
	v_max_u32_e32 v84, v86, v83
	v_min_u32_e32 v83, v86, v83
	v_max_u32_e32 v78, v65, v81
	v_min_u32_e32 v65, v65, v81
	v_max_u32_e32 v81, v79, v80
	v_min_u32_e32 v79, v79, v80
	v_max_u32_e32 v80, v90, v74
	v_min_u32_e32 v74, v90, v74
	v_max_u32_e32 v90, v68, v66
	v_min_u32_e32 v66, v68, v66
	v_max_u32_e32 v68, v62, v64
	v_min_u32_e32 v62, v62, v64
	v_max_u32_e32 v64, v77, v67
	v_min_u32_e32 v67, v77, v67
	v_max_u32_e32 v77, v75, v69
	v_min_u32_e32 v69, v75, v69
	v_max_u32_e32 v75, v76, v63
	v_min_u32_e32 v63, v76, v63
	v_max_u32_e32 v86, v3, v89
	v_min_u32_e32 v3, v3, v89
	v_max_u32_e32 v89, v87, v88
	v_min_u32_e32 v87, v87, v88
	v_max_u32_e32 v88, v98, v82
	v_min_u32_e32 v82, v98, v82
	v_max_u32_e32 v98, v72, v70
	v_min_u32_e32 v70, v72, v70
	v_max_u32_e32 v72, v0, v2
	v_min_u32_e32 v0, v0, v2
	v_max_u32_e32 v2, v85, v71
	v_min_u32_e32 v71, v85, v71
	v_max_u32_e32 v85, v83, v73
	v_min_u32_e32 v73, v83, v73
	v_max_u32_e32 v83, v84, v1
	v_min_u32_e32 v1, v84, v1
	v_max_u32_e32 v76, v78, v62
	v_min_u32_e32 v62, v78, v62
	v_max_u32_e32 v78, v65, v68
	v_min_u32_e32 v65, v65, v68
	v_max_u32_e32 v68, v81, v67
	v_min_u32_e32 v67, v81, v67
	v_max_u32_e32 v81, v79, v64
	v_min_u32_e32 v64, v79, v64
	v_max_u32_e32 v79, v80, v69
	v_min_u32_e32 v69, v80, v69
	v_max_u32_e32 v80, v74, v77
	v_min_u32_e32 v74, v74, v77
	v_max_u32_e32 v77, v90, v63
	v_min_u32_e32 v63, v90, v63
	v_max_u32_e32 v90, v66, v75
	v_min_u32_e32 v66, v66, v75
	v_max_u32_e32 v84, v86, v0
	v_min_u32_e32 v0, v86, v0
	v_max_u32_e32 v86, v3, v72
	v_min_u32_e32 v3, v3, v72
	v_max_u32_e32 v72, v89, v71
	v_min_u32_e32 v71, v89, v71
	v_max_u32_e32 v89, v87, v2
	v_min_u32_e32 v2, v87, v2
	v_max_u32_e32 v87, v88, v73
	v_min_u32_e32 v73, v88, v73
	v_max_u32_e32 v88, v82, v85
	v_min_u32_e32 v82, v82, v85
	v_max_u32_e32 v85, v98, v1
	v_min_u32_e32 v1, v98, v1
	v_max_u32_e32 v98, v70, v83
	v_min_u32_e32 v70, v70, v83
	v_max_u32_e32 v75, v76, v79
	v_min_u32_e32 v76, v76, v79
	v_max_u32_e32 v79, v78, v80
	v_min_u32_e32 v78, v78, v80
	v_max_u32_e32 v80, v68, v77
	v_min_u32_e32 v68, v68, v77
	v_max_u32_e32 v77, v81, v90
	v_min_u32_e32 v81, v81, v90
	v_max_u32_e32 v90, v62, v69
	v_min_u32_e32 v62, v62, v69
	v_max_u32_e32 v69, v65, v74
	v_min_u32_e32 v65, v65, v74
	v_max_u32_e32 v74, v67, v63
; #define CE_DESC(a, b) do { const unsigned _mx = (a) > (b) ? (a) : (b), _mn = (a) > (b) ? (b) : (a); (a) = _mx; (b) = _mn; } while (0)
; __device__ __forceinline__ void merge16(unsigned (&a)[16], const unsigned (&b)[16]) {
; #pragma unroll
;     for (int i = 0; i < 16; ++i) a[i] = a[i] > b[15 - i] ? a[i] : b[15 - i];
; #pragma unroll
;     for (int stride = 8; stride > 0; stride >>= 1)
; #pragma unroll
;         for (int i = 0; i < 16; ++i) { const int j = i ^ stride; if (j > i) CE_DESC(a[i], a[j]); }
; }
; __device__ __forceinline__ void peer_tile(const Args& A, LAS unsigned char* lds, int tile) {
;     ...
;                 for (int msk = 16; msk <= 32; msk <<= 1) {
; #pragma unroll
;                     for (int i = 0; i < 16; ++i) k1[i] = (unsigned)__shfl_xor((int)k0[i], msk);
;                     merge16(k0, k1); }
	v_min_u32_e32 v63, v67, v63
	v_max_u32_e32 v67, v64, v66
	v_min_u32_e32 v64, v64, v66
	v_max_u32_e32 v83, v84, v87
	v_min_u32_e32 v84, v84, v87
	v_max_u32_e32 v87, v86, v88
	v_min_u32_e32 v86, v86, v88
	v_max_u32_e32 v88, v72, v85
	v_min_u32_e32 v72, v72, v85
	v_max_u32_e32 v85, v89, v98
	v_min_u32_e32 v89, v89, v98
	v_max_u32_e32 v98, v0, v73
	v_min_u32_e32 v0, v0, v73
	v_max_u32_e32 v73, v3, v82
	v_min_u32_e32 v3, v3, v82
	v_max_u32_e32 v82, v71, v1
	v_min_u32_e32 v1, v71, v1
	v_max_u32_e32 v71, v2, v70
	v_min_u32_e32 v2, v2, v70
	v_max_u32_e32 v66, v75, v80
	v_min_u32_e32 v75, v75, v80
	v_max_u32_e32 v80, v79, v77
	v_min_u32_e32 v77, v79, v77
	v_max_u32_e32 v79, v76, v68
	v_min_u32_e32 v68, v76, v68
	v_max_u32_e32 v76, v78, v81
	v_min_u32_e32 v78, v78, v81
	v_max_u32_e32 v81, v90, v74
	v_min_u32_e32 v74, v90, v74
	v_max_u32_e32 v90, v69, v67
	v_min_u32_e32 v67, v69, v67
	v_max_u32_e32 v69, v62, v63
	v_min_u32_e32 v62, v62, v63
	v_max_u32_e32 v63, v65, v64
	v_min_u32_e32 v64, v65, v64
	v_max_u32_e32 v70, v83, v88
	v_min_u32_e32 v83, v83, v88
	v_max_u32_e32 v88, v87, v85
	v_min_u32_e32 v85, v87, v85
	v_max_u32_e32 v87, v84, v72
	v_min_u32_e32 v72, v84, v72
	v_max_u32_e32 v84, v86, v89
	v_min_u32_e32 v86, v86, v89
	v_max_u32_e32 v89, v98, v82
	v_min_u32_e32 v82, v98, v82
	v_max_u32_e32 v98, v73, v71
	v_min_u32_e32 v71, v73, v71
	v_max_u32_e32 v73, v0, v1
	v_min_u32_e32 v0, v0, v1
	v_max_u32_e32 v1, v3, v2
	v_min_u32_e32 v2, v3, v2
	v_min_u32_e32 v65, v66, v80
	v_min_u32_e32 v91, v75, v77
	v_min_u32_e32 v92, v79, v76
	v_min_u32_e32 v93, v68, v78
	v_min_u32_e32 v94, v81, v90
	v_min_u32_e32 v95, v74, v67
	v_min_u32_e32 v96, v69, v63
	v_min_u32_e32 v97, v62, v64
	v_min_u32_e32 v3, v70, v88
	v_min_u32_e32 v99, v83, v85
	v_min_u32_e32 v100, v87, v84
	v_min_u32_e32 v101, v72, v86
	v_min_u32_e32 v102, v89, v98
	v_min_u32_e32 v103, v82, v71
	v_min_u32_e32 v104, v73, v1
	v_min_u32_e32 v105, v0, v2
	v_max3_u32 v66, v66, v80, v105
	v_max3_u32 v0, v65, v0, v2
	v_max3_u32 v2, v75, v77, v104
	v_max3_u32 v1, v91, v73, v1
	v_max3_u32 v65, v79, v76, v103
	v_max3_u32 v71, v92, v82, v71
	v_max3_u32 v68, v68, v78, v102
	v_max3_u32 v73, v93, v89, v98
	v_max3_u32 v75, v81, v90, v101
	v_max3_u32 v72, v94, v72, v86
	v_max3_u32 v67, v74, v67, v100
	v_max3_u32 v74, v95, v87, v84
	v_max3_u32 v63, v69, v63, v99
	v_max3_u32 v69, v96, v83, v85
	v_max3_u32 v3, v62, v64, v3
	v_max3_u32 v62, v97, v70, v88
	v_max_u32_e32 v64, v66, v75
	v_min_u32_e32 v66, v66, v75
	v_max_u32_e32 v70, v0, v72
	v_min_u32_e32 v0, v0, v72
	v_max_u32_e32 v72, v2, v67
	v_min_u32_e32 v2, v2, v67
	v_max_u32_e32 v67, v1, v74
	v_min_u32_e32 v1, v1, v74
	v_max_u32_e32 v74, v65, v63
	v_min_u32_e32 v63, v65, v63
	v_max_u32_e32 v65, v71, v69
	v_min_u32_e32 v69, v71, v69
	v_max_u32_e32 v71, v68, v3
	v_min_u32_e32 v3, v68, v3
	v_max_u32_e32 v68, v73, v62
	v_min_u32_e32 v62, v73, v62
	v_max_u32_e32 v73, v64, v74
	v_min_u32_e32 v64, v64, v74
	v_max_u32_e32 v74, v70, v65
	v_min_u32_e32 v65, v70, v65
	v_max_u32_e32 v70, v72, v71
	v_min_u32_e32 v71, v72, v71
	v_max_u32_e32 v72, v67, v68
	v_min_u32_e32 v67, v67, v68
	v_max_u32_e32 v68, v66, v63
	v_min_u32_e32 v63, v66, v63
	v_max_u32_e32 v66, v0, v69
	v_min_u32_e32 v0, v0, v69
	v_max_u32_e32 v69, v2, v3
	v_min_u32_e32 v2, v2, v3
	v_max_u32_e32 v3, v1, v62
	v_min_u32_e32 v1, v1, v62
	v_max_u32_e32 v62, v73, v70
	v_min_u32_e32 v70, v73, v70
	v_max_u32_e32 v73, v74, v72
	v_min_u32_e32 v72, v74, v72
	v_max_u32_e32 v74, v64, v71
	v_min_u32_e32 v64, v64, v71
	v_max_u32_e32 v71, v65, v67
	v_min_u32_e32 v65, v65, v67
	v_max_u32_e32 v67, v68, v69
	v_min_u32_e32 v68, v68, v69
	v_max_u32_e32 v69, v66, v3
	v_min_u32_e32 v3, v66, v3
	v_max_u32_e32 v66, v63, v2
	v_min_u32_e32 v2, v63, v2
	v_max_u32_e32 v63, v0, v1
	v_min_u32_e32 v0, v0, v1
	v_max_u32_e32 v1, v62, v73
	v_min_u32_e32 v62, v62, v73
	v_max_u32_e32 v73, v70, v72
	v_min_u32_e32 v70, v70, v72
	v_max_u32_e32 v72, v74, v71
	v_min_u32_e32 v71, v74, v71
	v_max_u32_e32 v74, v64, v65
	v_min_u32_e32 v64, v64, v65
	v_max_u32_e32 v65, v67, v69
	v_min_u32_e32 v67, v67, v69
	v_max_u32_e32 v69, v68, v3
	v_min_u32_e32 v3, v68, v3
	v_max_u32_e32 v68, v66, v63
	v_min_u32_e32 v63, v66, v63
	v_max_u32_e32 v66, v2, v0
	v_min_u32_e32 v0, v2, v0
	ds_bpermute_b32 v2, v27, v1
	ds_bpermute_b32 v75, v27, v62
	ds_bpermute_b32 v76, v27, v73
	ds_bpermute_b32 v77, v27, v70
	ds_bpermute_b32 v78, v27, v72
	ds_bpermute_b32 v79, v27, v71
	ds_bpermute_b32 v80, v27, v74
	ds_bpermute_b32 v81, v27, v64
	ds_bpermute_b32 v82, v27, v65
	ds_bpermute_b32 v83, v27, v67
	ds_bpermute_b32 v84, v27, v69
	ds_bpermute_b32 v85, v27, v0
	ds_bpermute_b32 v86, v27, v66
	ds_bpermute_b32 v87, v27, v63
	ds_bpermute_b32 v88, v27, v68
	ds_bpermute_b32 v89, v27, v3
	s_waitcnt lgkmcnt(4)
	v_max_u32_e32 v1, v1, v85
	s_waitcnt lgkmcnt(3)
	v_max_u32_e32 v62, v62, v86
	s_waitcnt lgkmcnt(2)
	v_max_u32_e32 v73, v73, v87
	s_waitcnt lgkmcnt(1)
	v_max_u32_e32 v70, v70, v88
	s_waitcnt lgkmcnt(0)
; __device__ __forceinline__ void peer_tile(const Args& A, LAS unsigned char* lds, int tile) {
;     ...
;                 { const bf16_t* sp = QRY + m * 2048 + hp * 128 + 32 * g;
;                   const u32x4 s0 = *(const u32x4*)sp, s1 = *(const u32x4*)(sp + 8), s2 = *(const u32x4*)(sp + 16), s3 = *(const u32x4*)(sp + 24);
;     ...
;                 for (int msk = 16; msk <= 32; msk <<= 1) {
; #pragma unroll
;                     for (int i = 0; i < 16; ++i) k1[i] = (unsigned)__shfl_xor((int)k0[i], msk);
;                     merge16(k0, k1); }
; #pragma unroll
;                 for (int i = 0; i < 16; ++i) LA[hh][p][i] = k0[i];
	v_max_u32_e32 v72, v72, v89
	v_max_u32_e32 v71, v71, v84
	v_max_u32_e32 v74, v74, v83
	v_max_u32_e32 v64, v64, v82
	v_max_u32_e32 v65, v65, v81
	v_max_u32_e32 v67, v67, v80
	v_max_u32_e32 v69, v69, v79
	v_max_u32_e32 v3, v3, v78
	v_max_u32_e32 v68, v68, v77
	v_max_u32_e32 v63, v63, v76
	v_max_u32_e32 v66, v66, v75
	v_max_u32_e32 v0, v0, v2
	v_max_u32_e32 v2, v1, v65
	v_min_u32_e32 v1, v1, v65
	v_max_u32_e32 v65, v62, v67
	v_min_u32_e32 v62, v62, v67
	v_max_u32_e32 v67, v73, v69
	v_min_u32_e32 v69, v73, v69
	v_max_u32_e32 v73, v70, v3
	v_min_u32_e32 v3, v70, v3
	v_max_u32_e32 v70, v72, v68
	v_min_u32_e32 v68, v72, v68
	v_max_u32_e32 v72, v71, v63
	v_min_u32_e32 v63, v71, v63
	v_max_u32_e32 v71, v74, v66
	v_min_u32_e32 v66, v74, v66
	v_max_u32_e32 v74, v64, v0
	v_min_u32_e32 v0, v64, v0
	v_max_u32_e32 v64, v2, v70
	v_min_u32_e32 v2, v2, v70
	v_max_u32_e32 v70, v65, v72
	v_min_u32_e32 v65, v65, v72
	v_max_u32_e32 v72, v67, v71
	v_min_u32_e32 v67, v67, v71
	v_max_u32_e32 v71, v73, v74
	v_min_u32_e32 v73, v73, v74
	v_max_u32_e32 v74, v1, v68
	v_min_u32_e32 v1, v1, v68
	v_max_u32_e32 v68, v62, v63
	v_min_u32_e32 v62, v62, v63
	v_max_u32_e32 v63, v69, v66
	v_min_u32_e32 v66, v69, v66
	v_max_u32_e32 v69, v3, v0
	v_min_u32_e32 v0, v3, v0
	v_max_u32_e32 v3, v64, v72
	v_min_u32_e32 v64, v64, v72
	v_max_u32_e32 v72, v70, v71
	v_min_u32_e32 v70, v70, v71
	v_max_u32_e32 v71, v2, v67
	v_min_u32_e32 v2, v2, v67
	v_max_u32_e32 v67, v65, v73
	v_min_u32_e32 v65, v65, v73
	v_max_u32_e32 v73, v74, v63
	v_min_u32_e32 v63, v74, v63
	v_max_u32_e32 v74, v68, v69
	v_min_u32_e32 v68, v68, v69
	v_max_u32_e32 v69, v1, v66
	v_min_u32_e32 v1, v1, v66
	v_max_u32_e32 v66, v62, v0
	v_min_u32_e32 v0, v62, v0
	v_max_u32_e32 v62, v3, v72
	v_min_u32_e32 v3, v3, v72
	v_max_u32_e32 v72, v64, v70
	v_min_u32_e32 v64, v64, v70
	v_max_u32_e32 v70, v71, v67
	v_min_u32_e32 v67, v71, v67
	v_max_u32_e32 v71, v2, v65
	v_min_u32_e32 v2, v2, v65
	v_max_u32_e32 v65, v73, v74
	v_min_u32_e32 v73, v73, v74
	v_max_u32_e32 v74, v63, v68
	v_min_u32_e32 v63, v63, v68
	v_max_u32_e32 v68, v69, v66
	v_min_u32_e32 v66, v69, v66
	v_max_u32_e32 v69, v1, v0
	v_min_u32_e32 v0, v1, v0
	ds_bpermute_b32 v78, v29, v0
	ds_bpermute_b32 v1, v29, v62
	ds_bpermute_b32 v75, v29, v3
	ds_bpermute_b32 v76, v29, v72
	ds_bpermute_b32 v77, v29, v64
	s_waitcnt lgkmcnt(4)
	v_max_u32_e32 v62, v62, v78
	global_load_dwordx4 v[78:81], v[4:5], off offset:784
	global_load_dwordx4 v[82:85], v[4:5], off offset:768
	ds_bpermute_b32 v86, v29, v70
	ds_bpermute_b32 v87, v29, v67
	ds_bpermute_b32 v88, v29, v71
	ds_bpermute_b32 v89, v29, v2
	ds_bpermute_b32 v90, v29, v65
	ds_bpermute_b32 v91, v29, v73
	ds_bpermute_b32 v92, v29, v74
	ds_bpermute_b32 v93, v29, v63
	ds_bpermute_b32 v94, v29, v68
	ds_bpermute_b32 v95, v29, v69
	ds_bpermute_b32 v96, v29, v66
	s_waitcnt lgkmcnt(4)
	v_max_u32_e32 v67, v67, v92
	s_waitcnt lgkmcnt(3)
	v_max_u32_e32 v70, v70, v93
	s_waitcnt lgkmcnt(2)
	v_max_u32_e32 v64, v64, v94
	s_waitcnt lgkmcnt(1)
	v_max_u32_e32 v3, v3, v95
	s_waitcnt lgkmcnt(0)
	v_max_u32_e32 v72, v72, v96
	v_max_u32_e32 v71, v71, v91
	v_max_u32_e32 v2, v2, v90
	v_max_u32_e32 v65, v65, v89
	v_max_u32_e32 v73, v73, v88
	v_max_u32_e32 v74, v74, v87
	v_max_u32_e32 v63, v63, v86
	v_max_u32_e32 v68, v68, v77
	v_max_u32_e32 v66, v66, v76
	v_max_u32_e32 v69, v69, v75
	v_max_u32_e32 v0, v0, v1
	v_max_u32_e32 v1, v62, v65
	v_min_u32_e32 v62, v62, v65
	v_max_u32_e32 v65, v3, v73
	v_min_u32_e32 v3, v3, v73
	v_max_u32_e32 v73, v72, v74
	v_min_u32_e32 v72, v72, v74
	v_max_u32_e32 v74, v64, v63
	v_min_u32_e32 v63, v64, v63
	v_max_u32_e32 v64, v70, v68
	v_min_u32_e32 v68, v70, v68
	v_max_u32_e32 v70, v67, v66
	v_min_u32_e32 v66, v67, v66
	v_max_u32_e32 v67, v71, v69
	v_min_u32_e32 v69, v71, v69
	v_max_u32_e32 v71, v2, v0
	v_min_u32_e32 v0, v2, v0
	v_max_u32_e32 v2, v1, v64
	v_min_u32_e32 v1, v1, v64
	v_max_u32_e32 v64, v65, v70
	v_min_u32_e32 v65, v65, v70
	v_max_u32_e32 v70, v73, v67
	v_min_u32_e32 v67, v73, v67
	v_max_u32_e32 v73, v74, v71
	v_min_u32_e32 v71, v74, v71
	v_max_u32_e32 v74, v62, v68
	v_min_u32_e32 v62, v62, v68
	v_max_u32_e32 v68, v3, v66
	v_min_u32_e32 v3, v3, v66
	v_max_u32_e32 v66, v72, v69
	v_min_u32_e32 v69, v72, v69
	v_max_u32_e32 v72, v63, v0
	v_min_u32_e32 v0, v63, v0
	v_max_u32_e32 v63, v2, v70
	v_min_u32_e32 v2, v2, v70
	v_max_u32_e32 v70, v64, v73
	v_min_u32_e32 v64, v64, v73
	v_max_u32_e32 v86, v1, v67
	v_min_u32_e32 v1, v1, v67
	v_max_u32_e32 v67, v65, v71
	v_min_u32_e32 v65, v65, v71
	v_max_u32_e32 v87, v74, v66
	v_min_u32_e32 v66, v74, v66
	v_max_u32_e32 v88, v68, v72
	v_min_u32_e32 v89, v68, v72
	v_max_u32_e32 v90, v62, v69
	v_min_u32_e32 v62, v62, v69
	v_max_u32_e32 v91, v3, v0
	v_min_u32_e32 v0, v3, v0
	v_max_u32_e32 v77, v63, v70
	v_min_u32_e32 v76, v63, v70
	v_max_u32_e32 v75, v2, v64
	v_min_u32_e32 v74, v2, v64
	v_max_u32_e32 v73, v86, v67
	v_min_u32_e32 v72, v86, v67
	v_max_u32_e32 v71, v1, v65
	v_min_u32_e32 v70, v1, v65
	v_max_u32_e32 v69, v87, v88
	v_min_u32_e32 v68, v87, v88
	v_max_u32_e32 v67, v66, v89
	v_min_u32_e32 v66, v66, v89
	v_max_u32_e32 v63, v62, v0
	v_min_u32_e32 v62, v62, v0
	global_load_dwordx4 v[0:3], v[4:5], off offset:816
	global_load_dwordx4 v[86:89], v[4:5], off offset:800
	v_max_u32_e32 v65, v90, v91
	v_min_u32_e32 v64, v90, v91
	s_waitcnt vmcnt(2)
; __device__ __forceinline__ unsigned f2key(float f) { const unsigned u = __float_as_uint(f); return (u & 0x80000000u) ? ~u : (u | 0x80000000u); }
; __device__ __forceinline__ void peer_tile(const Args& A, LAS unsigned char* lds, int tile) {
;     ...
;                   for (int i = 0; i < 16; ++i) {
;                       const float lo = (float)__builtin_bit_cast(_Float16, (unsigned short)(sw[i] & 0xffffu)), hi = (float)__builtin_bit_cast(_Float16, (unsigned short)(sw[i] >> 16));
;                       const unsigned klo = (f2key(lo) & ~127u) | (unsigned)(127 - (32 * g + 2 * i)), khi = (f2key(hi) & ~127u) | (unsigned)(127 - (32 * g + 2 * i + 1));
;                       if (i < 8) { k0[2 * i] = klo; k0[2 * i + 1] = khi; } else { k1[2 * (i - 8)] = klo; k1[2 * (i - 8) + 1] = khi; } } }
;     ...
;                 for (int i = 0; i < 16; ++i) L2[p][i] = (g & 2) ? ((g & 1) ? LA[3][p][i] : LA[2][p][i]) : ((g & 1) ? LA[1][p][i] : LA[0][p][i]);
	v_cvt_f32_f16_sdwa v90, v82 dst_sel:DWORD dst_unused:UNUSED_PAD src0_sel:WORD_1
	v_cvt_f32_f16_e32 v82, v82
	v_cndmask_b32_e64 v38, v70, v38, s[0:1]
	v_cndmask_b32_e64 v37, v69, v37, s[0:1]
	v_not_b32_e32 v91, v90
	v_or_b32_e32 v92, 0x80000000, v90
	v_cmp_gt_i32_e32 vcc, 0, v90
	v_cndmask_b32_e64 v36, v68, v36, s[0:1]
	v_cndmask_b32_e64 v35, v67, v35, s[0:1]
	v_cndmask_b32_e32 v90, v92, v91, vcc
	v_not_b32_e32 v91, v82
	v_or_b32_e32 v92, 0x80000000, v82
	v_cmp_gt_i32_e32 vcc, 0, v82
	v_and_b32_e32 v90, 0xffffff80, v90
	v_sub_u32_e32 v90, v90, v15
	v_cndmask_b32_e32 v82, v92, v91, vcc
	v_cvt_f32_f16_sdwa v91, v83 dst_sel:DWORD dst_unused:UNUSED_PAD src0_sel:WORD_1
	v_cvt_f32_f16_e32 v83, v83
	v_and_b32_e32 v82, 0xffffff80, v82
	v_sub_u32_e32 v82, v82, v15
	v_not_b32_e32 v92, v91
	v_or_b32_e32 v93, 0x80000000, v91
	v_cmp_gt_i32_e32 vcc, 0, v91
	v_add_u32_e32 v90, 0x7e, v90
	v_add_u32_e32 v82, 0x7f, v82
	v_cndmask_b32_e32 v91, v93, v92, vcc
	v_not_b32_e32 v92, v83
	v_or_b32_e32 v93, 0x80000000, v83
	v_cmp_gt_i32_e32 vcc, 0, v83
	v_and_b32_e32 v91, 0xffffff80, v91
	v_sub_u32_e32 v91, v91, v14
	v_cndmask_b32_e32 v83, v93, v92, vcc
	v_cvt_f32_f16_sdwa v92, v84 dst_sel:DWORD dst_unused:UNUSED_PAD src0_sel:WORD_1
	v_cvt_f32_f16_e32 v84, v84
	v_and_b32_e32 v83, 0xffffff80, v83
	v_sub_u32_e32 v83, v83, v14
	v_not_b32_e32 v93, v92
	v_or_b32_e32 v94, 0x80000000, v92
	v_cmp_gt_i32_e32 vcc, 0, v92
	v_add_u32_e32 v91, 0x7e, v91
	v_add_u32_e32 v83, 0x7f, v83
	v_cndmask_b32_e32 v92, v94, v93, vcc
	v_not_b32_e32 v93, v84
	v_or_b32_e32 v94, 0x80000000, v84
	v_cmp_gt_i32_e32 vcc, 0, v84
	v_and_b32_e32 v92, 0xffffff80, v92
	v_sub_u32_e32 v92, v92, v12
	v_cndmask_b32_e32 v84, v94, v93, vcc
	v_cvt_f32_f16_sdwa v93, v85 dst_sel:DWORD dst_unused:UNUSED_PAD src0_sel:WORD_1
	v_cvt_f32_f16_e32 v85, v85
	v_and_b32_e32 v84, 0xffffff80, v84
	v_sub_u32_e32 v84, v84, v12
	v_not_b32_e32 v94, v93
	v_or_b32_e32 v95, 0x80000000, v93
	v_cmp_gt_i32_e32 vcc, 0, v93
	v_add_u32_e32 v92, 0x7e, v92
	v_add_u32_e32 v84, 0x7f, v84
	v_cndmask_b32_e32 v93, v95, v94, vcc
	v_not_b32_e32 v94, v85
	v_or_b32_e32 v95, 0x80000000, v85
	v_cmp_gt_i32_e32 vcc, 0, v85
	v_and_b32_e32 v93, 0xffffff80, v93
	v_sub_u32_e32 v93, v93, v10
	v_cndmask_b32_e32 v85, v95, v94, vcc
	v_cvt_f32_f16_sdwa v94, v78 dst_sel:DWORD dst_unused:UNUSED_PAD src0_sel:WORD_1
	v_cvt_f32_f16_e32 v78, v78
	v_and_b32_e32 v85, 0xffffff80, v85
	v_sub_u32_e32 v85, v85, v10
	v_not_b32_e32 v95, v94
	v_or_b32_e32 v96, 0x80000000, v94
	v_cmp_gt_i32_e32 vcc, 0, v94
	v_add_u32_e32 v93, 0x7e, v93
	v_add_u32_e32 v85, 0x7f, v85
	v_cndmask_b32_e32 v94, v96, v95, vcc
	v_not_b32_e32 v95, v78
	v_or_b32_e32 v96, 0x80000000, v78
	v_cmp_gt_i32_e32 vcc, 0, v78
	v_and_b32_e32 v94, 0xffffff80, v94
	v_sub_u32_e32 v94, v94, v8
	v_cndmask_b32_e32 v78, v96, v95, vcc
	v_cvt_f32_f16_sdwa v95, v79 dst_sel:DWORD dst_unused:UNUSED_PAD src0_sel:WORD_1
	v_cvt_f32_f16_e32 v79, v79
	v_and_b32_e32 v78, 0xffffff80, v78
	v_sub_u32_e32 v78, v78, v8
	v_not_b32_e32 v96, v95
	v_or_b32_e32 v97, 0x80000000, v95
	v_cmp_gt_i32_e32 vcc, 0, v95
	v_add_u32_e32 v94, 0x7e, v94
	v_add_u32_e32 v78, 0x7f, v78
	v_cndmask_b32_e32 v95, v97, v96, vcc
	v_not_b32_e32 v96, v79
	v_or_b32_e32 v97, 0x80000000, v79
	v_cmp_gt_i32_e32 vcc, 0, v79
	v_and_b32_e32 v95, 0xffffff80, v95
	v_sub_u32_e32 v95, v95, v16
	v_cndmask_b32_e32 v79, v97, v96, vcc
	v_cvt_f32_f16_sdwa v96, v80 dst_sel:DWORD dst_unused:UNUSED_PAD src0_sel:WORD_1
	v_cvt_f32_f16_e32 v80, v80
	v_and_b32_e32 v79, 0xffffff80, v79
	v_sub_u32_e32 v79, v79, v16
	v_not_b32_e32 v97, v96
	v_or_b32_e32 v98, 0x80000000, v96
	v_cmp_gt_i32_e32 vcc, 0, v96
	v_add_u32_e32 v95, 0x7e, v95
	v_add_u32_e32 v79, 0x7f, v79
	v_cndmask_b32_e32 v96, v98, v97, vcc
	v_not_b32_e32 v97, v80
	v_or_b32_e32 v98, 0x80000000, v80
	v_cmp_gt_i32_e32 vcc, 0, v80
	v_and_b32_e32 v96, 0xffffff80, v96
	v_sub_u32_e32 v96, v96, v17
	v_cndmask_b32_e32 v80, v98, v97, vcc
	v_cvt_f32_f16_sdwa v97, v81 dst_sel:DWORD dst_unused:UNUSED_PAD src0_sel:WORD_1
	v_cvt_f32_f16_e32 v81, v81
	v_and_b32_e32 v80, 0xffffff80, v80
	v_sub_u32_e32 v80, v80, v17
	v_not_b32_e32 v98, v97
	v_or_b32_e32 v99, 0x80000000, v97
	v_cmp_gt_i32_e32 vcc, 0, v97
	v_add_u32_e32 v96, 0x7e, v96
	v_add_u32_e32 v80, 0x7f, v80
	v_cndmask_b32_e32 v97, v99, v98, vcc
	v_not_b32_e32 v98, v81
	v_or_b32_e32 v99, 0x80000000, v81
	v_cmp_gt_i32_e32 vcc, 0, v81
	v_and_b32_e32 v97, 0xffffff80, v97
	v_sub_u32_e32 v97, v97, v18
	v_cndmask_b32_e32 v81, v99, v98, vcc
	s_waitcnt vmcnt(0)
; __device__ __forceinline__ unsigned f2key(float f) { const unsigned u = __float_as_uint(f); return (u & 0x80000000u) ? ~u : (u | 0x80000000u); }
; #define CE_DESC(a, b) do { const unsigned _mx = (a) > (b) ? (a) : (b), _mn = (a) > (b) ? (b) : (a); (a) = _mx; (b) = _mn; } while (0)
; __device__ __forceinline__ void sort16_desc(unsigned (&k)[16]) {
; #pragma unroll
;     for (int size = 2; size <= 16; size <<= 1)
; #pragma unroll
;         for (int stride = size >> 1; stride > 0; stride >>= 1)
; #pragma unroll
;             for (int i = 0; i < 16; ++i) { const int j = i ^ stride;
;                 if (j > i) { if ((i & size) == 0) CE_DESC(k[i], k[j]); else CE_DESC(k[j], k[i]); } }
; }
; __device__ __forceinline__ void peer_tile(const Args& A, LAS unsigned char* lds, int tile) {
;     ...
;                   for (int i = 0; i < 16; ++i) {
;                       const float lo = (float)__builtin_bit_cast(_Float16, (unsigned short)(sw[i] & 0xffffu)), hi = (float)__builtin_bit_cast(_Float16, (unsigned short)(sw[i] >> 16));
;                       const unsigned klo = (f2key(lo) & ~127u) | (unsigned)(127 - (32 * g + 2 * i)), khi = (f2key(hi) & ~127u) | (unsigned)(127 - (32 * g + 2 * i + 1));
;                       if (i < 8) { k0[2 * i] = klo; k0[2 * i + 1] = khi; } else { k1[2 * (i - 8)] = klo; k1[2 * (i - 8) + 1] = khi; } } }
	v_cvt_f32_f16_sdwa v98, v86 dst_sel:DWORD dst_unused:UNUSED_PAD src0_sel:WORD_1
	v_cvt_f32_f16_e32 v86, v86
	v_and_b32_e32 v81, 0xffffff80, v81
	v_sub_u32_e32 v81, v81, v18
	v_not_b32_e32 v99, v98
	v_or_b32_e32 v100, 0x80000000, v98
	v_cmp_gt_i32_e32 vcc, 0, v98
	v_add_u32_e32 v97, 0x7e, v97
	v_add_u32_e32 v81, 0x7f, v81
	v_cndmask_b32_e32 v98, v100, v99, vcc
	v_not_b32_e32 v99, v86
	v_or_b32_e32 v100, 0x80000000, v86
	v_cmp_gt_i32_e32 vcc, 0, v86
	v_and_b32_e32 v98, 0xffffff80, v98
	v_sub_u32_e32 v98, v98, v20
	v_cndmask_b32_e32 v86, v100, v99, vcc
	v_cvt_f32_f16_sdwa v99, v87 dst_sel:DWORD dst_unused:UNUSED_PAD src0_sel:WORD_1
	v_cvt_f32_f16_e32 v87, v87
	v_and_b32_e32 v86, 0xffffff80, v86
	v_sub_u32_e32 v86, v86, v20
	v_not_b32_e32 v100, v99
	v_or_b32_e32 v101, 0x80000000, v99
	v_cmp_gt_i32_e32 vcc, 0, v99
	v_add_u32_e32 v98, 0x7e, v98
	v_add_u32_e32 v86, 0x7f, v86
	v_cndmask_b32_e32 v99, v101, v100, vcc
	v_not_b32_e32 v100, v87
	v_or_b32_e32 v101, 0x80000000, v87
	v_cmp_gt_i32_e32 vcc, 0, v87
	v_and_b32_e32 v99, 0xffffff80, v99
	v_sub_u32_e32 v99, v99, v21
	v_cndmask_b32_e32 v87, v101, v100, vcc
	v_cvt_f32_f16_sdwa v100, v88 dst_sel:DWORD dst_unused:UNUSED_PAD src0_sel:WORD_1
	v_cvt_f32_f16_e32 v88, v88
	v_and_b32_e32 v87, 0xffffff80, v87
	v_sub_u32_e32 v87, v87, v21
	v_not_b32_e32 v101, v100
	v_or_b32_e32 v102, 0x80000000, v100
	v_cmp_gt_i32_e32 vcc, 0, v100
	v_add_u32_e32 v99, 0x7e, v99
	v_add_u32_e32 v87, 0x7f, v87
	v_cndmask_b32_e32 v100, v102, v101, vcc
	v_not_b32_e32 v101, v88
	v_or_b32_e32 v102, 0x80000000, v88
	v_cmp_gt_i32_e32 vcc, 0, v88
	v_and_b32_e32 v100, 0xffffff80, v100
	v_sub_u32_e32 v100, v100, v22
	v_cndmask_b32_e32 v88, v102, v101, vcc
	v_cvt_f32_f16_sdwa v101, v89 dst_sel:DWORD dst_unused:UNUSED_PAD src0_sel:WORD_1
	v_cvt_f32_f16_e32 v89, v89
	v_and_b32_e32 v88, 0xffffff80, v88
	v_sub_u32_e32 v88, v88, v22
	v_not_b32_e32 v102, v101
	v_or_b32_e32 v103, 0x80000000, v101
	v_cmp_gt_i32_e32 vcc, 0, v101
	v_add_u32_e32 v100, 0x7e, v100
	v_add_u32_e32 v88, 0x7f, v88
	v_cndmask_b32_e32 v101, v103, v102, vcc
	v_not_b32_e32 v102, v89
	v_or_b32_e32 v103, 0x80000000, v89
	v_cmp_gt_i32_e32 vcc, 0, v89
	v_and_b32_e32 v101, 0xffffff80, v101
	v_sub_u32_e32 v101, v101, v23
	v_cndmask_b32_e32 v89, v103, v102, vcc
	v_cvt_f32_f16_sdwa v102, v0 dst_sel:DWORD dst_unused:UNUSED_PAD src0_sel:WORD_1
	v_cvt_f32_f16_e32 v0, v0
	v_and_b32_e32 v89, 0xffffff80, v89
	v_sub_u32_e32 v89, v89, v23
	v_not_b32_e32 v103, v102
	v_or_b32_e32 v104, 0x80000000, v102
	v_cmp_gt_i32_e32 vcc, 0, v102
	v_add_u32_e32 v101, 0x7e, v101
	v_add_u32_e32 v89, 0x7f, v89
	v_cndmask_b32_e32 v102, v104, v103, vcc
	v_not_b32_e32 v103, v0
	v_or_b32_e32 v104, 0x80000000, v0
	v_cmp_gt_i32_e32 vcc, 0, v0
	v_and_b32_e32 v102, 0xffffff80, v102
	v_sub_u32_e32 v102, v102, v24
	v_cndmask_b32_e32 v0, v104, v103, vcc
	v_cvt_f32_f16_sdwa v103, v1 dst_sel:DWORD dst_unused:UNUSED_PAD src0_sel:WORD_1
	v_cvt_f32_f16_e32 v1, v1
	v_and_b32_e32 v0, 0xffffff80, v0
	v_sub_u32_e32 v0, v0, v24
	v_not_b32_e32 v104, v103
	v_or_b32_e32 v105, 0x80000000, v103
	v_cmp_gt_i32_e32 vcc, 0, v103
	v_add_u32_e32 v102, 0x7e, v102
	v_add_u32_e32 v0, 0x7f, v0
	v_cndmask_b32_e32 v103, v105, v104, vcc
	v_not_b32_e32 v104, v1
	v_or_b32_e32 v105, 0x80000000, v1
	v_cmp_gt_i32_e32 vcc, 0, v1
	v_and_b32_e32 v103, 0xffffff80, v103
	v_sub_u32_e32 v103, v103, v25
	v_cndmask_b32_e32 v1, v105, v104, vcc
	v_cvt_f32_f16_sdwa v104, v2 dst_sel:DWORD dst_unused:UNUSED_PAD src0_sel:WORD_1
	v_cvt_f32_f16_e32 v2, v2
	v_and_b32_e32 v1, 0xffffff80, v1
	v_sub_u32_e32 v1, v1, v25
	v_not_b32_e32 v105, v104
	v_or_b32_e32 v106, 0x80000000, v104
	v_cmp_gt_i32_e32 vcc, 0, v104
	v_add_u32_e32 v103, 0x7e, v103
	v_add_u32_e32 v1, 0x7f, v1
	v_cndmask_b32_e32 v104, v106, v105, vcc
	v_not_b32_e32 v105, v2
	v_or_b32_e32 v106, 0x80000000, v2
	v_cmp_gt_i32_e32 vcc, 0, v2
	v_and_b32_e32 v104, 0xffffff80, v104
	v_sub_u32_e32 v104, v104, v26
	v_cndmask_b32_e32 v2, v106, v105, vcc
	v_cvt_f32_f16_sdwa v105, v3 dst_sel:DWORD dst_unused:UNUSED_PAD src0_sel:WORD_1
	v_cvt_f32_f16_e32 v3, v3
	v_and_b32_e32 v2, 0xffffff80, v2
	v_sub_u32_e32 v2, v2, v26
	v_not_b32_e32 v106, v105
	v_or_b32_e32 v107, 0x80000000, v105
	v_cmp_gt_i32_e32 vcc, 0, v105
	v_add_u32_e32 v104, 0x7e, v104
	v_add_u32_e32 v2, 0x7f, v2
	v_cndmask_b32_e32 v105, v107, v106, vcc
	v_not_b32_e32 v106, v3
	v_or_b32_e32 v107, 0x80000000, v3
	v_cmp_gt_i32_e32 vcc, 0, v3
	v_and_b32_e32 v105, 0xffffff80, v105
	v_sub_u32_e32 v105, v105, v28
	v_cndmask_b32_e32 v3, v107, v106, vcc
	v_and_b32_e32 v3, 0xffffff80, v3
	v_sub_u32_e32 v3, v3, v28
	v_add_u32_e32 v105, 0x7e, v105
	v_add_u32_e32 v3, 0x7f, v3
	v_max_u32_e32 v106, v82, v90
	v_min_u32_e32 v82, v82, v90
	v_max_u32_e32 v90, v91, v83
	v_min_u32_e32 v83, v91, v83
	v_max_u32_e32 v91, v84, v92
	v_min_u32_e32 v84, v84, v92
	v_max_u32_e32 v92, v93, v85
	v_min_u32_e32 v85, v93, v85
	v_max_u32_e32 v93, v78, v94
	v_min_u32_e32 v78, v78, v94
	v_max_u32_e32 v94, v95, v79
	v_min_u32_e32 v79, v95, v79
	v_max_u32_e32 v95, v80, v96
	v_min_u32_e32 v80, v80, v96
	v_max_u32_e32 v96, v97, v81
	v_min_u32_e32 v81, v97, v81
	v_max_u32_e32 v115, v86, v98
	v_min_u32_e32 v86, v86, v98
	v_max_u32_e32 v98, v99, v87
	v_min_u32_e32 v87, v99, v87
	v_max_u32_e32 v99, v88, v100
	v_min_u32_e32 v88, v88, v100
	v_max_u32_e32 v100, v101, v89
	v_min_u32_e32 v89, v101, v89
	v_max_u32_e32 v101, v0, v102
	v_min_u32_e32 v0, v0, v102
	v_max_u32_e32 v102, v103, v1
	v_min_u32_e32 v1, v103, v1
	v_max_u32_e32 v103, v2, v104
	v_min_u32_e32 v2, v2, v104
	v_max_u32_e32 v104, v105, v3
	v_min_u32_e32 v3, v105, v3
	v_max_u32_e32 v97, v106, v83
	v_min_u32_e32 v83, v106, v83
	v_max_u32_e32 v106, v82, v90
; #define CE_DESC(a, b) do { const unsigned _mx = (a) > (b) ? (a) : (b), _mn = (a) > (b) ? (b) : (a); (a) = _mx; (b) = _mn; } while (0)
; __device__ __forceinline__ void sort16_desc(unsigned (&k)[16]) {
; #pragma unroll
;     for (int size = 2; size <= 16; size <<= 1)
; #pragma unroll
;         for (int stride = size >> 1; stride > 0; stride >>= 1)
; #pragma unroll
;             for (int i = 0; i < 16; ++i) { const int j = i ^ stride;
;                 if (j > i) { if ((i & size) == 0) CE_DESC(k[i], k[j]); else CE_DESC(k[j], k[i]); } }
; }
	v_min_u32_e32 v82, v82, v90
	v_max_u32_e32 v90, v85, v91
	v_min_u32_e32 v85, v85, v91
	v_max_u32_e32 v91, v92, v84
	v_min_u32_e32 v84, v92, v84
	v_max_u32_e32 v92, v93, v79
	v_min_u32_e32 v79, v93, v79
	v_max_u32_e32 v93, v78, v94
	v_min_u32_e32 v78, v78, v94
	v_max_u32_e32 v94, v81, v95
	v_min_u32_e32 v81, v81, v95
	v_max_u32_e32 v95, v96, v80
	v_min_u32_e32 v80, v96, v80
	v_max_u32_e32 v105, v115, v87
	v_min_u32_e32 v87, v115, v87
	v_max_u32_e32 v115, v86, v98
	v_min_u32_e32 v86, v86, v98
	v_max_u32_e32 v98, v89, v99
	v_min_u32_e32 v89, v89, v99
	v_max_u32_e32 v99, v100, v88
	v_min_u32_e32 v88, v100, v88
	v_max_u32_e32 v100, v101, v1
	v_min_u32_e32 v1, v101, v1
	v_max_u32_e32 v101, v0, v102
	v_min_u32_e32 v0, v0, v102
	v_max_u32_e32 v102, v3, v103
	v_min_u32_e32 v3, v3, v103
	v_max_u32_e32 v103, v104, v2
	v_min_u32_e32 v2, v104, v2
	v_max_u32_e32 v96, v97, v106
	v_min_u32_e32 v97, v97, v106
	v_max_u32_e32 v106, v83, v82
	v_min_u32_e32 v82, v83, v82
	v_max_u32_e32 v83, v84, v85
	v_min_u32_e32 v84, v84, v85
	v_max_u32_e32 v85, v91, v90
	v_min_u32_e32 v90, v91, v90
	v_max_u32_e32 v91, v92, v93
	v_min_u32_e32 v92, v92, v93
	v_max_u32_e32 v93, v79, v78
	v_min_u32_e32 v78, v79, v78
	v_max_u32_e32 v79, v80, v81
	v_min_u32_e32 v80, v80, v81
	v_max_u32_e32 v81, v95, v94
	v_min_u32_e32 v94, v95, v94
	v_max_u32_e32 v104, v105, v115
	v_min_u32_e32 v105, v105, v115
	v_max_u32_e32 v115, v87, v86
	v_min_u32_e32 v86, v87, v86
	v_max_u32_e32 v87, v88, v89
	v_min_u32_e32 v88, v88, v89
	v_max_u32_e32 v89, v99, v98
	v_min_u32_e32 v98, v99, v98
	v_max_u32_e32 v99, v100, v101
	v_min_u32_e32 v100, v100, v101
	v_max_u32_e32 v101, v1, v0
	v_min_u32_e32 v0, v1, v0
	v_max_u32_e32 v1, v2, v3
	v_min_u32_e32 v2, v2, v3
	v_max_u32_e32 v3, v103, v102
	v_min_u32_e32 v102, v103, v102
	v_max_u32_e32 v95, v96, v84
	v_min_u32_e32 v84, v96, v84
	v_max_u32_e32 v96, v97, v83
	v_min_u32_e32 v83, v97, v83
	v_max_u32_e32 v97, v106, v90
	v_min_u32_e32 v90, v106, v90
	v_max_u32_e32 v106, v82, v85
	v_min_u32_e32 v82, v82, v85
	v_max_u32_e32 v85, v80, v91
	v_min_u32_e32 v80, v80, v91
	v_max_u32_e32 v91, v79, v92
	v_min_u32_e32 v79, v79, v92
	v_max_u32_e32 v92, v94, v93
	v_min_u32_e32 v93, v94, v93
	v_max_u32_e32 v94, v81, v78
	v_min_u32_e32 v78, v81, v78
	v_max_u32_e32 v103, v104, v88
	v_min_u32_e32 v88, v104, v88
	v_max_u32_e32 v104, v105, v87
	v_min_u32_e32 v87, v105, v87
	v_max_u32_e32 v105, v115, v98
	v_min_u32_e32 v98, v115, v98
	v_max_u32_e32 v115, v86, v89
	v_min_u32_e32 v86, v86, v89
	v_max_u32_e32 v89, v2, v99
	v_min_u32_e32 v2, v2, v99
	v_max_u32_e32 v99, v1, v100
	v_min_u32_e32 v1, v1, v100
	v_max_u32_e32 v100, v102, v101
	v_min_u32_e32 v101, v102, v101
	v_max_u32_e32 v102, v3, v0
	v_min_u32_e32 v0, v3, v0
	v_max_u32_e32 v81, v95, v97
	v_min_u32_e32 v95, v95, v97
	v_max_u32_e32 v97, v96, v106
	v_min_u32_e32 v96, v96, v106
	v_max_u32_e32 v106, v84, v90
	v_min_u32_e32 v84, v84, v90
	v_max_u32_e32 v90, v83, v82
	v_min_u32_e32 v82, v83, v82
	v_max_u32_e32 v83, v93, v80
	v_min_u32_e32 v80, v93, v80
	v_max_u32_e32 v93, v78, v79
	v_min_u32_e32 v78, v78, v79
	v_max_u32_e32 v79, v92, v85
	v_min_u32_e32 v85, v92, v85
	v_max_u32_e32 v92, v94, v91
	v_min_u32_e32 v91, v94, v91
	v_max_u32_e32 v3, v103, v105
	v_min_u32_e32 v103, v103, v105
	v_max_u32_e32 v105, v104, v115
	v_min_u32_e32 v104, v104, v115
	v_max_u32_e32 v115, v88, v98
	v_min_u32_e32 v88, v88, v98
	v_max_u32_e32 v98, v87, v86
	v_min_u32_e32 v86, v87, v86
	v_max_u32_e32 v87, v101, v2
	v_min_u32_e32 v2, v101, v2
	v_max_u32_e32 v101, v0, v1
	v_min_u32_e32 v0, v0, v1
	v_max_u32_e32 v1, v100, v89
	v_min_u32_e32 v89, v100, v89
	v_max_u32_e32 v100, v102, v99
	v_min_u32_e32 v99, v102, v99
	v_max_u32_e32 v94, v81, v97
	v_min_u32_e32 v81, v81, v97
	v_max_u32_e32 v97, v95, v96
	v_min_u32_e32 v95, v95, v96
	v_max_u32_e32 v96, v106, v90
	v_min_u32_e32 v90, v106, v90
	v_max_u32_e32 v106, v84, v82
	v_min_u32_e32 v82, v84, v82
	v_max_u32_e32 v84, v78, v80
	v_min_u32_e32 v78, v78, v80
	v_max_u32_e32 v80, v93, v83
	v_min_u32_e32 v83, v93, v83
	v_max_u32_e32 v93, v91, v85
	v_min_u32_e32 v85, v91, v85
	v_max_u32_e32 v91, v92, v79
	v_min_u32_e32 v79, v92, v79
	v_max_u32_e32 v102, v3, v105
	v_min_u32_e32 v3, v3, v105
	v_max_u32_e32 v105, v103, v104
	v_min_u32_e32 v103, v103, v104
	v_max_u32_e32 v104, v115, v98
	v_min_u32_e32 v98, v115, v98
	v_max_u32_e32 v115, v88, v86
	v_min_u32_e32 v86, v88, v86
	v_max_u32_e32 v88, v0, v2
	v_min_u32_e32 v0, v0, v2
	v_max_u32_e32 v2, v101, v87
	v_min_u32_e32 v87, v101, v87
	v_max_u32_e32 v101, v99, v89
	v_min_u32_e32 v89, v99, v89
	v_max_u32_e32 v99, v100, v1
	v_min_u32_e32 v1, v100, v1
	v_max_u32_e32 v92, v94, v78
	v_min_u32_e32 v78, v94, v78
	v_max_u32_e32 v94, v81, v84
	v_min_u32_e32 v81, v81, v84
	v_max_u32_e32 v84, v97, v83
	v_min_u32_e32 v83, v97, v83
	v_max_u32_e32 v97, v95, v80
	v_min_u32_e32 v80, v95, v80
	v_max_u32_e32 v95, v96, v85
	v_min_u32_e32 v85, v96, v85
	v_max_u32_e32 v96, v90, v93
	v_min_u32_e32 v90, v90, v93
	v_max_u32_e32 v93, v106, v79
	v_min_u32_e32 v79, v106, v79
	v_max_u32_e32 v106, v82, v91
	v_min_u32_e32 v82, v82, v91
	v_max_u32_e32 v100, v102, v0
	v_min_u32_e32 v0, v102, v0
	v_max_u32_e32 v102, v3, v88
	v_min_u32_e32 v3, v3, v88
	v_max_u32_e32 v88, v105, v87
	v_min_u32_e32 v87, v105, v87
	v_max_u32_e32 v105, v103, v2
	v_min_u32_e32 v2, v103, v2
	v_max_u32_e32 v103, v104, v89
	v_min_u32_e32 v89, v104, v89
	v_max_u32_e32 v104, v98, v101
	v_min_u32_e32 v98, v98, v101
	v_max_u32_e32 v101, v115, v1
	v_min_u32_e32 v1, v115, v1
	v_max_u32_e32 v115, v86, v99
	v_min_u32_e32 v86, v86, v99
	v_max_u32_e32 v91, v92, v95
	v_min_u32_e32 v92, v92, v95
	v_max_u32_e32 v95, v94, v96
; #define CE_DESC(a, b) do { const unsigned _mx = (a) > (b) ? (a) : (b), _mn = (a) > (b) ? (b) : (a); (a) = _mx; (b) = _mn; } while (0)
; __device__ __forceinline__ void merge16(unsigned (&a)[16], const unsigned (&b)[16]) {
; #pragma unroll
;     for (int i = 0; i < 16; ++i) a[i] = a[i] > b[15 - i] ? a[i] : b[15 - i];
; #pragma unroll
;     for (int stride = 8; stride > 0; stride >>= 1)
; #pragma unroll
;         for (int i = 0; i < 16; ++i) { const int j = i ^ stride; if (j > i) CE_DESC(a[i], a[j]); }
; }
; __device__ __forceinline__ void peer_tile(const Args& A, LAS unsigned char* lds, int tile) {
;     ...
;                 for (int msk = 16; msk <= 32; msk <<= 1) {
; #pragma unroll
;                     for (int i = 0; i < 16; ++i) k1[i] = (unsigned)__shfl_xor((int)k0[i], msk);
;                     merge16(k0, k1); }
	v_min_u32_e32 v94, v94, v96
	v_max_u32_e32 v96, v84, v93
	v_min_u32_e32 v84, v84, v93
	v_max_u32_e32 v93, v97, v106
	v_min_u32_e32 v97, v97, v106
	v_max_u32_e32 v106, v78, v85
	v_min_u32_e32 v78, v78, v85
	v_max_u32_e32 v85, v81, v90
	v_min_u32_e32 v81, v81, v90
	v_max_u32_e32 v90, v83, v79
	v_min_u32_e32 v79, v83, v79
	v_max_u32_e32 v83, v80, v82
	v_min_u32_e32 v80, v80, v82
	v_max_u32_e32 v99, v100, v103
	v_min_u32_e32 v100, v100, v103
	v_max_u32_e32 v103, v102, v104
	v_min_u32_e32 v102, v102, v104
	v_max_u32_e32 v104, v88, v101
	v_min_u32_e32 v88, v88, v101
	v_max_u32_e32 v101, v105, v115
	v_min_u32_e32 v105, v105, v115
	v_max_u32_e32 v115, v0, v89
	v_min_u32_e32 v0, v0, v89
	v_max_u32_e32 v89, v3, v98
	v_min_u32_e32 v3, v3, v98
	v_max_u32_e32 v98, v87, v1
	v_min_u32_e32 v1, v87, v1
	v_max_u32_e32 v87, v2, v86
	v_min_u32_e32 v2, v2, v86
	v_max_u32_e32 v82, v91, v96
	v_min_u32_e32 v91, v91, v96
	v_max_u32_e32 v96, v95, v93
	v_min_u32_e32 v93, v95, v93
	v_max_u32_e32 v95, v92, v84
	v_min_u32_e32 v84, v92, v84
	v_max_u32_e32 v92, v94, v97
	v_min_u32_e32 v94, v94, v97
	v_max_u32_e32 v97, v106, v90
	v_min_u32_e32 v90, v106, v90
	v_max_u32_e32 v106, v85, v83
	v_min_u32_e32 v83, v85, v83
	v_max_u32_e32 v85, v78, v79
	v_min_u32_e32 v78, v78, v79
	v_max_u32_e32 v79, v81, v80
	v_min_u32_e32 v80, v81, v80
	v_max_u32_e32 v86, v99, v104
	v_min_u32_e32 v99, v99, v104
	v_max_u32_e32 v104, v103, v101
	v_min_u32_e32 v101, v103, v101
	v_max_u32_e32 v103, v100, v88
	v_min_u32_e32 v88, v100, v88
	v_max_u32_e32 v100, v102, v105
	v_min_u32_e32 v102, v102, v105
	v_max_u32_e32 v105, v115, v98
	v_min_u32_e32 v98, v115, v98
	v_max_u32_e32 v115, v89, v87
	v_min_u32_e32 v87, v89, v87
	v_max_u32_e32 v89, v0, v1
	v_min_u32_e32 v0, v0, v1
	v_max_u32_e32 v1, v3, v2
	v_min_u32_e32 v2, v3, v2
	v_min_u32_e32 v81, v82, v96
	v_min_u32_e32 v107, v91, v93
	v_min_u32_e32 v108, v95, v92
	v_min_u32_e32 v109, v84, v94
	v_min_u32_e32 v110, v97, v106
	v_min_u32_e32 v111, v90, v83
	v_min_u32_e32 v112, v85, v79
	v_min_u32_e32 v114, v78, v80
	v_min_u32_e32 v3, v86, v104
	v_min_u32_e32 v116, v99, v101
	v_min_u32_e32 v117, v103, v100
	v_min_u32_e32 v118, v88, v102
	v_min_u32_e32 v119, v105, v115
	v_min_u32_e32 v120, v98, v87
	v_min_u32_e32 v121, v89, v1
	v_min_u32_e32 v122, v0, v2
	v_max3_u32 v82, v82, v96, v122
	v_max3_u32 v0, v81, v0, v2
	v_max3_u32 v2, v91, v93, v121
	v_max3_u32 v1, v107, v89, v1
	v_max3_u32 v81, v95, v92, v120
	v_max3_u32 v87, v108, v98, v87
	v_max3_u32 v84, v84, v94, v119
	v_max3_u32 v89, v109, v105, v115
	v_max3_u32 v91, v97, v106, v118
	v_max3_u32 v88, v110, v88, v102
	v_max3_u32 v83, v90, v83, v117
	v_max3_u32 v90, v111, v103, v100
	v_max3_u32 v79, v85, v79, v116
	v_max3_u32 v85, v112, v99, v101
	v_max3_u32 v3, v78, v80, v3
	v_max3_u32 v78, v114, v86, v104
	v_max_u32_e32 v80, v82, v91
	v_min_u32_e32 v82, v82, v91
	v_max_u32_e32 v86, v0, v88
	v_min_u32_e32 v0, v0, v88
	v_max_u32_e32 v88, v2, v83
	v_min_u32_e32 v2, v2, v83
	v_max_u32_e32 v83, v1, v90
	v_min_u32_e32 v1, v1, v90
	v_max_u32_e32 v90, v81, v79
	v_min_u32_e32 v79, v81, v79
	v_max_u32_e32 v81, v87, v85
	v_min_u32_e32 v85, v87, v85
	v_max_u32_e32 v87, v84, v3
	v_min_u32_e32 v3, v84, v3
	v_max_u32_e32 v84, v89, v78
	v_min_u32_e32 v78, v89, v78
	v_max_u32_e32 v89, v80, v90
	v_min_u32_e32 v80, v80, v90
	v_max_u32_e32 v90, v86, v81
	v_min_u32_e32 v81, v86, v81
	v_max_u32_e32 v86, v88, v87
	v_min_u32_e32 v87, v88, v87
	v_max_u32_e32 v88, v83, v84
	v_min_u32_e32 v83, v83, v84
	v_max_u32_e32 v84, v82, v79
	v_min_u32_e32 v79, v82, v79
	v_max_u32_e32 v82, v0, v85
	v_min_u32_e32 v0, v0, v85
	v_max_u32_e32 v85, v2, v3
	v_min_u32_e32 v2, v2, v3
	v_max_u32_e32 v3, v1, v78
	v_min_u32_e32 v1, v1, v78
	v_max_u32_e32 v78, v89, v86
	v_min_u32_e32 v86, v89, v86
	v_max_u32_e32 v89, v90, v88
	v_min_u32_e32 v88, v90, v88
	v_max_u32_e32 v90, v80, v87
	v_min_u32_e32 v80, v80, v87
	v_max_u32_e32 v87, v81, v83
	v_min_u32_e32 v81, v81, v83
	v_max_u32_e32 v83, v84, v85
	v_min_u32_e32 v84, v84, v85
	v_max_u32_e32 v85, v82, v3
	v_min_u32_e32 v3, v82, v3
	v_max_u32_e32 v82, v79, v2
	v_min_u32_e32 v2, v79, v2
	v_max_u32_e32 v79, v0, v1
	v_min_u32_e32 v0, v0, v1
	v_max_u32_e32 v1, v78, v89
	v_min_u32_e32 v78, v78, v89
	v_max_u32_e32 v89, v86, v88
	v_min_u32_e32 v86, v86, v88
	v_max_u32_e32 v88, v90, v87
	v_min_u32_e32 v87, v90, v87
	v_max_u32_e32 v90, v80, v81
	v_min_u32_e32 v80, v80, v81
	v_max_u32_e32 v81, v83, v85
	v_min_u32_e32 v83, v83, v85
	v_max_u32_e32 v85, v84, v3
	v_min_u32_e32 v3, v84, v3
	v_max_u32_e32 v84, v82, v79
	v_min_u32_e32 v79, v82, v79
	v_max_u32_e32 v82, v2, v0
	v_min_u32_e32 v0, v2, v0
	ds_bpermute_b32 v2, v27, v1
	ds_bpermute_b32 v91, v27, v78
	ds_bpermute_b32 v92, v27, v89
	ds_bpermute_b32 v93, v27, v86
	ds_bpermute_b32 v94, v27, v88
	ds_bpermute_b32 v95, v27, v87
	ds_bpermute_b32 v96, v27, v90
	ds_bpermute_b32 v97, v27, v80
	ds_bpermute_b32 v98, v27, v81
	ds_bpermute_b32 v99, v27, v83
	ds_bpermute_b32 v100, v27, v85
	ds_bpermute_b32 v101, v27, v0
	ds_bpermute_b32 v102, v27, v82
	ds_bpermute_b32 v103, v27, v79
	ds_bpermute_b32 v104, v27, v84
	ds_bpermute_b32 v105, v27, v3
	s_waitcnt lgkmcnt(4)
	v_max_u32_e32 v1, v1, v101
	s_waitcnt lgkmcnt(3)
	v_max_u32_e32 v78, v78, v102
	s_waitcnt lgkmcnt(2)
	v_max_u32_e32 v89, v89, v103
	s_waitcnt lgkmcnt(1)
	v_max_u32_e32 v86, v86, v104
	s_waitcnt lgkmcnt(0)
; __device__ __forceinline__ void peer_tile(const Args& A, LAS unsigned char* lds, int tile) {
;     ...
;                 { const bf16_t* sp = QRY + m * 2048 + hp * 128 + 32 * g;
;                   const u32x4 s0 = *(const u32x4*)sp, s1 = *(const u32x4*)(sp + 8), s2 = *(const u32x4*)(sp + 16), s3 = *(const u32x4*)(sp + 24);
;     ...
;                 for (int msk = 16; msk <= 32; msk <<= 1) {
; #pragma unroll
;                     for (int i = 0; i < 16; ++i) k1[i] = (unsigned)__shfl_xor((int)k0[i], msk);
;                     merge16(k0, k1); }
; #pragma unroll
;                 for (int i = 0; i < 16; ++i) LA[hh][p][i] = k0[i];
	v_max_u32_e32 v88, v88, v105
	v_max_u32_e32 v87, v87, v100
	v_max_u32_e32 v90, v90, v99
	v_max_u32_e32 v80, v80, v98
	v_max_u32_e32 v81, v81, v97
	v_max_u32_e32 v83, v83, v96
	v_max_u32_e32 v85, v85, v95
	v_max_u32_e32 v3, v3, v94
	v_max_u32_e32 v84, v84, v93
	v_max_u32_e32 v79, v79, v92
	v_max_u32_e32 v82, v82, v91
	v_max_u32_e32 v0, v0, v2
	v_max_u32_e32 v2, v1, v81
	v_min_u32_e32 v1, v1, v81
	v_max_u32_e32 v81, v78, v83
	v_min_u32_e32 v78, v78, v83
	v_max_u32_e32 v83, v89, v85
	v_min_u32_e32 v85, v89, v85
	v_max_u32_e32 v89, v86, v3
	v_min_u32_e32 v3, v86, v3
	v_max_u32_e32 v86, v88, v84
	v_min_u32_e32 v84, v88, v84
	v_max_u32_e32 v88, v87, v79
	v_min_u32_e32 v79, v87, v79
	v_max_u32_e32 v87, v90, v82
	v_min_u32_e32 v82, v90, v82
	v_max_u32_e32 v90, v80, v0
	v_min_u32_e32 v0, v80, v0
	v_max_u32_e32 v80, v2, v86
	v_min_u32_e32 v2, v2, v86
	v_max_u32_e32 v86, v81, v88
	v_min_u32_e32 v81, v81, v88
	v_max_u32_e32 v88, v83, v87
	v_min_u32_e32 v83, v83, v87
	v_max_u32_e32 v87, v89, v90
	v_min_u32_e32 v89, v89, v90
	v_max_u32_e32 v90, v1, v84
	v_min_u32_e32 v1, v1, v84
	v_max_u32_e32 v84, v78, v79
	v_min_u32_e32 v78, v78, v79
	v_max_u32_e32 v79, v85, v82
	v_min_u32_e32 v82, v85, v82
	v_max_u32_e32 v85, v3, v0
	v_min_u32_e32 v0, v3, v0
	v_max_u32_e32 v3, v80, v88
	v_min_u32_e32 v80, v80, v88
	v_max_u32_e32 v88, v86, v87
	v_min_u32_e32 v86, v86, v87
	v_max_u32_e32 v87, v2, v83
	v_min_u32_e32 v2, v2, v83
	v_max_u32_e32 v83, v81, v89
	v_min_u32_e32 v81, v81, v89
	v_max_u32_e32 v89, v90, v79
	v_min_u32_e32 v79, v90, v79
	v_max_u32_e32 v90, v84, v85
	v_min_u32_e32 v84, v84, v85
	v_max_u32_e32 v85, v1, v82
	v_min_u32_e32 v1, v1, v82
	v_max_u32_e32 v82, v78, v0
	v_min_u32_e32 v0, v78, v0
	v_max_u32_e32 v78, v3, v88
	v_min_u32_e32 v3, v3, v88
	v_max_u32_e32 v88, v80, v86
	v_min_u32_e32 v80, v80, v86
	v_max_u32_e32 v86, v87, v83
	v_min_u32_e32 v83, v87, v83
	v_max_u32_e32 v87, v2, v81
	v_min_u32_e32 v2, v2, v81
	v_max_u32_e32 v81, v89, v90
	v_min_u32_e32 v89, v89, v90
	v_max_u32_e32 v90, v79, v84
	v_min_u32_e32 v79, v79, v84
	v_max_u32_e32 v84, v85, v82
	v_min_u32_e32 v82, v85, v82
	v_max_u32_e32 v85, v1, v0
	v_min_u32_e32 v0, v1, v0
	ds_bpermute_b32 v94, v29, v0
	ds_bpermute_b32 v1, v29, v78
	ds_bpermute_b32 v91, v29, v3
	ds_bpermute_b32 v92, v29, v88
	ds_bpermute_b32 v93, v29, v80
	s_waitcnt lgkmcnt(4)
	v_max_u32_e32 v78, v78, v94
	global_load_dwordx4 v[94:97], v[4:5], off offset:1040
	global_load_dwordx4 v[98:101], v[4:5], off offset:1024
	ds_bpermute_b32 v102, v29, v86
	ds_bpermute_b32 v103, v29, v83
	ds_bpermute_b32 v104, v29, v87
	ds_bpermute_b32 v105, v29, v2
	ds_bpermute_b32 v106, v29, v81
	ds_bpermute_b32 v107, v29, v89
	ds_bpermute_b32 v108, v29, v90
	ds_bpermute_b32 v109, v29, v79
	ds_bpermute_b32 v110, v29, v84
	ds_bpermute_b32 v111, v29, v85
	ds_bpermute_b32 v112, v29, v82
	s_waitcnt lgkmcnt(4)
	v_max_u32_e32 v83, v83, v108
	s_waitcnt lgkmcnt(3)
	v_max_u32_e32 v86, v86, v109
	s_waitcnt lgkmcnt(2)
	v_max_u32_e32 v80, v80, v110
	s_waitcnt lgkmcnt(1)
	v_max_u32_e32 v3, v3, v111
	s_waitcnt lgkmcnt(0)
	v_max_u32_e32 v88, v88, v112
	v_max_u32_e32 v87, v87, v107
	v_max_u32_e32 v2, v2, v106
	v_max_u32_e32 v81, v81, v105
	v_max_u32_e32 v89, v89, v104
	v_max_u32_e32 v90, v90, v103
	v_max_u32_e32 v79, v79, v102
	v_max_u32_e32 v84, v84, v93
	v_max_u32_e32 v82, v82, v92
	v_max_u32_e32 v85, v85, v91
	v_max_u32_e32 v0, v0, v1
	v_max_u32_e32 v1, v78, v81
	v_min_u32_e32 v78, v78, v81
	v_max_u32_e32 v81, v3, v89
	v_min_u32_e32 v3, v3, v89
	v_max_u32_e32 v89, v88, v90
	v_min_u32_e32 v88, v88, v90
	v_max_u32_e32 v90, v80, v79
	v_min_u32_e32 v79, v80, v79
	v_max_u32_e32 v80, v86, v84
	v_min_u32_e32 v84, v86, v84
	v_max_u32_e32 v86, v83, v82
	v_min_u32_e32 v82, v83, v82
	v_max_u32_e32 v83, v87, v85
	v_min_u32_e32 v85, v87, v85
	v_max_u32_e32 v87, v2, v0
	v_min_u32_e32 v0, v2, v0
	v_max_u32_e32 v2, v1, v80
	v_min_u32_e32 v1, v1, v80
	v_max_u32_e32 v80, v81, v86
	v_min_u32_e32 v81, v81, v86
	v_max_u32_e32 v86, v89, v83
	v_min_u32_e32 v83, v89, v83
	v_max_u32_e32 v89, v90, v87
	v_min_u32_e32 v87, v90, v87
	v_max_u32_e32 v90, v78, v84
	v_min_u32_e32 v78, v78, v84
	v_max_u32_e32 v84, v3, v82
	v_min_u32_e32 v3, v3, v82
	v_max_u32_e32 v82, v88, v85
	v_min_u32_e32 v85, v88, v85
	v_max_u32_e32 v88, v79, v0
	v_min_u32_e32 v0, v79, v0
	v_max_u32_e32 v79, v2, v86
	v_min_u32_e32 v2, v2, v86
	v_max_u32_e32 v86, v80, v89
	v_min_u32_e32 v80, v80, v89
	v_max_u32_e32 v102, v1, v83
	v_min_u32_e32 v1, v1, v83
	v_max_u32_e32 v83, v81, v87
	v_min_u32_e32 v81, v81, v87
	v_max_u32_e32 v103, v90, v82
	v_min_u32_e32 v82, v90, v82
	v_max_u32_e32 v104, v84, v88
	v_min_u32_e32 v105, v84, v88
	v_max_u32_e32 v106, v78, v85
	v_min_u32_e32 v78, v78, v85
	v_max_u32_e32 v107, v3, v0
	v_min_u32_e32 v0, v3, v0
	v_max_u32_e32 v93, v79, v86
	v_min_u32_e32 v92, v79, v86
	v_max_u32_e32 v91, v2, v80
	v_min_u32_e32 v90, v2, v80
	v_max_u32_e32 v89, v102, v83
	v_min_u32_e32 v88, v102, v83
	v_max_u32_e32 v87, v1, v81
	v_min_u32_e32 v86, v1, v81
	v_max_u32_e32 v85, v103, v104
	v_min_u32_e32 v84, v103, v104
	v_max_u32_e32 v83, v82, v105
	v_min_u32_e32 v82, v82, v105
	v_max_u32_e32 v79, v78, v0
	v_min_u32_e32 v78, v78, v0
	global_load_dwordx4 v[0:3], v[4:5], off offset:1072
	global_load_dwordx4 v[102:105], v[4:5], off offset:1056
	v_max_u32_e32 v81, v106, v107
	v_min_u32_e32 v80, v106, v107
	s_waitcnt vmcnt(2)
; __device__ __forceinline__ unsigned f2key(float f) { const unsigned u = __float_as_uint(f); return (u & 0x80000000u) ? ~u : (u | 0x80000000u); }
; __device__ __forceinline__ void peer_tile(const Args& A, LAS unsigned char* lds, int tile) {
;     ...
;                   for (int i = 0; i < 16; ++i) {
;                       const float lo = (float)__builtin_bit_cast(_Float16, (unsigned short)(sw[i] & 0xffffu)), hi = (float)__builtin_bit_cast(_Float16, (unsigned short)(sw[i] >> 16));
;                       const unsigned klo = (f2key(lo) & ~127u) | (unsigned)(127 - (32 * g + 2 * i)), khi = (f2key(hi) & ~127u) | (unsigned)(127 - (32 * g + 2 * i + 1));
;                       if (i < 8) { k0[2 * i] = klo; k0[2 * i + 1] = khi; } else { k1[2 * (i - 8)] = klo; k1[2 * (i - 8) + 1] = khi; } } }
;     ...
;                 for (int i = 0; i < 16; ++i) L2[p][i] = (g & 2) ? ((g & 1) ? LA[3][p][i] : LA[2][p][i]) : ((g & 1) ? LA[1][p][i] : LA[0][p][i]);
	v_cvt_f32_f16_sdwa v106, v98 dst_sel:DWORD dst_unused:UNUSED_PAD src0_sel:WORD_1
	v_cvt_f32_f16_e32 v98, v98
	v_cndmask_b32_e64 v34, v66, v34, s[0:1]
	v_cndmask_b32_e64 v33, v65, v33, s[0:1]
	v_not_b32_e32 v107, v106
	v_or_b32_e32 v108, 0x80000000, v106
	v_cmp_gt_i32_e32 vcc, 0, v106
	v_cndmask_b32_e64 v32, v64, v32, s[0:1]
	v_cndmask_b32_e64 v31, v63, v31, s[0:1]
	v_cndmask_b32_e32 v106, v108, v107, vcc
	v_not_b32_e32 v107, v98
	v_or_b32_e32 v108, 0x80000000, v98
	v_cmp_gt_i32_e32 vcc, 0, v98
	v_and_b32_e32 v106, 0xffffff80, v106
	v_sub_u32_e32 v106, v106, v15
	v_cndmask_b32_e32 v98, v108, v107, vcc
	v_cvt_f32_f16_sdwa v107, v99 dst_sel:DWORD dst_unused:UNUSED_PAD src0_sel:WORD_1
	v_cvt_f32_f16_e32 v99, v99
	v_and_b32_e32 v98, 0xffffff80, v98
	v_sub_u32_e32 v98, v98, v15
	v_not_b32_e32 v108, v107
	v_or_b32_e32 v109, 0x80000000, v107
	v_cmp_gt_i32_e32 vcc, 0, v107
	v_add_u32_e32 v106, 0x7e, v106
	v_add_u32_e32 v98, 0x7f, v98
	v_cndmask_b32_e32 v107, v109, v108, vcc
	v_not_b32_e32 v108, v99
	v_or_b32_e32 v109, 0x80000000, v99
	v_cmp_gt_i32_e32 vcc, 0, v99
	v_and_b32_e32 v107, 0xffffff80, v107
	v_sub_u32_e32 v107, v107, v14
	v_cndmask_b32_e32 v99, v109, v108, vcc
	v_cvt_f32_f16_sdwa v108, v100 dst_sel:DWORD dst_unused:UNUSED_PAD src0_sel:WORD_1
	v_cvt_f32_f16_e32 v100, v100
	v_and_b32_e32 v99, 0xffffff80, v99
	v_sub_u32_e32 v99, v99, v14
	v_not_b32_e32 v109, v108
	v_or_b32_e32 v110, 0x80000000, v108
	v_cmp_gt_i32_e32 vcc, 0, v108
	v_add_u32_e32 v107, 0x7e, v107
	v_add_u32_e32 v99, 0x7f, v99
	v_cndmask_b32_e32 v108, v110, v109, vcc
	v_not_b32_e32 v109, v100
	v_or_b32_e32 v110, 0x80000000, v100
	v_cmp_gt_i32_e32 vcc, 0, v100
	v_and_b32_e32 v108, 0xffffff80, v108
	v_sub_u32_e32 v108, v108, v12
	v_cndmask_b32_e32 v100, v110, v109, vcc
	v_cvt_f32_f16_sdwa v109, v101 dst_sel:DWORD dst_unused:UNUSED_PAD src0_sel:WORD_1
	v_cvt_f32_f16_e32 v101, v101
	v_and_b32_e32 v100, 0xffffff80, v100
	v_sub_u32_e32 v100, v100, v12
	v_not_b32_e32 v110, v109
	v_or_b32_e32 v111, 0x80000000, v109
	v_cmp_gt_i32_e32 vcc, 0, v109
	v_add_u32_e32 v108, 0x7e, v108
	v_add_u32_e32 v100, 0x7f, v100
	v_cndmask_b32_e32 v109, v111, v110, vcc
	v_not_b32_e32 v110, v101
	v_or_b32_e32 v111, 0x80000000, v101
	v_cmp_gt_i32_e32 vcc, 0, v101
	v_and_b32_e32 v109, 0xffffff80, v109
	v_sub_u32_e32 v109, v109, v10
	v_cndmask_b32_e32 v101, v111, v110, vcc
	v_cvt_f32_f16_sdwa v110, v94 dst_sel:DWORD dst_unused:UNUSED_PAD src0_sel:WORD_1
	v_cvt_f32_f16_e32 v94, v94
	v_and_b32_e32 v101, 0xffffff80, v101
	v_sub_u32_e32 v101, v101, v10
	v_not_b32_e32 v111, v110
	v_or_b32_e32 v112, 0x80000000, v110
	v_cmp_gt_i32_e32 vcc, 0, v110
	v_add_u32_e32 v109, 0x7e, v109
	v_add_u32_e32 v101, 0x7f, v101
	v_cndmask_b32_e32 v110, v112, v111, vcc
	v_not_b32_e32 v111, v94
	v_or_b32_e32 v112, 0x80000000, v94
	v_cmp_gt_i32_e32 vcc, 0, v94
	v_and_b32_e32 v110, 0xffffff80, v110
	v_sub_u32_e32 v110, v110, v8
	v_cndmask_b32_e32 v94, v112, v111, vcc
	v_cvt_f32_f16_sdwa v111, v95 dst_sel:DWORD dst_unused:UNUSED_PAD src0_sel:WORD_1
	v_cvt_f32_f16_e32 v95, v95
	v_and_b32_e32 v94, 0xffffff80, v94
	v_sub_u32_e32 v94, v94, v8
	v_not_b32_e32 v112, v111
	v_or_b32_e32 v114, 0x80000000, v111
	v_cmp_gt_i32_e32 vcc, 0, v111
	v_add_u32_e32 v110, 0x7e, v110
	v_add_u32_e32 v94, 0x7f, v94
	v_cndmask_b32_e32 v111, v114, v112, vcc
	v_not_b32_e32 v112, v95
	v_or_b32_e32 v114, 0x80000000, v95
	v_cmp_gt_i32_e32 vcc, 0, v95
	v_and_b32_e32 v111, 0xffffff80, v111
	v_sub_u32_e32 v111, v111, v16
	v_cndmask_b32_e32 v95, v114, v112, vcc
	v_cvt_f32_f16_sdwa v112, v96 dst_sel:DWORD dst_unused:UNUSED_PAD src0_sel:WORD_1
	v_cvt_f32_f16_e32 v96, v96
	v_and_b32_e32 v95, 0xffffff80, v95
	v_sub_u32_e32 v95, v95, v16
	v_not_b32_e32 v114, v112
	v_or_b32_e32 v115, 0x80000000, v112
	v_cmp_gt_i32_e32 vcc, 0, v112
	v_add_u32_e32 v111, 0x7e, v111
	v_add_u32_e32 v95, 0x7f, v95
	v_cndmask_b32_e32 v112, v115, v114, vcc
	v_not_b32_e32 v114, v96
	v_or_b32_e32 v115, 0x80000000, v96
	v_cmp_gt_i32_e32 vcc, 0, v96
	v_and_b32_e32 v112, 0xffffff80, v112
	v_sub_u32_e32 v112, v112, v17
	v_cndmask_b32_e32 v96, v115, v114, vcc
	v_cvt_f32_f16_sdwa v114, v97 dst_sel:DWORD dst_unused:UNUSED_PAD src0_sel:WORD_1
	v_cvt_f32_f16_e32 v97, v97
	v_and_b32_e32 v96, 0xffffff80, v96
	v_sub_u32_e32 v96, v96, v17
	v_not_b32_e32 v115, v114
	v_or_b32_e32 v116, 0x80000000, v114
	v_cmp_gt_i32_e32 vcc, 0, v114
	v_add_u32_e32 v112, 0x7e, v112
	v_add_u32_e32 v96, 0x7f, v96
	v_cndmask_b32_e32 v114, v116, v115, vcc
	v_not_b32_e32 v115, v97
	v_or_b32_e32 v116, 0x80000000, v97
	v_cmp_gt_i32_e32 vcc, 0, v97
	v_and_b32_e32 v114, 0xffffff80, v114
	v_sub_u32_e32 v114, v114, v18
	v_cndmask_b32_e32 v97, v116, v115, vcc
	s_waitcnt vmcnt(0)
; __device__ __forceinline__ unsigned f2key(float f) { const unsigned u = __float_as_uint(f); return (u & 0x80000000u) ? ~u : (u | 0x80000000u); }
; __device__ __forceinline__ void sort16_desc(unsigned (&k)[16]) {
; #pragma unroll
;     for (int size = 2; size <= 16; size <<= 1)
; #pragma unroll
;         for (int stride = size >> 1; stride > 0; stride >>= 1)
; __device__ __forceinline__ void peer_tile(const Args& A, LAS unsigned char* lds, int tile) {
;     ...
;                   for (int i = 0; i < 16; ++i) {
;                       const float lo = (float)__builtin_bit_cast(_Float16, (unsigned short)(sw[i] & 0xffffu)), hi = (float)__builtin_bit_cast(_Float16, (unsigned short)(sw[i] >> 16));
;                       const unsigned klo = (f2key(lo) & ~127u) | (unsigned)(127 - (32 * g + 2 * i)), khi = (f2key(hi) & ~127u) | (unsigned)(127 - (32 * g + 2 * i + 1));
;                       if (i < 8) { k0[2 * i] = klo; k0[2 * i + 1] = khi; } else { k1[2 * (i - 8)] = klo; k1[2 * (i - 8) + 1] = khi; } } }
;                 sort16_desc(k0); sort16_desc(k1); merge16(k0, k1);
	v_cvt_f32_f16_sdwa v115, v102 dst_sel:DWORD dst_unused:UNUSED_PAD src0_sel:WORD_1
	v_cvt_f32_f16_e32 v102, v102
	v_and_b32_e32 v97, 0xffffff80, v97
	v_sub_u32_e32 v97, v97, v18
	v_not_b32_e32 v116, v115
	v_or_b32_e32 v117, 0x80000000, v115
	v_cmp_gt_i32_e32 vcc, 0, v115
	v_add_u32_e32 v114, 0x7e, v114
	v_add_u32_e32 v97, 0x7f, v97
	v_cndmask_b32_e32 v115, v117, v116, vcc
	v_not_b32_e32 v116, v102
	v_or_b32_e32 v117, 0x80000000, v102
	v_cmp_gt_i32_e32 vcc, 0, v102
	v_and_b32_e32 v115, 0xffffff80, v115
	v_sub_u32_e32 v115, v115, v20
	v_cndmask_b32_e32 v102, v117, v116, vcc
	v_cvt_f32_f16_sdwa v116, v103 dst_sel:DWORD dst_unused:UNUSED_PAD src0_sel:WORD_1
	v_cvt_f32_f16_e32 v103, v103
	v_and_b32_e32 v102, 0xffffff80, v102
	v_sub_u32_e32 v102, v102, v20
	v_not_b32_e32 v117, v116
	v_or_b32_e32 v118, 0x80000000, v116
	v_cmp_gt_i32_e32 vcc, 0, v116
	v_add_u32_e32 v115, 0x7e, v115
	v_add_u32_e32 v102, 0x7f, v102
	v_cndmask_b32_e32 v116, v118, v117, vcc
	v_not_b32_e32 v117, v103
	v_or_b32_e32 v118, 0x80000000, v103
	v_cmp_gt_i32_e32 vcc, 0, v103
	v_and_b32_e32 v116, 0xffffff80, v116
	v_sub_u32_e32 v116, v116, v21
	v_cndmask_b32_e32 v103, v118, v117, vcc
	v_cvt_f32_f16_sdwa v117, v104 dst_sel:DWORD dst_unused:UNUSED_PAD src0_sel:WORD_1
	v_cvt_f32_f16_e32 v104, v104
	v_and_b32_e32 v103, 0xffffff80, v103
	v_sub_u32_e32 v103, v103, v21
	v_not_b32_e32 v118, v117
	v_or_b32_e32 v119, 0x80000000, v117
	v_cmp_gt_i32_e32 vcc, 0, v117
	v_add_u32_e32 v116, 0x7e, v116
	v_add_u32_e32 v103, 0x7f, v103
	v_cndmask_b32_e32 v117, v119, v118, vcc
	v_not_b32_e32 v118, v104
	v_or_b32_e32 v119, 0x80000000, v104
	v_cmp_gt_i32_e32 vcc, 0, v104
	v_and_b32_e32 v117, 0xffffff80, v117
	v_sub_u32_e32 v117, v117, v22
	v_cndmask_b32_e32 v104, v119, v118, vcc
	v_cvt_f32_f16_sdwa v118, v105 dst_sel:DWORD dst_unused:UNUSED_PAD src0_sel:WORD_1
	v_cvt_f32_f16_e32 v105, v105
	v_and_b32_e32 v104, 0xffffff80, v104
	v_sub_u32_e32 v104, v104, v22
	v_not_b32_e32 v119, v118
	v_or_b32_e32 v120, 0x80000000, v118
	v_cmp_gt_i32_e32 vcc, 0, v118
	v_add_u32_e32 v117, 0x7e, v117
	v_add_u32_e32 v104, 0x7f, v104
	v_cndmask_b32_e32 v118, v120, v119, vcc
	v_not_b32_e32 v119, v105
	v_or_b32_e32 v120, 0x80000000, v105
	v_cmp_gt_i32_e32 vcc, 0, v105
	v_and_b32_e32 v118, 0xffffff80, v118
	v_sub_u32_e32 v118, v118, v23
	v_cndmask_b32_e32 v105, v120, v119, vcc
	v_cvt_f32_f16_sdwa v119, v0 dst_sel:DWORD dst_unused:UNUSED_PAD src0_sel:WORD_1
	v_cvt_f32_f16_e32 v0, v0
	v_and_b32_e32 v105, 0xffffff80, v105
	v_sub_u32_e32 v105, v105, v23
	v_not_b32_e32 v120, v119
	v_or_b32_e32 v121, 0x80000000, v119
	v_cmp_gt_i32_e32 vcc, 0, v119
	v_add_u32_e32 v118, 0x7e, v118
	v_add_u32_e32 v105, 0x7f, v105
	v_cndmask_b32_e32 v119, v121, v120, vcc
	v_not_b32_e32 v120, v0
	v_or_b32_e32 v121, 0x80000000, v0
	v_cmp_gt_i32_e32 vcc, 0, v0
	v_and_b32_e32 v119, 0xffffff80, v119
	v_sub_u32_e32 v119, v119, v24
	v_cndmask_b32_e32 v0, v121, v120, vcc
	v_cvt_f32_f16_sdwa v120, v1 dst_sel:DWORD dst_unused:UNUSED_PAD src0_sel:WORD_1
	v_cvt_f32_f16_e32 v1, v1
	v_and_b32_e32 v0, 0xffffff80, v0
	v_sub_u32_e32 v0, v0, v24
	v_not_b32_e32 v121, v120
	v_or_b32_e32 v122, 0x80000000, v120
	v_cmp_gt_i32_e32 vcc, 0, v120
	v_add_u32_e32 v119, 0x7e, v119
	v_add_u32_e32 v0, 0x7f, v0
	v_cndmask_b32_e32 v120, v122, v121, vcc
	v_not_b32_e32 v121, v1
	v_or_b32_e32 v122, 0x80000000, v1
	v_cmp_gt_i32_e32 vcc, 0, v1
	v_and_b32_e32 v120, 0xffffff80, v120
	v_sub_u32_e32 v120, v120, v25
	v_cndmask_b32_e32 v1, v122, v121, vcc
	v_cvt_f32_f16_sdwa v121, v2 dst_sel:DWORD dst_unused:UNUSED_PAD src0_sel:WORD_1
	v_cvt_f32_f16_e32 v2, v2
	v_and_b32_e32 v1, 0xffffff80, v1
	v_sub_u32_e32 v1, v1, v25
	v_not_b32_e32 v122, v121
	v_or_b32_e32 v123, 0x80000000, v121
	v_cmp_gt_i32_e32 vcc, 0, v121
	v_add_u32_e32 v120, 0x7e, v120
	v_add_u32_e32 v1, 0x7f, v1
	v_cndmask_b32_e32 v121, v123, v122, vcc
	v_not_b32_e32 v122, v2
	v_or_b32_e32 v123, 0x80000000, v2
	v_cmp_gt_i32_e32 vcc, 0, v2
	v_and_b32_e32 v121, 0xffffff80, v121
	v_sub_u32_e32 v121, v121, v26
	v_cndmask_b32_e32 v2, v123, v122, vcc
	v_cvt_f32_f16_sdwa v122, v3 dst_sel:DWORD dst_unused:UNUSED_PAD src0_sel:WORD_1
	v_cvt_f32_f16_e32 v3, v3
	v_and_b32_e32 v2, 0xffffff80, v2
	v_sub_u32_e32 v2, v2, v26
	v_not_b32_e32 v123, v122
	v_or_b32_e32 v124, 0x80000000, v122
	v_cmp_gt_i32_e32 vcc, 0, v122
	v_add_u32_e32 v121, 0x7e, v121
	v_add_u32_e32 v2, 0x7f, v2
	v_cndmask_b32_e32 v122, v124, v123, vcc
	v_not_b32_e32 v123, v3
	v_or_b32_e32 v124, 0x80000000, v3
	v_cmp_gt_i32_e32 vcc, 0, v3
	v_and_b32_e32 v122, 0xffffff80, v122
	v_sub_u32_e32 v122, v122, v28
	v_cndmask_b32_e32 v3, v124, v123, vcc
	v_and_b32_e32 v3, 0xffffff80, v3
	v_sub_u32_e32 v3, v3, v28
	v_add_u32_e32 v122, 0x7e, v122
	v_add_u32_e32 v3, 0x7f, v3
	v_max_u32_e32 v123, v98, v106
	v_min_u32_e32 v98, v98, v106
	v_max_u32_e32 v106, v107, v99
	v_min_u32_e32 v99, v107, v99
	v_max_u32_e32 v107, v100, v108
	v_min_u32_e32 v100, v100, v108
	v_max_u32_e32 v108, v109, v101
	v_min_u32_e32 v101, v109, v101
	v_max_u32_e32 v109, v94, v110
	v_min_u32_e32 v94, v94, v110
	v_max_u32_e32 v110, v111, v95
	v_min_u32_e32 v95, v111, v95
	v_max_u32_e32 v111, v96, v112
	v_min_u32_e32 v96, v96, v112
	v_max_u32_e32 v112, v114, v97
	v_min_u32_e32 v97, v114, v97
	v_max_u32_e32 v131, v102, v115
	v_min_u32_e32 v102, v102, v115
	v_max_u32_e32 v115, v116, v103
	v_min_u32_e32 v103, v116, v103
	v_max_u32_e32 v116, v104, v117
	v_min_u32_e32 v104, v104, v117
	v_max_u32_e32 v117, v118, v105
	v_min_u32_e32 v105, v118, v105
	v_max_u32_e32 v118, v0, v119
	v_min_u32_e32 v0, v0, v119
	v_max_u32_e32 v119, v120, v1
	v_min_u32_e32 v1, v120, v1
	v_max_u32_e32 v120, v2, v121
	v_min_u32_e32 v2, v2, v121
; #define CE_DESC(a, b) do { const unsigned _mx = (a) > (b) ? (a) : (b), _mn = (a) > (b) ? (b) : (a); (a) = _mx; (b) = _mn; } while (0)
; __device__ __forceinline__ void sort16_desc(unsigned (&k)[16]) {
; #pragma unroll
;     for (int size = 2; size <= 16; size <<= 1)
; #pragma unroll
;         for (int stride = size >> 1; stride > 0; stride >>= 1)
; #pragma unroll
;             for (int i = 0; i < 16; ++i) { const int j = i ^ stride;
;                 if (j > i) { if ((i & size) == 0) CE_DESC(k[i], k[j]); else CE_DESC(k[j], k[i]); } }
; }
	v_max_u32_e32 v121, v122, v3
	v_min_u32_e32 v3, v122, v3
	v_max_u32_e32 v114, v123, v99
	v_min_u32_e32 v99, v123, v99
	v_max_u32_e32 v123, v98, v106
	v_min_u32_e32 v98, v98, v106
	v_max_u32_e32 v106, v101, v107
	v_min_u32_e32 v101, v101, v107
	v_max_u32_e32 v107, v108, v100
	v_min_u32_e32 v100, v108, v100
	v_max_u32_e32 v108, v109, v95
	v_min_u32_e32 v95, v109, v95
	v_max_u32_e32 v109, v94, v110
	v_min_u32_e32 v94, v94, v110
	v_max_u32_e32 v110, v97, v111
	v_min_u32_e32 v97, v97, v111
	v_max_u32_e32 v111, v112, v96
	v_min_u32_e32 v96, v112, v96
	v_max_u32_e32 v122, v131, v103
	v_min_u32_e32 v103, v131, v103
	v_max_u32_e32 v131, v102, v115
	v_min_u32_e32 v102, v102, v115
	v_max_u32_e32 v115, v105, v116
	v_min_u32_e32 v105, v105, v116
	v_max_u32_e32 v116, v117, v104
	v_min_u32_e32 v104, v117, v104
	v_max_u32_e32 v117, v118, v1
	v_min_u32_e32 v1, v118, v1
	v_max_u32_e32 v118, v0, v119
	v_min_u32_e32 v0, v0, v119
	v_max_u32_e32 v119, v3, v120
	v_min_u32_e32 v3, v3, v120
	v_max_u32_e32 v120, v121, v2
	v_min_u32_e32 v2, v121, v2
	v_max_u32_e32 v112, v114, v123
	v_min_u32_e32 v114, v114, v123
	v_max_u32_e32 v123, v99, v98
	v_min_u32_e32 v98, v99, v98
	v_max_u32_e32 v99, v100, v101
	v_min_u32_e32 v100, v100, v101
	v_max_u32_e32 v101, v107, v106
	v_min_u32_e32 v106, v107, v106
	v_max_u32_e32 v107, v108, v109
	v_min_u32_e32 v108, v108, v109
	v_max_u32_e32 v109, v95, v94
	v_min_u32_e32 v94, v95, v94
	v_max_u32_e32 v95, v96, v97
	v_min_u32_e32 v96, v96, v97
	v_max_u32_e32 v97, v111, v110
	v_min_u32_e32 v110, v111, v110
	v_max_u32_e32 v121, v122, v131
	v_min_u32_e32 v122, v122, v131
	v_max_u32_e32 v131, v103, v102
	v_min_u32_e32 v102, v103, v102
	v_max_u32_e32 v103, v104, v105
	v_min_u32_e32 v104, v104, v105
	v_max_u32_e32 v105, v116, v115
	v_min_u32_e32 v115, v116, v115
	v_max_u32_e32 v116, v117, v118
	v_min_u32_e32 v117, v117, v118
	v_max_u32_e32 v118, v1, v0
	v_min_u32_e32 v0, v1, v0
	v_max_u32_e32 v1, v2, v3
	v_min_u32_e32 v2, v2, v3
	v_max_u32_e32 v3, v120, v119
	v_min_u32_e32 v119, v120, v119
	v_max_u32_e32 v111, v112, v100
	v_min_u32_e32 v100, v112, v100
	v_max_u32_e32 v112, v114, v99
	v_min_u32_e32 v99, v114, v99
	v_max_u32_e32 v114, v123, v106
	v_min_u32_e32 v106, v123, v106
	v_max_u32_e32 v123, v98, v101
	v_min_u32_e32 v98, v98, v101
	v_max_u32_e32 v101, v96, v107
	v_min_u32_e32 v96, v96, v107
	v_max_u32_e32 v107, v95, v108
	v_min_u32_e32 v95, v95, v108
	v_max_u32_e32 v108, v110, v109
	v_min_u32_e32 v109, v110, v109
	v_max_u32_e32 v110, v97, v94
	v_min_u32_e32 v94, v97, v94
	v_max_u32_e32 v120, v121, v104
	v_min_u32_e32 v104, v121, v104
	v_max_u32_e32 v121, v122, v103
	v_min_u32_e32 v103, v122, v103
	v_max_u32_e32 v122, v131, v115
	v_min_u32_e32 v115, v131, v115
	v_max_u32_e32 v131, v102, v105
	v_min_u32_e32 v102, v102, v105
	v_max_u32_e32 v105, v2, v116
	v_min_u32_e32 v2, v2, v116
	v_max_u32_e32 v116, v1, v117
	v_min_u32_e32 v1, v1, v117
	v_max_u32_e32 v117, v119, v118
	v_min_u32_e32 v118, v119, v118
	v_max_u32_e32 v119, v3, v0
	v_min_u32_e32 v0, v3, v0
	v_max_u32_e32 v97, v111, v114
	v_min_u32_e32 v111, v111, v114
	v_max_u32_e32 v114, v112, v123
	v_min_u32_e32 v112, v112, v123
	v_max_u32_e32 v123, v100, v106
	v_min_u32_e32 v100, v100, v106
	v_max_u32_e32 v106, v99, v98
	v_min_u32_e32 v98, v99, v98
	v_max_u32_e32 v99, v109, v96
	v_min_u32_e32 v96, v109, v96
	v_max_u32_e32 v109, v94, v95
	v_min_u32_e32 v94, v94, v95
	v_max_u32_e32 v95, v108, v101
	v_min_u32_e32 v101, v108, v101
	v_max_u32_e32 v108, v110, v107
	v_min_u32_e32 v107, v110, v107
	v_max_u32_e32 v3, v120, v122
	v_min_u32_e32 v120, v120, v122
	v_max_u32_e32 v122, v121, v131
	v_min_u32_e32 v121, v121, v131
	v_max_u32_e32 v131, v104, v115
	v_min_u32_e32 v104, v104, v115
	v_max_u32_e32 v115, v103, v102
	v_min_u32_e32 v102, v103, v102
	v_max_u32_e32 v103, v118, v2
	v_min_u32_e32 v2, v118, v2
	v_max_u32_e32 v118, v0, v1
	v_min_u32_e32 v0, v0, v1
	v_max_u32_e32 v1, v117, v105
	v_min_u32_e32 v105, v117, v105
	v_max_u32_e32 v117, v119, v116
	v_min_u32_e32 v116, v119, v116
	v_max_u32_e32 v110, v97, v114
	v_min_u32_e32 v97, v97, v114
	v_max_u32_e32 v114, v111, v112
	v_min_u32_e32 v111, v111, v112
	v_max_u32_e32 v112, v123, v106
	v_min_u32_e32 v106, v123, v106
	v_max_u32_e32 v123, v100, v98
	v_min_u32_e32 v98, v100, v98
	v_max_u32_e32 v100, v94, v96
	v_min_u32_e32 v94, v94, v96
	v_max_u32_e32 v96, v109, v99
	v_min_u32_e32 v99, v109, v99
	v_max_u32_e32 v109, v107, v101
	v_min_u32_e32 v101, v107, v101
	v_max_u32_e32 v107, v108, v95
	v_min_u32_e32 v95, v108, v95
	v_max_u32_e32 v119, v3, v122
	v_min_u32_e32 v3, v3, v122
	v_max_u32_e32 v122, v120, v121
	v_min_u32_e32 v120, v120, v121
	v_max_u32_e32 v121, v131, v115
	v_min_u32_e32 v115, v131, v115
	v_max_u32_e32 v131, v104, v102
	v_min_u32_e32 v102, v104, v102
	v_max_u32_e32 v104, v0, v2
	v_min_u32_e32 v0, v0, v2
	v_max_u32_e32 v2, v118, v103
	v_min_u32_e32 v103, v118, v103
	v_max_u32_e32 v118, v116, v105
	v_min_u32_e32 v105, v116, v105
	v_max_u32_e32 v116, v117, v1
	v_min_u32_e32 v1, v117, v1
	v_max_u32_e32 v108, v110, v94
	v_min_u32_e32 v94, v110, v94
	v_max_u32_e32 v110, v97, v100
	v_min_u32_e32 v97, v97, v100
	v_max_u32_e32 v100, v114, v99
	v_min_u32_e32 v99, v114, v99
	v_max_u32_e32 v114, v111, v96
	v_min_u32_e32 v96, v111, v96
	v_max_u32_e32 v111, v112, v101
	v_min_u32_e32 v101, v112, v101
	v_max_u32_e32 v112, v106, v109
	v_min_u32_e32 v106, v106, v109
	v_max_u32_e32 v109, v123, v95
	v_min_u32_e32 v95, v123, v95
	v_max_u32_e32 v123, v98, v107
	v_min_u32_e32 v98, v98, v107
	v_max_u32_e32 v117, v119, v0
	v_min_u32_e32 v0, v119, v0
	v_max_u32_e32 v119, v3, v104
	v_min_u32_e32 v3, v3, v104
	v_max_u32_e32 v104, v122, v103
	v_min_u32_e32 v103, v122, v103
; #define CE_DESC(a, b) do { const unsigned _mx = (a) > (b) ? (a) : (b), _mn = (a) > (b) ? (b) : (a); (a) = _mx; (b) = _mn; } while (0)
; __device__ __forceinline__ void merge16(unsigned (&a)[16], const unsigned (&b)[16]) {
; #pragma unroll
;     for (int i = 0; i < 16; ++i) a[i] = a[i] > b[15 - i] ? a[i] : b[15 - i];
; #pragma unroll
;     for (int stride = 8; stride > 0; stride >>= 1)
; #pragma unroll
;         for (int i = 0; i < 16; ++i) { const int j = i ^ stride; if (j > i) CE_DESC(a[i], a[j]); }
; }
; __device__ __forceinline__ void peer_tile(const Args& A, LAS unsigned char* lds, int tile) {
;     ...
;                 for (int msk = 16; msk <= 32; msk <<= 1) {
; #pragma unroll
;                     for (int i = 0; i < 16; ++i) k1[i] = (unsigned)__shfl_xor((int)k0[i], msk);
;                     merge16(k0, k1); }
	v_max_u32_e32 v122, v120, v2
	v_min_u32_e32 v2, v120, v2
	v_max_u32_e32 v120, v121, v105
	v_min_u32_e32 v105, v121, v105
	v_max_u32_e32 v121, v115, v118
	v_min_u32_e32 v115, v115, v118
	v_max_u32_e32 v118, v131, v1
	v_min_u32_e32 v1, v131, v1
	v_max_u32_e32 v131, v102, v116
	v_min_u32_e32 v102, v102, v116
	v_max_u32_e32 v107, v108, v111
	v_min_u32_e32 v108, v108, v111
	v_max_u32_e32 v111, v110, v112
	v_min_u32_e32 v110, v110, v112
	v_max_u32_e32 v112, v100, v109
	v_min_u32_e32 v100, v100, v109
	v_max_u32_e32 v109, v114, v123
	v_min_u32_e32 v114, v114, v123
	v_max_u32_e32 v123, v94, v101
	v_min_u32_e32 v94, v94, v101
	v_max_u32_e32 v101, v97, v106
	v_min_u32_e32 v97, v97, v106
	v_max_u32_e32 v106, v99, v95
	v_min_u32_e32 v95, v99, v95
	v_max_u32_e32 v99, v96, v98
	v_min_u32_e32 v96, v96, v98
	v_max_u32_e32 v116, v117, v120
	v_min_u32_e32 v117, v117, v120
	v_max_u32_e32 v120, v119, v121
	v_min_u32_e32 v119, v119, v121
	v_max_u32_e32 v121, v104, v118
	v_min_u32_e32 v104, v104, v118
	v_max_u32_e32 v118, v122, v131
	v_min_u32_e32 v122, v122, v131
	v_max_u32_e32 v131, v0, v105
	v_min_u32_e32 v0, v0, v105
	v_max_u32_e32 v105, v3, v115
	v_min_u32_e32 v3, v3, v115
	v_max_u32_e32 v115, v103, v1
	v_min_u32_e32 v1, v103, v1
	v_max_u32_e32 v103, v2, v102
	v_min_u32_e32 v2, v2, v102
	v_max_u32_e32 v98, v107, v112
	v_min_u32_e32 v107, v107, v112
	v_max_u32_e32 v112, v111, v109
	v_min_u32_e32 v109, v111, v109
	v_max_u32_e32 v111, v108, v100
	v_min_u32_e32 v100, v108, v100
	v_max_u32_e32 v108, v110, v114
	v_min_u32_e32 v110, v110, v114
	v_max_u32_e32 v114, v123, v106
	v_min_u32_e32 v106, v123, v106
	v_max_u32_e32 v123, v101, v99
	v_min_u32_e32 v99, v101, v99
	v_max_u32_e32 v101, v94, v95
	v_min_u32_e32 v94, v94, v95
	v_max_u32_e32 v95, v97, v96
	v_min_u32_e32 v96, v97, v96
	v_max_u32_e32 v102, v116, v121
	v_min_u32_e32 v116, v116, v121
	v_max_u32_e32 v121, v120, v118
	v_min_u32_e32 v118, v120, v118
	v_max_u32_e32 v120, v117, v104
	v_min_u32_e32 v104, v117, v104
	v_max_u32_e32 v117, v119, v122
	v_min_u32_e32 v119, v119, v122
	v_max_u32_e32 v122, v131, v115
	v_min_u32_e32 v115, v131, v115
	v_max_u32_e32 v131, v105, v103
	v_min_u32_e32 v103, v105, v103
	v_max_u32_e32 v105, v0, v1
	v_min_u32_e32 v0, v0, v1
	v_max_u32_e32 v1, v3, v2
	v_min_u32_e32 v2, v3, v2
	v_min_u32_e32 v97, v98, v112
	v_min_u32_e32 v124, v107, v109
	v_min_u32_e32 v125, v111, v108
	v_min_u32_e32 v126, v100, v110
	v_min_u32_e32 v127, v114, v123
	v_min_u32_e32 v128, v106, v99
	v_min_u32_e32 v129, v101, v95
	v_min_u32_e32 v130, v94, v96
	v_min_u32_e32 v3, v102, v121
	v_min_u32_e32 v132, v116, v118
	v_min_u32_e32 v133, v120, v117
	v_min_u32_e32 v134, v104, v119
	v_min_u32_e32 v135, v122, v131
	v_min_u32_e32 v136, v115, v103
	v_min_u32_e32 v137, v105, v1
	v_min_u32_e32 v138, v0, v2
	v_max3_u32 v98, v98, v112, v138
	v_max3_u32 v0, v97, v0, v2
	v_max3_u32 v2, v107, v109, v137
	v_max3_u32 v1, v124, v105, v1
	v_max3_u32 v97, v111, v108, v136
	v_max3_u32 v103, v125, v115, v103
	v_max3_u32 v100, v100, v110, v135
	v_max3_u32 v105, v126, v122, v131
	v_max3_u32 v107, v114, v123, v134
	v_max3_u32 v104, v127, v104, v119
	v_max3_u32 v99, v106, v99, v133
	v_max3_u32 v106, v128, v120, v117
	v_max3_u32 v95, v101, v95, v132
	v_max3_u32 v101, v129, v116, v118
	v_max3_u32 v3, v94, v96, v3
	v_max3_u32 v94, v130, v102, v121
	v_max_u32_e32 v96, v98, v107
	v_min_u32_e32 v98, v98, v107
	v_max_u32_e32 v102, v0, v104
	v_min_u32_e32 v0, v0, v104
	v_max_u32_e32 v104, v2, v99
	v_min_u32_e32 v2, v2, v99
	v_max_u32_e32 v99, v1, v106
	v_min_u32_e32 v1, v1, v106
	v_max_u32_e32 v106, v97, v95
	v_min_u32_e32 v95, v97, v95
	v_max_u32_e32 v97, v103, v101
	v_min_u32_e32 v101, v103, v101
	v_max_u32_e32 v103, v100, v3
	v_min_u32_e32 v3, v100, v3
	v_max_u32_e32 v100, v105, v94
	v_min_u32_e32 v94, v105, v94
	v_max_u32_e32 v105, v96, v106
	v_min_u32_e32 v96, v96, v106
	v_max_u32_e32 v106, v102, v97
	v_min_u32_e32 v97, v102, v97
	v_max_u32_e32 v102, v104, v103
	v_min_u32_e32 v103, v104, v103
	v_max_u32_e32 v104, v99, v100
	v_min_u32_e32 v99, v99, v100
	v_max_u32_e32 v100, v98, v95
	v_min_u32_e32 v95, v98, v95
	v_max_u32_e32 v98, v0, v101
	v_min_u32_e32 v0, v0, v101
	v_max_u32_e32 v101, v2, v3
	v_min_u32_e32 v2, v2, v3
	v_max_u32_e32 v3, v1, v94
	v_min_u32_e32 v1, v1, v94
	v_max_u32_e32 v94, v105, v102
	v_min_u32_e32 v102, v105, v102
	v_max_u32_e32 v105, v106, v104
	v_min_u32_e32 v104, v106, v104
	v_max_u32_e32 v106, v96, v103
	v_min_u32_e32 v96, v96, v103
	v_max_u32_e32 v103, v97, v99
	v_min_u32_e32 v97, v97, v99
	v_max_u32_e32 v99, v100, v101
	v_min_u32_e32 v100, v100, v101
	v_max_u32_e32 v101, v98, v3
	v_min_u32_e32 v3, v98, v3
	v_max_u32_e32 v98, v95, v2
	v_min_u32_e32 v2, v95, v2
	v_max_u32_e32 v95, v0, v1
	v_min_u32_e32 v0, v0, v1
	v_max_u32_e32 v1, v94, v105
	v_min_u32_e32 v94, v94, v105
	v_max_u32_e32 v105, v102, v104
	v_min_u32_e32 v102, v102, v104
	v_max_u32_e32 v104, v106, v103
	v_min_u32_e32 v103, v106, v103
	v_max_u32_e32 v106, v96, v97
	v_min_u32_e32 v96, v96, v97
	v_max_u32_e32 v97, v99, v101
	v_min_u32_e32 v99, v99, v101
	v_max_u32_e32 v101, v100, v3
	v_min_u32_e32 v3, v100, v3
	v_max_u32_e32 v100, v98, v95
	v_min_u32_e32 v95, v98, v95
	v_max_u32_e32 v98, v2, v0
	v_min_u32_e32 v0, v2, v0
	ds_bpermute_b32 v2, v27, v1
	ds_bpermute_b32 v107, v27, v94
	ds_bpermute_b32 v108, v27, v105
	ds_bpermute_b32 v109, v27, v102
	ds_bpermute_b32 v110, v27, v104
	ds_bpermute_b32 v111, v27, v103
	ds_bpermute_b32 v112, v27, v106
	ds_bpermute_b32 v114, v27, v96
	ds_bpermute_b32 v115, v27, v97
	ds_bpermute_b32 v116, v27, v99
	ds_bpermute_b32 v117, v27, v101
	ds_bpermute_b32 v118, v27, v0
	ds_bpermute_b32 v119, v27, v98
	ds_bpermute_b32 v120, v27, v95
	ds_bpermute_b32 v121, v27, v100
	ds_bpermute_b32 v122, v27, v3
	s_waitcnt lgkmcnt(4)
; __device__ __forceinline__ void peer_tile(const Args& A, LAS unsigned char* lds, int tile) {
;     ...
;                 { const bf16_t* sp = QRY + m * 2048 + hp * 128 + 32 * g;
;                   const u32x4 s0 = *(const u32x4*)sp, s1 = *(const u32x4*)(sp + 8), s2 = *(const u32x4*)(sp + 16), s3 = *(const u32x4*)(sp + 24);
;     ...
;                 for (int msk = 16; msk <= 32; msk <<= 1) {
; #pragma unroll
;                     for (int i = 0; i < 16; ++i) k1[i] = (unsigned)__shfl_xor((int)k0[i], msk);
;                     merge16(k0, k1); }
	v_max_u32_e32 v1, v1, v118
	s_waitcnt lgkmcnt(3)
	v_max_u32_e32 v94, v94, v119
	s_waitcnt lgkmcnt(2)
	v_max_u32_e32 v105, v105, v120
	s_waitcnt lgkmcnt(1)
	v_max_u32_e32 v102, v102, v121
	s_waitcnt lgkmcnt(0)
	v_max_u32_e32 v104, v104, v122
	v_max_u32_e32 v103, v103, v117
	v_max_u32_e32 v106, v106, v116
	v_max_u32_e32 v96, v96, v115
	v_max_u32_e32 v97, v97, v114
	v_max_u32_e32 v99, v99, v112
	v_max_u32_e32 v101, v101, v111
	v_max_u32_e32 v3, v3, v110
	v_max_u32_e32 v100, v100, v109
	v_max_u32_e32 v95, v95, v108
	v_max_u32_e32 v98, v98, v107
	v_max_u32_e32 v0, v0, v2
	v_max_u32_e32 v2, v1, v97
	v_min_u32_e32 v1, v1, v97
	v_max_u32_e32 v97, v94, v99
	v_min_u32_e32 v94, v94, v99
	v_max_u32_e32 v99, v105, v101
	v_min_u32_e32 v101, v105, v101
	v_max_u32_e32 v105, v102, v3
	v_min_u32_e32 v3, v102, v3
	v_max_u32_e32 v102, v104, v100
	v_min_u32_e32 v100, v104, v100
	v_max_u32_e32 v104, v103, v95
	v_min_u32_e32 v95, v103, v95
	v_max_u32_e32 v103, v106, v98
	v_min_u32_e32 v98, v106, v98
	v_max_u32_e32 v106, v96, v0
	v_min_u32_e32 v0, v96, v0
	v_max_u32_e32 v96, v2, v102
	v_min_u32_e32 v2, v2, v102
	v_max_u32_e32 v102, v97, v104
	v_min_u32_e32 v97, v97, v104
	v_max_u32_e32 v104, v99, v103
	v_min_u32_e32 v99, v99, v103
	v_max_u32_e32 v103, v105, v106
	v_min_u32_e32 v105, v105, v106
	v_max_u32_e32 v106, v1, v100
	v_min_u32_e32 v1, v1, v100
	v_max_u32_e32 v100, v94, v95
	v_min_u32_e32 v94, v94, v95
	v_max_u32_e32 v95, v101, v98
	v_min_u32_e32 v98, v101, v98
	v_max_u32_e32 v101, v3, v0
	v_min_u32_e32 v0, v3, v0
	v_max_u32_e32 v3, v96, v104
	v_min_u32_e32 v96, v96, v104
	v_max_u32_e32 v104, v102, v103
	v_min_u32_e32 v102, v102, v103
	v_max_u32_e32 v103, v2, v99
	v_min_u32_e32 v2, v2, v99
	v_max_u32_e32 v99, v97, v105
	v_min_u32_e32 v97, v97, v105
	v_max_u32_e32 v105, v106, v95
	v_min_u32_e32 v95, v106, v95
	v_max_u32_e32 v106, v100, v101
	v_min_u32_e32 v100, v100, v101
	v_max_u32_e32 v101, v1, v98
	v_min_u32_e32 v1, v1, v98
	v_max_u32_e32 v98, v94, v0
	v_min_u32_e32 v0, v94, v0
	v_max_u32_e32 v94, v3, v104
	v_min_u32_e32 v3, v3, v104
	v_max_u32_e32 v104, v96, v102
	v_min_u32_e32 v96, v96, v102
	v_max_u32_e32 v102, v103, v99
	v_min_u32_e32 v99, v103, v99
	v_max_u32_e32 v103, v2, v97
	v_min_u32_e32 v2, v2, v97
	v_max_u32_e32 v97, v105, v106
	v_min_u32_e32 v105, v105, v106
	v_max_u32_e32 v106, v95, v100
	v_min_u32_e32 v95, v95, v100
	v_max_u32_e32 v100, v101, v98
	v_min_u32_e32 v98, v101, v98
	v_max_u32_e32 v101, v1, v0
	v_min_u32_e32 v0, v1, v0
	ds_bpermute_b32 v114, v29, v0
	ds_bpermute_b32 v1, v29, v94
	ds_bpermute_b32 v107, v29, v3
	ds_bpermute_b32 v108, v29, v104
	ds_bpermute_b32 v109, v29, v96
	s_waitcnt lgkmcnt(4)
	v_max_u32_e32 v94, v94, v114
	global_load_dwordx4 v[114:117], v[4:5], off offset:1296
	global_load_dwordx4 v[118:121], v[4:5], off offset:1280
	ds_bpermute_b32 v110, v29, v102
	ds_bpermute_b32 v111, v29, v99
	ds_bpermute_b32 v112, v29, v103
	ds_bpermute_b32 v122, v29, v2
	ds_bpermute_b32 v123, v29, v97
	ds_bpermute_b32 v124, v29, v105
	ds_bpermute_b32 v125, v29, v106
	ds_bpermute_b32 v126, v29, v95
	ds_bpermute_b32 v127, v29, v100
	ds_bpermute_b32 v128, v29, v101
	ds_bpermute_b32 v129, v29, v98
	s_waitcnt lgkmcnt(4)
	v_max_u32_e32 v99, v99, v125
	s_waitcnt lgkmcnt(3)
	v_max_u32_e32 v102, v102, v126
	s_waitcnt lgkmcnt(2)
	v_max_u32_e32 v96, v96, v127
	s_waitcnt lgkmcnt(1)
	v_max_u32_e32 v3, v3, v128
	s_waitcnt lgkmcnt(0)
	v_max_u32_e32 v104, v104, v129
	v_max_u32_e32 v103, v103, v124
	v_max_u32_e32 v2, v2, v123
	v_max_u32_e32 v97, v97, v122
	v_max_u32_e32 v105, v105, v112
	v_max_u32_e32 v106, v106, v111
	v_max_u32_e32 v95, v95, v110
	v_max_u32_e32 v100, v100, v109
	v_max_u32_e32 v98, v98, v108
	v_max_u32_e32 v101, v101, v107
	v_max_u32_e32 v0, v0, v1
	v_max_u32_e32 v1, v94, v97
	v_min_u32_e32 v94, v94, v97
	v_max_u32_e32 v97, v3, v105
	v_min_u32_e32 v3, v3, v105
	v_max_u32_e32 v105, v104, v106
	v_min_u32_e32 v104, v104, v106
	v_max_u32_e32 v106, v96, v95
	v_min_u32_e32 v95, v96, v95
	v_max_u32_e32 v96, v102, v100
	v_min_u32_e32 v100, v102, v100
	v_max_u32_e32 v102, v99, v98
	v_min_u32_e32 v98, v99, v98
	v_max_u32_e32 v99, v103, v101
	v_min_u32_e32 v101, v103, v101
	v_max_u32_e32 v103, v2, v0
	v_min_u32_e32 v0, v2, v0
	v_max_u32_e32 v2, v1, v96
	v_min_u32_e32 v1, v1, v96
	v_max_u32_e32 v96, v97, v102
	v_min_u32_e32 v97, v97, v102
	v_max_u32_e32 v102, v105, v99
	v_min_u32_e32 v99, v105, v99
	v_max_u32_e32 v105, v106, v103
	v_min_u32_e32 v103, v106, v103
	v_max_u32_e32 v106, v94, v100
	v_min_u32_e32 v94, v94, v100
	v_max_u32_e32 v100, v3, v98
	v_min_u32_e32 v3, v3, v98
	v_max_u32_e32 v98, v104, v101
	v_min_u32_e32 v101, v104, v101
	v_max_u32_e32 v104, v95, v0
	v_min_u32_e32 v0, v95, v0
	v_max_u32_e32 v95, v2, v102
	v_min_u32_e32 v2, v2, v102
	v_max_u32_e32 v102, v96, v105
	v_min_u32_e32 v96, v96, v105
	v_max_u32_e32 v110, v1, v99
	v_min_u32_e32 v1, v1, v99
	v_max_u32_e32 v99, v97, v103
	v_min_u32_e32 v97, v97, v103
	v_max_u32_e32 v111, v106, v98
	v_min_u32_e32 v98, v106, v98
	v_min_u32_e32 v122, v100, v104
	v_max_u32_e32 v123, v94, v101
	v_min_u32_e32 v94, v94, v101
	v_max_u32_e32 v124, v3, v0
	v_min_u32_e32 v0, v3, v0
	v_max_u32_e32 v112, v100, v104
	v_max_u32_e32 v109, v95, v102
	v_min_u32_e32 v108, v95, v102
	v_max_u32_e32 v107, v2, v96
	v_min_u32_e32 v106, v2, v96
	v_max_u32_e32 v105, v110, v99
	v_min_u32_e32 v104, v110, v99
	v_max_u32_e32 v103, v1, v97
	v_min_u32_e32 v102, v1, v97
	v_max_u32_e32 v99, v98, v122
	v_min_u32_e32 v98, v98, v122
	v_max_u32_e32 v97, v123, v124
	v_min_u32_e32 v96, v123, v124
	v_max_u32_e32 v95, v94, v0
	v_min_u32_e32 v94, v94, v0
	global_load_dwordx4 v[0:3], v[4:5], off offset:1328
	global_load_dwordx4 v[122:125], v[4:5], off offset:1312
	s_waitcnt vmcnt(2)
; __device__ __forceinline__ unsigned f2key(float f) { const unsigned u = __float_as_uint(f); return (u & 0x80000000u) ? ~u : (u | 0x80000000u); }
; __device__ __forceinline__ void peer_tile(const Args& A, LAS unsigned char* lds, int tile) {
;     ...
;                 { const bf16_t* sp = QRY + m * 2048 + hp * 128 + 32 * g;
;                   const u32x4 s0 = *(const u32x4*)sp, s1 = *(const u32x4*)(sp + 8), s2 = *(const u32x4*)(sp + 16), s3 = *(const u32x4*)(sp + 24);
;                   const unsigned sw[16] = {s0.x, s0.y, s0.z, s0.w, s1.x, s1.y, s1.z, s1.w, s2.x, s2.y, s2.z, s2.w, s3.x, s3.y, s3.z, s3.w};
; #pragma unroll
;                   for (int i = 0; i < 16; ++i) {
;                       const float lo = (float)__builtin_bit_cast(_Float16, (unsigned short)(sw[i] & 0xffffu)), hi = (float)__builtin_bit_cast(_Float16, (unsigned short)(sw[i] >> 16));
;                       const unsigned klo = (f2key(lo) & ~127u) | (unsigned)(127 - (32 * g + 2 * i)), khi = (f2key(hi) & ~127u) | (unsigned)(127 - (32 * g + 2 * i + 1));
;                       if (i < 8) { k0[2 * i] = klo; k0[2 * i + 1] = khi; } else { k1[2 * (i - 8)] = klo; k1[2 * (i - 8) + 1] = khi; } } }
	v_cvt_f32_f16_sdwa v110, v118 dst_sel:DWORD dst_unused:UNUSED_PAD src0_sel:WORD_1
	v_max_u32_e32 v101, v111, v112
	v_min_u32_e32 v100, v111, v112
	v_cvt_f32_f16_e32 v111, v118
	v_not_b32_e32 v112, v110
	v_or_b32_e32 v118, 0x80000000, v110
	v_cmp_gt_i32_e32 vcc, 0, v110
	v_cndmask_b32_e64 v30, v62, v30, s[0:1]
	s_nop 0
	v_cndmask_b32_e32 v110, v118, v112, vcc
	v_not_b32_e32 v112, v111
	v_or_b32_e32 v118, 0x80000000, v111
	v_cmp_gt_i32_e32 vcc, 0, v111
	v_and_b32_e32 v110, 0xffffff80, v110
	v_sub_u32_e32 v110, v110, v15
	v_cndmask_b32_e32 v111, v118, v112, vcc
	v_cvt_f32_f16_sdwa v112, v119 dst_sel:DWORD dst_unused:UNUSED_PAD src0_sel:WORD_1
	v_cvt_f32_f16_e32 v118, v119
	v_and_b32_e32 v111, 0xffffff80, v111
	v_sub_u32_e32 v111, v111, v15
	v_not_b32_e32 v119, v112
	v_or_b32_e32 v126, 0x80000000, v112
	v_cmp_gt_i32_e32 vcc, 0, v112
	v_add_u32_e32 v110, 0x7e, v110
	v_add_u32_e32 v111, 0x7f, v111
	v_cndmask_b32_e32 v112, v126, v119, vcc
	v_not_b32_e32 v119, v118
	v_or_b32_e32 v126, 0x80000000, v118
	v_cmp_gt_i32_e32 vcc, 0, v118
	v_and_b32_e32 v112, 0xffffff80, v112
	v_sub_u32_e32 v112, v112, v14
	v_cndmask_b32_e32 v118, v126, v119, vcc
	v_cvt_f32_f16_sdwa v119, v120 dst_sel:DWORD dst_unused:UNUSED_PAD src0_sel:WORD_1
	v_cvt_f32_f16_e32 v120, v120
	v_and_b32_e32 v118, 0xffffff80, v118
	v_sub_u32_e32 v118, v118, v14
	v_not_b32_e32 v126, v119
	v_or_b32_e32 v127, 0x80000000, v119
	v_cmp_gt_i32_e32 vcc, 0, v119
	v_add_u32_e32 v112, 0x7e, v112
	v_add_u32_e32 v118, 0x7f, v118
	v_cndmask_b32_e32 v119, v127, v126, vcc
	v_not_b32_e32 v126, v120
	v_or_b32_e32 v127, 0x80000000, v120
	v_cmp_gt_i32_e32 vcc, 0, v120
	v_and_b32_e32 v119, 0xffffff80, v119
	v_sub_u32_e32 v119, v119, v12
	v_cndmask_b32_e32 v120, v127, v126, vcc
	v_cvt_f32_f16_sdwa v126, v121 dst_sel:DWORD dst_unused:UNUSED_PAD src0_sel:WORD_1
	v_cvt_f32_f16_e32 v121, v121
	v_and_b32_e32 v120, 0xffffff80, v120
	v_sub_u32_e32 v120, v120, v12
	v_not_b32_e32 v127, v126
	v_or_b32_e32 v128, 0x80000000, v126
	v_cmp_gt_i32_e32 vcc, 0, v126
	v_add_u32_e32 v119, 0x7e, v119
	v_add_u32_e32 v120, 0x7f, v120
	v_cndmask_b32_e32 v126, v128, v127, vcc
	v_not_b32_e32 v127, v121
	v_or_b32_e32 v128, 0x80000000, v121
	v_cmp_gt_i32_e32 vcc, 0, v121
	v_and_b32_e32 v126, 0xffffff80, v126
	v_sub_u32_e32 v126, v126, v10
	v_cndmask_b32_e32 v121, v128, v127, vcc
	v_cvt_f32_f16_sdwa v127, v114 dst_sel:DWORD dst_unused:UNUSED_PAD src0_sel:WORD_1
	v_cvt_f32_f16_e32 v114, v114
	v_and_b32_e32 v121, 0xffffff80, v121
	v_sub_u32_e32 v121, v121, v10
	v_not_b32_e32 v128, v127
	v_or_b32_e32 v129, 0x80000000, v127
	v_cmp_gt_i32_e32 vcc, 0, v127
	v_add_u32_e32 v126, 0x7e, v126
	v_add_u32_e32 v121, 0x7f, v121
	v_cndmask_b32_e32 v127, v129, v128, vcc
	v_not_b32_e32 v128, v114
	v_or_b32_e32 v129, 0x80000000, v114
	v_cmp_gt_i32_e32 vcc, 0, v114
	v_and_b32_e32 v127, 0xffffff80, v127
	v_sub_u32_e32 v127, v127, v8
	v_cndmask_b32_e32 v114, v129, v128, vcc
	v_cvt_f32_f16_sdwa v128, v115 dst_sel:DWORD dst_unused:UNUSED_PAD src0_sel:WORD_1
	v_cvt_f32_f16_e32 v115, v115
	v_and_b32_e32 v114, 0xffffff80, v114
	v_sub_u32_e32 v114, v114, v8
	v_not_b32_e32 v129, v128
	v_or_b32_e32 v130, 0x80000000, v128
	v_cmp_gt_i32_e32 vcc, 0, v128
	v_add_u32_e32 v127, 0x7e, v127
	v_add_u32_e32 v114, 0x7f, v114
	v_cndmask_b32_e32 v128, v130, v129, vcc
	v_not_b32_e32 v129, v115
	v_or_b32_e32 v130, 0x80000000, v115
	v_cmp_gt_i32_e32 vcc, 0, v115
	v_and_b32_e32 v128, 0xffffff80, v128
	v_sub_u32_e32 v128, v128, v16
	v_cndmask_b32_e32 v115, v130, v129, vcc
	v_cvt_f32_f16_sdwa v129, v116 dst_sel:DWORD dst_unused:UNUSED_PAD src0_sel:WORD_1
	v_cvt_f32_f16_e32 v116, v116
	v_and_b32_e32 v115, 0xffffff80, v115
	v_sub_u32_e32 v115, v115, v16
	v_not_b32_e32 v130, v129
	v_or_b32_e32 v131, 0x80000000, v129
	v_cmp_gt_i32_e32 vcc, 0, v129
	v_add_u32_e32 v128, 0x7e, v128
	v_add_u32_e32 v115, 0x7f, v115
	v_cndmask_b32_e32 v129, v131, v130, vcc
	v_not_b32_e32 v130, v116
	v_or_b32_e32 v131, 0x80000000, v116
	v_cmp_gt_i32_e32 vcc, 0, v116
	v_and_b32_e32 v129, 0xffffff80, v129
	v_sub_u32_e32 v129, v129, v17
	v_cndmask_b32_e32 v116, v131, v130, vcc
	v_cvt_f32_f16_sdwa v130, v117 dst_sel:DWORD dst_unused:UNUSED_PAD src0_sel:WORD_1
	v_cvt_f32_f16_e32 v117, v117
	v_and_b32_e32 v116, 0xffffff80, v116
	v_sub_u32_e32 v116, v116, v17
	v_not_b32_e32 v131, v130
	v_or_b32_e32 v132, 0x80000000, v130
	v_cmp_gt_i32_e32 vcc, 0, v130
	v_add_u32_e32 v129, 0x7e, v129
	v_add_u32_e32 v116, 0x7f, v116
	v_cndmask_b32_e32 v130, v132, v131, vcc
	v_not_b32_e32 v131, v117
	v_or_b32_e32 v132, 0x80000000, v117
	v_cmp_gt_i32_e32 vcc, 0, v117
	v_and_b32_e32 v130, 0xffffff80, v130
	v_sub_u32_e32 v130, v130, v18
	v_cndmask_b32_e32 v117, v132, v131, vcc
	s_waitcnt vmcnt(0)
; __device__ __forceinline__ unsigned f2key(float f) { const unsigned u = __float_as_uint(f); return (u & 0x80000000u) ? ~u : (u | 0x80000000u); }
; __device__ __forceinline__ void sort16_desc(unsigned (&k)[16]) {
; #pragma unroll
;     for (int size = 2; size <= 16; size <<= 1)
; #pragma unroll
;         for (int stride = size >> 1; stride > 0; stride >>= 1)
; __device__ __forceinline__ void peer_tile(const Args& A, LAS unsigned char* lds, int tile) {
;     ...
;                   for (int i = 0; i < 16; ++i) {
;                       const float lo = (float)__builtin_bit_cast(_Float16, (unsigned short)(sw[i] & 0xffffu)), hi = (float)__builtin_bit_cast(_Float16, (unsigned short)(sw[i] >> 16));
;                       const unsigned klo = (f2key(lo) & ~127u) | (unsigned)(127 - (32 * g + 2 * i)), khi = (f2key(hi) & ~127u) | (unsigned)(127 - (32 * g + 2 * i + 1));
;                       if (i < 8) { k0[2 * i] = klo; k0[2 * i + 1] = khi; } else { k1[2 * (i - 8)] = klo; k1[2 * (i - 8) + 1] = khi; } } }
;                 sort16_desc(k0); sort16_desc(k1); merge16(k0, k1);
	v_cvt_f32_f16_sdwa v131, v122 dst_sel:DWORD dst_unused:UNUSED_PAD src0_sel:WORD_1
	v_cvt_f32_f16_e32 v122, v122
	v_and_b32_e32 v117, 0xffffff80, v117
	v_sub_u32_e32 v117, v117, v18
	v_not_b32_e32 v132, v131
	v_or_b32_e32 v133, 0x80000000, v131
	v_cmp_gt_i32_e32 vcc, 0, v131
	v_add_u32_e32 v130, 0x7e, v130
	v_add_u32_e32 v117, 0x7f, v117
	v_cndmask_b32_e32 v131, v133, v132, vcc
	v_not_b32_e32 v132, v122
	v_or_b32_e32 v133, 0x80000000, v122
	v_cmp_gt_i32_e32 vcc, 0, v122
	v_and_b32_e32 v131, 0xffffff80, v131
	v_sub_u32_e32 v131, v131, v20
	v_cndmask_b32_e32 v122, v133, v132, vcc
	v_cvt_f32_f16_sdwa v132, v123 dst_sel:DWORD dst_unused:UNUSED_PAD src0_sel:WORD_1
	v_cvt_f32_f16_e32 v123, v123
	v_and_b32_e32 v122, 0xffffff80, v122
	v_sub_u32_e32 v122, v122, v20
	v_not_b32_e32 v133, v132
	v_or_b32_e32 v134, 0x80000000, v132
	v_cmp_gt_i32_e32 vcc, 0, v132
	v_add_u32_e32 v131, 0x7e, v131
	v_add_u32_e32 v122, 0x7f, v122
	v_cndmask_b32_e32 v132, v134, v133, vcc
	v_not_b32_e32 v133, v123
	v_or_b32_e32 v134, 0x80000000, v123
	v_cmp_gt_i32_e32 vcc, 0, v123
	v_and_b32_e32 v132, 0xffffff80, v132
	v_sub_u32_e32 v132, v132, v21
	v_cndmask_b32_e32 v123, v134, v133, vcc
	v_cvt_f32_f16_sdwa v133, v124 dst_sel:DWORD dst_unused:UNUSED_PAD src0_sel:WORD_1
	v_cvt_f32_f16_e32 v124, v124
	v_and_b32_e32 v123, 0xffffff80, v123
	v_sub_u32_e32 v123, v123, v21
	v_not_b32_e32 v134, v133
	v_or_b32_e32 v135, 0x80000000, v133
	v_cmp_gt_i32_e32 vcc, 0, v133
	v_add_u32_e32 v132, 0x7e, v132
	v_add_u32_e32 v123, 0x7f, v123
	v_cndmask_b32_e32 v133, v135, v134, vcc
	v_not_b32_e32 v134, v124
	v_or_b32_e32 v135, 0x80000000, v124
	v_cmp_gt_i32_e32 vcc, 0, v124
	v_and_b32_e32 v133, 0xffffff80, v133
	v_sub_u32_e32 v133, v133, v22
	v_cndmask_b32_e32 v124, v135, v134, vcc
	v_cvt_f32_f16_sdwa v134, v125 dst_sel:DWORD dst_unused:UNUSED_PAD src0_sel:WORD_1
	v_cvt_f32_f16_e32 v125, v125
	v_and_b32_e32 v124, 0xffffff80, v124
	v_sub_u32_e32 v124, v124, v22
	v_not_b32_e32 v135, v134
	v_or_b32_e32 v136, 0x80000000, v134
	v_cmp_gt_i32_e32 vcc, 0, v134
	v_add_u32_e32 v133, 0x7e, v133
	v_add_u32_e32 v124, 0x7f, v124
	v_cndmask_b32_e32 v134, v136, v135, vcc
	v_not_b32_e32 v135, v125
	v_or_b32_e32 v136, 0x80000000, v125
	v_cmp_gt_i32_e32 vcc, 0, v125
	v_and_b32_e32 v134, 0xffffff80, v134
	v_sub_u32_e32 v134, v134, v23
	v_cndmask_b32_e32 v125, v136, v135, vcc
	v_cvt_f32_f16_sdwa v135, v0 dst_sel:DWORD dst_unused:UNUSED_PAD src0_sel:WORD_1
	v_cvt_f32_f16_e32 v0, v0
	v_and_b32_e32 v125, 0xffffff80, v125
	v_sub_u32_e32 v125, v125, v23
	v_not_b32_e32 v136, v135
	v_or_b32_e32 v137, 0x80000000, v135
	v_cmp_gt_i32_e32 vcc, 0, v135
	v_add_u32_e32 v134, 0x7e, v134
	v_add_u32_e32 v125, 0x7f, v125
	v_cndmask_b32_e32 v135, v137, v136, vcc
	v_not_b32_e32 v136, v0
	v_or_b32_e32 v137, 0x80000000, v0
	v_cmp_gt_i32_e32 vcc, 0, v0
	v_and_b32_e32 v135, 0xffffff80, v135
	v_sub_u32_e32 v135, v135, v24
	v_cndmask_b32_e32 v0, v137, v136, vcc
	v_cvt_f32_f16_sdwa v136, v1 dst_sel:DWORD dst_unused:UNUSED_PAD src0_sel:WORD_1
	v_cvt_f32_f16_e32 v1, v1
	v_and_b32_e32 v0, 0xffffff80, v0
	v_sub_u32_e32 v0, v0, v24
	v_not_b32_e32 v137, v136
	v_or_b32_e32 v138, 0x80000000, v136
	v_cmp_gt_i32_e32 vcc, 0, v136
	v_add_u32_e32 v135, 0x7e, v135
	v_add_u32_e32 v0, 0x7f, v0
	v_cndmask_b32_e32 v136, v138, v137, vcc
	v_not_b32_e32 v137, v1
	v_or_b32_e32 v138, 0x80000000, v1
	v_cmp_gt_i32_e32 vcc, 0, v1
	v_and_b32_e32 v136, 0xffffff80, v136
	v_sub_u32_e32 v136, v136, v25
	v_cndmask_b32_e32 v1, v138, v137, vcc
	v_cvt_f32_f16_sdwa v137, v2 dst_sel:DWORD dst_unused:UNUSED_PAD src0_sel:WORD_1
	v_cvt_f32_f16_e32 v2, v2
	v_and_b32_e32 v1, 0xffffff80, v1
	v_sub_u32_e32 v1, v1, v25
	v_not_b32_e32 v138, v137
	v_or_b32_e32 v139, 0x80000000, v137
	v_cmp_gt_i32_e32 vcc, 0, v137
	v_add_u32_e32 v136, 0x7e, v136
	v_add_u32_e32 v1, 0x7f, v1
	v_cndmask_b32_e32 v137, v139, v138, vcc
	v_not_b32_e32 v138, v2
	v_or_b32_e32 v139, 0x80000000, v2
	v_cmp_gt_i32_e32 vcc, 0, v2
	v_and_b32_e32 v137, 0xffffff80, v137
	v_sub_u32_e32 v137, v137, v26
	v_cndmask_b32_e32 v2, v139, v138, vcc
	v_cvt_f32_f16_sdwa v138, v3 dst_sel:DWORD dst_unused:UNUSED_PAD src0_sel:WORD_1
	v_cvt_f32_f16_e32 v3, v3
	v_and_b32_e32 v2, 0xffffff80, v2
	v_sub_u32_e32 v2, v2, v26
	v_not_b32_e32 v139, v138
	v_or_b32_e32 v140, 0x80000000, v138
	v_cmp_gt_i32_e32 vcc, 0, v138
	v_add_u32_e32 v137, 0x7e, v137
	v_add_u32_e32 v2, 0x7f, v2
	v_cndmask_b32_e32 v138, v140, v139, vcc
	v_not_b32_e32 v139, v3
	v_or_b32_e32 v140, 0x80000000, v3
	v_cmp_gt_i32_e32 vcc, 0, v3
	v_and_b32_e32 v138, 0xffffff80, v138
	v_sub_u32_e32 v138, v138, v28
	v_cndmask_b32_e32 v3, v140, v139, vcc
	v_and_b32_e32 v3, 0xffffff80, v3
	v_sub_u32_e32 v3, v3, v28
	v_add_u32_e32 v138, 0x7e, v138
	v_add_u32_e32 v3, 0x7f, v3
	v_max_u32_e32 v139, v111, v110
	v_min_u32_e32 v110, v111, v110
	v_max_u32_e32 v111, v112, v118
	v_min_u32_e32 v112, v112, v118
	v_max_u32_e32 v118, v120, v119
	v_min_u32_e32 v119, v120, v119
	v_max_u32_e32 v120, v126, v121
	v_min_u32_e32 v121, v126, v121
	v_max_u32_e32 v126, v114, v127
	v_min_u32_e32 v114, v114, v127
	v_max_u32_e32 v127, v128, v115
	v_min_u32_e32 v115, v128, v115
	v_max_u32_e32 v128, v116, v129
	v_min_u32_e32 v116, v116, v129
	v_max_u32_e32 v129, v130, v117
	v_min_u32_e32 v117, v130, v117
	v_max_u32_e32 v147, v122, v131
	v_min_u32_e32 v122, v122, v131
	v_max_u32_e32 v131, v132, v123
	v_min_u32_e32 v123, v132, v123
	v_max_u32_e32 v132, v124, v133
	v_min_u32_e32 v124, v124, v133
	v_max_u32_e32 v133, v134, v125
	v_min_u32_e32 v125, v134, v125
	v_max_u32_e32 v134, v0, v135
	v_min_u32_e32 v0, v0, v135
	v_max_u32_e32 v135, v136, v1
	v_min_u32_e32 v1, v136, v1
	v_max_u32_e32 v136, v2, v137
	v_min_u32_e32 v2, v2, v137
; #define CE_DESC(a, b) do { const unsigned _mx = (a) > (b) ? (a) : (b), _mn = (a) > (b) ? (b) : (a); (a) = _mx; (b) = _mn; } while (0)
; __device__ __forceinline__ void sort16_desc(unsigned (&k)[16]) {
; #pragma unroll
;     for (int size = 2; size <= 16; size <<= 1)
; #pragma unroll
;         for (int stride = size >> 1; stride > 0; stride >>= 1)
; #pragma unroll
;             for (int i = 0; i < 16; ++i) { const int j = i ^ stride;
;                 if (j > i) { if ((i & size) == 0) CE_DESC(k[i], k[j]); else CE_DESC(k[j], k[i]); } }
; }
	v_max_u32_e32 v137, v138, v3
	v_min_u32_e32 v3, v138, v3
	v_max_u32_e32 v130, v139, v112
	v_min_u32_e32 v112, v139, v112
	v_max_u32_e32 v139, v110, v111
	v_min_u32_e32 v110, v110, v111
	v_max_u32_e32 v111, v121, v118
	v_min_u32_e32 v118, v121, v118
	v_max_u32_e32 v121, v120, v119
	v_min_u32_e32 v119, v120, v119
	v_max_u32_e32 v120, v126, v115
	v_min_u32_e32 v115, v126, v115
	v_max_u32_e32 v126, v114, v127
	v_min_u32_e32 v114, v114, v127
	v_max_u32_e32 v127, v117, v128
	v_min_u32_e32 v117, v117, v128
	v_max_u32_e32 v128, v129, v116
	v_min_u32_e32 v116, v129, v116
	v_max_u32_e32 v138, v147, v123
	v_min_u32_e32 v123, v147, v123
	v_max_u32_e32 v147, v122, v131
	v_min_u32_e32 v122, v122, v131
	v_max_u32_e32 v131, v125, v132
	v_min_u32_e32 v125, v125, v132
	v_max_u32_e32 v132, v133, v124
	v_min_u32_e32 v124, v133, v124
	v_max_u32_e32 v133, v134, v1
	v_min_u32_e32 v1, v134, v1
	v_max_u32_e32 v134, v0, v135
	v_min_u32_e32 v0, v0, v135
	v_max_u32_e32 v135, v3, v136
	v_min_u32_e32 v3, v3, v136
	v_max_u32_e32 v136, v137, v2
	v_min_u32_e32 v2, v137, v2
	v_max_u32_e32 v129, v130, v139
	v_min_u32_e32 v130, v130, v139
	v_max_u32_e32 v139, v112, v110
	v_min_u32_e32 v110, v112, v110
	v_max_u32_e32 v112, v119, v118
	v_min_u32_e32 v118, v119, v118
	v_max_u32_e32 v119, v121, v111
	v_min_u32_e32 v111, v121, v111
	v_max_u32_e32 v121, v120, v126
	v_min_u32_e32 v120, v120, v126
	v_max_u32_e32 v126, v115, v114
	v_min_u32_e32 v114, v115, v114
	v_max_u32_e32 v115, v116, v117
	v_min_u32_e32 v116, v116, v117
	v_max_u32_e32 v117, v128, v127
	v_min_u32_e32 v127, v128, v127
	v_max_u32_e32 v137, v138, v147
	v_min_u32_e32 v138, v138, v147
	v_max_u32_e32 v147, v123, v122
	v_min_u32_e32 v122, v123, v122
	v_max_u32_e32 v123, v124, v125
	v_min_u32_e32 v124, v124, v125
	v_max_u32_e32 v125, v132, v131
	v_min_u32_e32 v131, v132, v131
	v_max_u32_e32 v132, v133, v134
	v_min_u32_e32 v133, v133, v134
	v_max_u32_e32 v134, v1, v0
	v_min_u32_e32 v0, v1, v0
	v_max_u32_e32 v1, v2, v3
	v_min_u32_e32 v2, v2, v3
	v_max_u32_e32 v3, v136, v135
	v_min_u32_e32 v135, v136, v135
	v_max_u32_e32 v128, v129, v118
	v_min_u32_e32 v118, v129, v118
	v_max_u32_e32 v129, v130, v112
	v_min_u32_e32 v112, v130, v112
	v_max_u32_e32 v130, v139, v111
	v_min_u32_e32 v111, v139, v111
	v_max_u32_e32 v139, v110, v119
	v_min_u32_e32 v110, v110, v119
	v_max_u32_e32 v119, v116, v121
	v_min_u32_e32 v116, v116, v121
	v_max_u32_e32 v121, v115, v120
	v_min_u32_e32 v115, v115, v120
	v_max_u32_e32 v120, v127, v126
	v_min_u32_e32 v126, v127, v126
	v_max_u32_e32 v127, v117, v114
	v_min_u32_e32 v114, v117, v114
	v_max_u32_e32 v136, v137, v124
	v_min_u32_e32 v124, v137, v124
	v_max_u32_e32 v137, v138, v123
	v_min_u32_e32 v123, v138, v123
	v_max_u32_e32 v138, v147, v131
	v_min_u32_e32 v131, v147, v131
	v_max_u32_e32 v147, v122, v125
	v_min_u32_e32 v122, v122, v125
	v_max_u32_e32 v125, v2, v132
	v_min_u32_e32 v2, v2, v132
	v_max_u32_e32 v132, v1, v133
	v_min_u32_e32 v1, v1, v133
	v_max_u32_e32 v133, v135, v134
	v_min_u32_e32 v134, v135, v134
	v_max_u32_e32 v135, v3, v0
	v_min_u32_e32 v0, v3, v0
	v_max_u32_e32 v117, v128, v130
	v_min_u32_e32 v128, v128, v130
	v_max_u32_e32 v130, v129, v139
	v_min_u32_e32 v129, v129, v139
	v_max_u32_e32 v139, v118, v111
	v_min_u32_e32 v111, v118, v111
	v_max_u32_e32 v118, v112, v110
	v_min_u32_e32 v110, v112, v110
	v_max_u32_e32 v112, v126, v116
	v_min_u32_e32 v116, v126, v116
	v_max_u32_e32 v126, v114, v115
	v_min_u32_e32 v114, v114, v115
	v_max_u32_e32 v115, v120, v119
	v_min_u32_e32 v119, v120, v119
	v_max_u32_e32 v120, v127, v121
	v_min_u32_e32 v121, v127, v121
	v_max_u32_e32 v3, v136, v138
	v_min_u32_e32 v136, v136, v138
	v_max_u32_e32 v138, v137, v147
	v_min_u32_e32 v137, v137, v147
	v_max_u32_e32 v147, v124, v131
	v_min_u32_e32 v124, v124, v131
	v_max_u32_e32 v131, v123, v122
	v_min_u32_e32 v122, v123, v122
	v_max_u32_e32 v123, v134, v2
	v_min_u32_e32 v2, v134, v2
	v_max_u32_e32 v134, v0, v1
	v_min_u32_e32 v0, v0, v1
	v_max_u32_e32 v1, v133, v125
	v_min_u32_e32 v125, v133, v125
	v_max_u32_e32 v133, v135, v132
	v_min_u32_e32 v132, v135, v132
	v_max_u32_e32 v127, v117, v130
	v_min_u32_e32 v117, v117, v130
	v_max_u32_e32 v130, v128, v129
	v_min_u32_e32 v128, v128, v129
	v_max_u32_e32 v129, v139, v118
	v_min_u32_e32 v118, v139, v118
	v_max_u32_e32 v139, v111, v110
	v_min_u32_e32 v110, v111, v110
	v_max_u32_e32 v111, v114, v116
	v_min_u32_e32 v114, v114, v116
	v_max_u32_e32 v116, v126, v112
	v_min_u32_e32 v112, v126, v112
	v_max_u32_e32 v126, v121, v119
	v_min_u32_e32 v119, v121, v119
	v_max_u32_e32 v121, v120, v115
	v_min_u32_e32 v115, v120, v115
	v_max_u32_e32 v135, v3, v138
	v_min_u32_e32 v3, v3, v138
	v_max_u32_e32 v138, v136, v137
	v_min_u32_e32 v136, v136, v137
	v_max_u32_e32 v137, v147, v131
	v_min_u32_e32 v131, v147, v131
	v_max_u32_e32 v147, v124, v122
	v_min_u32_e32 v122, v124, v122
	v_max_u32_e32 v124, v0, v2
	v_min_u32_e32 v0, v0, v2
	v_max_u32_e32 v2, v134, v123
	v_min_u32_e32 v123, v134, v123
	v_max_u32_e32 v134, v132, v125
	v_min_u32_e32 v125, v132, v125
	v_max_u32_e32 v132, v133, v1
	v_min_u32_e32 v1, v133, v1
	v_max_u32_e32 v120, v127, v114
	v_min_u32_e32 v114, v127, v114
	v_max_u32_e32 v127, v117, v111
	v_min_u32_e32 v111, v117, v111
	v_max_u32_e32 v117, v130, v112
	v_min_u32_e32 v112, v130, v112
	v_max_u32_e32 v130, v128, v116
	v_min_u32_e32 v116, v128, v116
	v_max_u32_e32 v128, v129, v119
	v_min_u32_e32 v119, v129, v119
	v_max_u32_e32 v129, v118, v126
	v_min_u32_e32 v118, v118, v126
	v_max_u32_e32 v126, v139, v115
	v_min_u32_e32 v115, v139, v115
	v_max_u32_e32 v139, v110, v121
	v_min_u32_e32 v110, v110, v121
	v_max_u32_e32 v133, v135, v0
	v_min_u32_e32 v0, v135, v0
; #define CE_DESC(a, b) do { const unsigned _mx = (a) > (b) ? (a) : (b), _mn = (a) > (b) ? (b) : (a); (a) = _mx; (b) = _mn; } while (0)
; __device__ __forceinline__ void sort16_desc(unsigned (&k)[16]) {
; #pragma unroll
;     for (int size = 2; size <= 16; size <<= 1)
; #pragma unroll
;         for (int stride = size >> 1; stride > 0; stride >>= 1)
; #pragma unroll
;             for (int i = 0; i < 16; ++i) { const int j = i ^ stride;
;                 if (j > i) { if ((i & size) == 0) CE_DESC(k[i], k[j]); else CE_DESC(k[j], k[i]); } }
; }
; __device__ __forceinline__ void merge16(unsigned (&a)[16], const unsigned (&b)[16]) {
; #pragma unroll
;     for (int i = 0; i < 16; ++i) a[i] = a[i] > b[15 - i] ? a[i] : b[15 - i];
; #pragma unroll
;     for (int stride = 8; stride > 0; stride >>= 1)
; #pragma unroll
;         for (int i = 0; i < 16; ++i) { const int j = i ^ stride; if (j > i) CE_DESC(a[i], a[j]); }
; }
; __device__ __forceinline__ void peer_tile(const Args& A, LAS unsigned char* lds, int tile) {
;     ...
;                 for (int msk = 16; msk <= 32; msk <<= 1) {
; #pragma unroll
;                     for (int i = 0; i < 16; ++i) k1[i] = (unsigned)__shfl_xor((int)k0[i], msk);
;                     merge16(k0, k1); }
	v_max_u32_e32 v135, v3, v124
	v_min_u32_e32 v3, v3, v124
	v_max_u32_e32 v124, v138, v123
	v_min_u32_e32 v123, v138, v123
	v_max_u32_e32 v138, v136, v2
	v_min_u32_e32 v2, v136, v2
	v_max_u32_e32 v136, v137, v125
	v_min_u32_e32 v125, v137, v125
	v_max_u32_e32 v137, v131, v134
	v_min_u32_e32 v131, v131, v134
	v_max_u32_e32 v134, v147, v1
	v_min_u32_e32 v1, v147, v1
	v_max_u32_e32 v147, v122, v132
	v_min_u32_e32 v122, v122, v132
	v_max_u32_e32 v121, v120, v128
	v_min_u32_e32 v120, v120, v128
	v_max_u32_e32 v128, v127, v129
	v_min_u32_e32 v127, v127, v129
	v_max_u32_e32 v129, v117, v126
	v_min_u32_e32 v117, v117, v126
	v_max_u32_e32 v126, v130, v139
	v_min_u32_e32 v130, v130, v139
	v_max_u32_e32 v139, v114, v119
	v_min_u32_e32 v114, v114, v119
	v_max_u32_e32 v119, v111, v118
	v_min_u32_e32 v111, v111, v118
	v_max_u32_e32 v118, v112, v115
	v_min_u32_e32 v112, v112, v115
	v_max_u32_e32 v115, v116, v110
	v_min_u32_e32 v110, v116, v110
	v_max_u32_e32 v132, v133, v136
	v_min_u32_e32 v133, v133, v136
	v_max_u32_e32 v136, v135, v137
	v_min_u32_e32 v135, v135, v137
	v_max_u32_e32 v137, v124, v134
	v_min_u32_e32 v124, v124, v134
	v_max_u32_e32 v134, v138, v147
	v_min_u32_e32 v138, v138, v147
	v_max_u32_e32 v147, v0, v125
	v_min_u32_e32 v0, v0, v125
	v_max_u32_e32 v125, v3, v131
	v_min_u32_e32 v3, v3, v131
	v_max_u32_e32 v131, v123, v1
	v_min_u32_e32 v1, v123, v1
	v_max_u32_e32 v123, v2, v122
	v_min_u32_e32 v2, v2, v122
	v_max_u32_e32 v116, v121, v129
	v_min_u32_e32 v121, v121, v129
	v_max_u32_e32 v129, v128, v126
	v_min_u32_e32 v126, v128, v126
	v_max_u32_e32 v128, v120, v117
	v_min_u32_e32 v117, v120, v117
	v_max_u32_e32 v120, v127, v130
	v_min_u32_e32 v127, v127, v130
	v_max_u32_e32 v130, v139, v118
	v_min_u32_e32 v118, v139, v118
	v_max_u32_e32 v139, v119, v115
	v_min_u32_e32 v115, v119, v115
	v_max_u32_e32 v119, v114, v112
	v_min_u32_e32 v112, v114, v112
	v_max_u32_e32 v114, v111, v110
	v_min_u32_e32 v110, v111, v110
	v_max_u32_e32 v122, v132, v137
	v_min_u32_e32 v132, v132, v137
	v_max_u32_e32 v137, v136, v134
	v_min_u32_e32 v134, v136, v134
	v_max_u32_e32 v136, v133, v124
	v_min_u32_e32 v124, v133, v124
	v_max_u32_e32 v133, v135, v138
	v_min_u32_e32 v135, v135, v138
	v_max_u32_e32 v138, v147, v131
	v_min_u32_e32 v131, v147, v131
	v_max_u32_e32 v147, v125, v123
	v_min_u32_e32 v123, v125, v123
	v_max_u32_e32 v125, v0, v1
	v_min_u32_e32 v0, v0, v1
	v_max_u32_e32 v1, v3, v2
	v_min_u32_e32 v2, v3, v2
	v_min_u32_e32 v111, v116, v129
	v_min_u32_e32 v140, v121, v126
	v_min_u32_e32 v141, v128, v120
	v_min_u32_e32 v142, v117, v127
	v_min_u32_e32 v143, v130, v139
	v_min_u32_e32 v144, v118, v115
	v_min_u32_e32 v145, v119, v114
	v_min_u32_e32 v146, v112, v110
	v_min_u32_e32 v3, v122, v137
	v_min_u32_e32 v148, v132, v134
	v_min_u32_e32 v149, v136, v133
	v_min_u32_e32 v150, v124, v135
	v_min_u32_e32 v151, v138, v147
	v_min_u32_e32 v152, v131, v123
	v_min_u32_e32 v153, v125, v1
	v_min_u32_e32 v154, v0, v2
	v_max3_u32 v116, v116, v129, v154
	v_max3_u32 v0, v111, v0, v2
	v_max3_u32 v2, v121, v126, v153
	v_max3_u32 v1, v140, v125, v1
	v_max3_u32 v111, v128, v120, v152
	v_max3_u32 v120, v141, v131, v123
	v_max3_u32 v117, v117, v127, v151
	v_max3_u32 v121, v142, v138, v147
	v_max3_u32 v123, v130, v139, v150
	v_max3_u32 v124, v143, v124, v135
	v_max3_u32 v115, v118, v115, v149
	v_max3_u32 v118, v144, v136, v133
	v_max3_u32 v114, v119, v114, v148
	v_max3_u32 v119, v145, v132, v134
	v_max3_u32 v3, v112, v110, v3
	v_max3_u32 v110, v146, v122, v137
	v_max_u32_e32 v112, v116, v123
	v_min_u32_e32 v116, v116, v123
	v_max_u32_e32 v122, v0, v124
	v_min_u32_e32 v0, v0, v124
	v_max_u32_e32 v123, v2, v115
	v_min_u32_e32 v2, v2, v115
	v_max_u32_e32 v115, v1, v118
	v_min_u32_e32 v1, v1, v118
	v_max_u32_e32 v118, v111, v114
	v_min_u32_e32 v111, v111, v114
	v_max_u32_e32 v114, v120, v119
	v_min_u32_e32 v119, v120, v119
	v_max_u32_e32 v120, v117, v3
	v_min_u32_e32 v3, v117, v3
	v_max_u32_e32 v117, v121, v110
	v_min_u32_e32 v110, v121, v110
	v_max_u32_e32 v121, v112, v118
	v_min_u32_e32 v112, v112, v118
	v_max_u32_e32 v118, v122, v114
	v_min_u32_e32 v114, v122, v114
	v_max_u32_e32 v122, v123, v120
	v_min_u32_e32 v120, v123, v120
	v_max_u32_e32 v123, v115, v117
	v_min_u32_e32 v115, v115, v117
	v_max_u32_e32 v117, v116, v111
	v_min_u32_e32 v111, v116, v111
	v_max_u32_e32 v116, v0, v119
	v_min_u32_e32 v0, v0, v119
	v_max_u32_e32 v119, v2, v3
	v_min_u32_e32 v2, v2, v3
	v_max_u32_e32 v3, v1, v110
	v_min_u32_e32 v1, v1, v110
	v_max_u32_e32 v110, v121, v122
	v_min_u32_e32 v121, v121, v122
	v_max_u32_e32 v122, v118, v123
	v_min_u32_e32 v118, v118, v123
	v_max_u32_e32 v123, v112, v120
	v_min_u32_e32 v112, v112, v120
	v_max_u32_e32 v120, v114, v115
	v_min_u32_e32 v114, v114, v115
	v_max_u32_e32 v115, v117, v119
	v_min_u32_e32 v117, v117, v119
	v_max_u32_e32 v119, v116, v3
	v_min_u32_e32 v3, v116, v3
	v_max_u32_e32 v116, v111, v2
	v_min_u32_e32 v2, v111, v2
	v_max_u32_e32 v111, v0, v1
	v_min_u32_e32 v0, v0, v1
	v_max_u32_e32 v1, v110, v122
	v_min_u32_e32 v110, v110, v122
	v_max_u32_e32 v122, v121, v118
	v_min_u32_e32 v118, v121, v118
	v_max_u32_e32 v121, v123, v120
	v_min_u32_e32 v120, v123, v120
	v_max_u32_e32 v123, v112, v114
	v_min_u32_e32 v112, v112, v114
	v_max_u32_e32 v114, v115, v119
	v_min_u32_e32 v115, v115, v119
	v_max_u32_e32 v119, v117, v3
	v_min_u32_e32 v3, v117, v3
	v_max_u32_e32 v117, v116, v111
	v_min_u32_e32 v111, v116, v111
	v_max_u32_e32 v116, v2, v0
	v_min_u32_e32 v0, v2, v0
	ds_bpermute_b32 v2, v27, v1
	ds_bpermute_b32 v124, v27, v110
	ds_bpermute_b32 v125, v27, v122
	ds_bpermute_b32 v126, v27, v118
	ds_bpermute_b32 v127, v27, v121
	ds_bpermute_b32 v128, v27, v120
	ds_bpermute_b32 v129, v27, v123
	ds_bpermute_b32 v130, v27, v112
	ds_bpermute_b32 v131, v27, v114
	ds_bpermute_b32 v132, v27, v115
	ds_bpermute_b32 v133, v27, v119
	ds_bpermute_b32 v134, v27, v0
	ds_bpermute_b32 v135, v27, v116
	ds_bpermute_b32 v136, v27, v111
	ds_bpermute_b32 v137, v27, v117
	ds_bpermute_b32 v138, v27, v3
	s_waitcnt lgkmcnt(4)
; __device__ __forceinline__ void peer_tile(const Args& A, LAS unsigned char* lds, int tile) {
;     ...
;                 { const bf16_t* sp = QRY + m * 2048 + hp * 128 + 32 * g;
;                   const u32x4 s0 = *(const u32x4*)sp, s1 = *(const u32x4*)(sp + 8), s2 = *(const u32x4*)(sp + 16), s3 = *(const u32x4*)(sp + 24);
;     ...
;                 for (int msk = 16; msk <= 32; msk <<= 1) {
; #pragma unroll
;                     for (int i = 0; i < 16; ++i) k1[i] = (unsigned)__shfl_xor((int)k0[i], msk);
;                     merge16(k0, k1); }
	v_max_u32_e32 v1, v1, v134
	s_waitcnt lgkmcnt(3)
	v_max_u32_e32 v110, v110, v135
	s_waitcnt lgkmcnt(2)
	v_max_u32_e32 v122, v122, v136
	s_waitcnt lgkmcnt(1)
	v_max_u32_e32 v118, v118, v137
	s_waitcnt lgkmcnt(0)
	v_max_u32_e32 v121, v121, v138
	v_max_u32_e32 v120, v120, v133
	v_max_u32_e32 v123, v123, v132
	v_max_u32_e32 v112, v112, v131
	v_max_u32_e32 v114, v114, v130
	v_max_u32_e32 v115, v115, v129
	v_max_u32_e32 v119, v119, v128
	v_max_u32_e32 v3, v3, v127
	v_max_u32_e32 v117, v117, v126
	v_max_u32_e32 v111, v111, v125
	v_max_u32_e32 v116, v116, v124
	v_max_u32_e32 v0, v0, v2
	v_max_u32_e32 v2, v1, v114
	v_min_u32_e32 v1, v1, v114
	v_max_u32_e32 v114, v110, v115
	v_min_u32_e32 v110, v110, v115
	v_max_u32_e32 v115, v122, v119
	v_min_u32_e32 v119, v122, v119
	v_max_u32_e32 v122, v118, v3
	v_min_u32_e32 v3, v118, v3
	v_max_u32_e32 v118, v121, v117
	v_min_u32_e32 v117, v121, v117
	v_max_u32_e32 v121, v120, v111
	v_min_u32_e32 v111, v120, v111
	v_max_u32_e32 v120, v123, v116
	v_min_u32_e32 v116, v123, v116
	v_max_u32_e32 v123, v112, v0
	v_min_u32_e32 v0, v112, v0
	v_max_u32_e32 v112, v2, v118
	v_min_u32_e32 v2, v2, v118
	v_max_u32_e32 v118, v114, v121
	v_min_u32_e32 v114, v114, v121
	v_max_u32_e32 v121, v115, v120
	v_min_u32_e32 v115, v115, v120
	v_max_u32_e32 v120, v122, v123
	v_min_u32_e32 v122, v122, v123
	v_max_u32_e32 v123, v1, v117
	v_min_u32_e32 v1, v1, v117
	v_max_u32_e32 v117, v110, v111
	v_min_u32_e32 v110, v110, v111
	v_max_u32_e32 v111, v119, v116
	v_min_u32_e32 v116, v119, v116
	v_max_u32_e32 v119, v3, v0
	v_min_u32_e32 v0, v3, v0
	v_max_u32_e32 v3, v112, v121
	v_min_u32_e32 v112, v112, v121
	v_max_u32_e32 v121, v118, v120
	v_min_u32_e32 v118, v118, v120
	v_max_u32_e32 v120, v2, v115
	v_min_u32_e32 v2, v2, v115
	v_max_u32_e32 v115, v114, v122
	v_min_u32_e32 v114, v114, v122
	v_max_u32_e32 v122, v123, v111
	v_min_u32_e32 v111, v123, v111
	v_max_u32_e32 v123, v117, v119
	v_min_u32_e32 v117, v117, v119
	v_max_u32_e32 v119, v1, v116
	v_min_u32_e32 v1, v1, v116
	v_max_u32_e32 v116, v110, v0
	v_min_u32_e32 v0, v110, v0
	v_max_u32_e32 v110, v3, v121
	v_min_u32_e32 v3, v3, v121
	v_max_u32_e32 v121, v112, v118
	v_min_u32_e32 v112, v112, v118
	v_max_u32_e32 v118, v120, v115
	v_min_u32_e32 v115, v120, v115
	v_max_u32_e32 v120, v2, v114
	v_min_u32_e32 v2, v2, v114
	v_max_u32_e32 v114, v122, v123
	v_min_u32_e32 v122, v122, v123
	v_max_u32_e32 v123, v111, v117
	v_min_u32_e32 v111, v111, v117
	v_max_u32_e32 v117, v119, v116
	v_min_u32_e32 v116, v119, v116
	v_max_u32_e32 v119, v1, v0
	v_min_u32_e32 v0, v1, v0
	ds_bpermute_b32 v128, v29, v0
	ds_bpermute_b32 v1, v29, v110
	ds_bpermute_b32 v124, v29, v3
	ds_bpermute_b32 v125, v29, v121
	ds_bpermute_b32 v126, v29, v112
	s_waitcnt lgkmcnt(4)
	v_max_u32_e32 v110, v110, v128
	global_load_dwordx4 v[128:131], v[4:5], off offset:1552
	global_load_dwordx4 v[132:135], v[4:5], off offset:1536
	ds_bpermute_b32 v127, v29, v118
	ds_bpermute_b32 v136, v29, v115
	ds_bpermute_b32 v137, v29, v120
	ds_bpermute_b32 v138, v29, v2
	ds_bpermute_b32 v139, v29, v114
	ds_bpermute_b32 v140, v29, v122
	ds_bpermute_b32 v141, v29, v123
	ds_bpermute_b32 v142, v29, v111
	ds_bpermute_b32 v143, v29, v117
	ds_bpermute_b32 v144, v29, v119
	ds_bpermute_b32 v145, v29, v116
	s_waitcnt lgkmcnt(4)
	v_max_u32_e32 v115, v115, v141
	s_waitcnt lgkmcnt(3)
	v_max_u32_e32 v118, v118, v142
	s_waitcnt lgkmcnt(2)
	v_max_u32_e32 v112, v112, v143
	s_waitcnt lgkmcnt(1)
	v_max_u32_e32 v3, v3, v144
	s_waitcnt lgkmcnt(0)
	v_max_u32_e32 v121, v121, v145
	v_max_u32_e32 v120, v120, v140
	v_max_u32_e32 v2, v2, v139
	v_max_u32_e32 v114, v114, v138
	v_max_u32_e32 v122, v122, v137
	v_max_u32_e32 v123, v123, v136
	v_max_u32_e32 v111, v111, v127
	v_max_u32_e32 v117, v117, v126
	v_max_u32_e32 v116, v116, v125
	v_max_u32_e32 v119, v119, v124
	v_max_u32_e32 v0, v0, v1
	v_max_u32_e32 v1, v110, v114
	v_min_u32_e32 v110, v110, v114
	v_max_u32_e32 v114, v3, v122
	v_min_u32_e32 v3, v3, v122
	v_max_u32_e32 v122, v121, v123
	v_min_u32_e32 v121, v121, v123
	v_max_u32_e32 v123, v112, v111
	v_min_u32_e32 v111, v112, v111
	v_max_u32_e32 v112, v118, v117
	v_min_u32_e32 v117, v118, v117
	v_max_u32_e32 v118, v115, v116
	v_min_u32_e32 v115, v115, v116
	v_max_u32_e32 v116, v120, v119
	v_min_u32_e32 v119, v120, v119
	v_max_u32_e32 v120, v2, v0
	v_min_u32_e32 v0, v2, v0
	v_max_u32_e32 v2, v1, v112
	v_min_u32_e32 v1, v1, v112
	v_max_u32_e32 v112, v114, v118
	v_min_u32_e32 v114, v114, v118
	v_max_u32_e32 v118, v122, v116
	v_min_u32_e32 v116, v122, v116
	v_max_u32_e32 v122, v123, v120
	v_min_u32_e32 v120, v123, v120
	v_max_u32_e32 v123, v110, v117
	v_min_u32_e32 v110, v110, v117
	v_max_u32_e32 v117, v3, v115
	v_min_u32_e32 v3, v3, v115
	v_max_u32_e32 v115, v121, v119
	v_min_u32_e32 v119, v121, v119
	v_max_u32_e32 v121, v111, v0
	v_min_u32_e32 v0, v111, v0
	v_max_u32_e32 v111, v2, v118
	v_min_u32_e32 v2, v2, v118
	v_max_u32_e32 v118, v112, v122
	v_min_u32_e32 v112, v112, v122
	v_max_u32_e32 v127, v1, v116
	v_min_u32_e32 v1, v1, v116
	v_max_u32_e32 v116, v114, v120
	v_min_u32_e32 v114, v114, v120
	v_max_u32_e32 v136, v123, v115
	v_min_u32_e32 v115, v123, v115
	v_max_u32_e32 v137, v117, v121
	v_min_u32_e32 v138, v117, v121
	v_max_u32_e32 v139, v110, v119
	v_min_u32_e32 v110, v110, v119
	v_max_u32_e32 v140, v3, v0
	v_min_u32_e32 v0, v3, v0
	v_max_u32_e32 v126, v111, v118
	v_min_u32_e32 v125, v111, v118
	v_max_u32_e32 v124, v2, v112
	v_min_u32_e32 v123, v2, v112
	v_max_u32_e32 v122, v127, v116
	v_min_u32_e32 v121, v127, v116
	v_max_u32_e32 v120, v1, v114
	v_min_u32_e32 v119, v1, v114
	v_max_u32_e32 v118, v136, v137
	v_min_u32_e32 v117, v136, v137
	v_max_u32_e32 v116, v115, v138
	v_min_u32_e32 v115, v115, v138
	v_max_u32_e32 v114, v139, v140
	v_min_u32_e32 v112, v139, v140
	v_max_u32_e32 v111, v110, v0
	v_min_u32_e32 v110, v110, v0
	global_load_dwordx4 v[0:3], v[4:5], off offset:1584
	global_load_dwordx4 v[136:139], v[4:5], off offset:1568
	s_waitcnt vmcnt(2)
; __device__ __forceinline__ unsigned f2key(float f) { const unsigned u = __float_as_uint(f); return (u & 0x80000000u) ? ~u : (u | 0x80000000u); }
; __device__ __forceinline__ void peer_tile(const Args& A, LAS unsigned char* lds, int tile) {
;     ...
;                 { const bf16_t* sp = QRY + m * 2048 + hp * 128 + 32 * g;
;                   const u32x4 s0 = *(const u32x4*)sp, s1 = *(const u32x4*)(sp + 8), s2 = *(const u32x4*)(sp + 16), s3 = *(const u32x4*)(sp + 24);
;                   const unsigned sw[16] = {s0.x, s0.y, s0.z, s0.w, s1.x, s1.y, s1.z, s1.w, s2.x, s2.y, s2.z, s2.w, s3.x, s3.y, s3.z, s3.w};
; #pragma unroll
;                   for (int i = 0; i < 16; ++i) {
;                       const float lo = (float)__builtin_bit_cast(_Float16, (unsigned short)(sw[i] & 0xffffu)), hi = (float)__builtin_bit_cast(_Float16, (unsigned short)(sw[i] >> 16));
;                       const unsigned klo = (f2key(lo) & ~127u) | (unsigned)(127 - (32 * g + 2 * i)), khi = (f2key(hi) & ~127u) | (unsigned)(127 - (32 * g + 2 * i + 1));
;                       if (i < 8) { k0[2 * i] = klo; k0[2 * i + 1] = khi; } else { k1[2 * (i - 8)] = klo; k1[2 * (i - 8) + 1] = khi; } } }
	v_cvt_f32_f16_sdwa v127, v132 dst_sel:DWORD dst_unused:UNUSED_PAD src0_sel:WORD_1
	v_cvt_f32_f16_e32 v132, v132
	v_not_b32_e32 v140, v127
	v_or_b32_e32 v141, 0x80000000, v127
	v_cmp_gt_i32_e32 vcc, 0, v127
	s_nop 1
	v_cndmask_b32_e32 v127, v141, v140, vcc
	v_not_b32_e32 v140, v132
	v_or_b32_e32 v141, 0x80000000, v132
	v_cmp_gt_i32_e32 vcc, 0, v132
	v_and_b32_e32 v127, 0xffffff80, v127
	v_sub_u32_e32 v127, v127, v15
	v_cndmask_b32_e32 v132, v141, v140, vcc
	v_cvt_f32_f16_sdwa v140, v133 dst_sel:DWORD dst_unused:UNUSED_PAD src0_sel:WORD_1
	v_cvt_f32_f16_e32 v133, v133
	v_and_b32_e32 v132, 0xffffff80, v132
	v_sub_u32_e32 v132, v132, v15
	v_not_b32_e32 v141, v140
	v_or_b32_e32 v142, 0x80000000, v140
	v_cmp_gt_i32_e32 vcc, 0, v140
	v_add_u32_e32 v127, 0x7e, v127
	v_add_u32_e32 v132, 0x7f, v132
	v_cndmask_b32_e32 v140, v142, v141, vcc
	v_not_b32_e32 v141, v133
	v_or_b32_e32 v142, 0x80000000, v133
	v_cmp_gt_i32_e32 vcc, 0, v133
	v_and_b32_e32 v140, 0xffffff80, v140
	v_sub_u32_e32 v140, v140, v14
	v_cndmask_b32_e32 v133, v142, v141, vcc
	v_cvt_f32_f16_sdwa v141, v134 dst_sel:DWORD dst_unused:UNUSED_PAD src0_sel:WORD_1
	v_cvt_f32_f16_e32 v134, v134
	v_and_b32_e32 v133, 0xffffff80, v133
	v_sub_u32_e32 v133, v133, v14
	v_not_b32_e32 v142, v141
	v_or_b32_e32 v143, 0x80000000, v141
	v_cmp_gt_i32_e32 vcc, 0, v141
	v_add_u32_e32 v140, 0x7e, v140
	v_add_u32_e32 v133, 0x7f, v133
	v_cndmask_b32_e32 v141, v143, v142, vcc
	v_not_b32_e32 v142, v134
	v_or_b32_e32 v143, 0x80000000, v134
	v_cmp_gt_i32_e32 vcc, 0, v134
	v_and_b32_e32 v141, 0xffffff80, v141
	v_sub_u32_e32 v141, v141, v12
	v_cndmask_b32_e32 v134, v143, v142, vcc
	v_cvt_f32_f16_sdwa v142, v135 dst_sel:DWORD dst_unused:UNUSED_PAD src0_sel:WORD_1
	v_cvt_f32_f16_e32 v135, v135
	v_and_b32_e32 v134, 0xffffff80, v134
	v_sub_u32_e32 v134, v134, v12
	v_not_b32_e32 v143, v142
	v_or_b32_e32 v144, 0x80000000, v142
	v_cmp_gt_i32_e32 vcc, 0, v142
	v_add_u32_e32 v141, 0x7e, v141
	v_add_u32_e32 v134, 0x7f, v134
	v_cndmask_b32_e32 v142, v144, v143, vcc
	v_not_b32_e32 v143, v135
	v_or_b32_e32 v144, 0x80000000, v135
	v_cmp_gt_i32_e32 vcc, 0, v135
	v_and_b32_e32 v142, 0xffffff80, v142
	v_sub_u32_e32 v142, v142, v10
	v_cndmask_b32_e32 v135, v144, v143, vcc
	v_cvt_f32_f16_sdwa v143, v128 dst_sel:DWORD dst_unused:UNUSED_PAD src0_sel:WORD_1
	v_cvt_f32_f16_e32 v128, v128
	v_and_b32_e32 v135, 0xffffff80, v135
	v_sub_u32_e32 v135, v135, v10
	v_not_b32_e32 v144, v143
	v_or_b32_e32 v145, 0x80000000, v143
	v_cmp_gt_i32_e32 vcc, 0, v143
	v_add_u32_e32 v142, 0x7e, v142
	v_add_u32_e32 v135, 0x7f, v135
	v_cndmask_b32_e32 v143, v145, v144, vcc
	v_not_b32_e32 v144, v128
	v_or_b32_e32 v145, 0x80000000, v128
	v_cmp_gt_i32_e32 vcc, 0, v128
	v_and_b32_e32 v143, 0xffffff80, v143
	v_sub_u32_e32 v143, v143, v8
	v_cndmask_b32_e32 v128, v145, v144, vcc
	v_cvt_f32_f16_sdwa v144, v129 dst_sel:DWORD dst_unused:UNUSED_PAD src0_sel:WORD_1
	v_cvt_f32_f16_e32 v129, v129
	v_and_b32_e32 v128, 0xffffff80, v128
	v_sub_u32_e32 v128, v128, v8
	v_not_b32_e32 v145, v144
	v_or_b32_e32 v146, 0x80000000, v144
	v_cmp_gt_i32_e32 vcc, 0, v144
	v_add_u32_e32 v143, 0x7e, v143
	v_add_u32_e32 v128, 0x7f, v128
	v_cndmask_b32_e32 v144, v146, v145, vcc
	v_not_b32_e32 v145, v129
	v_or_b32_e32 v146, 0x80000000, v129
	v_cmp_gt_i32_e32 vcc, 0, v129
	v_and_b32_e32 v144, 0xffffff80, v144
	v_sub_u32_e32 v144, v144, v16
	v_cndmask_b32_e32 v129, v146, v145, vcc
	v_cvt_f32_f16_sdwa v145, v130 dst_sel:DWORD dst_unused:UNUSED_PAD src0_sel:WORD_1
	v_cvt_f32_f16_e32 v130, v130
	v_and_b32_e32 v129, 0xffffff80, v129
	v_sub_u32_e32 v129, v129, v16
	v_not_b32_e32 v146, v145
	v_or_b32_e32 v147, 0x80000000, v145
	v_cmp_gt_i32_e32 vcc, 0, v145
	v_add_u32_e32 v144, 0x7e, v144
	v_add_u32_e32 v129, 0x7f, v129
	v_cndmask_b32_e32 v145, v147, v146, vcc
	v_not_b32_e32 v146, v130
	v_or_b32_e32 v147, 0x80000000, v130
	v_cmp_gt_i32_e32 vcc, 0, v130
	v_and_b32_e32 v145, 0xffffff80, v145
	v_sub_u32_e32 v145, v145, v17
	v_cndmask_b32_e32 v130, v147, v146, vcc
	v_cvt_f32_f16_sdwa v146, v131 dst_sel:DWORD dst_unused:UNUSED_PAD src0_sel:WORD_1
	v_cvt_f32_f16_e32 v131, v131
	v_and_b32_e32 v130, 0xffffff80, v130
	v_sub_u32_e32 v130, v130, v17
	v_not_b32_e32 v147, v146
	v_or_b32_e32 v148, 0x80000000, v146
	v_cmp_gt_i32_e32 vcc, 0, v146
	v_add_u32_e32 v145, 0x7e, v145
	v_add_u32_e32 v130, 0x7f, v130
	v_cndmask_b32_e32 v146, v148, v147, vcc
	v_not_b32_e32 v147, v131
	v_or_b32_e32 v148, 0x80000000, v131
	v_cmp_gt_i32_e32 vcc, 0, v131
	v_and_b32_e32 v146, 0xffffff80, v146
	v_sub_u32_e32 v146, v146, v18
	v_cndmask_b32_e32 v131, v148, v147, vcc
	s_waitcnt vmcnt(0)
; __device__ __forceinline__ unsigned f2key(float f) { const unsigned u = __float_as_uint(f); return (u & 0x80000000u) ? ~u : (u | 0x80000000u); }
; __device__ __forceinline__ void sort16_desc(unsigned (&k)[16]) {
; #pragma unroll
;     for (int size = 2; size <= 16; size <<= 1)
; #pragma unroll
;         for (int stride = size >> 1; stride > 0; stride >>= 1)
; __device__ __forceinline__ void peer_tile(const Args& A, LAS unsigned char* lds, int tile) {
;     ...
;                   for (int i = 0; i < 16; ++i) {
;                       const float lo = (float)__builtin_bit_cast(_Float16, (unsigned short)(sw[i] & 0xffffu)), hi = (float)__builtin_bit_cast(_Float16, (unsigned short)(sw[i] >> 16));
;                       const unsigned klo = (f2key(lo) & ~127u) | (unsigned)(127 - (32 * g + 2 * i)), khi = (f2key(hi) & ~127u) | (unsigned)(127 - (32 * g + 2 * i + 1));
;                       if (i < 8) { k0[2 * i] = klo; k0[2 * i + 1] = khi; } else { k1[2 * (i - 8)] = klo; k1[2 * (i - 8) + 1] = khi; } } }
;                 sort16_desc(k0); sort16_desc(k1); merge16(k0, k1);
	v_cvt_f32_f16_sdwa v147, v136 dst_sel:DWORD dst_unused:UNUSED_PAD src0_sel:WORD_1
	v_cvt_f32_f16_e32 v136, v136
	v_and_b32_e32 v131, 0xffffff80, v131
	v_sub_u32_e32 v131, v131, v18
	v_not_b32_e32 v148, v147
	v_or_b32_e32 v149, 0x80000000, v147
	v_cmp_gt_i32_e32 vcc, 0, v147
	v_add_u32_e32 v146, 0x7e, v146
	v_add_u32_e32 v131, 0x7f, v131
	v_cndmask_b32_e32 v147, v149, v148, vcc
	v_not_b32_e32 v148, v136
	v_or_b32_e32 v149, 0x80000000, v136
	v_cmp_gt_i32_e32 vcc, 0, v136
	v_and_b32_e32 v147, 0xffffff80, v147
	v_sub_u32_e32 v147, v147, v20
	v_cndmask_b32_e32 v136, v149, v148, vcc
	v_cvt_f32_f16_sdwa v148, v137 dst_sel:DWORD dst_unused:UNUSED_PAD src0_sel:WORD_1
	v_cvt_f32_f16_e32 v137, v137
	v_and_b32_e32 v136, 0xffffff80, v136
	v_sub_u32_e32 v136, v136, v20
	v_not_b32_e32 v149, v148
	v_or_b32_e32 v150, 0x80000000, v148
	v_cmp_gt_i32_e32 vcc, 0, v148
	v_add_u32_e32 v147, 0x7e, v147
	v_add_u32_e32 v136, 0x7f, v136
	v_cndmask_b32_e32 v148, v150, v149, vcc
	v_not_b32_e32 v149, v137
	v_or_b32_e32 v150, 0x80000000, v137
	v_cmp_gt_i32_e32 vcc, 0, v137
	v_and_b32_e32 v148, 0xffffff80, v148
	v_sub_u32_e32 v148, v148, v21
	v_cndmask_b32_e32 v137, v150, v149, vcc
	v_cvt_f32_f16_sdwa v149, v138 dst_sel:DWORD dst_unused:UNUSED_PAD src0_sel:WORD_1
	v_cvt_f32_f16_e32 v138, v138
	v_and_b32_e32 v137, 0xffffff80, v137
	v_sub_u32_e32 v137, v137, v21
	v_not_b32_e32 v150, v149
	v_or_b32_e32 v151, 0x80000000, v149
	v_cmp_gt_i32_e32 vcc, 0, v149
	v_add_u32_e32 v148, 0x7e, v148
	v_add_u32_e32 v137, 0x7f, v137
	v_cndmask_b32_e32 v149, v151, v150, vcc
	v_not_b32_e32 v150, v138
	v_or_b32_e32 v151, 0x80000000, v138
	v_cmp_gt_i32_e32 vcc, 0, v138
	v_and_b32_e32 v149, 0xffffff80, v149
	v_sub_u32_e32 v149, v149, v22
	v_cndmask_b32_e32 v138, v151, v150, vcc
	v_cvt_f32_f16_sdwa v150, v139 dst_sel:DWORD dst_unused:UNUSED_PAD src0_sel:WORD_1
	v_cvt_f32_f16_e32 v139, v139
	v_and_b32_e32 v138, 0xffffff80, v138
	v_sub_u32_e32 v138, v138, v22
	v_not_b32_e32 v151, v150
	v_or_b32_e32 v152, 0x80000000, v150
	v_cmp_gt_i32_e32 vcc, 0, v150
	v_add_u32_e32 v149, 0x7e, v149
	v_add_u32_e32 v138, 0x7f, v138
	v_cndmask_b32_e32 v150, v152, v151, vcc
	v_not_b32_e32 v151, v139
	v_or_b32_e32 v152, 0x80000000, v139
	v_cmp_gt_i32_e32 vcc, 0, v139
	v_and_b32_e32 v150, 0xffffff80, v150
	v_sub_u32_e32 v150, v150, v23
	v_cndmask_b32_e32 v139, v152, v151, vcc
	v_cvt_f32_f16_sdwa v151, v0 dst_sel:DWORD dst_unused:UNUSED_PAD src0_sel:WORD_1
	v_cvt_f32_f16_e32 v0, v0
	v_and_b32_e32 v139, 0xffffff80, v139
	v_sub_u32_e32 v139, v139, v23
	v_not_b32_e32 v152, v151
	v_or_b32_e32 v153, 0x80000000, v151
	v_cmp_gt_i32_e32 vcc, 0, v151
	v_add_u32_e32 v150, 0x7e, v150
	v_add_u32_e32 v139, 0x7f, v139
	v_cndmask_b32_e32 v151, v153, v152, vcc
	v_not_b32_e32 v152, v0
	v_or_b32_e32 v153, 0x80000000, v0
	v_cmp_gt_i32_e32 vcc, 0, v0
	v_and_b32_e32 v151, 0xffffff80, v151
	v_sub_u32_e32 v151, v151, v24
	v_cndmask_b32_e32 v0, v153, v152, vcc
	v_cvt_f32_f16_sdwa v152, v1 dst_sel:DWORD dst_unused:UNUSED_PAD src0_sel:WORD_1
	v_cvt_f32_f16_e32 v1, v1
	v_and_b32_e32 v0, 0xffffff80, v0
	v_sub_u32_e32 v0, v0, v24
	v_not_b32_e32 v153, v152
	v_or_b32_e32 v154, 0x80000000, v152
	v_cmp_gt_i32_e32 vcc, 0, v152
	v_add_u32_e32 v151, 0x7e, v151
	v_add_u32_e32 v0, 0x7f, v0
	v_cndmask_b32_e32 v152, v154, v153, vcc
	v_not_b32_e32 v153, v1
	v_or_b32_e32 v154, 0x80000000, v1
	v_cmp_gt_i32_e32 vcc, 0, v1
	v_and_b32_e32 v152, 0xffffff80, v152
	v_sub_u32_e32 v152, v152, v25
	v_cndmask_b32_e32 v1, v154, v153, vcc
	v_cvt_f32_f16_sdwa v153, v2 dst_sel:DWORD dst_unused:UNUSED_PAD src0_sel:WORD_1
	v_cvt_f32_f16_e32 v2, v2
	v_and_b32_e32 v1, 0xffffff80, v1
	v_sub_u32_e32 v1, v1, v25
	v_not_b32_e32 v154, v153
	v_or_b32_e32 v155, 0x80000000, v153
	v_cmp_gt_i32_e32 vcc, 0, v153
	v_add_u32_e32 v152, 0x7e, v152
	v_add_u32_e32 v1, 0x7f, v1
	v_cndmask_b32_e32 v153, v155, v154, vcc
	v_not_b32_e32 v154, v2
	v_or_b32_e32 v155, 0x80000000, v2
	v_cmp_gt_i32_e32 vcc, 0, v2
	v_and_b32_e32 v153, 0xffffff80, v153
	v_sub_u32_e32 v153, v153, v26
	v_cndmask_b32_e32 v2, v155, v154, vcc
	v_cvt_f32_f16_sdwa v154, v3 dst_sel:DWORD dst_unused:UNUSED_PAD src0_sel:WORD_1
	v_cvt_f32_f16_e32 v3, v3
	v_and_b32_e32 v2, 0xffffff80, v2
	v_sub_u32_e32 v2, v2, v26
	v_not_b32_e32 v155, v154
	v_or_b32_e32 v156, 0x80000000, v154
	v_cmp_gt_i32_e32 vcc, 0, v154
	v_add_u32_e32 v153, 0x7e, v153
	v_add_u32_e32 v2, 0x7f, v2
	v_cndmask_b32_e32 v154, v156, v155, vcc
	v_not_b32_e32 v155, v3
	v_or_b32_e32 v156, 0x80000000, v3
	v_cmp_gt_i32_e32 vcc, 0, v3
	v_and_b32_e32 v154, 0xffffff80, v154
	v_sub_u32_e32 v154, v154, v28
	v_cndmask_b32_e32 v3, v156, v155, vcc
	v_and_b32_e32 v3, 0xffffff80, v3
	v_sub_u32_e32 v3, v3, v28
	v_add_u32_e32 v154, 0x7e, v154
	v_add_u32_e32 v3, 0x7f, v3
	v_max_u32_e32 v155, v132, v127
	v_min_u32_e32 v127, v132, v127
	v_max_u32_e32 v132, v140, v133
	v_min_u32_e32 v133, v140, v133
	v_max_u32_e32 v140, v134, v141
	v_min_u32_e32 v134, v134, v141
	v_max_u32_e32 v141, v142, v135
	v_min_u32_e32 v135, v142, v135
	v_max_u32_e32 v142, v128, v143
	v_min_u32_e32 v128, v128, v143
	v_max_u32_e32 v143, v144, v129
	v_min_u32_e32 v129, v144, v129
	v_max_u32_e32 v144, v130, v145
	v_min_u32_e32 v130, v130, v145
	v_max_u32_e32 v145, v146, v131
	v_min_u32_e32 v131, v146, v131
	v_max_u32_e32 v163, v136, v147
	v_min_u32_e32 v136, v136, v147
	v_max_u32_e32 v147, v148, v137
	v_min_u32_e32 v137, v148, v137
	v_max_u32_e32 v148, v138, v149
	v_min_u32_e32 v138, v138, v149
	v_max_u32_e32 v149, v150, v139
	v_min_u32_e32 v139, v150, v139
	v_max_u32_e32 v150, v0, v151
	v_min_u32_e32 v0, v0, v151
	v_max_u32_e32 v151, v152, v1
	v_min_u32_e32 v1, v152, v1
	v_max_u32_e32 v152, v2, v153
	v_min_u32_e32 v2, v2, v153
; #define CE_DESC(a, b) do { const unsigned _mx = (a) > (b) ? (a) : (b), _mn = (a) > (b) ? (b) : (a); (a) = _mx; (b) = _mn; } while (0)
; __device__ __forceinline__ void sort16_desc(unsigned (&k)[16]) {
; #pragma unroll
;     for (int size = 2; size <= 16; size <<= 1)
; #pragma unroll
;         for (int stride = size >> 1; stride > 0; stride >>= 1)
; #pragma unroll
;             for (int i = 0; i < 16; ++i) { const int j = i ^ stride;
;                 if (j > i) { if ((i & size) == 0) CE_DESC(k[i], k[j]); else CE_DESC(k[j], k[i]); } }
; }
	v_max_u32_e32 v153, v154, v3
	v_min_u32_e32 v3, v154, v3
	v_max_u32_e32 v146, v155, v133
	v_min_u32_e32 v133, v155, v133
	v_max_u32_e32 v155, v127, v132
	v_min_u32_e32 v127, v127, v132
	v_max_u32_e32 v132, v135, v140
	v_min_u32_e32 v135, v135, v140
	v_max_u32_e32 v140, v141, v134
	v_min_u32_e32 v134, v141, v134
	v_max_u32_e32 v141, v142, v129
	v_min_u32_e32 v129, v142, v129
	v_max_u32_e32 v142, v128, v143
	v_min_u32_e32 v128, v128, v143
	v_max_u32_e32 v143, v131, v144
	v_min_u32_e32 v131, v131, v144
	v_max_u32_e32 v144, v145, v130
	v_min_u32_e32 v130, v145, v130
	v_max_u32_e32 v154, v163, v137
	v_min_u32_e32 v137, v163, v137
	v_max_u32_e32 v163, v136, v147
	v_min_u32_e32 v136, v136, v147
	v_max_u32_e32 v147, v139, v148
	v_min_u32_e32 v139, v139, v148
	v_max_u32_e32 v148, v149, v138
	v_min_u32_e32 v138, v149, v138
	v_max_u32_e32 v149, v150, v1
	v_min_u32_e32 v1, v150, v1
	v_max_u32_e32 v150, v0, v151
	v_min_u32_e32 v0, v0, v151
	v_max_u32_e32 v151, v3, v152
	v_min_u32_e32 v3, v3, v152
	v_max_u32_e32 v152, v153, v2
	v_min_u32_e32 v2, v153, v2
	v_max_u32_e32 v145, v146, v155
	v_min_u32_e32 v146, v146, v155
	v_max_u32_e32 v155, v133, v127
	v_min_u32_e32 v127, v133, v127
	v_max_u32_e32 v133, v134, v135
	v_min_u32_e32 v134, v134, v135
	v_max_u32_e32 v135, v140, v132
	v_min_u32_e32 v132, v140, v132
	v_max_u32_e32 v140, v141, v142
	v_min_u32_e32 v141, v141, v142
	v_max_u32_e32 v142, v129, v128
	v_min_u32_e32 v128, v129, v128
	v_max_u32_e32 v129, v130, v131
	v_min_u32_e32 v130, v130, v131
	v_max_u32_e32 v131, v144, v143
	v_min_u32_e32 v143, v144, v143
	v_max_u32_e32 v153, v154, v163
	v_min_u32_e32 v154, v154, v163
	v_max_u32_e32 v163, v137, v136
	v_min_u32_e32 v136, v137, v136
	v_max_u32_e32 v137, v138, v139
	v_min_u32_e32 v138, v138, v139
	v_max_u32_e32 v139, v148, v147
	v_min_u32_e32 v147, v148, v147
	v_max_u32_e32 v148, v149, v150
	v_min_u32_e32 v149, v149, v150
	v_max_u32_e32 v150, v1, v0
	v_min_u32_e32 v0, v1, v0
	v_max_u32_e32 v1, v2, v3
	v_min_u32_e32 v2, v2, v3
	v_max_u32_e32 v3, v152, v151
	v_min_u32_e32 v151, v152, v151
	v_max_u32_e32 v144, v145, v134
	v_min_u32_e32 v134, v145, v134
	v_max_u32_e32 v145, v146, v133
	v_min_u32_e32 v133, v146, v133
	v_max_u32_e32 v146, v155, v132
	v_min_u32_e32 v132, v155, v132
	v_max_u32_e32 v155, v127, v135
	v_min_u32_e32 v127, v127, v135
	v_max_u32_e32 v135, v130, v140
	v_min_u32_e32 v130, v130, v140
	v_max_u32_e32 v140, v129, v141
	v_min_u32_e32 v129, v129, v141
	v_max_u32_e32 v141, v143, v142
	v_min_u32_e32 v142, v143, v142
	v_max_u32_e32 v143, v131, v128
	v_min_u32_e32 v128, v131, v128
	v_max_u32_e32 v152, v153, v138
	v_min_u32_e32 v138, v153, v138
	v_max_u32_e32 v153, v154, v137
	v_min_u32_e32 v137, v154, v137
	v_max_u32_e32 v154, v163, v147
	v_min_u32_e32 v147, v163, v147
	v_max_u32_e32 v163, v136, v139
	v_min_u32_e32 v136, v136, v139
	v_max_u32_e32 v139, v2, v148
	v_min_u32_e32 v2, v2, v148
	v_max_u32_e32 v148, v1, v149
	v_min_u32_e32 v1, v1, v149
	v_max_u32_e32 v149, v151, v150
	v_min_u32_e32 v150, v151, v150
	v_max_u32_e32 v151, v3, v0
	v_min_u32_e32 v0, v3, v0
	v_max_u32_e32 v131, v144, v146
	v_min_u32_e32 v144, v144, v146
	v_max_u32_e32 v146, v145, v155
	v_min_u32_e32 v145, v145, v155
	v_max_u32_e32 v155, v134, v132
	v_min_u32_e32 v132, v134, v132
	v_max_u32_e32 v134, v133, v127
	v_min_u32_e32 v127, v133, v127
	v_max_u32_e32 v133, v142, v130
	v_min_u32_e32 v130, v142, v130
	v_max_u32_e32 v142, v128, v129
	v_min_u32_e32 v128, v128, v129
	v_max_u32_e32 v129, v141, v135
	v_min_u32_e32 v135, v141, v135
	v_max_u32_e32 v141, v143, v140
	v_min_u32_e32 v140, v143, v140
	v_max_u32_e32 v3, v152, v154
	v_min_u32_e32 v152, v152, v154
	v_max_u32_e32 v154, v153, v163
	v_min_u32_e32 v153, v153, v163
	v_max_u32_e32 v163, v138, v147
	v_min_u32_e32 v138, v138, v147
	v_max_u32_e32 v147, v137, v136
	v_min_u32_e32 v136, v137, v136
	v_max_u32_e32 v137, v150, v2
	v_min_u32_e32 v2, v150, v2
	v_max_u32_e32 v150, v0, v1
	v_min_u32_e32 v0, v0, v1
	v_max_u32_e32 v1, v149, v139
	v_min_u32_e32 v139, v149, v139
	v_max_u32_e32 v149, v151, v148
	v_min_u32_e32 v148, v151, v148
	v_max_u32_e32 v143, v131, v146
	v_min_u32_e32 v131, v131, v146
	v_max_u32_e32 v146, v144, v145
	v_min_u32_e32 v144, v144, v145
	v_max_u32_e32 v145, v155, v134
	v_min_u32_e32 v134, v155, v134
	v_max_u32_e32 v155, v132, v127
	v_min_u32_e32 v127, v132, v127
	v_max_u32_e32 v132, v128, v130
	v_min_u32_e32 v128, v128, v130
	v_max_u32_e32 v130, v142, v133
	v_min_u32_e32 v133, v142, v133
	v_max_u32_e32 v142, v140, v135
	v_min_u32_e32 v135, v140, v135
	v_max_u32_e32 v140, v141, v129
	v_min_u32_e32 v129, v141, v129
	v_max_u32_e32 v151, v3, v154
	v_min_u32_e32 v3, v3, v154
	v_max_u32_e32 v154, v152, v153
	v_min_u32_e32 v152, v152, v153
	v_max_u32_e32 v153, v163, v147
	v_min_u32_e32 v147, v163, v147
	v_max_u32_e32 v163, v138, v136
	v_min_u32_e32 v136, v138, v136
	v_max_u32_e32 v138, v0, v2
	v_min_u32_e32 v0, v0, v2
	v_max_u32_e32 v2, v150, v137
	v_min_u32_e32 v137, v150, v137
	v_max_u32_e32 v150, v148, v139
	v_min_u32_e32 v139, v148, v139
	v_max_u32_e32 v148, v149, v1
	v_min_u32_e32 v1, v149, v1
	v_max_u32_e32 v141, v143, v128
	v_min_u32_e32 v128, v143, v128
	v_max_u32_e32 v143, v131, v132
	v_min_u32_e32 v131, v131, v132
	v_max_u32_e32 v132, v146, v133
	v_min_u32_e32 v133, v146, v133
	v_max_u32_e32 v146, v144, v130
	v_min_u32_e32 v130, v144, v130
	v_max_u32_e32 v144, v145, v135
	v_min_u32_e32 v135, v145, v135
	v_max_u32_e32 v145, v134, v142
	v_min_u32_e32 v134, v134, v142
	v_max_u32_e32 v142, v155, v129
	v_min_u32_e32 v129, v155, v129
	v_max_u32_e32 v155, v127, v140
	v_min_u32_e32 v127, v127, v140
	v_max_u32_e32 v149, v151, v0
	v_min_u32_e32 v0, v151, v0
; #define CE_DESC(a, b) do { const unsigned _mx = (a) > (b) ? (a) : (b), _mn = (a) > (b) ? (b) : (a); (a) = _mx; (b) = _mn; } while (0)
; __device__ __forceinline__ void sort16_desc(unsigned (&k)[16]) {
; #pragma unroll
;     for (int size = 2; size <= 16; size <<= 1)
; #pragma unroll
;         for (int stride = size >> 1; stride > 0; stride >>= 1)
; #pragma unroll
;             for (int i = 0; i < 16; ++i) { const int j = i ^ stride;
;                 if (j > i) { if ((i & size) == 0) CE_DESC(k[i], k[j]); else CE_DESC(k[j], k[i]); } }
; }
; __device__ __forceinline__ void merge16(unsigned (&a)[16], const unsigned (&b)[16]) {
; #pragma unroll
;     for (int i = 0; i < 16; ++i) a[i] = a[i] > b[15 - i] ? a[i] : b[15 - i];
; #pragma unroll
;     for (int stride = 8; stride > 0; stride >>= 1)
; #pragma unroll
;         for (int i = 0; i < 16; ++i) { const int j = i ^ stride; if (j > i) CE_DESC(a[i], a[j]); }
; }
; __device__ __forceinline__ void peer_tile(const Args& A, LAS unsigned char* lds, int tile) {
;     ...
;                 for (int msk = 16; msk <= 32; msk <<= 1) {
; #pragma unroll
;                     for (int i = 0; i < 16; ++i) k1[i] = (unsigned)__shfl_xor((int)k0[i], msk);
;                     merge16(k0, k1); }
	v_max_u32_e32 v151, v3, v138
	v_min_u32_e32 v3, v3, v138
	v_max_u32_e32 v138, v154, v137
	v_min_u32_e32 v137, v154, v137
	v_max_u32_e32 v154, v152, v2
	v_min_u32_e32 v2, v152, v2
	v_max_u32_e32 v152, v153, v139
	v_min_u32_e32 v139, v153, v139
	v_max_u32_e32 v153, v147, v150
	v_min_u32_e32 v147, v147, v150
	v_max_u32_e32 v150, v163, v1
	v_min_u32_e32 v1, v163, v1
	v_max_u32_e32 v163, v136, v148
	v_min_u32_e32 v136, v136, v148
	v_max_u32_e32 v140, v141, v144
	v_min_u32_e32 v141, v141, v144
	v_max_u32_e32 v144, v143, v145
	v_min_u32_e32 v143, v143, v145
	v_max_u32_e32 v145, v132, v142
	v_min_u32_e32 v132, v132, v142
	v_max_u32_e32 v142, v146, v155
	v_min_u32_e32 v146, v146, v155
	v_max_u32_e32 v155, v128, v135
	v_min_u32_e32 v128, v128, v135
	v_max_u32_e32 v135, v131, v134
	v_min_u32_e32 v131, v131, v134
	v_max_u32_e32 v134, v133, v129
	v_min_u32_e32 v129, v133, v129
	v_max_u32_e32 v133, v130, v127
	v_min_u32_e32 v127, v130, v127
	v_max_u32_e32 v148, v149, v152
	v_min_u32_e32 v149, v149, v152
	v_max_u32_e32 v152, v151, v153
	v_min_u32_e32 v151, v151, v153
	v_max_u32_e32 v153, v138, v150
	v_min_u32_e32 v138, v138, v150
	v_max_u32_e32 v150, v154, v163
	v_min_u32_e32 v154, v154, v163
	v_max_u32_e32 v163, v0, v139
	v_min_u32_e32 v0, v0, v139
	v_max_u32_e32 v139, v3, v147
	v_min_u32_e32 v3, v3, v147
	v_max_u32_e32 v147, v137, v1
	v_min_u32_e32 v1, v137, v1
	v_max_u32_e32 v137, v2, v136
	v_min_u32_e32 v2, v2, v136
	v_max_u32_e32 v130, v140, v145
	v_min_u32_e32 v140, v140, v145
	v_max_u32_e32 v145, v144, v142
	v_min_u32_e32 v142, v144, v142
	v_max_u32_e32 v144, v141, v132
	v_min_u32_e32 v132, v141, v132
	v_max_u32_e32 v141, v143, v146
	v_min_u32_e32 v143, v143, v146
	v_max_u32_e32 v146, v155, v134
	v_min_u32_e32 v134, v155, v134
	v_max_u32_e32 v155, v135, v133
	v_min_u32_e32 v133, v135, v133
	v_max_u32_e32 v135, v128, v129
	v_min_u32_e32 v128, v128, v129
	v_max_u32_e32 v129, v131, v127
	v_min_u32_e32 v127, v131, v127
	v_max_u32_e32 v136, v148, v153
	v_min_u32_e32 v148, v148, v153
	v_max_u32_e32 v153, v152, v150
	v_min_u32_e32 v150, v152, v150
	v_max_u32_e32 v152, v149, v138
	v_min_u32_e32 v138, v149, v138
	v_max_u32_e32 v149, v151, v154
	v_min_u32_e32 v151, v151, v154
	v_max_u32_e32 v154, v163, v147
	v_min_u32_e32 v147, v163, v147
	v_max_u32_e32 v163, v139, v137
	v_min_u32_e32 v137, v139, v137
	v_max_u32_e32 v139, v0, v1
	v_min_u32_e32 v0, v0, v1
	v_max_u32_e32 v1, v3, v2
	v_min_u32_e32 v2, v3, v2
	v_min_u32_e32 v131, v130, v145
	v_min_u32_e32 v156, v140, v142
	v_min_u32_e32 v157, v144, v141
	v_min_u32_e32 v158, v132, v143
	v_min_u32_e32 v159, v146, v155
	v_min_u32_e32 v160, v134, v133
	v_min_u32_e32 v161, v135, v129
	v_min_u32_e32 v162, v128, v127
	v_min_u32_e32 v3, v136, v153
	v_min_u32_e32 v164, v148, v150
	v_min_u32_e32 v165, v152, v149
	v_min_u32_e32 v166, v138, v151
	v_min_u32_e32 v167, v154, v163
	v_min_u32_e32 v168, v147, v137
	v_min_u32_e32 v169, v139, v1
	v_min_u32_e32 v170, v0, v2
	v_max3_u32 v130, v130, v145, v170
	v_max3_u32 v0, v131, v0, v2
	v_max3_u32 v2, v140, v142, v169
	v_max3_u32 v1, v156, v139, v1
	v_max3_u32 v131, v144, v141, v168
	v_max3_u32 v137, v157, v147, v137
	v_max3_u32 v132, v132, v143, v167
	v_max3_u32 v139, v158, v154, v163
	v_max3_u32 v140, v146, v155, v166
	v_max3_u32 v138, v159, v138, v151
	v_max3_u32 v133, v134, v133, v165
	v_max3_u32 v134, v160, v152, v149
	v_max3_u32 v129, v135, v129, v164
	v_max3_u32 v135, v161, v148, v150
	v_max3_u32 v3, v128, v127, v3
	v_max3_u32 v127, v162, v136, v153
	v_max_u32_e32 v128, v130, v140
	v_min_u32_e32 v130, v130, v140
	v_max_u32_e32 v136, v0, v138
	v_min_u32_e32 v0, v0, v138
	v_max_u32_e32 v138, v2, v133
	v_min_u32_e32 v2, v2, v133
	v_max_u32_e32 v133, v1, v134
	v_min_u32_e32 v1, v1, v134
	v_max_u32_e32 v134, v131, v129
	v_min_u32_e32 v129, v131, v129
	v_max_u32_e32 v131, v137, v135
	v_min_u32_e32 v135, v137, v135
	v_max_u32_e32 v137, v132, v3
	v_min_u32_e32 v3, v132, v3
	v_max_u32_e32 v132, v139, v127
	v_min_u32_e32 v127, v139, v127
	v_max_u32_e32 v139, v128, v134
	v_min_u32_e32 v128, v128, v134
	v_max_u32_e32 v134, v136, v131
	v_min_u32_e32 v131, v136, v131
	v_max_u32_e32 v136, v138, v137
	v_min_u32_e32 v137, v138, v137
	v_max_u32_e32 v138, v133, v132
	v_min_u32_e32 v132, v133, v132
	v_max_u32_e32 v133, v130, v129
	v_min_u32_e32 v129, v130, v129
	v_max_u32_e32 v130, v0, v135
	v_min_u32_e32 v0, v0, v135
	v_max_u32_e32 v135, v2, v3
	v_min_u32_e32 v2, v2, v3
	v_max_u32_e32 v3, v1, v127
	v_min_u32_e32 v1, v1, v127
	v_max_u32_e32 v127, v139, v136
	v_min_u32_e32 v136, v139, v136
	v_max_u32_e32 v139, v134, v138
	v_min_u32_e32 v134, v134, v138
	v_max_u32_e32 v138, v128, v137
	v_min_u32_e32 v128, v128, v137
	v_max_u32_e32 v137, v131, v132
	v_min_u32_e32 v131, v131, v132
	v_max_u32_e32 v132, v133, v135
	v_min_u32_e32 v133, v133, v135
	v_max_u32_e32 v135, v130, v3
	v_min_u32_e32 v3, v130, v3
	v_max_u32_e32 v130, v129, v2
	v_min_u32_e32 v2, v129, v2
	v_max_u32_e32 v129, v0, v1
	v_min_u32_e32 v0, v0, v1
	v_max_u32_e32 v1, v127, v139
	v_min_u32_e32 v127, v127, v139
	v_max_u32_e32 v139, v136, v134
	v_min_u32_e32 v134, v136, v134
	v_max_u32_e32 v136, v138, v137
	v_min_u32_e32 v137, v138, v137
	v_max_u32_e32 v138, v128, v131
	v_min_u32_e32 v128, v128, v131
	v_max_u32_e32 v131, v132, v135
	v_min_u32_e32 v132, v132, v135
	v_max_u32_e32 v135, v133, v3
	v_min_u32_e32 v3, v133, v3
	v_max_u32_e32 v133, v130, v129
	v_min_u32_e32 v129, v130, v129
	v_max_u32_e32 v130, v2, v0
	v_min_u32_e32 v0, v2, v0
	ds_bpermute_b32 v2, v27, v1
	ds_bpermute_b32 v140, v27, v127
	ds_bpermute_b32 v141, v27, v139
	ds_bpermute_b32 v142, v27, v134
	ds_bpermute_b32 v143, v27, v136
	ds_bpermute_b32 v144, v27, v137
	ds_bpermute_b32 v145, v27, v138
	ds_bpermute_b32 v146, v27, v128
	ds_bpermute_b32 v147, v27, v131
	ds_bpermute_b32 v148, v27, v132
	ds_bpermute_b32 v149, v27, v135
	ds_bpermute_b32 v150, v27, v0
	ds_bpermute_b32 v151, v27, v130
	ds_bpermute_b32 v152, v27, v129
	ds_bpermute_b32 v153, v27, v133
	ds_bpermute_b32 v154, v27, v3
	s_waitcnt lgkmcnt(4)
; __device__ __forceinline__ void peer_tile(const Args& A, LAS unsigned char* lds, int tile) {
;     ...
;                 { const bf16_t* sp = QRY + m * 2048 + hp * 128 + 32 * g;
;                   const u32x4 s0 = *(const u32x4*)sp, s1 = *(const u32x4*)(sp + 8), s2 = *(const u32x4*)(sp + 16), s3 = *(const u32x4*)(sp + 24);
;     ...
;                 for (int msk = 16; msk <= 32; msk <<= 1) {
; #pragma unroll
;                     for (int i = 0; i < 16; ++i) k1[i] = (unsigned)__shfl_xor((int)k0[i], msk);
;                     merge16(k0, k1); }
	v_max_u32_e32 v1, v1, v150
	s_waitcnt lgkmcnt(3)
	v_max_u32_e32 v127, v127, v151
	s_waitcnt lgkmcnt(2)
	v_max_u32_e32 v139, v139, v152
	s_waitcnt lgkmcnt(1)
	v_max_u32_e32 v134, v134, v153
	s_waitcnt lgkmcnt(0)
	v_max_u32_e32 v136, v136, v154
	v_max_u32_e32 v137, v137, v149
	v_max_u32_e32 v138, v138, v148
	v_max_u32_e32 v128, v128, v147
	v_max_u32_e32 v131, v131, v146
	v_max_u32_e32 v132, v132, v145
	v_max_u32_e32 v135, v135, v144
	v_max_u32_e32 v3, v3, v143
	v_max_u32_e32 v133, v133, v142
	v_max_u32_e32 v129, v129, v141
	v_max_u32_e32 v130, v130, v140
	v_max_u32_e32 v0, v0, v2
	v_max_u32_e32 v2, v1, v131
	v_min_u32_e32 v1, v1, v131
	v_max_u32_e32 v131, v127, v132
	v_min_u32_e32 v127, v127, v132
	v_max_u32_e32 v132, v139, v135
	v_min_u32_e32 v135, v139, v135
	v_max_u32_e32 v139, v134, v3
	v_min_u32_e32 v3, v134, v3
	v_max_u32_e32 v134, v136, v133
	v_min_u32_e32 v133, v136, v133
	v_max_u32_e32 v136, v137, v129
	v_min_u32_e32 v129, v137, v129
	v_max_u32_e32 v137, v138, v130
	v_min_u32_e32 v130, v138, v130
	v_max_u32_e32 v138, v128, v0
	v_min_u32_e32 v0, v128, v0
	v_max_u32_e32 v128, v2, v134
	v_min_u32_e32 v2, v2, v134
	v_max_u32_e32 v134, v131, v136
	v_min_u32_e32 v131, v131, v136
	v_max_u32_e32 v136, v132, v137
	v_min_u32_e32 v132, v132, v137
	v_max_u32_e32 v137, v139, v138
	v_min_u32_e32 v138, v139, v138
	v_max_u32_e32 v139, v1, v133
	v_min_u32_e32 v1, v1, v133
	v_max_u32_e32 v133, v127, v129
	v_min_u32_e32 v127, v127, v129
	v_max_u32_e32 v129, v135, v130
	v_min_u32_e32 v130, v135, v130
	v_max_u32_e32 v135, v3, v0
	v_min_u32_e32 v0, v3, v0
	v_max_u32_e32 v3, v128, v136
	v_min_u32_e32 v128, v128, v136
	v_max_u32_e32 v136, v134, v137
	v_min_u32_e32 v134, v134, v137
	v_max_u32_e32 v137, v2, v132
	v_min_u32_e32 v2, v2, v132
	v_max_u32_e32 v132, v131, v138
	v_min_u32_e32 v131, v131, v138
	v_max_u32_e32 v138, v139, v129
	v_min_u32_e32 v129, v139, v129
	v_max_u32_e32 v139, v133, v135
	v_min_u32_e32 v133, v133, v135
	v_max_u32_e32 v135, v1, v130
	v_min_u32_e32 v1, v1, v130
	v_max_u32_e32 v130, v127, v0
	v_min_u32_e32 v0, v127, v0
	v_max_u32_e32 v127, v3, v136
	v_min_u32_e32 v3, v3, v136
	v_max_u32_e32 v136, v128, v134
	v_min_u32_e32 v128, v128, v134
	v_max_u32_e32 v134, v137, v132
	v_min_u32_e32 v132, v137, v132
	v_max_u32_e32 v137, v2, v131
	v_min_u32_e32 v2, v2, v131
	v_max_u32_e32 v131, v138, v139
	v_min_u32_e32 v138, v138, v139
	v_max_u32_e32 v139, v129, v133
	v_min_u32_e32 v129, v129, v133
	v_max_u32_e32 v133, v135, v130
	v_min_u32_e32 v130, v135, v130
	v_max_u32_e32 v135, v1, v0
	v_min_u32_e32 v0, v1, v0
	ds_bpermute_b32 v144, v29, v0
	ds_bpermute_b32 v1, v29, v127
	ds_bpermute_b32 v140, v29, v3
	ds_bpermute_b32 v141, v29, v136
	ds_bpermute_b32 v142, v29, v128
	s_waitcnt lgkmcnt(4)
	v_max_u32_e32 v127, v127, v144
	global_load_dwordx4 v[144:147], v[4:5], off offset:1808
	global_load_dwordx4 v[148:151], v[4:5], off offset:1792
	ds_bpermute_b32 v143, v29, v134
	ds_bpermute_b32 v152, v29, v132
	ds_bpermute_b32 v153, v29, v137
	ds_bpermute_b32 v154, v29, v2
	ds_bpermute_b32 v155, v29, v131
	ds_bpermute_b32 v156, v29, v138
	ds_bpermute_b32 v157, v29, v139
	ds_bpermute_b32 v158, v29, v129
	ds_bpermute_b32 v159, v29, v133
	ds_bpermute_b32 v160, v29, v135
	ds_bpermute_b32 v161, v29, v130
	s_waitcnt lgkmcnt(4)
	v_max_u32_e32 v132, v132, v157
	s_waitcnt lgkmcnt(3)
	v_max_u32_e32 v134, v134, v158
	s_waitcnt lgkmcnt(2)
	v_max_u32_e32 v128, v128, v159
	s_waitcnt lgkmcnt(1)
	v_max_u32_e32 v3, v3, v160
	s_waitcnt lgkmcnt(0)
	v_max_u32_e32 v136, v136, v161
	v_max_u32_e32 v137, v137, v156
	v_max_u32_e32 v2, v2, v155
	v_max_u32_e32 v131, v131, v154
	v_max_u32_e32 v138, v138, v153
	v_max_u32_e32 v139, v139, v152
	v_max_u32_e32 v129, v129, v143
	v_max_u32_e32 v133, v133, v142
	v_max_u32_e32 v130, v130, v141
	v_max_u32_e32 v135, v135, v140
	v_max_u32_e32 v0, v0, v1
	v_max_u32_e32 v1, v127, v131
	v_min_u32_e32 v127, v127, v131
	v_max_u32_e32 v131, v3, v138
	v_min_u32_e32 v3, v3, v138
	v_max_u32_e32 v138, v136, v139
	v_min_u32_e32 v136, v136, v139
	v_max_u32_e32 v139, v128, v129
	v_min_u32_e32 v128, v128, v129
	v_max_u32_e32 v129, v134, v133
	v_min_u32_e32 v133, v134, v133
	v_max_u32_e32 v134, v132, v130
	v_min_u32_e32 v130, v132, v130
	v_max_u32_e32 v132, v137, v135
	v_min_u32_e32 v135, v137, v135
	v_max_u32_e32 v137, v2, v0
	v_min_u32_e32 v0, v2, v0
	v_max_u32_e32 v2, v1, v129
	v_min_u32_e32 v1, v1, v129
	v_max_u32_e32 v129, v131, v134
	v_min_u32_e32 v131, v131, v134
	v_max_u32_e32 v134, v138, v132
	v_min_u32_e32 v132, v138, v132
	v_max_u32_e32 v138, v139, v137
	v_min_u32_e32 v137, v139, v137
	v_max_u32_e32 v139, v127, v133
	v_min_u32_e32 v127, v127, v133
	v_max_u32_e32 v133, v3, v130
	v_min_u32_e32 v3, v3, v130
	v_max_u32_e32 v130, v136, v135
	v_min_u32_e32 v135, v136, v135
	v_max_u32_e32 v136, v128, v0
	v_min_u32_e32 v0, v128, v0
	v_max_u32_e32 v128, v2, v134
	v_min_u32_e32 v2, v2, v134
	v_max_u32_e32 v134, v129, v138
	v_min_u32_e32 v129, v129, v138
	v_max_u32_e32 v143, v1, v132
	v_min_u32_e32 v1, v1, v132
	v_max_u32_e32 v132, v131, v137
	v_min_u32_e32 v131, v131, v137
	v_max_u32_e32 v152, v139, v130
	v_min_u32_e32 v130, v139, v130
	v_max_u32_e32 v153, v133, v136
	v_min_u32_e32 v154, v133, v136
	v_max_u32_e32 v155, v127, v135
	v_min_u32_e32 v127, v127, v135
	v_max_u32_e32 v156, v3, v0
	v_min_u32_e32 v0, v3, v0
	v_max_u32_e32 v142, v128, v134
	v_min_u32_e32 v141, v128, v134
	v_max_u32_e32 v140, v2, v129
	v_min_u32_e32 v139, v2, v129
	v_max_u32_e32 v138, v143, v132
	v_min_u32_e32 v137, v143, v132
	v_max_u32_e32 v136, v1, v131
	v_min_u32_e32 v135, v1, v131
	v_max_u32_e32 v134, v152, v153
	v_min_u32_e32 v133, v152, v153
	v_max_u32_e32 v132, v130, v154
	v_min_u32_e32 v131, v130, v154
	v_max_u32_e32 v130, v155, v156
	v_min_u32_e32 v129, v155, v156
	v_max_u32_e32 v128, v127, v0
	v_min_u32_e32 v127, v127, v0
	global_load_dwordx4 v[0:3], v[4:5], off offset:1840
	global_load_dwordx4 v[152:155], v[4:5], off offset:1824
	s_waitcnt vmcnt(2)
; __device__ __forceinline__ unsigned f2key(float f) { const unsigned u = __float_as_uint(f); return (u & 0x80000000u) ? ~u : (u | 0x80000000u); }
; __device__ __forceinline__ void peer_tile(const Args& A, LAS unsigned char* lds, int tile) {
;     ...
;                   for (int i = 0; i < 16; ++i) {
;                       const float lo = (float)__builtin_bit_cast(_Float16, (unsigned short)(sw[i] & 0xffffu)), hi = (float)__builtin_bit_cast(_Float16, (unsigned short)(sw[i] >> 16));
;                       const unsigned klo = (f2key(lo) & ~127u) | (unsigned)(127 - (32 * g + 2 * i)), khi = (f2key(hi) & ~127u) | (unsigned)(127 - (32 * g + 2 * i + 1));
;                       if (i < 8) { k0[2 * i] = klo; k0[2 * i + 1] = khi; } else { k1[2 * (i - 8)] = klo; k1[2 * (i - 8) + 1] = khi; } } }
	v_cvt_f32_f16_sdwa v143, v148 dst_sel:DWORD dst_unused:UNUSED_PAD src0_sel:WORD_1
	v_cvt_f32_f16_e32 v4, v148
	v_not_b32_e32 v5, v143
	v_or_b32_e32 v148, 0x80000000, v143
	v_cmp_gt_i32_e32 vcc, 0, v143
	v_not_b32_e32 v143, v4
	s_nop 0
	v_cndmask_b32_e32 v5, v148, v5, vcc
	v_or_b32_e32 v148, 0x80000000, v4
	v_cmp_gt_i32_e32 vcc, 0, v4
	v_and_b32_e32 v5, 0xffffff80, v5
	v_sub_u32_e32 v5, v5, v15
	v_cndmask_b32_e32 v4, v148, v143, vcc
	v_and_b32_e32 v4, 0xffffff80, v4
	v_cvt_f32_f16_sdwa v143, v149 dst_sel:DWORD dst_unused:UNUSED_PAD src0_sel:WORD_1
	v_sub_u32_e32 v4, v4, v15
	v_cvt_f32_f16_e32 v15, v149
	v_add_u32_e32 v5, 0x7e, v5
	v_not_b32_e32 v148, v143
	v_or_b32_e32 v149, 0x80000000, v143
	v_cmp_gt_i32_e32 vcc, 0, v143
	v_add_u32_e32 v4, 0x7f, v4
	s_nop 0
	v_cndmask_b32_e32 v143, v149, v148, vcc
	v_not_b32_e32 v148, v15
	v_or_b32_e32 v149, 0x80000000, v15
	v_cmp_gt_i32_e32 vcc, 0, v15
	v_and_b32_e32 v143, 0xffffff80, v143
	v_sub_u32_e32 v143, v143, v14
	v_cndmask_b32_e32 v15, v149, v148, vcc
	v_and_b32_e32 v15, 0xffffff80, v15
	v_cvt_f32_f16_sdwa v148, v150 dst_sel:DWORD dst_unused:UNUSED_PAD src0_sel:WORD_1
	v_sub_u32_e32 v14, v15, v14
	v_cvt_f32_f16_e32 v15, v150
	v_add_u32_e32 v143, 0x7e, v143
	v_not_b32_e32 v149, v148
	v_or_b32_e32 v150, 0x80000000, v148
	v_cmp_gt_i32_e32 vcc, 0, v148
	v_add_u32_e32 v14, 0x7f, v14
	s_nop 0
	v_cndmask_b32_e32 v148, v150, v149, vcc
	v_not_b32_e32 v149, v15
	v_or_b32_e32 v150, 0x80000000, v15
	v_cmp_gt_i32_e32 vcc, 0, v15
	v_and_b32_e32 v148, 0xffffff80, v148
	v_sub_u32_e32 v148, v148, v12
	v_cndmask_b32_e32 v15, v150, v149, vcc
	v_and_b32_e32 v15, 0xffffff80, v15
	v_cvt_f32_f16_sdwa v149, v151 dst_sel:DWORD dst_unused:UNUSED_PAD src0_sel:WORD_1
	v_sub_u32_e32 v12, v15, v12
	v_cvt_f32_f16_e32 v15, v151
	v_add_u32_e32 v148, 0x7e, v148
	v_not_b32_e32 v150, v149
	v_or_b32_e32 v151, 0x80000000, v149
	v_cmp_gt_i32_e32 vcc, 0, v149
	v_add_u32_e32 v12, 0x7f, v12
	s_nop 0
	v_cndmask_b32_e32 v149, v151, v150, vcc
	v_not_b32_e32 v150, v15
	v_or_b32_e32 v151, 0x80000000, v15
	v_cmp_gt_i32_e32 vcc, 0, v15
	v_and_b32_e32 v149, 0xffffff80, v149
	v_sub_u32_e32 v149, v149, v10
	v_cndmask_b32_e32 v15, v151, v150, vcc
	v_and_b32_e32 v15, 0xffffff80, v15
	v_cvt_f32_f16_sdwa v150, v144 dst_sel:DWORD dst_unused:UNUSED_PAD src0_sel:WORD_1
	v_sub_u32_e32 v10, v15, v10
	v_cvt_f32_f16_e32 v15, v144
	v_add_u32_e32 v149, 0x7e, v149
	v_not_b32_e32 v144, v150
	v_or_b32_e32 v151, 0x80000000, v150
	v_cmp_gt_i32_e32 vcc, 0, v150
	v_not_b32_e32 v150, v15
	v_add_u32_e32 v10, 0x7f, v10
	v_cndmask_b32_e32 v144, v151, v144, vcc
	v_or_b32_e32 v151, 0x80000000, v15
	v_cmp_gt_i32_e32 vcc, 0, v15
	v_and_b32_e32 v144, 0xffffff80, v144
	v_sub_u32_e32 v144, v144, v8
	v_cndmask_b32_e32 v15, v151, v150, vcc
	v_and_b32_e32 v15, 0xffffff80, v15
	v_cvt_f32_f16_sdwa v150, v145 dst_sel:DWORD dst_unused:UNUSED_PAD src0_sel:WORD_1
	v_sub_u32_e32 v8, v15, v8
	v_cvt_f32_f16_e32 v15, v145
	v_add_u32_e32 v144, 0x7e, v144
	v_not_b32_e32 v145, v150
	v_or_b32_e32 v151, 0x80000000, v150
	v_cmp_gt_i32_e32 vcc, 0, v150
	v_not_b32_e32 v150, v15
	v_add_u32_e32 v8, 0x7f, v8
	v_cndmask_b32_e32 v145, v151, v145, vcc
	v_or_b32_e32 v151, 0x80000000, v15
	v_cmp_gt_i32_e32 vcc, 0, v15
	v_and_b32_e32 v145, 0xffffff80, v145
	v_sub_u32_e32 v145, v145, v16
	v_cndmask_b32_e32 v15, v151, v150, vcc
	v_and_b32_e32 v15, 0xffffff80, v15
	v_cvt_f32_f16_sdwa v150, v146 dst_sel:DWORD dst_unused:UNUSED_PAD src0_sel:WORD_1
	v_sub_u32_e32 v15, v15, v16
	v_cvt_f32_f16_e32 v16, v146
	v_add_u32_e32 v145, 0x7e, v145
	v_not_b32_e32 v146, v150
	v_or_b32_e32 v151, 0x80000000, v150
	v_cmp_gt_i32_e32 vcc, 0, v150
	v_not_b32_e32 v150, v16
	v_add_u32_e32 v15, 0x7f, v15
	v_cndmask_b32_e32 v146, v151, v146, vcc
	v_or_b32_e32 v151, 0x80000000, v16
	v_cmp_gt_i32_e32 vcc, 0, v16
	v_and_b32_e32 v146, 0xffffff80, v146
	v_sub_u32_e32 v146, v146, v17
	v_cndmask_b32_e32 v16, v151, v150, vcc
	v_and_b32_e32 v16, 0xffffff80, v16
	v_cvt_f32_f16_sdwa v150, v147 dst_sel:DWORD dst_unused:UNUSED_PAD src0_sel:WORD_1
	v_sub_u32_e32 v16, v16, v17
	v_cvt_f32_f16_e32 v17, v147
	v_add_u32_e32 v146, 0x7e, v146
	v_not_b32_e32 v147, v150
	v_or_b32_e32 v151, 0x80000000, v150
	v_cmp_gt_i32_e32 vcc, 0, v150
	v_not_b32_e32 v150, v17
	v_add_u32_e32 v16, 0x7f, v16
	v_cndmask_b32_e32 v147, v151, v147, vcc
	v_or_b32_e32 v151, 0x80000000, v17
	v_cmp_gt_i32_e32 vcc, 0, v17
	v_and_b32_e32 v147, 0xffffff80, v147
	v_sub_u32_e32 v147, v147, v18
	v_cndmask_b32_e32 v17, v151, v150, vcc
	v_and_b32_e32 v17, 0xffffff80, v17
	s_waitcnt vmcnt(0)
; __device__ __forceinline__ unsigned f2key(float f) { const unsigned u = __float_as_uint(f); return (u & 0x80000000u) ? ~u : (u | 0x80000000u); }
; __device__ __forceinline__ void sort16_desc(unsigned (&k)[16]) {
; #pragma unroll
;     for (int size = 2; size <= 16; size <<= 1)
; #pragma unroll
;         for (int stride = size >> 1; stride > 0; stride >>= 1)
; __device__ __forceinline__ void peer_tile(const Args& A, LAS unsigned char* lds, int tile) {
;     ...
;                   for (int i = 0; i < 16; ++i) {
;                       const float lo = (float)__builtin_bit_cast(_Float16, (unsigned short)(sw[i] & 0xffffu)), hi = (float)__builtin_bit_cast(_Float16, (unsigned short)(sw[i] >> 16));
;                       const unsigned klo = (f2key(lo) & ~127u) | (unsigned)(127 - (32 * g + 2 * i)), khi = (f2key(hi) & ~127u) | (unsigned)(127 - (32 * g + 2 * i + 1));
;                       if (i < 8) { k0[2 * i] = klo; k0[2 * i + 1] = khi; } else { k1[2 * (i - 8)] = klo; k1[2 * (i - 8) + 1] = khi; } } }
;                 sort16_desc(k0); sort16_desc(k1); merge16(k0, k1);
	v_cvt_f32_f16_sdwa v150, v152 dst_sel:DWORD dst_unused:UNUSED_PAD src0_sel:WORD_1
	v_sub_u32_e32 v17, v17, v18
	v_cvt_f32_f16_e32 v18, v152
	v_add_u32_e32 v147, 0x7e, v147
	v_not_b32_e32 v151, v150
	v_or_b32_e32 v152, 0x80000000, v150
	v_cmp_gt_i32_e32 vcc, 0, v150
	v_add_u32_e32 v17, 0x7f, v17
	s_nop 0
	v_cndmask_b32_e32 v150, v152, v151, vcc
	v_not_b32_e32 v151, v18
	v_or_b32_e32 v152, 0x80000000, v18
	v_cmp_gt_i32_e32 vcc, 0, v18
	v_and_b32_e32 v150, 0xffffff80, v150
	v_sub_u32_e32 v150, v150, v20
	v_cndmask_b32_e32 v18, v152, v151, vcc
	v_and_b32_e32 v18, 0xffffff80, v18
	v_cvt_f32_f16_sdwa v151, v153 dst_sel:DWORD dst_unused:UNUSED_PAD src0_sel:WORD_1
	v_sub_u32_e32 v18, v18, v20
	v_cvt_f32_f16_e32 v20, v153
	v_add_u32_e32 v150, 0x7e, v150
	v_not_b32_e32 v152, v151
	v_or_b32_e32 v153, 0x80000000, v151
	v_cmp_gt_i32_e32 vcc, 0, v151
	v_add_u32_e32 v18, 0x7f, v18
	v_max_u32_e32 v161, v18, v150
	v_cndmask_b32_e32 v151, v153, v152, vcc
	v_not_b32_e32 v152, v20
	v_or_b32_e32 v153, 0x80000000, v20
	v_cmp_gt_i32_e32 vcc, 0, v20
	v_and_b32_e32 v151, 0xffffff80, v151
	v_sub_u32_e32 v151, v151, v21
	v_cndmask_b32_e32 v20, v153, v152, vcc
	v_and_b32_e32 v20, 0xffffff80, v20
	v_cvt_f32_f16_sdwa v152, v154 dst_sel:DWORD dst_unused:UNUSED_PAD src0_sel:WORD_1
	v_sub_u32_e32 v20, v20, v21
	v_cvt_f32_f16_e32 v21, v154
	v_add_u32_e32 v151, 0x7e, v151
	v_not_b32_e32 v153, v152
	v_or_b32_e32 v154, 0x80000000, v152
	v_cmp_gt_i32_e32 vcc, 0, v152
	v_add_u32_e32 v20, 0x7f, v20
	v_min_u32_e32 v18, v18, v150
	v_cndmask_b32_e32 v152, v154, v153, vcc
	v_not_b32_e32 v153, v21
	v_or_b32_e32 v154, 0x80000000, v21
	v_cmp_gt_i32_e32 vcc, 0, v21
	v_and_b32_e32 v152, 0xffffff80, v152
	v_sub_u32_e32 v152, v152, v22
	v_cndmask_b32_e32 v21, v154, v153, vcc
	v_and_b32_e32 v21, 0xffffff80, v21
	v_cvt_f32_f16_sdwa v153, v155 dst_sel:DWORD dst_unused:UNUSED_PAD src0_sel:WORD_1
	v_sub_u32_e32 v21, v21, v22
	v_cvt_f32_f16_e32 v22, v155
	v_add_u32_e32 v152, 0x7e, v152
	v_not_b32_e32 v154, v153
	v_or_b32_e32 v155, 0x80000000, v153
	v_cmp_gt_i32_e32 vcc, 0, v153
	v_add_u32_e32 v21, 0x7f, v21
	v_max_u32_e32 v150, v151, v20
	v_cndmask_b32_e32 v153, v155, v154, vcc
	v_not_b32_e32 v154, v22
	v_or_b32_e32 v155, 0x80000000, v22
	v_cmp_gt_i32_e32 vcc, 0, v22
	v_and_b32_e32 v153, 0xffffff80, v153
	v_sub_u32_e32 v153, v153, v23
	v_cndmask_b32_e32 v22, v155, v154, vcc
	v_cvt_f32_f16_sdwa v154, v0 dst_sel:DWORD dst_unused:UNUSED_PAD src0_sel:WORD_1
	v_cvt_f32_f16_e32 v0, v0
	v_and_b32_e32 v22, 0xffffff80, v22
	v_sub_u32_e32 v22, v22, v23
	v_not_b32_e32 v23, v154
	v_or_b32_e32 v155, 0x80000000, v154
	v_cmp_gt_i32_e32 vcc, 0, v154
	v_not_b32_e32 v154, v0
	v_add_u32_e32 v153, 0x7e, v153
	v_cndmask_b32_e32 v23, v155, v23, vcc
	v_or_b32_e32 v155, 0x80000000, v0
	v_cmp_gt_i32_e32 vcc, 0, v0
	v_and_b32_e32 v23, 0xffffff80, v23
	v_sub_u32_e32 v23, v23, v24
	v_cndmask_b32_e32 v0, v155, v154, vcc
	v_cvt_f32_f16_sdwa v154, v1 dst_sel:DWORD dst_unused:UNUSED_PAD src0_sel:WORD_1
	v_cvt_f32_f16_e32 v1, v1
	v_and_b32_e32 v0, 0xffffff80, v0
	v_sub_u32_e32 v0, v0, v24
	v_not_b32_e32 v24, v154
	v_or_b32_e32 v155, 0x80000000, v154
	v_cmp_gt_i32_e32 vcc, 0, v154
	v_not_b32_e32 v154, v1
	v_add_u32_e32 v22, 0x7f, v22
	v_cndmask_b32_e32 v24, v155, v24, vcc
	v_or_b32_e32 v155, 0x80000000, v1
	v_cmp_gt_i32_e32 vcc, 0, v1
	v_and_b32_e32 v24, 0xffffff80, v24
	v_sub_u32_e32 v24, v24, v25
	v_cndmask_b32_e32 v1, v155, v154, vcc
	v_cvt_f32_f16_sdwa v154, v2 dst_sel:DWORD dst_unused:UNUSED_PAD src0_sel:WORD_1
	v_cvt_f32_f16_e32 v2, v2
	v_and_b32_e32 v1, 0xffffff80, v1
	v_sub_u32_e32 v1, v1, v25
	v_not_b32_e32 v25, v154
	v_or_b32_e32 v155, 0x80000000, v154
	v_cmp_gt_i32_e32 vcc, 0, v154
	v_not_b32_e32 v154, v2
	v_add_u32_e32 v23, 0x7e, v23
	v_cndmask_b32_e32 v25, v155, v25, vcc
	v_or_b32_e32 v155, 0x80000000, v2
	v_cmp_gt_i32_e32 vcc, 0, v2
	v_and_b32_e32 v25, 0xffffff80, v25
	v_sub_u32_e32 v25, v25, v26
	v_cndmask_b32_e32 v2, v155, v154, vcc
	v_cvt_f32_f16_sdwa v154, v3 dst_sel:DWORD dst_unused:UNUSED_PAD src0_sel:WORD_1
	v_cvt_f32_f16_e32 v3, v3
	v_and_b32_e32 v2, 0xffffff80, v2
	v_sub_u32_e32 v2, v2, v26
	v_not_b32_e32 v26, v154
	v_or_b32_e32 v155, 0x80000000, v154
	v_cmp_gt_i32_e32 vcc, 0, v154
	v_not_b32_e32 v154, v3
	v_add_u32_e32 v0, 0x7f, v0
	v_cndmask_b32_e32 v26, v155, v26, vcc
	v_or_b32_e32 v155, 0x80000000, v3
	v_cmp_gt_i32_e32 vcc, 0, v3
	v_and_b32_e32 v26, 0xffffff80, v26
	v_sub_u32_e32 v26, v26, v28
	v_cndmask_b32_e32 v3, v155, v154, vcc
	v_and_b32_e32 v3, 0xffffff80, v3
	v_sub_u32_e32 v3, v3, v28
	v_add_u32_e32 v24, 0x7e, v24
	v_add_u32_e32 v1, 0x7f, v1
	v_add_u32_e32 v25, 0x7e, v25
	v_add_u32_e32 v2, 0x7f, v2
	v_add_u32_e32 v26, 0x7e, v26
	v_add_u32_e32 v3, 0x7f, v3
	v_max_u32_e32 v28, v4, v5
	v_min_u32_e32 v4, v4, v5
	v_max_u32_e32 v5, v143, v14
	v_min_u32_e32 v14, v143, v14
	v_max_u32_e32 v143, v12, v148
	v_min_u32_e32 v12, v12, v148
	v_max_u32_e32 v148, v149, v10
	v_min_u32_e32 v10, v149, v10
	v_max_u32_e32 v149, v8, v144
	v_min_u32_e32 v8, v8, v144
	v_max_u32_e32 v144, v145, v15
	v_min_u32_e32 v15, v145, v15
	v_max_u32_e32 v145, v16, v146
	v_min_u32_e32 v16, v16, v146
	v_max_u32_e32 v146, v147, v17
	v_min_u32_e32 v17, v147, v17
	v_min_u32_e32 v20, v151, v20
	v_max_u32_e32 v151, v21, v152
	v_min_u32_e32 v21, v21, v152
	v_max_u32_e32 v152, v153, v22
	v_min_u32_e32 v22, v153, v22
	v_max_u32_e32 v153, v0, v23
	v_min_u32_e32 v0, v0, v23
	v_max_u32_e32 v23, v24, v1
	v_min_u32_e32 v1, v24, v1
	v_max_u32_e32 v24, v2, v25
	v_min_u32_e32 v2, v2, v25
	v_max_u32_e32 v25, v26, v3
	v_min_u32_e32 v3, v26, v3
	v_max_u32_e32 v147, v28, v14
	v_min_u32_e32 v14, v28, v14
	v_max_u32_e32 v28, v4, v5
	v_min_u32_e32 v4, v4, v5
; #define CE_DESC(a, b) do { const unsigned _mx = (a) > (b) ? (a) : (b), _mn = (a) > (b) ? (b) : (a); (a) = _mx; (b) = _mn; } while (0)
; __device__ __forceinline__ void sort16_desc(unsigned (&k)[16]) {
; #pragma unroll
;     for (int size = 2; size <= 16; size <<= 1)
; #pragma unroll
;         for (int stride = size >> 1; stride > 0; stride >>= 1)
; #pragma unroll
;             for (int i = 0; i < 16; ++i) { const int j = i ^ stride;
;                 if (j > i) { if ((i & size) == 0) CE_DESC(k[i], k[j]); else CE_DESC(k[j], k[i]); } }
; }
	v_max_u32_e32 v5, v10, v143
	v_min_u32_e32 v10, v10, v143
	v_max_u32_e32 v143, v148, v12
	v_min_u32_e32 v12, v148, v12
	v_max_u32_e32 v148, v149, v15
	v_min_u32_e32 v15, v149, v15
	v_max_u32_e32 v149, v8, v144
	v_min_u32_e32 v8, v8, v144
	v_max_u32_e32 v144, v17, v145
	v_min_u32_e32 v17, v17, v145
	v_max_u32_e32 v145, v146, v16
	v_min_u32_e32 v16, v146, v16
	v_max_u32_e32 v26, v161, v20
	v_min_u32_e32 v20, v161, v20
	v_max_u32_e32 v161, v18, v150
	v_min_u32_e32 v18, v18, v150
	v_max_u32_e32 v150, v22, v151
	v_min_u32_e32 v22, v22, v151
	v_max_u32_e32 v151, v152, v21
	v_min_u32_e32 v21, v152, v21
	v_max_u32_e32 v152, v153, v1
	v_min_u32_e32 v1, v153, v1
	v_max_u32_e32 v153, v0, v23
	v_min_u32_e32 v0, v0, v23
	v_max_u32_e32 v23, v3, v24
	v_min_u32_e32 v3, v3, v24
	v_max_u32_e32 v24, v25, v2
	v_min_u32_e32 v2, v25, v2
	v_max_u32_e32 v146, v147, v28
	v_min_u32_e32 v28, v147, v28
	v_max_u32_e32 v147, v14, v4
	v_min_u32_e32 v4, v14, v4
	v_max_u32_e32 v14, v12, v10
	v_min_u32_e32 v10, v12, v10
	v_max_u32_e32 v12, v143, v5
	v_min_u32_e32 v5, v143, v5
	v_max_u32_e32 v143, v148, v149
	v_min_u32_e32 v148, v148, v149
	v_max_u32_e32 v149, v15, v8
	v_min_u32_e32 v8, v15, v8
	v_max_u32_e32 v15, v16, v17
	v_min_u32_e32 v16, v16, v17
	v_max_u32_e32 v17, v145, v144
	v_min_u32_e32 v144, v145, v144
	v_max_u32_e32 v25, v26, v161
	v_min_u32_e32 v26, v26, v161
	v_max_u32_e32 v161, v20, v18
	v_min_u32_e32 v18, v20, v18
	v_max_u32_e32 v20, v21, v22
	v_min_u32_e32 v21, v21, v22
	v_max_u32_e32 v22, v151, v150
	v_min_u32_e32 v150, v151, v150
	v_max_u32_e32 v151, v152, v153
	v_min_u32_e32 v152, v152, v153
	v_max_u32_e32 v153, v1, v0
	v_min_u32_e32 v0, v1, v0
	v_max_u32_e32 v1, v2, v3
	v_min_u32_e32 v2, v2, v3
	v_max_u32_e32 v3, v24, v23
	v_min_u32_e32 v23, v24, v23
	v_max_u32_e32 v145, v146, v10
	v_min_u32_e32 v10, v146, v10
	v_max_u32_e32 v146, v28, v14
	v_min_u32_e32 v14, v28, v14
	v_max_u32_e32 v28, v147, v5
	v_min_u32_e32 v5, v147, v5
	v_max_u32_e32 v147, v4, v12
	v_min_u32_e32 v4, v4, v12
	v_max_u32_e32 v12, v16, v143
	v_min_u32_e32 v16, v16, v143
	v_max_u32_e32 v143, v15, v148
	v_min_u32_e32 v15, v15, v148
	v_max_u32_e32 v148, v144, v149
	v_min_u32_e32 v144, v144, v149
	v_max_u32_e32 v149, v17, v8
	v_min_u32_e32 v8, v17, v8
	v_max_u32_e32 v24, v25, v21
	v_min_u32_e32 v21, v25, v21
	v_max_u32_e32 v25, v26, v20
	v_min_u32_e32 v20, v26, v20
	v_max_u32_e32 v26, v161, v150
	v_min_u32_e32 v150, v161, v150
	v_max_u32_e32 v161, v18, v22
	v_min_u32_e32 v18, v18, v22
	v_max_u32_e32 v22, v2, v151
	v_min_u32_e32 v2, v2, v151
	v_max_u32_e32 v151, v1, v152
	v_min_u32_e32 v1, v1, v152
	v_max_u32_e32 v152, v23, v153
	v_min_u32_e32 v23, v23, v153
	v_max_u32_e32 v153, v3, v0
	v_min_u32_e32 v0, v3, v0
	v_max_u32_e32 v17, v145, v28
	v_min_u32_e32 v28, v145, v28
	v_max_u32_e32 v145, v146, v147
	v_min_u32_e32 v146, v146, v147
	v_max_u32_e32 v147, v10, v5
	v_min_u32_e32 v5, v10, v5
	v_max_u32_e32 v10, v14, v4
	v_min_u32_e32 v4, v14, v4
	v_max_u32_e32 v14, v144, v16
	v_min_u32_e32 v16, v144, v16
	v_max_u32_e32 v144, v8, v15
	v_min_u32_e32 v8, v8, v15
	v_max_u32_e32 v15, v148, v12
	v_min_u32_e32 v12, v148, v12
	v_max_u32_e32 v148, v149, v143
	v_min_u32_e32 v143, v149, v143
	v_max_u32_e32 v3, v24, v26
	v_min_u32_e32 v24, v24, v26
	v_max_u32_e32 v26, v25, v161
	v_min_u32_e32 v25, v25, v161
	v_max_u32_e32 v161, v21, v150
	v_min_u32_e32 v21, v21, v150
	v_max_u32_e32 v150, v20, v18
	v_min_u32_e32 v18, v20, v18
	v_max_u32_e32 v20, v23, v2
	v_min_u32_e32 v2, v23, v2
	v_max_u32_e32 v23, v0, v1
	v_min_u32_e32 v0, v0, v1
	v_max_u32_e32 v1, v152, v22
	v_min_u32_e32 v22, v152, v22
	v_max_u32_e32 v152, v153, v151
	v_min_u32_e32 v151, v153, v151
	v_max_u32_e32 v149, v17, v145
	v_min_u32_e32 v17, v17, v145
	v_max_u32_e32 v145, v28, v146
	v_min_u32_e32 v28, v28, v146
	v_max_u32_e32 v146, v147, v10
	v_min_u32_e32 v10, v147, v10
	v_max_u32_e32 v147, v5, v4
	v_min_u32_e32 v4, v5, v4
	v_max_u32_e32 v5, v8, v16
	v_min_u32_e32 v8, v8, v16
	v_max_u32_e32 v16, v144, v14
	v_min_u32_e32 v14, v144, v14
	v_max_u32_e32 v144, v143, v12
	v_min_u32_e32 v12, v143, v12
	v_max_u32_e32 v143, v148, v15
	v_min_u32_e32 v15, v148, v15
	v_max_u32_e32 v153, v3, v26
	v_min_u32_e32 v3, v3, v26
	v_max_u32_e32 v26, v24, v25
	v_min_u32_e32 v24, v24, v25
	v_max_u32_e32 v25, v161, v150
	v_min_u32_e32 v150, v161, v150
	v_max_u32_e32 v161, v21, v18
	v_min_u32_e32 v18, v21, v18
	v_max_u32_e32 v21, v0, v2
	v_min_u32_e32 v0, v0, v2
	v_max_u32_e32 v2, v23, v20
	v_min_u32_e32 v20, v23, v20
	v_max_u32_e32 v23, v151, v22
	v_min_u32_e32 v22, v151, v22
	v_max_u32_e32 v151, v152, v1
	v_min_u32_e32 v1, v152, v1
	v_max_u32_e32 v148, v149, v8
	v_min_u32_e32 v8, v149, v8
	v_max_u32_e32 v149, v17, v5
	v_min_u32_e32 v5, v17, v5
	v_max_u32_e32 v17, v145, v14
	v_min_u32_e32 v14, v145, v14
	v_max_u32_e32 v145, v28, v16
	v_min_u32_e32 v16, v28, v16
	v_max_u32_e32 v28, v146, v12
	v_min_u32_e32 v12, v146, v12
	v_max_u32_e32 v146, v10, v144
	v_min_u32_e32 v10, v10, v144
	v_max_u32_e32 v144, v147, v15
	v_min_u32_e32 v15, v147, v15
	v_max_u32_e32 v147, v4, v143
	v_min_u32_e32 v4, v4, v143
	v_max_u32_e32 v152, v153, v0
	v_min_u32_e32 v0, v153, v0
	v_max_u32_e32 v153, v3, v21
	v_min_u32_e32 v3, v3, v21
	v_max_u32_e32 v21, v26, v20
	v_min_u32_e32 v20, v26, v20
	v_max_u32_e32 v26, v24, v2
	v_min_u32_e32 v2, v24, v2
	v_max_u32_e32 v24, v25, v22
	v_min_u32_e32 v22, v25, v22
	v_max_u32_e32 v25, v150, v23
	v_min_u32_e32 v23, v150, v23
	v_max_u32_e32 v150, v161, v1
	v_min_u32_e32 v1, v161, v1
	v_max_u32_e32 v161, v18, v151
	v_min_u32_e32 v18, v18, v151
	v_max_u32_e32 v143, v148, v28
	v_min_u32_e32 v28, v148, v28
	v_max_u32_e32 v148, v149, v146
	v_min_u32_e32 v146, v149, v146
; #define CE_DESC(a, b) do { const unsigned _mx = (a) > (b) ? (a) : (b), _mn = (a) > (b) ? (b) : (a); (a) = _mx; (b) = _mn; } while (0)
; __device__ __forceinline__ void sort16_desc(unsigned (&k)[16]) {
; #pragma unroll
;     for (int size = 2; size <= 16; size <<= 1)
; #pragma unroll
;         for (int stride = size >> 1; stride > 0; stride >>= 1)
; #pragma unroll
;             for (int i = 0; i < 16; ++i) { const int j = i ^ stride;
;                 if (j > i) { if ((i & size) == 0) CE_DESC(k[i], k[j]); else CE_DESC(k[j], k[i]); } }
; }
; __device__ __forceinline__ void merge16(unsigned (&a)[16], const unsigned (&b)[16]) {
; #pragma unroll
;     for (int i = 0; i < 16; ++i) a[i] = a[i] > b[15 - i] ? a[i] : b[15 - i];
; #pragma unroll
;     for (int stride = 8; stride > 0; stride >>= 1)
; #pragma unroll
;         for (int i = 0; i < 16; ++i) { const int j = i ^ stride; if (j > i) CE_DESC(a[i], a[j]); }
; }
; __device__ __forceinline__ void peer_tile(const Args& A, LAS unsigned char* lds, int tile) {
;     ...
;                 for (int msk = 16; msk <= 32; msk <<= 1) {
; #pragma unroll
;                     for (int i = 0; i < 16; ++i) k1[i] = (unsigned)__shfl_xor((int)k0[i], msk);
;                     merge16(k0, k1); }
	v_max_u32_e32 v149, v17, v144
	v_min_u32_e32 v17, v17, v144
	v_max_u32_e32 v144, v145, v147
	v_min_u32_e32 v145, v145, v147
	v_max_u32_e32 v147, v8, v12
	v_min_u32_e32 v8, v8, v12
	v_max_u32_e32 v12, v5, v10
	v_min_u32_e32 v5, v5, v10
	v_max_u32_e32 v10, v14, v15
	v_min_u32_e32 v14, v14, v15
	v_max_u32_e32 v15, v16, v4
	v_min_u32_e32 v4, v16, v4
	v_max_u32_e32 v151, v152, v24
	v_min_u32_e32 v24, v152, v24
	v_max_u32_e32 v152, v153, v25
	v_min_u32_e32 v25, v153, v25
	v_max_u32_e32 v153, v21, v150
	v_min_u32_e32 v21, v21, v150
	v_max_u32_e32 v150, v26, v161
	v_min_u32_e32 v26, v26, v161
	v_max_u32_e32 v161, v0, v22
	v_min_u32_e32 v0, v0, v22
	v_max_u32_e32 v22, v3, v23
	v_min_u32_e32 v3, v3, v23
	v_max_u32_e32 v23, v20, v1
	v_min_u32_e32 v1, v20, v1
	v_max_u32_e32 v20, v2, v18
	v_min_u32_e32 v2, v2, v18
	v_max_u32_e32 v16, v143, v149
	v_min_u32_e32 v143, v143, v149
	v_max_u32_e32 v149, v148, v144
	v_min_u32_e32 v144, v148, v144
	v_max_u32_e32 v148, v28, v17
	v_min_u32_e32 v17, v28, v17
	v_max_u32_e32 v28, v146, v145
	v_min_u32_e32 v145, v146, v145
	v_max_u32_e32 v146, v147, v10
	v_min_u32_e32 v10, v147, v10
	v_max_u32_e32 v147, v12, v15
	v_min_u32_e32 v12, v12, v15
	v_max_u32_e32 v15, v8, v14
	v_min_u32_e32 v8, v8, v14
	v_max_u32_e32 v14, v5, v4
	v_min_u32_e32 v4, v5, v4
	v_max_u32_e32 v18, v151, v153
	v_min_u32_e32 v151, v151, v153
	v_max_u32_e32 v153, v152, v150
	v_min_u32_e32 v150, v152, v150
	v_max_u32_e32 v152, v24, v21
	v_min_u32_e32 v21, v24, v21
	v_max_u32_e32 v24, v25, v26
	v_min_u32_e32 v25, v25, v26
	v_max_u32_e32 v26, v161, v23
	v_min_u32_e32 v23, v161, v23
	v_max_u32_e32 v161, v22, v20
	v_min_u32_e32 v20, v22, v20
	v_max_u32_e32 v22, v0, v1
	v_min_u32_e32 v0, v0, v1
	v_max_u32_e32 v1, v3, v2
	v_min_u32_e32 v2, v3, v2
	v_min_u32_e32 v5, v16, v149
	v_min_u32_e32 v154, v143, v144
	v_min_u32_e32 v155, v148, v28
	v_min_u32_e32 v156, v17, v145
	v_min_u32_e32 v157, v146, v147
	v_min_u32_e32 v158, v10, v12
	v_min_u32_e32 v159, v15, v14
	v_min_u32_e32 v160, v8, v4
	v_min_u32_e32 v3, v18, v153
	v_min_u32_e32 v162, v151, v150
	v_min_u32_e32 v163, v152, v24
	v_min_u32_e32 v164, v21, v25
	v_min_u32_e32 v165, v26, v161
	v_min_u32_e32 v166, v23, v20
	v_min_u32_e32 v167, v22, v1
	v_min_u32_e32 v168, v0, v2
	v_max3_u32 v16, v16, v149, v168
	v_max3_u32 v0, v5, v0, v2
	v_max3_u32 v2, v143, v144, v167
	v_max3_u32 v1, v154, v22, v1
	v_max3_u32 v5, v148, v28, v166
	v_max3_u32 v20, v155, v23, v20
	v_max3_u32 v17, v17, v145, v165
	v_max3_u32 v22, v156, v26, v161
	v_max3_u32 v23, v146, v147, v164
	v_max3_u32 v21, v157, v21, v25
	v_max3_u32 v10, v10, v12, v163
	v_max3_u32 v12, v158, v152, v24
	v_max3_u32 v14, v15, v14, v162
	v_max3_u32 v15, v159, v151, v150
	v_max3_u32 v3, v8, v4, v3
	v_max3_u32 v4, v160, v18, v153
	v_max_u32_e32 v8, v16, v23
	v_min_u32_e32 v16, v16, v23
	v_max_u32_e32 v18, v0, v21
	v_min_u32_e32 v0, v0, v21
	v_max_u32_e32 v21, v2, v10
	v_min_u32_e32 v2, v2, v10
	v_max_u32_e32 v10, v1, v12
	v_min_u32_e32 v1, v1, v12
	v_max_u32_e32 v12, v5, v14
	v_min_u32_e32 v5, v5, v14
	v_max_u32_e32 v14, v20, v15
	v_min_u32_e32 v15, v20, v15
	v_max_u32_e32 v20, v17, v3
	v_min_u32_e32 v3, v17, v3
	v_max_u32_e32 v17, v22, v4
	v_min_u32_e32 v4, v22, v4
	v_max_u32_e32 v22, v8, v12
	v_min_u32_e32 v8, v8, v12
	v_max_u32_e32 v12, v18, v14
	v_min_u32_e32 v14, v18, v14
	v_max_u32_e32 v18, v21, v20
	v_min_u32_e32 v20, v21, v20
	v_max_u32_e32 v21, v10, v17
	v_min_u32_e32 v10, v10, v17
	v_max_u32_e32 v17, v16, v5
	v_min_u32_e32 v5, v16, v5
	v_max_u32_e32 v16, v0, v15
	v_min_u32_e32 v0, v0, v15
	v_max_u32_e32 v15, v2, v3
	v_min_u32_e32 v2, v2, v3
	v_max_u32_e32 v3, v1, v4
	v_min_u32_e32 v1, v1, v4
	v_max_u32_e32 v4, v22, v18
	v_min_u32_e32 v18, v22, v18
	v_max_u32_e32 v22, v12, v21
	v_min_u32_e32 v12, v12, v21
	v_max_u32_e32 v21, v8, v20
	v_min_u32_e32 v8, v8, v20
	v_max_u32_e32 v20, v14, v10
	v_min_u32_e32 v10, v14, v10
	v_max_u32_e32 v14, v17, v15
	v_min_u32_e32 v15, v17, v15
	v_max_u32_e32 v17, v16, v3
	v_min_u32_e32 v3, v16, v3
	v_max_u32_e32 v16, v5, v2
	v_min_u32_e32 v2, v5, v2
	v_max_u32_e32 v5, v0, v1
	v_min_u32_e32 v0, v0, v1
	v_max_u32_e32 v1, v4, v22
	v_min_u32_e32 v4, v4, v22
	v_max_u32_e32 v22, v18, v12
	v_min_u32_e32 v12, v18, v12
	v_max_u32_e32 v18, v21, v20
	v_min_u32_e32 v20, v21, v20
	v_max_u32_e32 v21, v8, v10
	v_min_u32_e32 v8, v8, v10
	v_max_u32_e32 v10, v14, v17
	v_min_u32_e32 v14, v14, v17
	v_max_u32_e32 v17, v15, v3
	v_min_u32_e32 v3, v15, v3
	v_max_u32_e32 v15, v16, v5
	v_min_u32_e32 v5, v16, v5
	v_max_u32_e32 v16, v2, v0
	v_min_u32_e32 v0, v2, v0
	ds_bpermute_b32 v2, v27, v1
	ds_bpermute_b32 v23, v27, v4
	ds_bpermute_b32 v24, v27, v22
	ds_bpermute_b32 v25, v27, v12
	ds_bpermute_b32 v26, v27, v18
	ds_bpermute_b32 v28, v27, v20
	ds_bpermute_b32 v143, v27, v21
	ds_bpermute_b32 v144, v27, v8
	ds_bpermute_b32 v145, v27, v10
	ds_bpermute_b32 v146, v27, v14
	ds_bpermute_b32 v147, v27, v17
	ds_bpermute_b32 v148, v27, v0
	ds_bpermute_b32 v149, v27, v16
	ds_bpermute_b32 v150, v27, v5
	ds_bpermute_b32 v151, v27, v15
	ds_bpermute_b32 v27, v27, v3
	s_waitcnt lgkmcnt(4)
	v_max_u32_e32 v1, v1, v148
	s_waitcnt lgkmcnt(3)
	v_max_u32_e32 v4, v4, v149
	s_waitcnt lgkmcnt(2)
	v_max_u32_e32 v22, v22, v150
	s_waitcnt lgkmcnt(1)
	v_max_u32_e32 v12, v12, v151
	s_waitcnt lgkmcnt(0)
; __device__ __forceinline__ void peer_tile(const Args& A, LAS unsigned char* lds, int tile) {
;     ...
;                 for (int msk = 16; msk <= 32; msk <<= 1) {
; #pragma unroll
;                     for (int i = 0; i < 16; ++i) k1[i] = (unsigned)__shfl_xor((int)k0[i], msk);
;                     merge16(k0, k1); }
; #pragma unroll
;                 for (int i = 0; i < 16; ++i) LA[hh][p][i] = k0[i];
;             }
;         }
;         {
;             const int h = 4 * hg + g;
;             unsigned L2[2][16];
; #pragma unroll
;             for (int p = 0; p < 2; ++p)
; #pragma unroll
;                 for (int i = 0; i < 16; ++i) L2[p][i] = (g & 2) ? ((g & 1) ? LA[3][p][i] : LA[2][p][i]) : ((g & 1) ? LA[1][p][i] : LA[0][p][i]);
	v_max_u32_e32 v18, v18, v27
	v_max_u32_e32 v20, v20, v147
	v_max_u32_e32 v21, v21, v146
	v_max_u32_e32 v8, v8, v145
	v_max_u32_e32 v10, v10, v144
	v_max_u32_e32 v14, v14, v143
	v_max_u32_e32 v17, v17, v28
	v_max_u32_e32 v3, v3, v26
	v_max_u32_e32 v15, v15, v25
	v_max_u32_e32 v5, v5, v24
	v_max_u32_e32 v16, v16, v23
	v_max_u32_e32 v0, v0, v2
	v_max_u32_e32 v2, v1, v10
	v_min_u32_e32 v1, v1, v10
	v_max_u32_e32 v10, v4, v14
	v_min_u32_e32 v4, v4, v14
	v_max_u32_e32 v14, v22, v17
	v_min_u32_e32 v17, v22, v17
	v_max_u32_e32 v22, v12, v3
	v_min_u32_e32 v3, v12, v3
	v_max_u32_e32 v12, v18, v15
	v_min_u32_e32 v15, v18, v15
	v_max_u32_e32 v18, v20, v5
	v_min_u32_e32 v5, v20, v5
	v_max_u32_e32 v20, v21, v16
	v_min_u32_e32 v16, v21, v16
	v_max_u32_e32 v21, v8, v0
	v_min_u32_e32 v0, v8, v0
	v_max_u32_e32 v8, v2, v12
	v_min_u32_e32 v2, v2, v12
	v_max_u32_e32 v12, v10, v18
	v_min_u32_e32 v10, v10, v18
	v_max_u32_e32 v18, v14, v20
	v_min_u32_e32 v14, v14, v20
	v_max_u32_e32 v20, v22, v21
	v_min_u32_e32 v21, v22, v21
	v_max_u32_e32 v22, v1, v15
	v_min_u32_e32 v1, v1, v15
	v_max_u32_e32 v15, v4, v5
	v_min_u32_e32 v4, v4, v5
	v_max_u32_e32 v5, v17, v16
	v_min_u32_e32 v16, v17, v16
	v_max_u32_e32 v17, v3, v0
	v_min_u32_e32 v0, v3, v0
	v_max_u32_e32 v3, v8, v18
	v_min_u32_e32 v8, v8, v18
	v_max_u32_e32 v18, v12, v20
	v_min_u32_e32 v12, v12, v20
	v_max_u32_e32 v20, v2, v14
	v_min_u32_e32 v2, v2, v14
	v_max_u32_e32 v14, v10, v21
	v_min_u32_e32 v10, v10, v21
	v_max_u32_e32 v21, v22, v5
	v_min_u32_e32 v5, v22, v5
	v_max_u32_e32 v22, v15, v17
	v_min_u32_e32 v15, v15, v17
	v_max_u32_e32 v17, v1, v16
	v_min_u32_e32 v1, v1, v16
	v_max_u32_e32 v16, v4, v0
	v_min_u32_e32 v0, v4, v0
	v_max_u32_e32 v4, v3, v18
	v_min_u32_e32 v3, v3, v18
	v_max_u32_e32 v18, v8, v12
	v_min_u32_e32 v8, v8, v12
	v_max_u32_e32 v12, v20, v14
	v_min_u32_e32 v14, v20, v14
	v_max_u32_e32 v20, v2, v10
	v_min_u32_e32 v2, v2, v10
	v_max_u32_e32 v10, v21, v22
	v_min_u32_e32 v21, v21, v22
	v_max_u32_e32 v22, v5, v15
	v_min_u32_e32 v5, v5, v15
	v_max_u32_e32 v15, v17, v16
	v_min_u32_e32 v16, v17, v16
	v_max_u32_e32 v17, v1, v0
	v_min_u32_e32 v0, v1, v0
	ds_bpermute_b32 v1, v29, v4
	ds_bpermute_b32 v23, v29, v3
	ds_bpermute_b32 v24, v29, v18
	ds_bpermute_b32 v25, v29, v8
	ds_bpermute_b32 v26, v29, v12
	ds_bpermute_b32 v27, v29, v14
	ds_bpermute_b32 v28, v29, v20
	ds_bpermute_b32 v143, v29, v2
	ds_bpermute_b32 v144, v29, v10
	ds_bpermute_b32 v145, v29, v21
	ds_bpermute_b32 v146, v29, v22
	ds_bpermute_b32 v147, v29, v0
	ds_bpermute_b32 v148, v29, v17
	ds_bpermute_b32 v149, v29, v16
	ds_bpermute_b32 v150, v29, v15
	ds_bpermute_b32 v29, v29, v5
	s_waitcnt lgkmcnt(4)
	v_max_u32_e32 v4, v4, v147
	s_waitcnt lgkmcnt(3)
	v_max_u32_e32 v3, v3, v148
	s_waitcnt lgkmcnt(2)
	v_max_u32_e32 v18, v18, v149
	s_waitcnt lgkmcnt(1)
	v_max_u32_e32 v8, v8, v150
	s_waitcnt lgkmcnt(0)
	v_max_u32_e32 v12, v12, v29
	v_max_u32_e32 v14, v14, v146
	v_max_u32_e32 v20, v20, v145
	v_max_u32_e32 v2, v2, v144
	v_max_u32_e32 v10, v10, v143
	v_max_u32_e32 v21, v21, v28
	v_max_u32_e32 v22, v22, v27
	v_max_u32_e32 v5, v5, v26
	v_max_u32_e32 v15, v15, v25
	v_max_u32_e32 v16, v16, v24
	v_max_u32_e32 v17, v17, v23
	v_max_u32_e32 v0, v0, v1
	v_max_u32_e32 v1, v4, v10
	v_min_u32_e32 v4, v4, v10
	v_max_u32_e32 v10, v3, v21
	v_min_u32_e32 v3, v3, v21
	v_max_u32_e32 v21, v18, v22
	v_min_u32_e32 v18, v18, v22
	v_max_u32_e32 v22, v8, v5
	v_min_u32_e32 v5, v8, v5
	v_max_u32_e32 v8, v12, v15
	v_min_u32_e32 v12, v12, v15
	v_max_u32_e32 v15, v14, v16
	v_min_u32_e32 v14, v14, v16
	v_max_u32_e32 v16, v20, v17
	v_min_u32_e32 v17, v20, v17
	v_max_u32_e32 v20, v2, v0
	v_min_u32_e32 v0, v2, v0
	v_max_u32_e32 v2, v1, v8
	v_min_u32_e32 v1, v1, v8
	v_max_u32_e32 v8, v10, v15
	v_min_u32_e32 v10, v10, v15
	v_max_u32_e32 v15, v21, v16
	v_min_u32_e32 v16, v21, v16
	v_max_u32_e32 v21, v22, v20
	v_min_u32_e32 v20, v22, v20
	v_max_u32_e32 v22, v4, v12
	v_min_u32_e32 v4, v4, v12
	v_max_u32_e32 v12, v3, v14
	v_min_u32_e32 v3, v3, v14
	v_max_u32_e32 v14, v18, v17
	v_min_u32_e32 v17, v18, v17
	v_max_u32_e32 v18, v5, v0
	v_min_u32_e32 v0, v5, v0
	v_max_u32_e32 v5, v2, v15
	v_min_u32_e32 v2, v2, v15
	v_max_u32_e32 v15, v8, v21
	v_min_u32_e32 v8, v8, v21
	v_max_u32_e32 v21, v1, v16
	v_min_u32_e32 v1, v1, v16
	v_max_u32_e32 v16, v10, v20
	v_min_u32_e32 v10, v10, v20
	v_max_u32_e32 v20, v22, v14
	v_min_u32_e32 v14, v22, v14
	v_max_u32_e32 v22, v12, v18
	v_min_u32_e32 v12, v12, v18
	v_max_u32_e32 v18, v4, v17
	v_min_u32_e32 v4, v4, v17
	v_max_u32_e32 v17, v3, v0
	v_min_u32_e32 v0, v3, v0
	v_max_u32_e32 v3, v5, v15
	v_min_u32_e32 v5, v5, v15
	v_max_u32_e32 v15, v2, v8
	v_min_u32_e32 v2, v2, v8
	v_max_u32_e32 v8, v21, v16
	v_min_u32_e32 v16, v21, v16
	v_max_u32_e32 v21, v1, v10
	v_min_u32_e32 v1, v1, v10
	v_max_u32_e32 v10, v20, v22
	v_min_u32_e32 v20, v20, v22
	v_max_u32_e32 v22, v14, v12
	v_min_u32_e32 v12, v14, v12
	v_max_u32_e32 v14, v18, v17
	v_min_u32_e32 v17, v18, v17
	v_max_u32_e32 v18, v4, v0
	v_min_u32_e32 v0, v4, v0
	v_and_b32_e32 v4, 16, v19
	v_cmp_eq_u32_e32 vcc, 0, v4
	v_cndmask_b32_e64 v23, v77, v45, s[0:1]
	v_cndmask_b32_e64 v24, v76, v44, s[0:1]
	v_cndmask_b32_e32 v4, v142, v109, vcc
	v_cndmask_b32_e64 v4, v4, v23, s[4:5]
	v_cndmask_b32_e32 v23, v141, v108, vcc
	v_cndmask_b32_e64 v23, v23, v24, s[4:5]
	v_cndmask_b32_e32 v24, v140, v107, vcc
	v_cndmask_b32_e64 v25, v75, v43, s[0:1]
	v_cndmask_b32_e64 v24, v24, v25, s[4:5]
	v_cndmask_b32_e32 v25, v139, v106, vcc
	v_cndmask_b32_e64 v26, v74, v42, s[0:1]
	v_cndmask_b32_e64 v25, v25, v26, s[4:5]
	v_cndmask_b32_e32 v26, v138, v105, vcc
	v_cndmask_b32_e64 v27, v73, v41, s[0:1]
	v_cndmask_b32_e64 v26, v26, v27, s[4:5]
; __device__ __forceinline__ float key2f(unsigned k) { const unsigned u = (k & 0x80000000u) ? (k & 0x7fffffffu) : ~k; return __uint_as_float(u); }
; __device__ __forceinline__ void peer_tile(const Args& A, LAS unsigned char* lds, int tile) {
;     ...
;                 for (int i = 0; i < 16; ++i) L2[p][i] = (g & 2) ? ((g & 1) ? LA[3][p][i] : LA[2][p][i]) : ((g & 1) ? LA[1][p][i] : LA[0][p][i]);
;             float va[16], vb[16];
; #pragma unroll
;             for (int i = 0; i < 16; ++i) { va[i] = key2f(L2[0][i] & ~127u); vb[i] = key2f(L2[1][i] & ~127u); idx[i] = 127u - (L2[0][i] & 127u); idx[16 + i] = 127u - (L2[1][i] & 127u); }
	v_cndmask_b32_e32 v27, v137, v104, vcc
	v_cndmask_b32_e64 v28, v72, v40, s[0:1]
	v_cndmask_b32_e64 v27, v27, v28, s[4:5]
	v_cndmask_b32_e32 v28, v136, v103, vcc
	v_cndmask_b32_e64 v29, v71, v39, s[0:1]
	v_cndmask_b32_e64 v28, v28, v29, s[4:5]
	v_cndmask_b32_e32 v29, v135, v102, vcc
	v_cndmask_b32_e64 v29, v29, v38, s[4:5]
	v_cndmask_b32_e32 v38, v134, v101, vcc
	v_cndmask_b32_e64 v37, v38, v37, s[4:5]
	v_cndmask_b32_e32 v38, v133, v100, vcc
	v_cndmask_b32_e64 v36, v38, v36, s[4:5]
	v_cndmask_b32_e32 v38, v132, v99, vcc
	v_cndmask_b32_e64 v38, v38, v35, s[4:5]
	v_cndmask_b32_e32 v35, v131, v98, vcc
	v_cndmask_b32_e64 v39, v35, v34, s[4:5]
	v_cndmask_b32_e32 v34, v130, v97, vcc
	v_cndmask_b32_e64 v33, v34, v33, s[4:5]
	v_cndmask_b32_e32 v34, v129, v96, vcc
	v_cndmask_b32_e64 v40, v34, v32, s[4:5]
	v_cndmask_b32_e32 v32, v128, v95, vcc
	v_cndmask_b32_e64 v42, v32, v31, s[4:5]
	v_cndmask_b32_e32 v31, v127, v94, vcc
	v_cndmask_b32_e64 v43, v31, v30, s[4:5]
	v_cndmask_b32_e32 v3, v3, v126, vcc
	v_cndmask_b32_e64 v30, v93, v61, s[0:1]
	v_cndmask_b32_e64 v3, v3, v30, s[4:5]
	v_cndmask_b32_e32 v5, v5, v125, vcc
	v_cndmask_b32_e64 v30, v92, v60, s[0:1]
	v_cndmask_b32_e64 v30, v5, v30, s[4:5]
	v_cndmask_b32_e32 v5, v15, v124, vcc
	v_cndmask_b32_e64 v15, v91, v59, s[0:1]
	v_cndmask_b32_e64 v15, v5, v15, s[4:5]
	v_cndmask_b32_e32 v2, v2, v123, vcc
	v_cndmask_b32_e64 v5, v90, v58, s[0:1]
	v_cndmask_b32_e64 v31, v2, v5, s[4:5]
	v_cndmask_b32_e32 v2, v8, v122, vcc
	v_cndmask_b32_e64 v5, v89, v57, s[0:1]
	v_cndmask_b32_e64 v8, v2, v5, s[4:5]
	v_cndmask_b32_e32 v2, v16, v121, vcc
	v_cndmask_b32_e64 v5, v88, v56, s[0:1]
	v_cndmask_b32_e64 v32, v2, v5, s[4:5]
	v_cndmask_b32_e32 v2, v21, v120, vcc
	v_cndmask_b32_e64 v5, v87, v55, s[0:1]
	v_cndmask_b32_e64 v21, v2, v5, s[4:5]
	v_cndmask_b32_e32 v1, v1, v119, vcc
	v_cndmask_b32_e64 v2, v86, v54, s[0:1]
	v_cndmask_b32_e64 v34, v1, v2, s[4:5]
	v_cndmask_b32_e32 v1, v10, v118, vcc
	v_cndmask_b32_e64 v2, v85, v53, s[0:1]
	v_cndmask_b32_e64 v41, v1, v2, s[4:5]
	v_cndmask_b32_e32 v1, v20, v117, vcc
	v_cndmask_b32_e64 v2, v84, v52, s[0:1]
	v_cndmask_b32_e64 v44, v1, v2, s[4:5]
	v_cndmask_b32_e32 v1, v22, v116, vcc
	v_cndmask_b32_e64 v2, v83, v51, s[0:1]
	v_cndmask_b32_e64 v45, v1, v2, s[4:5]
	v_cndmask_b32_e32 v1, v12, v115, vcc
	v_cndmask_b32_e64 v2, v82, v50, s[0:1]
	v_cndmask_b32_e64 v50, v1, v2, s[4:5]
	v_cndmask_b32_e32 v1, v14, v114, vcc
	v_cndmask_b32_e64 v2, v81, v49, s[0:1]
	v_cndmask_b32_e64 v49, v1, v2, s[4:5]
	v_cndmask_b32_e32 v1, v17, v112, vcc
	v_cndmask_b32_e64 v2, v80, v48, s[0:1]
	v_cndmask_b32_e64 v48, v1, v2, s[4:5]
	v_cndmask_b32_e32 v1, v18, v111, vcc
	v_cndmask_b32_e64 v2, v79, v47, s[0:1]
	v_cndmask_b32_e64 v47, v1, v2, s[4:5]
	v_cndmask_b32_e32 v0, v0, v110, vcc
	v_cndmask_b32_e64 v1, v78, v46, s[0:1]
	v_cndmask_b32_e64 v46, v0, v1, s[4:5]
	v_and_b32_e32 v0, 0x7fffff80, v4
	v_bitop3_b32 v1, v4, s19, v4 bitop3:0xcf
	v_cmp_gt_i32_e32 vcc, 0, v4
	v_bitop3_b32 v2, v4, s19, v4 bitop3:0xc
	v_bitop3_b32 v4, v23, s19, v23 bitop3:0xcf
	v_cndmask_b32_e32 v20, v1, v0, vcc
	v_and_b32_e32 v0, 0x7fffff80, v3
	v_bitop3_b32 v1, v3, s19, v3 bitop3:0xcf
	v_cmp_gt_i32_e32 vcc, 0, v3
	v_add_u32_e32 v5, 0, v6
	v_bitop3_b32 v3, v3, s19, v3 bitop3:0xc
	v_cndmask_b32_e32 v1, v1, v0, vcc
	v_and_b32_e32 v0, 0x7fffff80, v23
	v_cmp_gt_i32_e32 vcc, 0, v23
	v_bitop3_b32 v14, v31, s19, v31 bitop3:0xcf
	v_bitop3_b32 v6, v24, s19, v24 bitop3:0xc
	v_cndmask_b32_e32 v18, v4, v0, vcc
	v_and_b32_e32 v0, 0x7fffff80, v30
	v_bitop3_b32 v4, v30, s19, v30 bitop3:0xcf
	v_cmp_gt_i32_e32 vcc, 0, v30
	v_bitop3_b32 v10, v15, s19, v15 bitop3:0xc
	v_bitop3_b32 v16, v32, s19, v32 bitop3:0xcf
	v_cndmask_b32_e32 v0, v4, v0, vcc
	v_bitop3_b32 v4, v23, s19, v23 bitop3:0xc
	ds_write2_b32 v5, v2, v4 offset1:1
	v_bitop3_b32 v2, v30, s19, v30 bitop3:0xc
	ds_write2_b32 v5, v3, v2 offset0:16 offset1:17
	v_and_b32_e32 v2, 0x7fffff80, v24
	v_bitop3_b32 v3, v24, s19, v24 bitop3:0xcf
	v_cmp_gt_i32_e32 vcc, 0, v24
	v_bitop3_b32 v4, v25, s19, v25 bitop3:0xcf
	v_bitop3_b32 v22, v29, s19, v29 bitop3:0xcf
	v_cndmask_b32_e32 v12, v3, v2, vcc
	v_and_b32_e32 v2, 0x7fffff80, v15
	v_bitop3_b32 v3, v15, s19, v15 bitop3:0xcf
	v_cmp_gt_i32_e32 vcc, 0, v15
	v_bitop3_b32 v15, v27, s19, v27 bitop3:0xcf
	v_bitop3_b32 v24, v34, s19, v34 bitop3:0xcf
	v_cndmask_b32_e32 v3, v3, v2, vcc
	v_and_b32_e32 v2, 0x7fffff80, v25
	v_cmp_gt_i32_e32 vcc, 0, v25
	s_nop 1
	v_cndmask_b32_e32 v4, v4, v2, vcc
	v_and_b32_e32 v2, 0x7fffff80, v31
	v_cmp_gt_i32_e32 vcc, 0, v31
	s_nop 1
	v_cndmask_b32_e32 v2, v14, v2, vcc
	v_bitop3_b32 v14, v25, s19, v25 bitop3:0xc
	ds_write2_b32 v5, v6, v14 offset0:2 offset1:3
	v_bitop3_b32 v6, v31, s19, v31 bitop3:0xc
	ds_write2_b32 v5, v10, v6 offset0:18 offset1:19
	v_and_b32_e32 v6, 0x7fffff80, v26
	v_bitop3_b32 v10, v26, s19, v26 bitop3:0xcf
	v_cmp_gt_i32_e32 vcc, 0, v26
	v_bitop3_b32 v25, v36, s19, v36 bitop3:0xcf
	s_nop 0
	v_cndmask_b32_e32 v14, v10, v6, vcc
	v_and_b32_e32 v6, 0x7fffff80, v8
	v_bitop3_b32 v10, v8, s19, v8 bitop3:0xcf
	v_cmp_gt_i32_e32 vcc, 0, v8
	v_bitop3_b32 v8, v8, s19, v8 bitop3:0xc
	s_nop 0
	v_cndmask_b32_e32 v17, v10, v6, vcc
	v_and_b32_e32 v10, 0x7fffff80, v27
	v_cmp_gt_i32_e32 vcc, 0, v27
	v_bitop3_b32 v6, v26, s19, v26 bitop3:0xc
	v_bitop3_b32 v26, v43, s19, v43 bitop3:0xcf
	v_cndmask_b32_e32 v10, v15, v10, vcc
	v_and_b32_e32 v15, 0x7fffff80, v32
	v_cmp_gt_i32_e32 vcc, 0, v32
	s_nop 1
	v_cndmask_b32_e32 v16, v16, v15, vcc
	v_bitop3_b32 v15, v27, s19, v27 bitop3:0xc
	ds_write2_b32 v5, v6, v15 offset0:4 offset1:5
	v_bitop3_b32 v6, v32, s19, v32 bitop3:0xc
	ds_write2_b32 v5, v8, v6 offset0:20 offset1:21
	v_and_b32_e32 v6, 0x7fffff80, v28
; __device__ __forceinline__ float key2f(unsigned k) { const unsigned u = (k & 0x80000000u) ? (k & 0x7fffffffu) : ~k; return __uint_as_float(u); }
; #define CK(i, j) ((f2key(va[i] + vb[j]) & ~255u) | (unsigned)(255 - (16 * (i) + (j))))
; __device__ __forceinline__ void peer_tile(const Args& A, LAS unsigned char* lds, int tile) {
;     ...
;             for (int i = 0; i < 16; ++i) { va[i] = key2f(L2[0][i] & ~127u); vb[i] = key2f(L2[1][i] & ~127u); idx[i] = 127u - (L2[0][i] & 127u); idx[16 + i] = 127u - (L2[1][i] & 127u); }
;     ...
;             unsigned Lf[16], Bt[16];
; #pragma unroll
;             for (int j = 0; j < 16; ++j) Lf[j] = CK(0, j);
	v_bitop3_b32 v8, v28, s19, v28 bitop3:0xcf
	v_cmp_gt_i32_e32 vcc, 0, v28
	v_bitop3_b32 v15, v21, s19, v21 bitop3:0xcf
	s_nop 0
	v_cndmask_b32_e32 v8, v8, v6, vcc
	v_and_b32_e32 v6, 0x7fffff80, v21
	v_cmp_gt_i32_e32 vcc, 0, v21
	v_bitop3_b32 v21, v21, s19, v21 bitop3:0xc
	s_nop 0
	v_cndmask_b32_e32 v23, v15, v6, vcc
	v_and_b32_e32 v6, 0x7fffff80, v29
	v_cmp_gt_i32_e32 vcc, 0, v29
	v_bitop3_b32 v15, v28, s19, v28 bitop3:0xc
	s_nop 0
	v_cndmask_b32_e32 v6, v22, v6, vcc
	v_and_b32_e32 v22, 0x7fffff80, v34
	v_cmp_gt_i32_e32 vcc, 0, v34
	s_nop 1
	v_cndmask_b32_e32 v22, v24, v22, vcc
	v_bitop3_b32 v24, v29, s19, v29 bitop3:0xc
	ds_write2_b32 v5, v15, v24 offset0:6 offset1:7
	v_bitop3_b32 v15, v34, s19, v34 bitop3:0xc
	ds_write2_b32 v5, v21, v15 offset0:22 offset1:23
	v_and_b32_e32 v15, 0x7fffff80, v37
	v_bitop3_b32 v21, v37, s19, v37 bitop3:0xcf
	v_cmp_gt_i32_e32 vcc, 0, v37
	v_and_b32_e32 v24, 0x7fffff80, v36
	s_nop 0
	v_cndmask_b32_e32 v27, v21, v15, vcc
	v_and_b32_e32 v15, 0x7fffff80, v41
	v_bitop3_b32 v21, v41, s19, v41 bitop3:0xcf
	v_cmp_gt_i32_e32 vcc, 0, v41
	s_nop 1
	v_cndmask_b32_e32 v35, v21, v15, vcc
	v_cmp_gt_i32_e32 vcc, 0, v36
	v_bitop3_b32 v15, v37, s19, v37 bitop3:0xc
	v_bitop3_b32 v21, v41, s19, v41 bitop3:0xc
	v_cndmask_b32_e32 v28, v25, v24, vcc
	v_and_b32_e32 v24, 0x7fffff80, v44
	v_bitop3_b32 v25, v44, s19, v44 bitop3:0xcf
	v_cmp_gt_i32_e32 vcc, 0, v44
	s_nop 1
	v_cndmask_b32_e32 v34, v25, v24, vcc
	v_bitop3_b32 v24, v36, s19, v36 bitop3:0xc
	ds_write2_b32 v5, v15, v24 offset0:8 offset1:9
	v_bitop3_b32 v15, v44, s19, v44 bitop3:0xc
	ds_write2_b32 v5, v21, v15 offset0:24 offset1:25
	v_and_b32_e32 v15, 0x7fffff80, v38
	v_bitop3_b32 v21, v38, s19, v38 bitop3:0xcf
	v_cmp_gt_i32_e32 vcc, 0, v38
	v_and_b32_e32 v24, 0x7fffff80, v39
	v_bitop3_b32 v25, v39, s19, v39 bitop3:0xcf
	v_cndmask_b32_e32 v29, v21, v15, vcc
	v_and_b32_e32 v15, 0x7fffff80, v45
	v_bitop3_b32 v21, v45, s19, v45 bitop3:0xcf
	v_cmp_gt_i32_e32 vcc, 0, v45
	s_nop 1
	v_cndmask_b32_e32 v37, v21, v15, vcc
	v_cmp_gt_i32_e32 vcc, 0, v39
	v_bitop3_b32 v15, v38, s19, v38 bitop3:0xc
	v_bitop3_b32 v21, v45, s19, v45 bitop3:0xc
	v_cndmask_b32_e32 v30, v25, v24, vcc
	v_and_b32_e32 v24, 0x7fffff80, v50
	v_bitop3_b32 v25, v50, s19, v50 bitop3:0xcf
	v_cmp_gt_i32_e32 vcc, 0, v50
	s_nop 1
	v_cndmask_b32_e32 v36, v25, v24, vcc
	v_bitop3_b32 v24, v39, s19, v39 bitop3:0xc
	ds_write2_b32 v5, v15, v24 offset0:10 offset1:11
	v_bitop3_b32 v15, v50, s19, v50 bitop3:0xc
	ds_write2_b32 v5, v21, v15 offset0:26 offset1:27
	v_and_b32_e32 v15, 0x7fffff80, v33
	v_bitop3_b32 v21, v33, s19, v33 bitop3:0xcf
	v_cmp_gt_i32_e32 vcc, 0, v33
	v_and_b32_e32 v24, 0x7fffff80, v40
	v_bitop3_b32 v25, v40, s19, v40 bitop3:0xcf
	v_cndmask_b32_e32 v31, v21, v15, vcc
	v_and_b32_e32 v15, 0x7fffff80, v49
	v_bitop3_b32 v21, v49, s19, v49 bitop3:0xcf
	v_cmp_gt_i32_e32 vcc, 0, v49
	s_nop 1
	v_cndmask_b32_e32 v39, v21, v15, vcc
	v_cmp_gt_i32_e32 vcc, 0, v40
	v_bitop3_b32 v15, v33, s19, v33 bitop3:0xc
	v_bitop3_b32 v21, v49, s19, v49 bitop3:0xc
	v_cndmask_b32_e32 v32, v25, v24, vcc
	v_and_b32_e32 v24, 0x7fffff80, v48
	v_bitop3_b32 v25, v48, s19, v48 bitop3:0xcf
	v_cmp_gt_i32_e32 vcc, 0, v48
	v_bitop3_b32 v33, v46, s19, v46 bitop3:0xcf
	s_nop 0
	v_cndmask_b32_e32 v38, v25, v24, vcc
	v_bitop3_b32 v24, v40, s19, v40 bitop3:0xc
	ds_write2_b32 v5, v15, v24 offset0:12 offset1:13
	v_bitop3_b32 v15, v48, s19, v48 bitop3:0xc
	ds_write2_b32 v5, v21, v15 offset0:28 offset1:29
	v_and_b32_e32 v15, 0x7fffff80, v42
	v_bitop3_b32 v21, v42, s19, v42 bitop3:0xcf
	v_cmp_gt_i32_e32 vcc, 0, v42
	v_and_b32_e32 v24, 0x7fffff80, v43
	s_nop 0
	v_cndmask_b32_e32 v25, v21, v15, vcc
	v_and_b32_e32 v15, 0x7fffff80, v47
	v_bitop3_b32 v21, v47, s19, v47 bitop3:0xcf
	v_cmp_gt_i32_e32 vcc, 0, v47
	s_nop 1
	v_cndmask_b32_e32 v41, v21, v15, vcc
	v_cmp_gt_i32_e32 vcc, 0, v43
	v_bitop3_b32 v21, v47, s19, v47 bitop3:0xc
	v_bitop3_b32 v15, v42, s19, v42 bitop3:0xc
	v_cndmask_b32_e32 v26, v26, v24, vcc
	v_and_b32_e32 v24, 0x7fffff80, v46
	v_cmp_gt_i32_e32 vcc, 0, v46
	v_pk_add_f32 v[34:35], v[20:21], v[34:35] op_sel_hi:[0,1]
	s_nop 0
	v_cndmask_b32_e32 v40, v33, v24, vcc
	v_bitop3_b32 v24, v43, s19, v43 bitop3:0xc
	v_pk_add_f32 v[42:43], v[20:21], v[0:1] op_sel_hi:[0,1]
	ds_write2_b32 v5, v15, v24 offset0:14 offset1:15
	v_not_b32_e32 v15, v43
	v_or_b32_e32 v33, 0x80000000, v43
	v_cmp_gt_i32_e32 vcc, 0, v43
	v_or_b32_e32 v43, 0x80000000, v42
	v_bitop3_b32 v24, v46, s19, v46 bitop3:0xc
	v_cndmask_b32_e32 v15, v33, v15, vcc
	v_or_b32_e32 v33, 0xff, v15
	v_not_b32_e32 v15, v42
	v_cmp_gt_i32_e32 vcc, 0, v42
	ds_write2_b32 v5, v21, v24 offset0:30 offset1:31
	s_waitcnt lgkmcnt(0)
; #define CK(i, j) ((f2key(va[i] + vb[j]) & ~255u) | (unsigned)(255 - (16 * (i) + (j))))
; __device__ __forceinline__ void peer_tile(const Args& A, LAS unsigned char* lds, int tile) {
;     ...
;             unsigned Lf[16], Bt[16];
; #pragma unroll
;             for (int j = 0; j < 16; ++j) Lf[j] = CK(0, j);
; #pragma unroll
;             for (int j = 0; j < 8; ++j) Bt[j] = CK(1, j);
; #pragma unroll
;             for (int j = 0; j < 5; ++j) Bt[8 + j] = CK(2, j);
	s_nop 0
	v_cndmask_b32_e32 v15, v43, v15, vcc
	v_and_b32_e32 v15, 0xffffff00, v15
	v_pk_add_f32 v[42:43], v[20:21], v[2:3] op_sel_hi:[0,1]
	v_or_b32_e32 v44, 0xfe, v15
	v_not_b32_e32 v15, v43
	v_or_b32_e32 v45, 0x80000000, v43
	v_cmp_gt_i32_e32 vcc, 0, v43
	v_or_b32_e32 v43, 0x80000000, v42
	s_nop 0
	v_cndmask_b32_e32 v15, v45, v15, vcc
	v_and_b32_e32 v15, 0xffffff00, v15
	v_or_b32_e32 v45, 0xfd, v15
	v_not_b32_e32 v15, v42
	v_cmp_gt_i32_e32 vcc, 0, v42
	s_nop 1
	v_cndmask_b32_e32 v15, v43, v15, vcc
	v_and_b32_e32 v15, 0xffffff00, v15
	v_pk_add_f32 v[42:43], v[20:21], v[16:17] op_sel_hi:[0,1]
	v_or_b32_e32 v46, 0xfc, v15
	v_not_b32_e32 v15, v43
	v_or_b32_e32 v47, 0x80000000, v43
	v_cmp_gt_i32_e32 vcc, 0, v43
	v_or_b32_e32 v43, 0x80000000, v42
	s_nop 0
	v_cndmask_b32_e32 v15, v47, v15, vcc
	v_and_b32_e32 v15, 0xffffff00, v15
	v_or_b32_e32 v47, 0xfb, v15
	v_not_b32_e32 v15, v42
	v_cmp_gt_i32_e32 vcc, 0, v42
	s_nop 1
	v_cndmask_b32_e32 v15, v43, v15, vcc
	v_and_b32_e32 v15, 0xffffff00, v15
	v_pk_add_f32 v[42:43], v[20:21], v[22:23] op_sel_hi:[0,1]
	v_or_b32_e32 v48, 0xfa, v15
	v_not_b32_e32 v15, v43
	v_or_b32_e32 v49, 0x80000000, v43
	v_cmp_gt_i32_e32 vcc, 0, v43
	v_pk_add_f32 v[22:23], v[18:19], v[22:23] op_sel_hi:[0,1]
	s_nop 0
	v_cndmask_b32_e32 v15, v49, v15, vcc
	v_and_b32_e32 v15, 0xffffff00, v15
	v_or_b32_e32 v43, 0xf9, v15
	v_not_b32_e32 v15, v42
	v_or_b32_e32 v49, 0x80000000, v42
	v_cmp_gt_i32_e32 vcc, 0, v42
	s_nop 1
	v_cndmask_b32_e32 v15, v49, v15, vcc
	v_and_b32_e32 v15, 0xffffff00, v15
	v_or_b32_e32 v42, 0xf8, v15
	v_not_b32_e32 v15, v35
	v_or_b32_e32 v49, 0x80000000, v35
	v_cmp_gt_i32_e32 vcc, 0, v35
	v_or_b32_e32 v35, 0x80000000, v34
	s_nop 0
	v_cndmask_b32_e32 v15, v49, v15, vcc
	v_and_b32_e32 v15, 0xffffff00, v15
	v_or_b32_e32 v49, 0xf7, v15
	v_not_b32_e32 v15, v34
	v_cmp_gt_i32_e32 vcc, 0, v34
	s_nop 1
	v_cndmask_b32_e32 v15, v35, v15, vcc
	v_and_b32_e32 v15, 0xffffff00, v15
	v_pk_add_f32 v[34:35], v[20:21], v[36:37] op_sel_hi:[0,1]
	v_or_b32_e32 v50, 0xf6, v15
	v_not_b32_e32 v15, v35
	v_or_b32_e32 v36, 0x80000000, v35
	v_cmp_gt_i32_e32 vcc, 0, v35
	v_or_b32_e32 v35, 0x80000000, v34
	s_nop 0
	v_cndmask_b32_e32 v15, v36, v15, vcc
	v_and_b32_e32 v15, 0xffffff00, v15
	v_or_b32_e32 v36, 0xf5, v15
	v_not_b32_e32 v15, v34
	v_cmp_gt_i32_e32 vcc, 0, v34
	s_nop 1
	v_cndmask_b32_e32 v15, v35, v15, vcc
	v_and_b32_e32 v15, 0xffffff00, v15
	v_pk_add_f32 v[34:35], v[20:21], v[38:39] op_sel_hi:[0,1]
	v_or_b32_e32 v37, 0xf4, v15
	v_not_b32_e32 v15, v35
	v_or_b32_e32 v38, 0x80000000, v35
	v_cmp_gt_i32_e32 vcc, 0, v35
	v_or_b32_e32 v35, 0x80000000, v34
	s_nop 0
	v_cndmask_b32_e32 v15, v38, v15, vcc
	v_and_b32_e32 v15, 0xffffff00, v15
	v_or_b32_e32 v38, 0xf3, v15
	v_not_b32_e32 v15, v34
	v_cmp_gt_i32_e32 vcc, 0, v34
	s_nop 1
	v_cndmask_b32_e32 v15, v35, v15, vcc
	v_and_b32_e32 v15, 0xffffff00, v15
	v_pk_add_f32 v[34:35], v[20:21], v[40:41] op_sel_hi:[0,1]
	v_or_b32_e32 v39, 0xf2, v15
	v_not_b32_e32 v15, v35
	v_or_b32_e32 v20, 0x80000000, v35
	v_cmp_gt_i32_e32 vcc, 0, v35
	v_or_b32_e32 v35, 0x80000000, v34
	s_nop 0
	v_cndmask_b32_e32 v15, v20, v15, vcc
	v_and_b32_e32 v15, 0xffffff00, v15
	v_or_b32_e32 v20, 0xf1, v15
	v_not_b32_e32 v15, v34
	v_cmp_gt_i32_e32 vcc, 0, v34
	s_nop 1
	v_cndmask_b32_e32 v15, v35, v15, vcc
	v_and_b32_e32 v15, 0xffffff00, v15
	v_pk_add_f32 v[34:35], v[18:19], v[0:1] op_sel_hi:[0,1]
	v_or_b32_e32 v40, 0xf0, v15
	v_not_b32_e32 v15, v35
	v_or_b32_e32 v41, 0x80000000, v35
	v_cmp_gt_i32_e32 vcc, 0, v35
	v_or_b32_e32 v35, 0x80000000, v34
	s_nop 0
	v_cndmask_b32_e32 v15, v41, v15, vcc
	v_and_b32_e32 v15, 0xffffff00, v15
	v_or_b32_e32 v41, 0xef, v15
	v_not_b32_e32 v15, v34
	v_cmp_gt_i32_e32 vcc, 0, v34
	s_nop 1
	v_cndmask_b32_e32 v15, v35, v15, vcc
	v_and_b32_e32 v15, 0xffffff00, v15
	v_pk_add_f32 v[34:35], v[18:19], v[2:3] op_sel_hi:[0,1]
	v_or_b32_e32 v51, 0xee, v15
	v_not_b32_e32 v15, v35
	v_or_b32_e32 v52, 0x80000000, v35
	v_cmp_gt_i32_e32 vcc, 0, v35
	v_or_b32_e32 v35, 0x80000000, v34
	s_nop 0
	v_cndmask_b32_e32 v15, v52, v15, vcc
	v_and_b32_e32 v15, 0xffffff00, v15
	v_or_b32_e32 v52, 0xed, v15
	v_not_b32_e32 v15, v34
	v_cmp_gt_i32_e32 vcc, 0, v34
	s_nop 1
	v_cndmask_b32_e32 v15, v35, v15, vcc
	v_and_b32_e32 v15, 0xffffff00, v15
	v_pk_add_f32 v[34:35], v[18:19], v[16:17] op_sel_hi:[0,1]
	v_or_b32_e32 v53, 0xec, v15
	v_not_b32_e32 v15, v35
	v_or_b32_e32 v16, 0x80000000, v35
	v_cmp_gt_i32_e32 vcc, 0, v35
	s_nop 1
	v_cndmask_b32_e32 v15, v16, v15, vcc
	v_and_b32_e32 v15, 0xffffff00, v15
	v_or_b32_e32 v35, 0xeb, v15
	v_not_b32_e32 v15, v34
	v_or_b32_e32 v16, 0x80000000, v34
	v_cmp_gt_i32_e32 vcc, 0, v34
	s_nop 1
	v_cndmask_b32_e32 v15, v16, v15, vcc
	v_and_b32_e32 v15, 0xffffff00, v15
	v_or_b32_e32 v34, 0xea, v15
	v_not_b32_e32 v15, v23
	v_or_b32_e32 v16, 0x80000000, v23
	v_cmp_gt_i32_e32 vcc, 0, v23
	s_nop 1
	v_cndmask_b32_e32 v15, v16, v15, vcc
	v_and_b32_e32 v15, 0xffffff00, v15
	v_or_b32_e32 v18, 0xe9, v15
	v_not_b32_e32 v15, v22
	v_or_b32_e32 v16, 0x80000000, v22
	v_cmp_gt_i32_e32 vcc, 0, v22
	v_pk_add_f32 v[22:23], v[12:13], v[0:1] op_sel_hi:[0,1]
	s_nop 0
	v_cndmask_b32_e32 v15, v16, v15, vcc
	v_and_b32_e32 v15, 0xffffff00, v15
	v_or_b32_e32 v54, 0xe8, v15
	v_not_b32_e32 v15, v23
	v_or_b32_e32 v16, 0x80000000, v23
	v_cmp_gt_i32_e32 vcc, 0, v23
	s_nop 1
	v_cndmask_b32_e32 v15, v16, v15, vcc
	v_and_b32_e32 v15, 0xffffff00, v15
	v_or_b32_e32 v55, 0xdf, v15
	v_not_b32_e32 v15, v22
	v_or_b32_e32 v16, 0x80000000, v22
	v_cmp_gt_i32_e32 vcc, 0, v22
	v_pk_add_f32 v[22:23], v[12:13], v[2:3] op_sel_hi:[0,1]
	v_lshl_add_u32 v13, v13, 10, s35
	v_cndmask_b32_e32 v15, v16, v15, vcc
	v_and_b32_e32 v15, 0xffffff00, v15
; #define CE_DESC(a, b) do { const unsigned _mx = (a) > (b) ? (a) : (b), _mn = (a) > (b) ? (b) : (a); (a) = _mx; (b) = _mn; } while (0)
; #define CK(i, j) ((f2key(va[i] + vb[j]) & ~255u) | (unsigned)(255 - (16 * (i) + (j))))
; __device__ __forceinline__ void sort16_desc(unsigned (&k)[16]) {
; #pragma unroll
;     for (int size = 2; size <= 16; size <<= 1)
; #pragma unroll
;         for (int stride = size >> 1; stride > 0; stride >>= 1)
; #pragma unroll
;             for (int i = 0; i < 16; ++i) { const int j = i ^ stride;
;                 if (j > i) { if ((i & size) == 0) CE_DESC(k[i], k[j]); else CE_DESC(k[j], k[i]); } }
; }
; __device__ __forceinline__ void peer_tile(const Args& A, LAS unsigned char* lds, int tile) {
;     ...
;             unsigned Lf[16], Bt[16];
; #pragma unroll
;             for (int j = 0; j < 16; ++j) Lf[j] = CK(0, j);
; #pragma unroll
;             for (int j = 0; j < 8; ++j) Bt[j] = CK(1, j);
; #pragma unroll
;             for (int j = 0; j < 5; ++j) Bt[8 + j] = CK(2, j);
; #pragma unroll
;             for (int j = 0; j < 3; ++j) Bt[13 + j] = CK(4, j);
;             sort16_desc(Bt); merge16(Lf, Bt);
	v_or_b32_e32 v56, 0xde, v15
	v_not_b32_e32 v15, v23
	v_or_b32_e32 v16, 0x80000000, v23
	v_cmp_gt_i32_e32 vcc, 0, v23
	s_nop 1
	v_cndmask_b32_e32 v15, v16, v15, vcc
	v_and_b32_e32 v15, 0xffffff00, v15
	v_or_b32_e32 v23, 0xdd, v15
	v_not_b32_e32 v15, v22
	v_or_b32_e32 v16, 0x80000000, v22
	v_cmp_gt_i32_e32 vcc, 0, v22
	s_nop 1
	v_cndmask_b32_e32 v15, v16, v15, vcc
	v_and_b32_e32 v15, 0xffffff00, v15
	v_or_b32_e32 v22, 0xdc, v15
	v_mov_b32_e32 v15, v12
	v_mov_b32_e32 v16, v1
	v_pk_add_f32 v[16:17], v[14:15], v[16:17]
	s_nop 0
	v_not_b32_e32 v12, v17
	v_or_b32_e32 v15, 0x80000000, v17
	v_cmp_gt_i32_e32 vcc, 0, v17
	v_or_b32_e32 v17, 0x80000000, v16
	s_nop 0
	v_cndmask_b32_e32 v12, v15, v12, vcc
	v_not_b32_e32 v15, v16
	v_cmp_gt_i32_e32 vcc, 0, v16
	v_mov_b32_e32 v16, v3
	v_and_b32_e32 v12, 0xffffff00, v12
	v_cndmask_b32_e32 v15, v17, v15, vcc
	v_and_b32_e32 v15, 0xffffff00, v15
	v_mov_b32_e32 v17, v0
	v_or_b32_e32 v57, 0xbf, v15
	v_pk_add_f32 v[14:15], v[14:15], v[16:17] op_sel_hi:[0,1]
	v_not_b32_e32 v16, v15
	v_or_b32_e32 v17, 0x80000000, v15
	v_cmp_gt_i32_e32 vcc, 0, v15
	v_or_b32_e32 v12, 0xdb, v12
	v_pk_add_f32 v[2:3], v[4:5], v[2:3] op_sel_hi:[0,1]
	v_cndmask_b32_e32 v15, v17, v16, vcc
	v_not_b32_e32 v16, v14
	v_or_b32_e32 v17, 0x80000000, v14
	v_cmp_gt_i32_e32 vcc, 0, v14
	v_and_b32_e32 v15, 0xffffff00, v15
	v_or_b32_e32 v15, 0xbe, v15
	v_cndmask_b32_e32 v14, v17, v16, vcc
	v_and_b32_e32 v14, 0xffffff00, v14
	v_or_b32_e32 v14, 0xbd, v14
	v_max_u32_e32 v16, v41, v51
	v_min_u32_e32 v17, v41, v51
	v_max_u32_e32 v41, v53, v52
	v_min_u32_e32 v51, v53, v52
	v_max_u32_e32 v52, v35, v34
	v_min_u32_e32 v34, v35, v34
	v_max_u32_e32 v35, v54, v18
	v_min_u32_e32 v18, v54, v18
	v_max_u32_e32 v53, v55, v56
	v_min_u32_e32 v54, v55, v56
	v_max_u32_e32 v55, v22, v23
	v_min_u32_e32 v22, v22, v23
	v_max_u32_e32 v23, v12, v57
	v_min_u32_e32 v12, v12, v57
	v_max_u32_e32 v56, v14, v15
	v_min_u32_e32 v14, v14, v15
	v_max_u32_e32 v15, v16, v51
	v_min_u32_e32 v16, v16, v51
	v_max_u32_e32 v51, v17, v41
	v_min_u32_e32 v17, v17, v41
	v_max_u32_e32 v41, v18, v52
	v_min_u32_e32 v18, v18, v52
	v_max_u32_e32 v52, v35, v34
	v_min_u32_e32 v34, v35, v34
	v_max_u32_e32 v35, v53, v22
	v_min_u32_e32 v22, v53, v22
	v_max_u32_e32 v53, v54, v55
	v_min_u32_e32 v54, v54, v55
	v_max_u32_e32 v55, v14, v23
	v_min_u32_e32 v14, v14, v23
	v_max_u32_e32 v23, v56, v12
	v_min_u32_e32 v12, v56, v12
	v_max_u32_e32 v56, v15, v51
	v_min_u32_e32 v15, v15, v51
	v_max_u32_e32 v51, v16, v17
	v_min_u32_e32 v16, v16, v17
	v_max_u32_e32 v17, v34, v18
	v_min_u32_e32 v18, v34, v18
	v_max_u32_e32 v34, v52, v41
	v_min_u32_e32 v41, v52, v41
	v_max_u32_e32 v52, v35, v53
	v_min_u32_e32 v35, v35, v53
	v_max_u32_e32 v53, v22, v54
	v_min_u32_e32 v22, v22, v54
	v_max_u32_e32 v54, v12, v14
	v_min_u32_e32 v12, v12, v14
	v_max_u32_e32 v14, v23, v55
	v_min_u32_e32 v23, v23, v55
	v_max_u32_e32 v55, v56, v18
	v_min_u32_e32 v18, v56, v18
	v_max_u32_e32 v56, v15, v17
	v_min_u32_e32 v15, v15, v17
	v_max_u32_e32 v17, v51, v41
	v_min_u32_e32 v41, v51, v41
	v_max_u32_e32 v51, v16, v34
	v_min_u32_e32 v16, v16, v34
	v_max_u32_e32 v34, v12, v52
	v_min_u32_e32 v12, v12, v52
	v_max_u32_e32 v52, v54, v35
	v_min_u32_e32 v35, v54, v35
	v_max_u32_e32 v54, v23, v53
	v_min_u32_e32 v23, v23, v53
	v_max_u32_e32 v53, v14, v22
	v_min_u32_e32 v14, v14, v22
	v_max_u32_e32 v22, v55, v17
	v_min_u32_e32 v17, v55, v17
	v_max_u32_e32 v55, v56, v51
	v_min_u32_e32 v51, v56, v51
	v_max_u32_e32 v56, v18, v41
	v_min_u32_e32 v18, v18, v41
	v_max_u32_e32 v41, v15, v16
	v_min_u32_e32 v15, v15, v16
	v_max_u32_e32 v16, v23, v12
	v_min_u32_e32 v12, v23, v12
	v_max_u32_e32 v23, v14, v35
	v_min_u32_e32 v14, v14, v35
	v_max_u32_e32 v35, v54, v34
	v_min_u32_e32 v34, v54, v34
	v_max_u32_e32 v54, v53, v52
	v_min_u32_e32 v52, v53, v52
	v_max_u32_e32 v53, v22, v55
	v_min_u32_e32 v22, v22, v55
	v_max_u32_e32 v55, v17, v51
	v_min_u32_e32 v17, v17, v51
	v_max_u32_e32 v51, v56, v41
	v_min_u32_e32 v41, v56, v41
	v_max_u32_e32 v56, v18, v15
	v_min_u32_e32 v15, v18, v15
	v_max_u32_e32 v18, v14, v12
	v_min_u32_e32 v12, v14, v12
	v_max_u32_e32 v14, v23, v16
	v_min_u32_e32 v16, v23, v16
	v_max_u32_e32 v23, v52, v34
	v_min_u32_e32 v34, v52, v34
	v_max_u32_e32 v52, v54, v35
	v_min_u32_e32 v35, v54, v35
	v_max_u32_e32 v54, v53, v12
	v_min_u32_e32 v12, v53, v12
	v_max_u32_e32 v53, v22, v18
	v_min_u32_e32 v18, v22, v18
	v_max_u32_e32 v22, v55, v16
	v_min_u32_e32 v16, v55, v16
	v_max_u32_e32 v55, v17, v14
	v_min_u32_e32 v14, v17, v14
	v_max_u32_e32 v17, v51, v34
	v_min_u32_e32 v34, v51, v34
	v_max_u32_e32 v51, v41, v23
	v_min_u32_e32 v23, v41, v23
	v_max_u32_e32 v41, v56, v35
	v_min_u32_e32 v35, v56, v35
	v_max_u32_e32 v56, v15, v52
	v_min_u32_e32 v15, v15, v52
	v_max_u32_e32 v52, v54, v17
	v_min_u32_e32 v17, v54, v17
	v_max_u32_e32 v54, v53, v51
	v_min_u32_e32 v51, v53, v51
	v_max_u32_e32 v53, v22, v41
	v_min_u32_e32 v22, v22, v41
	v_max_u32_e32 v41, v55, v56
	v_min_u32_e32 v55, v55, v56
	v_max_u32_e32 v56, v12, v34
	v_min_u32_e32 v12, v12, v34
	v_max_u32_e32 v34, v18, v23
	v_min_u32_e32 v18, v18, v23
	v_max_u32_e32 v23, v16, v35
	v_min_u32_e32 v16, v16, v35
	v_max_u32_e32 v35, v14, v15
	v_min_u32_e32 v14, v14, v15
	v_max_u32_e32 v15, v52, v53
	v_min_u32_e32 v52, v52, v53
	v_max_u32_e32 v53, v54, v41
	v_min_u32_e32 v41, v54, v41
	v_max_u32_e32 v54, v17, v22
	v_min_u32_e32 v17, v17, v22
	v_max_u32_e32 v22, v51, v55
	v_min_u32_e32 v51, v51, v55
	v_max_u32_e32 v55, v56, v23
	v_min_u32_e32 v23, v56, v23
	v_max_u32_e32 v56, v34, v35
	v_min_u32_e32 v34, v34, v35
	v_max_u32_e32 v35, v12, v16
	v_min_u32_e32 v12, v12, v16
	v_max_u32_e32 v16, v18, v14
	v_min_u32_e32 v14, v18, v14
; #define CE_DESC(a, b) do { const unsigned _mx = (a) > (b) ? (a) : (b), _mn = (a) > (b) ? (b) : (a); (a) = _mx; (b) = _mn; } while (0)
; #define CK(i, j) ((f2key(va[i] + vb[j]) & ~255u) | (unsigned)(255 - (16 * (i) + (j))))
; __device__ __forceinline__ void merge16(unsigned (&a)[16], const unsigned (&b)[16]) {
; #pragma unroll
;     for (int i = 0; i < 16; ++i) a[i] = a[i] > b[15 - i] ? a[i] : b[15 - i];
; #pragma unroll
;     for (int stride = 8; stride > 0; stride >>= 1)
; #pragma unroll
;         for (int i = 0; i < 16; ++i) { const int j = i ^ stride; if (j > i) CE_DESC(a[i], a[j]); }
; }
; __device__ __forceinline__ void peer_tile(const Args& A, LAS unsigned char* lds, int tile) {
;     ...
;             sort16_desc(Bt); merge16(Lf, Bt);
; #pragma unroll
;             for (int j = 0; j < 4; ++j) Bt[j] = CK(3, j);
;             Bt[4] = CK(5, 0); Bt[5] = CK(5, 1); Bt[6] = CK(6, 0); Bt[7] = CK(6, 1); Bt[8] = CK(7, 0); Bt[9] = CK(7, 1);
;             Bt[10] = CK(8, 0); Bt[11] = CK(9, 0); Bt[12] = CK(10, 0); Bt[13] = CK(11, 0); Bt[14] = CK(12, 0); Bt[15] = CK(13, 0);
;             sort16_desc(Bt); merge16(Lf, Bt);
	v_min_u32_e32 v18, v15, v53
	v_min_u32_e32 v57, v52, v41
	v_min_u32_e32 v58, v54, v22
	v_min_u32_e32 v59, v17, v51
	v_min_u32_e32 v60, v55, v56
	v_min_u32_e32 v61, v23, v34
	v_min_u32_e32 v62, v35, v16
	v_min_u32_e32 v63, v12, v14
	v_max_u32_e32 v33, v33, v63
	v_max3_u32 v12, v44, v12, v14
	v_max_u32_e32 v14, v45, v62
	v_max3_u32 v16, v46, v35, v16
	v_max_u32_e32 v35, v47, v61
	v_max3_u32 v23, v48, v23, v34
	v_max_u32_e32 v34, v43, v60
	v_max3_u32 v42, v42, v55, v56
	v_max_u32_e32 v43, v49, v59
	v_max3_u32 v17, v50, v17, v51
	v_max_u32_e32 v36, v36, v58
	v_max3_u32 v22, v37, v54, v22
	v_max_u32_e32 v37, v38, v57
	v_max3_u32 v38, v39, v52, v41
	v_max_u32_e32 v18, v20, v18
	v_max3_u32 v15, v40, v15, v53
	v_max_u32_e32 v20, v33, v43
	v_min_u32_e32 v33, v33, v43
	v_max_u32_e32 v39, v12, v17
	v_min_u32_e32 v12, v12, v17
	v_max_u32_e32 v17, v14, v36
	v_min_u32_e32 v14, v14, v36
	v_max_u32_e32 v36, v16, v22
	v_min_u32_e32 v16, v16, v22
	v_max_u32_e32 v22, v35, v37
	v_min_u32_e32 v35, v35, v37
	v_max_u32_e32 v37, v23, v38
	v_min_u32_e32 v23, v23, v38
	v_max_u32_e32 v38, v34, v18
	v_min_u32_e32 v18, v34, v18
	v_max_u32_e32 v34, v42, v15
	v_min_u32_e32 v15, v42, v15
	v_max_u32_e32 v40, v20, v22
	v_min_u32_e32 v20, v20, v22
	v_max_u32_e32 v22, v39, v37
	v_min_u32_e32 v37, v39, v37
	v_max_u32_e32 v39, v17, v38
	v_min_u32_e32 v17, v17, v38
	v_max_u32_e32 v38, v36, v34
	v_min_u32_e32 v34, v36, v34
	v_max_u32_e32 v36, v33, v35
	v_min_u32_e32 v33, v33, v35
	v_max_u32_e32 v35, v12, v23
	v_min_u32_e32 v12, v12, v23
	v_max_u32_e32 v23, v14, v18
	v_min_u32_e32 v14, v14, v18
	v_max_u32_e32 v18, v16, v15
	v_min_u32_e32 v15, v16, v15
	v_max_u32_e32 v16, v40, v39
	v_min_u32_e32 v39, v40, v39
	v_max_u32_e32 v40, v22, v38
	v_min_u32_e32 v22, v22, v38
	v_max_u32_e32 v38, v20, v17
	v_min_u32_e32 v17, v20, v17
	v_max_u32_e32 v20, v37, v34
	v_min_u32_e32 v34, v37, v34
	v_max_u32_e32 v37, v36, v23
	v_min_u32_e32 v23, v36, v23
	v_max_u32_e32 v36, v35, v18
	v_min_u32_e32 v18, v35, v18
	v_max_u32_e32 v35, v33, v14
	v_min_u32_e32 v33, v33, v14
	v_max_u32_e32 v41, v12, v15
	v_min_u32_e32 v12, v12, v15
	v_pk_add_f32 v[14:15], v[4:5], v[0:1] op_sel_hi:[0,1]
	v_not_b32_e32 v50, v15
	v_or_b32_e32 v51, 0x80000000, v15
	v_cmp_gt_i32_e32 vcc, 0, v15
	v_not_b32_e32 v4, v3
	v_min_u32_e32 v42, v16, v40
	v_cndmask_b32_e32 v15, v51, v50, vcc
	v_not_b32_e32 v50, v14
	v_or_b32_e32 v51, 0x80000000, v14
	v_cmp_gt_i32_e32 vcc, 0, v14
	v_and_b32_e32 v15, 0xffffff00, v15
	v_or_b32_e32 v15, 0xcf, v15
	v_cndmask_b32_e32 v14, v51, v50, vcc
	v_or_b32_e32 v50, 0x80000000, v3
	v_cmp_gt_i32_e32 vcc, 0, v3
	v_and_b32_e32 v14, 0xffffff00, v14
	v_or_b32_e32 v14, 0xce, v14
	v_cndmask_b32_e32 v3, v50, v4, vcc
	v_and_b32_e32 v3, 0xffffff00, v3
	v_or_b32_e32 v4, 0xcd, v3
	v_not_b32_e32 v3, v2
	v_or_b32_e32 v50, 0x80000000, v2
	v_cmp_gt_i32_e32 vcc, 0, v2
	v_min_u32_e32 v43, v39, v22
	v_min_u32_e32 v44, v38, v20
	v_cndmask_b32_e32 v2, v50, v3, vcc
	v_and_b32_e32 v2, 0xffffff00, v2
	v_or_b32_e32 v50, 0xcc, v2
	v_pk_add_f32 v[2:3], v[10:11], v[0:1] op_sel_hi:[0,1]
	v_not_b32_e32 v10, v3
	v_or_b32_e32 v51, 0x80000000, v3
	v_cmp_gt_i32_e32 vcc, 0, v3
	v_min_u32_e32 v45, v17, v34
	v_min_u32_e32 v46, v37, v36
	v_cndmask_b32_e32 v3, v51, v10, vcc
	v_and_b32_e32 v3, 0xffffff00, v3
	v_or_b32_e32 v10, 0xaf, v3
	v_not_b32_e32 v3, v2
	v_or_b32_e32 v51, 0x80000000, v2
	v_cmp_gt_i32_e32 vcc, 0, v2
	v_min_u32_e32 v47, v23, v18
	v_min_u32_e32 v48, v35, v41
	v_cndmask_b32_e32 v2, v51, v3, vcc
	v_and_b32_e32 v2, 0xffffff00, v2
	v_or_b32_e32 v51, 0xae, v2
	v_pk_add_f32 v[2:3], v[8:9], v[0:1] op_sel_hi:[0,1]
	v_not_b32_e32 v8, v3
	v_or_b32_e32 v52, 0x80000000, v3
	v_cmp_gt_i32_e32 vcc, 0, v3
	v_min_u32_e32 v49, v33, v12
	v_lshlrev_b32_e32 v11, 9, v11
	v_cndmask_b32_e32 v3, v52, v8, vcc
	v_and_b32_e32 v3, 0xffffff00, v3
	v_or_b32_e32 v8, 0x9f, v3
	v_not_b32_e32 v3, v2
	v_or_b32_e32 v52, 0x80000000, v2
	v_cmp_gt_i32_e32 vcc, 0, v2
	s_nop 1
	v_cndmask_b32_e32 v2, v52, v3, vcc
	v_and_b32_e32 v2, 0xffffff00, v2
	v_or_b32_e32 v52, 0x9e, v2
	v_pk_add_f32 v[2:3], v[6:7], v[0:1] op_sel_hi:[0,1]
	v_not_b32_e32 v0, v3
	v_or_b32_e32 v6, 0x80000000, v3
	v_cmp_gt_i32_e32 vcc, 0, v3
	v_not_b32_e32 v3, v2
	s_nop 0
	v_cndmask_b32_e32 v0, v6, v0, vcc
	v_or_b32_e32 v6, 0x80000000, v2
	v_cmp_gt_i32_e32 vcc, 0, v2
	v_and_b32_e32 v0, 0xffffff00, v0
	v_or_b32_e32 v0, 0x8f, v0
	v_cndmask_b32_e32 v2, v6, v3, vcc
	v_add_f32_e32 v3, v27, v1
	v_not_b32_e32 v6, v3
	v_or_b32_e32 v27, 0x80000000, v3
	v_cmp_gt_i32_e32 vcc, 0, v3
	v_and_b32_e32 v2, 0xffffff00, v2
	v_or_b32_e32 v2, 0x8e, v2
	v_cndmask_b32_e32 v3, v27, v6, vcc
	v_add_f32_e32 v6, v28, v1
	v_not_b32_e32 v27, v6
	v_or_b32_e32 v28, 0x80000000, v6
	v_cmp_gt_i32_e32 vcc, 0, v6
	v_and_b32_e32 v3, 0xffffff00, v3
	v_or_b32_e32 v3, 0x7f, v3
	v_cndmask_b32_e32 v6, v28, v27, vcc
	v_add_f32_e32 v27, v29, v1
	v_not_b32_e32 v28, v27
	v_or_b32_e32 v29, 0x80000000, v27
	v_cmp_gt_i32_e32 vcc, 0, v27
	v_and_b32_e32 v6, 0xffffff00, v6
	v_or_b32_e32 v6, 0x6f, v6
	v_cndmask_b32_e32 v27, v29, v28, vcc
	v_add_f32_e32 v28, v30, v1
	v_not_b32_e32 v29, v28
	v_or_b32_e32 v30, 0x80000000, v28
	v_cmp_gt_i32_e32 vcc, 0, v28
	v_and_b32_e32 v27, 0xffffff00, v27
	v_or_b32_e32 v27, 0x5f, v27
	v_cndmask_b32_e32 v28, v30, v29, vcc
	v_add_f32_e32 v29, v31, v1
	v_not_b32_e32 v30, v29
	v_or_b32_e32 v31, 0x80000000, v29
	v_cmp_gt_i32_e32 vcc, 0, v29
	v_and_b32_e32 v28, 0xffffff00, v28
	v_or_b32_e32 v28, 0x4f, v28
	v_cndmask_b32_e32 v29, v31, v30, vcc
	v_add_f32_e32 v30, v32, v1
	v_not_b32_e32 v31, v30
	v_or_b32_e32 v32, 0x80000000, v30
	v_cmp_gt_i32_e32 vcc, 0, v30
	v_and_or_b32 v29, v29, s34, 63
	s_nop 0
	v_cndmask_b32_e32 v30, v32, v31, vcc
; #define CE_DESC(a, b) do { const unsigned _mx = (a) > (b) ? (a) : (b), _mn = (a) > (b) ? (b) : (a); (a) = _mx; (b) = _mn; } while (0)
; #define CK(i, j) ((f2key(va[i] + vb[j]) & ~255u) | (unsigned)(255 - (16 * (i) + (j))))
; __device__ __forceinline__ void merge16(unsigned (&a)[16], const unsigned (&b)[16]) {
; #pragma unroll
;     for (int i = 0; i < 16; ++i) a[i] = a[i] > b[15 - i] ? a[i] : b[15 - i];
; #pragma unroll
;     for (int stride = 8; stride > 0; stride >>= 1)
; #pragma unroll
;         for (int i = 0; i < 16; ++i) { const int j = i ^ stride; if (j > i) CE_DESC(a[i], a[j]); }
; }
; __device__ __forceinline__ void peer_tile(const Args& A, LAS unsigned char* lds, int tile) {
;     ...
;             for (int j = 0; j < 4; ++j) Bt[j] = CK(3, j);
;             Bt[4] = CK(5, 0); Bt[5] = CK(5, 1); Bt[6] = CK(6, 0); Bt[7] = CK(6, 1); Bt[8] = CK(7, 0); Bt[9] = CK(7, 1);
;             Bt[10] = CK(8, 0); Bt[11] = CK(9, 0); Bt[12] = CK(10, 0); Bt[13] = CK(11, 0); Bt[14] = CK(12, 0); Bt[15] = CK(13, 0);
;             sort16_desc(Bt); merge16(Lf, Bt);
	v_and_or_b32 v30, v30, s34, 47
	v_max_u32_e32 v31, v15, v14
	v_min_u32_e32 v14, v15, v14
	v_max_u32_e32 v15, v50, v4
	v_min_u32_e32 v4, v50, v4
	v_max_u32_e32 v32, v10, v51
	v_min_u32_e32 v10, v10, v51
	v_max_u32_e32 v50, v52, v8
	v_min_u32_e32 v8, v52, v8
	v_max_u32_e32 v51, v0, v2
	v_min_u32_e32 v0, v0, v2
	v_max_u32_e32 v2, v6, v3
	v_min_u32_e32 v3, v6, v3
	v_max_u32_e32 v6, v27, v28
	v_min_u32_e32 v27, v27, v28
	v_max_u32_e32 v28, v30, v29
	v_min_u32_e32 v29, v30, v29
	v_max_u32_e32 v30, v31, v4
	v_min_u32_e32 v4, v31, v4
	v_max_u32_e32 v31, v14, v15
	v_min_u32_e32 v14, v14, v15
	v_max_u32_e32 v15, v8, v32
	v_min_u32_e32 v8, v8, v32
	v_max_u32_e32 v32, v50, v10
	v_min_u32_e32 v10, v50, v10
	v_max_u32_e32 v50, v51, v3
	v_min_u32_e32 v3, v51, v3
	v_max_u32_e32 v51, v0, v2
	v_min_u32_e32 v0, v0, v2
	v_max_u32_e32 v2, v29, v6
	v_min_u32_e32 v6, v29, v6
	v_max_u32_e32 v29, v28, v27
	v_min_u32_e32 v27, v28, v27
	v_max_u32_e32 v28, v30, v31
	v_min_u32_e32 v30, v30, v31
	v_max_u32_e32 v31, v4, v14
	v_min_u32_e32 v4, v4, v14
	v_max_u32_e32 v14, v10, v8
	v_min_u32_e32 v8, v10, v8
	v_max_u32_e32 v10, v32, v15
	v_min_u32_e32 v15, v32, v15
	v_max_u32_e32 v32, v50, v51
	v_min_u32_e32 v50, v50, v51
	v_max_u32_e32 v51, v3, v0
	v_min_u32_e32 v0, v3, v0
	v_max_u32_e32 v3, v27, v6
	v_min_u32_e32 v6, v27, v6
	v_max_u32_e32 v27, v29, v2
	v_min_u32_e32 v2, v29, v2
	v_max_u32_e32 v29, v28, v8
	v_min_u32_e32 v8, v28, v8
	v_max_u32_e32 v28, v30, v14
	v_min_u32_e32 v14, v30, v14
	v_max_u32_e32 v30, v31, v15
	v_min_u32_e32 v15, v31, v15
	v_max_u32_e32 v31, v4, v10
	v_min_u32_e32 v4, v4, v10
	v_max_u32_e32 v10, v6, v32
	v_min_u32_e32 v6, v6, v32
	v_max_u32_e32 v32, v3, v50
	v_min_u32_e32 v3, v3, v50
	v_max_u32_e32 v50, v2, v51
	v_min_u32_e32 v2, v2, v51
	v_max_u32_e32 v51, v27, v0
	v_min_u32_e32 v0, v27, v0
	v_max_u32_e32 v27, v29, v30
	v_min_u32_e32 v29, v29, v30
	v_max_u32_e32 v30, v28, v31
	v_min_u32_e32 v28, v28, v31
	v_max_u32_e32 v31, v8, v15
	v_min_u32_e32 v8, v8, v15
	v_max_u32_e32 v15, v14, v4
	v_min_u32_e32 v4, v14, v4
	v_max_u32_e32 v14, v2, v6
	v_min_u32_e32 v2, v2, v6
	v_max_u32_e32 v6, v0, v3
	v_min_u32_e32 v0, v0, v3
	v_max_u32_e32 v3, v50, v10
	v_min_u32_e32 v10, v50, v10
	v_max_u32_e32 v50, v51, v32
	v_min_u32_e32 v32, v51, v32
	v_max_u32_e32 v51, v27, v30
	v_min_u32_e32 v27, v27, v30
	v_max_u32_e32 v30, v29, v28
	v_min_u32_e32 v28, v29, v28
	v_max_u32_e32 v29, v31, v15
	v_min_u32_e32 v15, v31, v15
	v_max_u32_e32 v31, v8, v4
	v_min_u32_e32 v4, v8, v4
	v_max_u32_e32 v8, v0, v2
	v_min_u32_e32 v0, v0, v2
	v_max_u32_e32 v2, v6, v14
	v_min_u32_e32 v6, v6, v14
	v_max_u32_e32 v14, v32, v10
	v_min_u32_e32 v10, v32, v10
	v_max_u32_e32 v32, v50, v3
	v_min_u32_e32 v3, v50, v3
	v_max_u32_e32 v50, v51, v0
	v_min_u32_e32 v0, v51, v0
	v_max_u32_e32 v51, v27, v8
	v_min_u32_e32 v8, v27, v8
	v_max_u32_e32 v27, v30, v6
	v_min_u32_e32 v6, v30, v6
	v_max_u32_e32 v30, v28, v2
	v_min_u32_e32 v2, v28, v2
	v_max_u32_e32 v28, v29, v10
	v_min_u32_e32 v10, v29, v10
	v_max_u32_e32 v29, v15, v14
	v_min_u32_e32 v14, v15, v14
	v_max_u32_e32 v15, v31, v3
	v_min_u32_e32 v3, v31, v3
	v_max_u32_e32 v31, v4, v32
	v_min_u32_e32 v4, v4, v32
	v_max_u32_e32 v32, v50, v28
	v_min_u32_e32 v28, v50, v28
	v_max_u32_e32 v50, v51, v29
	v_min_u32_e32 v29, v51, v29
	v_max_u32_e32 v51, v27, v15
	v_min_u32_e32 v15, v27, v15
	v_max_u32_e32 v27, v30, v31
	v_min_u32_e32 v30, v30, v31
	v_max_u32_e32 v31, v0, v10
	v_min_u32_e32 v0, v0, v10
	v_max_u32_e32 v10, v8, v14
	v_min_u32_e32 v8, v8, v14
	v_max_u32_e32 v14, v6, v3
	v_min_u32_e32 v3, v6, v3
	v_max_u32_e32 v6, v2, v4
	v_min_u32_e32 v2, v2, v4
	v_max_u32_e32 v4, v32, v51
	v_min_u32_e32 v32, v32, v51
	v_max_u32_e32 v51, v50, v27
	v_min_u32_e32 v27, v50, v27
	v_max_u32_e32 v50, v28, v15
	v_min_u32_e32 v15, v28, v15
	v_max_u32_e32 v28, v29, v30
	v_min_u32_e32 v29, v29, v30
	v_max_u32_e32 v30, v31, v14
	v_min_u32_e32 v14, v31, v14
	v_max_u32_e32 v31, v10, v6
	v_min_u32_e32 v6, v10, v6
	v_max_u32_e32 v10, v0, v3
	v_min_u32_e32 v0, v0, v3
	v_max_u32_e32 v3, v8, v2
	v_min_u32_e32 v2, v8, v2
	v_min_u32_e32 v8, v4, v51
	v_min_u32_e32 v52, v32, v27
	v_min_u32_e32 v53, v50, v28
	v_min_u32_e32 v54, v15, v29
	v_min_u32_e32 v55, v30, v31
	v_min_u32_e32 v56, v14, v6
	v_min_u32_e32 v57, v10, v3
	v_min_u32_e32 v58, v0, v2
	v_max3_u32 v16, v16, v40, v58
	v_max3_u32 v0, v42, v0, v2
	v_max3_u32 v2, v39, v22, v57
	v_max3_u32 v3, v43, v10, v3
	v_max3_u32 v10, v38, v20, v56
	v_max3_u32 v6, v44, v14, v6
	v_max3_u32 v14, v17, v34, v55
	v_max3_u32 v17, v45, v30, v31
	v_max3_u32 v20, v37, v36, v54
	v_max3_u32 v15, v46, v15, v29
	v_max3_u32 v18, v23, v18, v53
	v_max3_u32 v22, v47, v50, v28
	v_max3_u32 v23, v35, v41, v52
	v_max3_u32 v27, v48, v32, v27
	v_max3_u32 v8, v33, v12, v8
	v_max3_u32 v4, v49, v4, v51
	v_max_u32_e32 v12, v16, v20
	v_min_u32_e32 v16, v16, v20
	v_max_u32_e32 v20, v0, v15
	v_min_u32_e32 v0, v0, v15
	v_max_u32_e32 v15, v2, v18
	v_min_u32_e32 v2, v2, v18
	v_max_u32_e32 v18, v3, v22
	v_min_u32_e32 v3, v3, v22
	v_max_u32_e32 v22, v10, v23
	v_min_u32_e32 v10, v10, v23
	v_max_u32_e32 v23, v6, v27
	v_min_u32_e32 v6, v6, v27
	v_max_u32_e32 v27, v14, v8
	v_min_u32_e32 v8, v14, v8
	v_max_u32_e32 v14, v17, v4
	v_min_u32_e32 v4, v17, v4
	v_max_u32_e32 v17, v12, v22
	v_min_u32_e32 v12, v12, v22
	v_max_u32_e32 v22, v20, v23
	v_min_u32_e32 v20, v20, v23
	v_max_u32_e32 v23, v15, v27
	v_min_u32_e32 v15, v15, v27
	v_max_u32_e32 v27, v18, v14
	v_min_u32_e32 v14, v18, v14
	v_max_u32_e32 v18, v16, v10
	v_min_u32_e32 v10, v16, v10
	v_max_u32_e32 v16, v0, v6
	v_min_u32_e32 v0, v0, v6
	v_max_u32_e32 v6, v2, v8
	v_min_u32_e32 v2, v2, v8
	v_max_u32_e32 v8, v3, v4
; __device__ __forceinline__ float key2f(unsigned k) { const unsigned u = (k & 0x80000000u) ? (k & 0x7fffffffu) : ~k; return __uint_as_float(u); }
; #define CE_DESC(a, b) do { const unsigned _mx = (a) > (b) ? (a) : (b), _mn = (a) > (b) ? (b) : (a); (a) = _mx; (b) = _mn; } while (0)
; #define CK(i, j) ((f2key(va[i] + vb[j]) & ~255u) | (unsigned)(255 - (16 * (i) + (j))))
; __device__ __forceinline__ void peer_tile(const Args& A, LAS unsigned char* lds, int tile) {
;     ...
;             { unsigned x0 = CK(14, 0), x1 = CK(15, 0);
; #pragma unroll
;               for (int i = 0; i < 16; ++i) CE_DESC(Lf[i], x0);
; #pragma unroll
;               for (int i = 0; i < 16; ++i) CE_DESC(Lf[i], x1); }
;     ...
;             float fv[16], den = 0.f; const float f0 = key2f(Lf[0] & ~255u);
; #pragma unroll
;             for (int k = 0; k < 16; ++k) { fv[k] = __expf(key2f(Lf[k] & ~255u) - f0); den += fv[k]; }
	v_min_u32_e32 v3, v3, v4
	v_max_u32_e32 v4, v17, v23
	v_min_u32_e32 v17, v17, v23
	v_max_u32_e32 v23, v22, v27
	v_min_u32_e32 v22, v22, v27
	v_max_u32_e32 v27, v12, v15
	v_min_u32_e32 v12, v12, v15
	v_max_u32_e32 v15, v20, v14
	v_min_u32_e32 v14, v20, v14
	v_max_u32_e32 v20, v18, v6
	v_min_u32_e32 v6, v18, v6
	v_max_u32_e32 v18, v16, v8
	v_min_u32_e32 v8, v16, v8
	v_max_u32_e32 v16, v10, v2
	v_min_u32_e32 v2, v10, v2
	v_max_u32_e32 v10, v0, v3
	v_min_u32_e32 v0, v0, v3
	v_max_u32_e32 v41, v2, v0
	v_min_u32_e32 v0, v2, v0
	v_add_f32_e32 v2, v25, v1
	v_not_b32_e32 v25, v2
	v_or_b32_e32 v42, 0x80000000, v2
	v_cmp_gt_i32_e32 vcc, 0, v2
	v_add_f32_e32 v1, v26, v1
	v_max_u32_e32 v3, v4, v23
	v_cndmask_b32_e32 v2, v42, v25, vcc
	v_and_or_b32 v2, v2, s34, 31
	v_not_b32_e32 v25, v1
	v_or_b32_e32 v26, 0x80000000, v1
	v_cmp_gt_i32_e32 vcc, 0, v1
	v_min_u32_e32 v28, v4, v23
	v_max_u32_e32 v29, v17, v22
	v_cndmask_b32_e32 v1, v26, v25, vcc
	v_max_u32_e32 v25, v3, v2
	v_min_u32_e32 v3, v3, v2
	v_min_u32_e32 v3, v28, v3
	v_min_u32_e32 v30, v17, v22
	v_med3_u32 v2, v4, v23, v2
	v_min_u32_e32 v23, v29, v3
	v_max_u32_e32 v31, v27, v15
	v_max_u32_e32 v4, v29, v3
	v_med3_u32 v3, v17, v22, v3
	v_min_u32_e32 v17, v30, v23
	v_min_u32_e32 v32, v27, v15
	v_min_u32_e32 v23, v31, v17
	v_max_u32_e32 v33, v12, v14
	v_max_u32_e32 v22, v31, v17
	v_med3_u32 v15, v27, v15, v17
	v_min_u32_e32 v17, v32, v23
	v_min_u32_e32 v34, v12, v14
	v_min_u32_e32 v26, v33, v17
	v_max_u32_e32 v35, v20, v18
	v_med3_u32 v12, v12, v14, v17
	v_min_u32_e32 v14, v34, v26
	v_min_u32_e32 v36, v20, v18
	v_min_u32_e32 v26, v35, v14
	v_max_u32_e32 v37, v6, v8
	v_max_u32_e32 v23, v33, v17
	v_max_u32_e32 v17, v35, v14
	v_med3_u32 v14, v20, v18, v14
	v_min_u32_e32 v18, v36, v26
	v_min_u32_e32 v38, v6, v8
	v_min_u32_e32 v26, v37, v18
	v_max_u32_e32 v39, v16, v10
	v_med3_u32 v6, v6, v8, v18
	v_min_u32_e32 v8, v38, v26
	v_min_u32_e32 v40, v16, v10
	v_min_u32_e32 v26, v39, v8
	v_and_or_b32 v1, v1, s34, 15
	v_max_u32_e32 v20, v37, v18
	v_max_u32_e32 v18, v39, v8
	v_med3_u32 v8, v16, v10, v8
	v_min_u32_e32 v10, v40, v26
	v_max_u32_e32 v26, v25, v1
	v_min_u32_e32 v1, v25, v1
	v_max_u32_e32 v25, v2, v1
	v_min_u32_e32 v1, v2, v1
	v_max_u32_e32 v2, v4, v1
	v_min_u32_e32 v1, v4, v1
	v_max_u32_e32 v4, v3, v1
	v_min_u32_e32 v1, v3, v1
	v_max_u32_e32 v3, v22, v1
	v_min_u32_e32 v1, v22, v1
	v_max_u32_e32 v22, v15, v1
	v_min_u32_e32 v1, v15, v1
	v_max_u32_e32 v15, v23, v1
	v_min_u32_e32 v1, v23, v1
	v_max_u32_e32 v23, v12, v1
	v_min_u32_e32 v1, v12, v1
	v_max_u32_e32 v12, v17, v1
	v_min_u32_e32 v1, v17, v1
	v_max_u32_e32 v17, v14, v1
	v_min_u32_e32 v1, v14, v1
	v_max_u32_e32 v14, v20, v1
	v_min_u32_e32 v1, v20, v1
	v_max_u32_e32 v20, v6, v1
	v_min_u32_e32 v1, v6, v1
	v_max_u32_e32 v6, v18, v1
	v_min_u32_e32 v1, v18, v1
	v_max_u32_e32 v16, v41, v10
	v_max_u32_e32 v18, v8, v1
	v_min_u32_e32 v1, v8, v1
	v_min_u32_e32 v10, v41, v10
	v_max_u32_e32 v8, v16, v1
	v_min_u32_e32 v1, v16, v1
	v_max3_u32 v10, v0, v10, v1
	v_and_b32_e32 v0, 0x7fffff00, v26
	v_bitop3_b32 v1, v26, s33, v26 bitop3:0xcf
	v_cmp_gt_i32_e32 vcc, 0, v26
	v_and_b32_e32 v16, 0x7fffff00, v25
	v_bitop3_b32 v27, v25, s33, v25 bitop3:0xcf
	v_cndmask_b32_e32 v0, v1, v0, vcc
	v_cmp_gt_i32_e32 vcc, 0, v25
	v_sub_f32_e32 v1, v0, v0
	v_bitop3_b32 v28, v2, s33, v2 bitop3:0xcf
	v_cndmask_b32_e32 v16, v27, v16, vcc
	v_and_b32_e32 v27, 0x7fffff00, v2
	v_cmp_gt_i32_e32 vcc, 0, v2
	v_mul_f32_e32 v1, 0x3fb8aa3b, v1
	v_sub_f32_e32 v16, v16, v0
	v_cndmask_b32_e32 v27, v28, v27, vcc
	v_and_b32_e32 v28, 0x7fffff00, v4
	v_bitop3_b32 v29, v4, s33, v4 bitop3:0xcf
	v_cmp_gt_i32_e32 vcc, 0, v4
	v_exp_f32_e32 v1, v1
	v_mul_f32_e32 v16, 0x3fb8aa3b, v16
	v_sub_f32_e32 v27, v27, v0
	v_cndmask_b32_e32 v28, v29, v28, vcc
	v_and_b32_e32 v30, 0x7fffff00, v3
	v_bitop3_b32 v31, v3, s33, v3 bitop3:0xcf
	v_cmp_gt_i32_e32 vcc, 0, v3
	v_exp_f32_e32 v16, v16
	v_mul_f32_e32 v27, 0x3fb8aa3b, v27
	v_sub_f32_e32 v28, v28, v0
	v_cndmask_b32_e32 v30, v31, v30, vcc
	v_and_b32_e32 v31, 0x7fffff00, v22
	v_bitop3_b32 v32, v22, s33, v22 bitop3:0xcf
	v_cmp_gt_i32_e32 vcc, 0, v22
	v_exp_f32_e32 v27, v27
	v_mul_f32_e32 v28, 0x3fb8aa3b, v28
	v_sub_f32_e32 v30, v30, v0
	v_cndmask_b32_e32 v31, v32, v31, vcc
	v_and_b32_e32 v32, 0x7fffff00, v15
	v_bitop3_b32 v33, v15, s33, v15 bitop3:0xcf
	v_cmp_gt_i32_e32 vcc, 0, v15
	v_exp_f32_e32 v28, v28
	v_mul_f32_e32 v30, 0x3fb8aa3b, v30
	v_sub_f32_e32 v31, v31, v0
	v_cndmask_b32_e32 v32, v33, v32, vcc
	v_and_b32_e32 v33, 0x7fffff00, v23
	v_bitop3_b32 v34, v23, s33, v23 bitop3:0xcf
	v_cmp_gt_i32_e32 vcc, 0, v23
	v_add_f32_e32 v29, 0, v1
	v_exp_f32_e32 v30, v30
	v_mul_f32_e32 v31, 0x3fb8aa3b, v31
	v_sub_f32_e32 v32, v32, v0
	v_cndmask_b32_e32 v33, v34, v33, vcc
	v_and_b32_e32 v34, 0x7fffff00, v12
	v_bitop3_b32 v35, v12, s33, v12 bitop3:0xcf
	v_cmp_gt_i32_e32 vcc, 0, v12
	v_add_f32_e32 v29, v29, v16
	v_exp_f32_e32 v31, v31
	v_mul_f32_e32 v32, 0x3fb8aa3b, v32
	v_sub_f32_e32 v33, v33, v0
	v_cndmask_b32_e32 v34, v35, v34, vcc
	v_and_b32_e32 v35, 0x7fffff00, v17
	v_bitop3_b32 v36, v17, s33, v17 bitop3:0xcf
	v_cmp_gt_i32_e32 vcc, 0, v17
	v_add_f32_e32 v29, v29, v27
	v_exp_f32_e32 v32, v32
	v_mul_f32_e32 v33, 0x3fb8aa3b, v33
	v_sub_f32_e32 v34, v34, v0
	v_cndmask_b32_e32 v35, v36, v35, vcc
	v_and_b32_e32 v36, 0x7fffff00, v14
	v_bitop3_b32 v37, v14, s33, v14 bitop3:0xcf
	v_cmp_gt_i32_e32 vcc, 0, v14
	v_add_f32_e32 v29, v29, v28
	v_exp_f32_e32 v33, v33
	v_mul_f32_e32 v34, 0x3fb8aa3b, v34
	v_sub_f32_e32 v35, v35, v0
	v_cndmask_b32_e32 v36, v37, v36, vcc
	v_and_b32_e32 v37, 0x7fffff00, v20
	v_bitop3_b32 v38, v20, s33, v20 bitop3:0xcf
	v_cmp_gt_i32_e32 vcc, 0, v20
	v_add_f32_e32 v29, v29, v30
; #define LDS_WAIT() asm volatile("s_waitcnt lgkmcnt(0)" ::: "memory")
; __device__ __forceinline__ float key2f(unsigned k) { const unsigned u = (k & 0x80000000u) ? (k & 0x7fffffffu) : ~k; return __uint_as_float(u); }
; __device__ __forceinline__ void peer_tile(const Args& A, LAS unsigned char* lds, int tile) {
;     ...
;             float fv[16], den = 0.f; const float f0 = key2f(Lf[0] & ~255u);
; #pragma unroll
;             for (int k = 0; k < 16; ++k) { fv[k] = __expf(key2f(Lf[k] & ~255u) - f0); den += fv[k]; }
;             const float rden = 1.f / den;
;             LDS_WAIT();
; #pragma unroll
;             for (int k = 0; k < 16; ++k) { const unsigned code = 255u - (Lf[k] & 255u); const unsigned e = idx[code >> 4] * 128u + idx[16 + (code & 15u)];
;                 u32x2 sv; sv.x = e; sv.y = __float_as_uint(fv[k] * rden); SEL[(tl * 8 + h) * 16 + k] = sv; }
	v_exp_f32_e32 v34, v34
	v_mul_f32_e32 v35, 0x3fb8aa3b, v35
	v_sub_f32_e32 v36, v36, v0
	v_cndmask_b32_e32 v37, v38, v37, vcc
	v_and_b32_e32 v38, 0x7fffff00, v6
	v_bitop3_b32 v39, v6, s33, v6 bitop3:0xcf
	v_cmp_gt_i32_e32 vcc, 0, v6
	v_add_f32_e32 v29, v29, v31
	v_exp_f32_e32 v35, v35
	v_mul_f32_e32 v36, 0x3fb8aa3b, v36
	v_sub_f32_e32 v37, v37, v0
	v_cndmask_b32_e32 v38, v39, v38, vcc
	v_and_b32_e32 v39, 0x7fffff00, v18
	v_bitop3_b32 v40, v18, s33, v18 bitop3:0xcf
	v_cmp_gt_i32_e32 vcc, 0, v18
	v_add_f32_e32 v29, v29, v32
	v_exp_f32_e32 v36, v36
	v_mul_f32_e32 v37, 0x3fb8aa3b, v37
	v_sub_f32_e32 v38, v38, v0
	v_cndmask_b32_e32 v39, v40, v39, vcc
	v_and_b32_e32 v40, 0x7fffff00, v8
	v_bitop3_b32 v41, v8, s33, v8 bitop3:0xcf
	v_cmp_gt_i32_e32 vcc, 0, v8
	v_add_f32_e32 v29, v29, v33
	v_exp_f32_e32 v37, v37
	v_mul_f32_e32 v38, 0x3fb8aa3b, v38
	v_sub_f32_e32 v39, v39, v0
	v_cndmask_b32_e32 v40, v41, v40, vcc
	v_and_b32_e32 v41, 0x7fffff00, v10
	v_bitop3_b32 v42, v10, s33, v10 bitop3:0xcf
	v_cmp_gt_i32_e32 vcc, 0, v10
	v_add_f32_e32 v29, v29, v34
	v_exp_f32_e32 v38, v38
	v_mul_f32_e32 v39, 0x3fb8aa3b, v39
	v_sub_f32_e32 v40, v40, v0
	v_cndmask_b32_e32 v41, v42, v41, vcc
	v_add_f32_e32 v29, v29, v35
	v_exp_f32_e32 v39, v39
	v_mul_f32_e32 v40, 0x3fb8aa3b, v40
	v_sub_f32_e32 v0, v41, v0
	v_add_f32_e32 v29, v29, v36
	v_exp_f32_e32 v40, v40
	v_mul_f32_e32 v0, 0x3fb8aa3b, v0
	v_add_f32_e32 v29, v29, v37
	v_exp_f32_e32 v41, v0
	v_add_f32_e32 v0, v29, v38
	v_add_f32_e32 v0, v0, v39
	v_add_f32_e32 v0, v0, v40
	v_add_f32_e32 v0, v0, v41
	v_div_scale_f32 v29, s[0:1], v0, v0, 1.0
	v_rcp_f32_e32 v42, v29
	v_not_b32_e32 v21, v26
	v_not_b32_e32 v24, v25
	v_fma_f32 v43, -v29, v42, 1.0
	v_fmac_f32_e32 v42, v43, v42
	v_div_scale_f32 v43, vcc, 1.0, v0, 1.0
	v_mul_f32_e32 v44, v43, v42
	v_fma_f32 v45, -v29, v44, v43
	v_fmac_f32_e32 v44, v45, v42
	v_fma_f32 v29, -v29, v44, v43
	v_div_fmas_f32 v29, v29, v42, v44
	v_div_fixup_f32 v29, v29, v0, 1.0
	v_and_b32_e32 v0, 48, v19
	v_lshrrev_b32_e32 v19, 2, v21
	v_and_b32_e32 v19, 60, v19
	v_bitop3_b32 v21, v26, 15, v26 bitop3:0xc
	v_add_u32_e32 v19, v5, v19
	v_lshl_add_u32 v21, v21, 2, v5
	ds_read_b32 v19, v19
	ds_read_b32 v21, v21 offset:64
	v_lshlrev_b32_e32 v0, 3, v0
	v_add3_u32 v11, v13, v11, v0
	v_mul_f32_e32 v1, v1, v29
	v_not_b32_e32 v13, v2
	s_waitcnt lgkmcnt(0)
	v_lshl_add_u32 v0, v19, 7, v21
	ds_write_b64 v11, v[0:1]
	v_lshrrev_b32_e32 v0, 2, v24
	v_and_b32_e32 v0, 60, v0
	v_bitop3_b32 v1, v25, 15, v25 bitop3:0xc
	v_add_u32_e32 v0, v5, v0
	v_lshl_add_u32 v1, v1, 2, v5
	ds_read_b32 v0, v0
	ds_read_b32 v1, v1 offset:64
	v_cmp_eq_u32_e32 vcc, 0, v9
	s_waitcnt lgkmcnt(0)
	v_lshl_add_u32 v0, v0, 7, v1
	v_mul_f32_e32 v1, v16, v29
	ds_write_b64 v11, v[0:1] offset:8
	v_lshrrev_b32_e32 v0, 2, v13
	v_and_b32_e32 v0, 60, v0
	v_bitop3_b32 v1, v2, 15, v2 bitop3:0xc
	v_add_u32_e32 v0, v5, v0
	v_lshl_add_u32 v1, v1, 2, v5
	ds_read_b32 v0, v0
	ds_read_b32 v1, v1 offset:64
	v_not_b32_e32 v2, v4
	s_waitcnt lgkmcnt(0)
	v_lshl_add_u32 v0, v0, 7, v1
	v_mul_f32_e32 v1, v27, v29
	ds_write_b64 v11, v[0:1] offset:16
	v_lshrrev_b32_e32 v0, 2, v2
	v_and_b32_e32 v0, 60, v0
	v_bitop3_b32 v1, v4, 15, v4 bitop3:0xc
	v_add_u32_e32 v0, v5, v0
	v_lshl_add_u32 v1, v1, 2, v5
	ds_read_b32 v0, v0
	ds_read_b32 v1, v1 offset:64
	v_not_b32_e32 v2, v3
	v_mul_lo_u32 v4, v7, s36
	s_waitcnt lgkmcnt(0)
	v_lshl_add_u32 v0, v0, 7, v1
	v_mul_f32_e32 v1, v28, v29
	ds_write_b64 v11, v[0:1] offset:24
	v_lshrrev_b32_e32 v0, 2, v2
	v_and_b32_e32 v0, 60, v0
	v_bitop3_b32 v1, v3, 15, v3 bitop3:0xc
	v_add_u32_e32 v0, v5, v0
	v_lshl_add_u32 v1, v1, 2, v5
	ds_read_b32 v0, v0
	ds_read_b32 v1, v1 offset:64
	v_not_b32_e32 v2, v22
	s_waitcnt lgkmcnt(0)
	v_lshl_add_u32 v0, v0, 7, v1
	v_mul_f32_e32 v1, v30, v29
	ds_write_b64 v11, v[0:1] offset:32
	v_lshrrev_b32_e32 v0, 2, v2
	v_and_b32_e32 v0, 60, v0
	v_bitop3_b32 v1, v22, 15, v22 bitop3:0xc
	v_add_u32_e32 v0, v5, v0
	v_lshl_add_u32 v1, v1, 2, v5
	ds_read_b32 v0, v0
	ds_read_b32 v1, v1 offset:64
	v_not_b32_e32 v2, v15
	s_waitcnt lgkmcnt(0)
	v_lshl_add_u32 v0, v0, 7, v1
	v_mul_f32_e32 v1, v31, v29
	ds_write_b64 v11, v[0:1] offset:40
	v_lshrrev_b32_e32 v0, 2, v2
	v_and_b32_e32 v0, 60, v0
	v_bitop3_b32 v1, v15, 15, v15 bitop3:0xc
	v_add_u32_e32 v0, v5, v0
	v_lshl_add_u32 v1, v1, 2, v5
	ds_read_b32 v0, v0
	ds_read_b32 v1, v1 offset:64
	v_not_b32_e32 v2, v23
	s_waitcnt lgkmcnt(0)
	v_lshl_add_u32 v0, v0, 7, v1
	v_mul_f32_e32 v1, v32, v29
	ds_write_b64 v11, v[0:1] offset:48
	v_lshrrev_b32_e32 v0, 2, v2
	v_and_b32_e32 v0, 60, v0
	v_bitop3_b32 v1, v23, 15, v23 bitop3:0xc
	v_add_u32_e32 v0, v5, v0
	v_lshl_add_u32 v1, v1, 2, v5
	ds_read_b32 v0, v0
	ds_read_b32 v1, v1 offset:64
	v_not_b32_e32 v2, v12
	s_waitcnt lgkmcnt(0)
	v_lshl_add_u32 v0, v0, 7, v1
	v_mul_f32_e32 v1, v33, v29
	ds_write_b64 v11, v[0:1] offset:56
	v_lshrrev_b32_e32 v0, 2, v2
	v_and_b32_e32 v0, 60, v0
	v_bitop3_b32 v1, v12, 15, v12 bitop3:0xc
	v_add_u32_e32 v0, v5, v0
	v_lshl_add_u32 v1, v1, 2, v5
	ds_read_b32 v0, v0
	ds_read_b32 v1, v1 offset:64
	v_not_b32_e32 v2, v17
	s_waitcnt lgkmcnt(0)
	v_lshl_add_u32 v0, v0, 7, v1
	v_mul_f32_e32 v1, v34, v29
	ds_write_b64 v11, v[0:1] offset:64
	v_lshrrev_b32_e32 v0, 2, v2
	v_and_b32_e32 v0, 60, v0
	v_bitop3_b32 v1, v17, 15, v17 bitop3:0xc
	v_add_u32_e32 v0, v5, v0
	v_lshl_add_u32 v1, v1, 2, v5
	ds_read_b32 v0, v0
	ds_read_b32 v1, v1 offset:64
	v_not_b32_e32 v2, v14
	s_waitcnt lgkmcnt(0)
	v_lshl_add_u32 v0, v0, 7, v1
	v_mul_f32_e32 v1, v35, v29
	ds_write_b64 v11, v[0:1] offset:72
	v_lshrrev_b32_e32 v0, 2, v2
	v_and_b32_e32 v0, 60, v0
	v_bitop3_b32 v1, v14, 15, v14 bitop3:0xc
	v_add_u32_e32 v0, v5, v0
	v_lshl_add_u32 v1, v1, 2, v5
	ds_read_b32 v0, v0
	ds_read_b32 v1, v1 offset:64
	v_not_b32_e32 v2, v20
	s_waitcnt lgkmcnt(0)
; __device__ __forceinline__ unsigned pk2(float lo, float hi) { const f32x2 v = {lo, hi}; const bf16x2_t b = __builtin_convertvector(v, bf16x2_t); return __builtin_bit_cast(unsigned, b); }
; __device__ __forceinline__ float bflo(unsigned u) { return __uint_as_float(u << 16); }
; __device__ __forceinline__ float bfhi(unsigned u) { return __uint_as_float(u & 0xffff0000u); }
; #define LDS_WAIT() asm volatile("s_waitcnt lgkmcnt(0)" ::: "memory")
; __device__ __forceinline__ void peer_tile(const Args& A, LAS unsigned char* lds, int tile) {
;     ...
;             LDS_WAIT();
; #pragma unroll
;             for (int k = 0; k < 16; ++k) { const unsigned code = 255u - (Lf[k] & 255u); const unsigned e = idx[code >> 4] * 128u + idx[16 + (code & 15u)];
;                 u32x2 sv; sv.x = e; sv.y = __float_as_uint(fv[k] * rden); SEL[(tl * 8 + h) * 16 + k] = sv; }
;         }
;     }
;     __syncthreads();
;     ...
;     const unsigned char* T8v = T8 + (size_t)16384 * 1024;
;     const bf16_t* A3 = (const bf16_t*)(A.ws + WS_A3); const float* RSq = (const float*)(A.ws + WS_RS);
;     for (int pass = 0; pass < 2; ++pass) {
;         const int tb = 8 * w + 4 * pass;
;         u32x4 xpa[4], xpb[4]; f32x2 oacc[4][8];
; #pragma unroll
;         for (int tk = 0; tk < 4; ++tk) { const size_t m = (size_t)tile * 64 + tb + tk;
;             { const u32x4 ra = *(const u32x4*)(A3 + m * 1024 + 16 * lane), rb = *(const u32x4*)(A3 + m * 1024 + 16 * lane + 8);
;               float xr_; { const f32x4 p0 = *(const f32x4*)(RSq + m * 16), p1 = *(const f32x4*)(RSq + m * 16 + 4), p2 = *(const f32x4*)(RSq + m * 16 + 8), p3 = *(const f32x4*)(RSq + m * 16 + 12);
;                 const f32x4 ps = (p0 + p1) + (p2 + p3); xr_ = rsqrtf(((ps[0] + ps[1]) + (ps[2] + ps[3])) * (1.f / 1024.f) + 1e-6f); }
;               const unsigned rr[8] = {ra.x, ra.y, ra.z, ra.w, rb.x, rb.y, rb.z, rb.w}; unsigned hh[8];
;               const float* sp = MOD + (int)(m >> 11) * 6144 + 3072 + 16 * lane;
; #pragma unroll
;               for (int q = 0; q < 8; ++q) { const f32x2 sh = *(const f32x2*)(sp + 2 * q); hh[q] = pk2(bflo(rr[q]) * xr_ + sh[0], bfhi(rr[q]) * xr_ + sh[1]); }
;               xpa[tk] = (u32x4){hh[0], hh[1], hh[2], hh[3]}; xpb[tk] = (u32x4){hh[4], hh[5], hh[6], hh[7]}; }
	v_lshl_add_u32 v0, v0, 7, v1
	v_mul_f32_e32 v1, v36, v29
	ds_write_b64 v11, v[0:1] offset:80
	v_lshrrev_b32_e32 v0, 2, v2
	v_and_b32_e32 v0, 60, v0
	v_bitop3_b32 v1, v20, 15, v20 bitop3:0xc
	v_add_u32_e32 v0, v5, v0
	v_lshl_add_u32 v1, v1, 2, v5
	ds_read_b32 v0, v0
	ds_read_b32 v1, v1 offset:64
	v_not_b32_e32 v2, v6
	s_waitcnt lgkmcnt(0)
	v_lshl_add_u32 v0, v0, 7, v1
	v_mul_f32_e32 v1, v37, v29
	ds_write_b64 v11, v[0:1] offset:88
	v_lshrrev_b32_e32 v0, 2, v2
	v_and_b32_e32 v0, 60, v0
	v_bitop3_b32 v1, v6, 15, v6 bitop3:0xc
	v_add_u32_e32 v0, v5, v0
	v_lshl_add_u32 v1, v1, 2, v5
	ds_read_b32 v0, v0
	ds_read_b32 v1, v1 offset:64
	v_not_b32_e32 v2, v18
	s_waitcnt lgkmcnt(0)
	v_lshl_add_u32 v0, v0, 7, v1
	v_mul_f32_e32 v1, v38, v29
	ds_write_b64 v11, v[0:1] offset:96
	v_lshrrev_b32_e32 v0, 2, v2
	v_and_b32_e32 v0, 60, v0
	v_bitop3_b32 v1, v18, 15, v18 bitop3:0xc
	v_add_u32_e32 v0, v5, v0
	v_lshl_add_u32 v1, v1, 2, v5
	ds_read_b32 v0, v0
	ds_read_b32 v1, v1 offset:64
	v_not_b32_e32 v2, v8
	s_waitcnt lgkmcnt(0)
	v_lshl_add_u32 v0, v0, 7, v1
	v_mul_f32_e32 v1, v39, v29
	ds_write_b64 v11, v[0:1] offset:104
	v_lshrrev_b32_e32 v0, 2, v2
	v_and_b32_e32 v0, 60, v0
	v_bitop3_b32 v1, v8, 15, v8 bitop3:0xc
	v_add_u32_e32 v0, v5, v0
	v_lshl_add_u32 v1, v1, 2, v5
	ds_read_b32 v0, v0
	ds_read_b32 v1, v1 offset:64
	v_not_b32_e32 v2, v10
	s_waitcnt lgkmcnt(0)
	v_lshl_add_u32 v0, v0, 7, v1
	v_mul_f32_e32 v1, v40, v29
	ds_write_b64 v11, v[0:1] offset:112
	v_lshrrev_b32_e32 v0, 2, v2
	v_and_b32_e32 v0, 60, v0
	v_bitop3_b32 v1, v10, 15, v10 bitop3:0xc
	v_add_u32_e32 v0, v5, v0
	v_lshl_add_u32 v1, v1, 2, v5
	ds_read_b32 v0, v0
	ds_read_b32 v1, v1 offset:64
	v_lshlrev_b32_e32 v5, 13, v7
	v_lshl_or_b32 v6, v9, 3, v5
	s_waitcnt lgkmcnt(0)
	v_lshl_add_u32 v0, v0, 7, v1
	v_mul_f32_e32 v1, v41, v29
	ds_write_b64 v11, v[0:1] offset:120
	s_mov_b64 exec, -1
	v_and_b32_e32 v240, 63, v214
	v_lshrrev_b32_e32 v242, 6, v214
	v_lshlrev_b32_e32 v240, 4, v240
	v_readfirstlane_b32 s16, v242
	v_lshlrev_b32_e32 v245, 1, v240
	v_lshlrev_b32_e32 v246, 2, v240
	v_lshrrev_b32_e32 v247, 4, v240
	v_and_b32_e32 v247, 48, v247
	v_mov_b32_e32 v244, 0
	v_mov_b32_e32 v243, 0x358637bd
	v_mov_b32_e32 v242, 0xbf3a00e3
	s_add_u32 s4, s50, 0x1000000
	s_addc_u32 s5, s51, 0
	s_add_u32 s6, s50, 0x2000000
	s_addc_u32 s7, s51, 0
	s_add_u32 s8, s50, 0x3000000
	s_addc_u32 s9, s51, 0
	s_add_u32 s52, s50, 0x3010000
	s_addc_u32 s53, s51, 0
	s_add_u32 s12, s50, 0xb000000
	s_addc_u32 s13, s51, 0
	s_add_u32 s14, s50, 0xd000000
	s_addc_u32 s15, s51, 0
	s_lshr_b32 s0, s2, 5
	s_mul_i32 s0, s0, 0x6000
	s_add_u32 s10, s50, s0
	s_addc_u32 s11, s51, 0
	s_add_u32 s80, s10, 0x4000
	s_addc_u32 s81, s11, 0
	s_add_u32 s82, s10, 0x6000
	s_addc_u32 s83, s11, 0
	s_mul_i32 s22, s16, 9920
	s_cmp_eq_u32 s16, 7
	s_cselect_b32 s22, 0x21000, s22
	s_mov_b32 s85, 0xffffffff
	s_mov_b32 s72, 0x3e6d3388
	s_mov_b32 s56, s4
	s_and_b32 s57, s5, 0xffff
	s_or_b32 s57, s57, 0x04000000
	s_mov_b32 s58, 16384
	s_mov_b32 s59, 0x00027000
	s_mov_b32 s60, s6
	s_and_b32 s61, s7, 0xffff
	s_or_b32 s61, s61, 0x04000000
	s_mov_b32 s62, 16384
	s_mov_b32 s63, 0x00027000
	s_lshl_b32 s76, s16, 3
	s_lshl_b32 s0, s2, 6
	s_add_i32 s77, s0, s76
	global_load_dwordx4 v[192:195], v246, s[80:81] offset:0
	global_load_dwordx4 v[196:199], v246, s[80:81] offset:16
	global_load_dwordx4 v[200:203], v246, s[80:81] offset:32
	global_load_dwordx4 v[204:207], v246, s[80:81] offset:48
	s_add_i32 s0, s77, 0
	s_lshl_b32 s1, s0, 11
	s_add_u32 s78, s12, s1
	s_addc_u32 s79, s13, 0
	global_load_dwordx4 v[128:131], v245, s[78:79]
	global_load_dwordx4 v[132:135], v245, s[78:79] offset:16
	global_load_dwordx4 v[136:139], v245, s[78:79] offset:2048
	global_load_dwordx4 v[140:143], v245, s[78:79] offset:2064
	s_lshl_b32 s1, s0, 6
	s_add_u32 s78, s14, s1
	s_addc_u32 s79, s15, 0
	global_load_dwordx4 v[144:147], v244, s[78:79] offset:0
	global_load_dwordx4 v[148:151], v244, s[78:79] offset:16
	global_load_dwordx4 v[152:155], v244, s[78:79] offset:32
	global_load_dwordx4 v[156:159], v244, s[78:79] offset:48
	global_load_dwordx4 v[160:163], v244, s[78:79] offset:64
	global_load_dwordx4 v[164:167], v244, s[78:79] offset:80
	global_load_dwordx4 v[168:171], v244, s[78:79] offset:96
	global_load_dwordx4 v[172:175], v244, s[78:79] offset:112
	s_waitcnt lgkmcnt(0)
	s_barrier
; __device__ __forceinline__ unsigned pk2(float lo, float hi) { const f32x2 v = {lo, hi}; const bf16x2_t b = __builtin_convertvector(v, bf16x2_t); return __builtin_bit_cast(unsigned, b); }
; __device__ __forceinline__ float bflo(unsigned u) { return __uint_as_float(u << 16); }
; __device__ __forceinline__ float bfhi(unsigned u) { return __uint_as_float(u & 0xffff0000u); }
; __device__ __forceinline__ void peer_tile(const Args& A, LAS unsigned char* lds, int tile) {
;     ...
;     for (int pass = 0; pass < 2; ++pass) {
;         const int tb = 8 * w + 4 * pass;
;         u32x4 xpa[4], xpb[4]; f32x2 oacc[4][8];
; #pragma unroll
;         for (int tk = 0; tk < 4; ++tk) { const size_t m = (size_t)tile * 64 + tb + tk;
;             { const u32x4 ra = *(const u32x4*)(A3 + m * 1024 + 16 * lane), rb = *(const u32x4*)(A3 + m * 1024 + 16 * lane + 8);
;               float xr_; { const f32x4 p0 = *(const f32x4*)(RSq + m * 16), p1 = *(const f32x4*)(RSq + m * 16 + 4), p2 = *(const f32x4*)(RSq + m * 16 + 8), p3 = *(const f32x4*)(RSq + m * 16 + 12);
;                 const f32x4 ps = (p0 + p1) + (p2 + p3); xr_ = rsqrtf(((ps[0] + ps[1]) + (ps[2] + ps[3])) * (1.f / 1024.f) + 1e-6f); }
;               const unsigned rr[8] = {ra.x, ra.y, ra.z, ra.w, rb.x, rb.y, rb.z, rb.w}; unsigned hh[8];
;               const float* sp = MOD + (int)(m >> 11) * 6144 + 3072 + 16 * lane;
; #pragma unroll
;               for (int q = 0; q < 8; ++q) { const f32x2 sh = *(const f32x2*)(sp + 2 * q); hh[q] = pk2(bflo(rr[q]) * xr_ + sh[0], bfhi(rr[q]) * xr_ + sh[1]); }
;               xpa[tk] = (u32x4){hh[0], hh[1], hh[2], hh[3]}; xpb[tk] = (u32x4){hh[4], hh[5], hh[6], hh[7]}; }
	s_add_i32 s0, s77, 2
	s_lshl_b32 s1, s0, 11
	s_add_u32 s78, s12, s1
	s_addc_u32 s79, s13, 0
	global_load_dwordx4 v[176:179], v245, s[78:79]
	global_load_dwordx4 v[180:183], v245, s[78:79] offset:16
	global_load_dwordx4 v[184:187], v245, s[78:79] offset:2048
	global_load_dwordx4 v[188:191], v245, s[78:79] offset:2064
	s_lshl_b32 s1, s0, 6
	s_add_u32 s78, s14, s1
	s_addc_u32 s79, s15, 0
	global_load_dwordx4 v[216:219], v244, s[78:79] offset:0
	global_load_dwordx4 v[220:223], v244, s[78:79] offset:16
	global_load_dwordx4 v[224:227], v244, s[78:79] offset:32
	global_load_dwordx4 v[228:231], v244, s[78:79] offset:48
	global_load_dwordx4 v[232:235], v244, s[78:79] offset:64
	global_load_dwordx4 v[236:239], v244, s[78:79] offset:80
	global_load_dwordx4 v[248:251], v244, s[78:79] offset:96
	global_load_dwordx4 v[252:255], v244, s[78:79] offset:112
	s_waitcnt vmcnt(12)
	v_pk_add_f32 v[144:145], v[144:145], v[148:149]
	v_pk_add_f32 v[146:147], v[146:147], v[150:151]
	v_pk_add_f32 v[152:153], v[152:153], v[156:157]
	v_pk_add_f32 v[154:155], v[154:155], v[158:159]
	v_pk_add_f32 v[144:145], v[144:145], v[152:153]
	v_pk_add_f32 v[146:147], v[146:147], v[154:155]
	v_add_f32_e32 v144, v144, v145
	v_add_f32_e32 v146, v146, v147
	v_add_f32_e32 v144, v144, v146
	v_fmamk_f32 v144, v144, 0x3a800000, v243
	v_rsq_f32_e32 v144, v144
	v_pk_add_f32 v[160:161], v[160:161], v[164:165]
	v_pk_add_f32 v[162:163], v[162:163], v[166:167]
	v_pk_add_f32 v[168:169], v[168:169], v[172:173]
	v_pk_add_f32 v[170:171], v[170:171], v[174:175]
	v_pk_add_f32 v[160:161], v[160:161], v[168:169]
	v_pk_add_f32 v[162:163], v[162:163], v[170:171]
	v_add_f32_e32 v160, v160, v161
	v_add_f32_e32 v162, v162, v163
	v_add_f32_e32 v160, v160, v162
	v_fmamk_f32 v160, v160, 0x3a800000, v243
	v_rsq_f32_e32 v160, v160
	v_lshlrev_b32_e32 v208, 16, v128
	v_and_b32_e32 v209, 0xffff0000, v128
	v_fma_f32 v208, v208, v144, v192
	v_fma_f32 v209, v209, v144, v193
	v_cvt_pk_bf16_f32 v210, v208, v209
	v_lshlrev_b32_e32 v0, 16, v210
	v_and_b32_e32 v1, 0xffff0000, v210
	v_lshlrev_b32_e32 v208, 16, v129
	v_and_b32_e32 v209, 0xffff0000, v129
	v_fma_f32 v208, v208, v144, v194
	v_fma_f32 v209, v209, v144, v195
	v_cvt_pk_bf16_f32 v210, v208, v209
	v_lshlrev_b32_e32 v2, 16, v210
	v_and_b32_e32 v3, 0xffff0000, v210
	v_lshlrev_b32_e32 v208, 16, v130
	v_and_b32_e32 v209, 0xffff0000, v130
	v_fma_f32 v208, v208, v144, v196
	v_fma_f32 v209, v209, v144, v197
	v_cvt_pk_bf16_f32 v210, v208, v209
	v_lshlrev_b32_e32 v4, 16, v210
	v_and_b32_e32 v5, 0xffff0000, v210
	v_lshlrev_b32_e32 v208, 16, v131
	v_and_b32_e32 v209, 0xffff0000, v131
	v_fma_f32 v208, v208, v144, v198
	v_fma_f32 v209, v209, v144, v199
	v_cvt_pk_bf16_f32 v210, v208, v209
	v_lshlrev_b32_e32 v6, 16, v210
	v_and_b32_e32 v7, 0xffff0000, v210
	v_lshlrev_b32_e32 v208, 16, v132
	v_and_b32_e32 v209, 0xffff0000, v132
	v_fma_f32 v208, v208, v144, v200
	v_fma_f32 v209, v209, v144, v201
	v_cvt_pk_bf16_f32 v210, v208, v209
	v_lshlrev_b32_e32 v8, 16, v210
	v_and_b32_e32 v9, 0xffff0000, v210
	v_lshlrev_b32_e32 v208, 16, v133
	v_and_b32_e32 v209, 0xffff0000, v133
	v_fma_f32 v208, v208, v144, v202
	v_fma_f32 v209, v209, v144, v203
	v_cvt_pk_bf16_f32 v210, v208, v209
	v_lshlrev_b32_e32 v10, 16, v210
	v_and_b32_e32 v11, 0xffff0000, v210
	v_lshlrev_b32_e32 v208, 16, v134
	v_and_b32_e32 v209, 0xffff0000, v134
	v_fma_f32 v208, v208, v144, v204
	v_fma_f32 v209, v209, v144, v205
	v_cvt_pk_bf16_f32 v210, v208, v209
	v_lshlrev_b32_e32 v12, 16, v210
	v_and_b32_e32 v13, 0xffff0000, v210
	v_lshlrev_b32_e32 v208, 16, v135
	v_and_b32_e32 v209, 0xffff0000, v135
	v_fma_f32 v208, v208, v144, v206
	v_fma_f32 v209, v209, v144, v207
	v_cvt_pk_bf16_f32 v210, v208, v209
	v_lshlrev_b32_e32 v14, 16, v210
	v_and_b32_e32 v15, 0xffff0000, v210
	v_lshlrev_b32_e32 v208, 16, v136
	v_and_b32_e32 v209, 0xffff0000, v136
	v_fma_f32 v208, v208, v160, v192
	v_fma_f32 v209, v209, v160, v193
	v_cvt_pk_bf16_f32 v210, v208, v209
	v_lshlrev_b32_e32 v16, 16, v210
	v_and_b32_e32 v17, 0xffff0000, v210
	v_lshlrev_b32_e32 v208, 16, v137
	v_and_b32_e32 v209, 0xffff0000, v137
	v_fma_f32 v208, v208, v160, v194
	v_fma_f32 v209, v209, v160, v195
	v_cvt_pk_bf16_f32 v210, v208, v209
	v_lshlrev_b32_e32 v18, 16, v210
	v_and_b32_e32 v19, 0xffff0000, v210
	v_lshlrev_b32_e32 v208, 16, v138
	v_and_b32_e32 v209, 0xffff0000, v138
	v_fma_f32 v208, v208, v160, v196
	v_fma_f32 v209, v209, v160, v197
	v_cvt_pk_bf16_f32 v210, v208, v209
	v_lshlrev_b32_e32 v20, 16, v210
	v_and_b32_e32 v21, 0xffff0000, v210
	v_lshlrev_b32_e32 v208, 16, v139
	v_and_b32_e32 v209, 0xffff0000, v139
	v_fma_f32 v208, v208, v160, v198
	v_fma_f32 v209, v209, v160, v199
	v_cvt_pk_bf16_f32 v210, v208, v209
	v_lshlrev_b32_e32 v22, 16, v210
	v_and_b32_e32 v23, 0xffff0000, v210
	v_lshlrev_b32_e32 v208, 16, v140
	v_and_b32_e32 v209, 0xffff0000, v140
	v_fma_f32 v208, v208, v160, v200
	v_fma_f32 v209, v209, v160, v201
	v_cvt_pk_bf16_f32 v210, v208, v209
	v_lshlrev_b32_e32 v24, 16, v210
	v_and_b32_e32 v25, 0xffff0000, v210
	v_lshlrev_b32_e32 v208, 16, v141
	v_and_b32_e32 v209, 0xffff0000, v141
	v_fma_f32 v208, v208, v160, v202
	v_fma_f32 v209, v209, v160, v203
	v_cvt_pk_bf16_f32 v210, v208, v209
	v_lshlrev_b32_e32 v26, 16, v210
	v_and_b32_e32 v27, 0xffff0000, v210
	v_lshlrev_b32_e32 v208, 16, v142
	v_and_b32_e32 v209, 0xffff0000, v142
	v_fma_f32 v208, v208, v160, v204
	v_fma_f32 v209, v209, v160, v205
	v_cvt_pk_bf16_f32 v210, v208, v209
	v_lshlrev_b32_e32 v28, 16, v210
	v_and_b32_e32 v29, 0xffff0000, v210
	v_lshlrev_b32_e32 v208, 16, v143
	v_and_b32_e32 v209, 0xffff0000, v143
	v_fma_f32 v208, v208, v160, v206
	v_fma_f32 v209, v209, v160, v207
	v_cvt_pk_bf16_f32 v210, v208, v209
	v_lshlrev_b32_e32 v30, 16, v210
	v_and_b32_e32 v31, 0xffff0000, v210
	s_nop 0
	s_add_i32 s0, s77, 4
	s_lshl_b32 s1, s0, 11
	s_add_u32 s78, s12, s1
	s_addc_u32 s79, s13, 0
	global_load_dwordx4 v[128:131], v245, s[78:79]
	global_load_dwordx4 v[132:135], v245, s[78:79] offset:16
	global_load_dwordx4 v[136:139], v245, s[78:79] offset:2048
	global_load_dwordx4 v[140:143], v245, s[78:79] offset:2064
	s_lshl_b32 s1, s0, 6
	s_add_u32 s78, s14, s1
	s_addc_u32 s79, s15, 0
	global_load_dwordx4 v[144:147], v244, s[78:79] offset:0
	global_load_dwordx4 v[148:151], v244, s[78:79] offset:16
	global_load_dwordx4 v[152:155], v244, s[78:79] offset:32
	global_load_dwordx4 v[156:159], v244, s[78:79] offset:48
	global_load_dwordx4 v[160:163], v244, s[78:79] offset:64
	global_load_dwordx4 v[164:167], v244, s[78:79] offset:80
	global_load_dwordx4 v[168:171], v244, s[78:79] offset:96
	global_load_dwordx4 v[172:175], v244, s[78:79] offset:112
	s_waitcnt vmcnt(12)
; __device__ __forceinline__ unsigned pk2(float lo, float hi) { const f32x2 v = {lo, hi}; const bf16x2_t b = __builtin_convertvector(v, bf16x2_t); return __builtin_bit_cast(unsigned, b); }
; __device__ __forceinline__ float bflo(unsigned u) { return __uint_as_float(u << 16); }
; __device__ __forceinline__ float bfhi(unsigned u) { return __uint_as_float(u & 0xffff0000u); }
; __device__ __forceinline__ void peer_tile(const Args& A, LAS unsigned char* lds, int tile) {
;     ...
;         for (int tk = 0; tk < 4; ++tk) { const size_t m = (size_t)tile * 64 + tb + tk;
;             { const u32x4 ra = *(const u32x4*)(A3 + m * 1024 + 16 * lane), rb = *(const u32x4*)(A3 + m * 1024 + 16 * lane + 8);
;               float xr_; { const f32x4 p0 = *(const f32x4*)(RSq + m * 16), p1 = *(const f32x4*)(RSq + m * 16 + 4), p2 = *(const f32x4*)(RSq + m * 16 + 8), p3 = *(const f32x4*)(RSq + m * 16 + 12);
;                 const f32x4 ps = (p0 + p1) + (p2 + p3); xr_ = rsqrtf(((ps[0] + ps[1]) + (ps[2] + ps[3])) * (1.f / 1024.f) + 1e-6f); }
;               const unsigned rr[8] = {ra.x, ra.y, ra.z, ra.w, rb.x, rb.y, rb.z, rb.w}; unsigned hh[8];
;               const float* sp = MOD + (int)(m >> 11) * 6144 + 3072 + 16 * lane;
; #pragma unroll
;               for (int q = 0; q < 8; ++q) { const f32x2 sh = *(const f32x2*)(sp + 2 * q); hh[q] = pk2(bflo(rr[q]) * xr_ + sh[0], bfhi(rr[q]) * xr_ + sh[1]); }
;               xpa[tk] = (u32x4){hh[0], hh[1], hh[2], hh[3]}; xpb[tk] = (u32x4){hh[4], hh[5], hh[6], hh[7]}; }
	v_pk_add_f32 v[216:217], v[216:217], v[220:221]
	v_pk_add_f32 v[218:219], v[218:219], v[222:223]
	v_pk_add_f32 v[224:225], v[224:225], v[228:229]
	v_pk_add_f32 v[226:227], v[226:227], v[230:231]
	v_pk_add_f32 v[216:217], v[216:217], v[224:225]
	v_pk_add_f32 v[218:219], v[218:219], v[226:227]
	v_add_f32_e32 v216, v216, v217
	v_add_f32_e32 v218, v218, v219
	v_add_f32_e32 v216, v216, v218
	v_fmamk_f32 v216, v216, 0x3a800000, v243
	v_rsq_f32_e32 v216, v216
	v_pk_add_f32 v[232:233], v[232:233], v[236:237]
	v_pk_add_f32 v[234:235], v[234:235], v[238:239]
	v_pk_add_f32 v[248:249], v[248:249], v[252:253]
	v_pk_add_f32 v[250:251], v[250:251], v[254:255]
	v_pk_add_f32 v[232:233], v[232:233], v[248:249]
	v_pk_add_f32 v[234:235], v[234:235], v[250:251]
	v_add_f32_e32 v232, v232, v233
	v_add_f32_e32 v234, v234, v235
	v_add_f32_e32 v232, v232, v234
	v_fmamk_f32 v232, v232, 0x3a800000, v243
	v_rsq_f32_e32 v232, v232
	v_lshlrev_b32_e32 v208, 16, v176
	v_and_b32_e32 v209, 0xffff0000, v176
	v_fma_f32 v208, v208, v216, v192
	v_fma_f32 v209, v209, v216, v193
	v_cvt_pk_bf16_f32 v210, v208, v209
	v_lshlrev_b32_e32 v32, 16, v210
	v_and_b32_e32 v33, 0xffff0000, v210
	v_lshlrev_b32_e32 v208, 16, v177
	v_and_b32_e32 v209, 0xffff0000, v177
	v_fma_f32 v208, v208, v216, v194
	v_fma_f32 v209, v209, v216, v195
	v_cvt_pk_bf16_f32 v210, v208, v209
	v_lshlrev_b32_e32 v34, 16, v210
	v_and_b32_e32 v35, 0xffff0000, v210
	v_lshlrev_b32_e32 v208, 16, v178
	v_and_b32_e32 v209, 0xffff0000, v178
	v_fma_f32 v208, v208, v216, v196
	v_fma_f32 v209, v209, v216, v197
	v_cvt_pk_bf16_f32 v210, v208, v209
	v_lshlrev_b32_e32 v36, 16, v210
	v_and_b32_e32 v37, 0xffff0000, v210
	v_lshlrev_b32_e32 v208, 16, v179
	v_and_b32_e32 v209, 0xffff0000, v179
	v_fma_f32 v208, v208, v216, v198
	v_fma_f32 v209, v209, v216, v199
	v_cvt_pk_bf16_f32 v210, v208, v209
	v_lshlrev_b32_e32 v38, 16, v210
	v_and_b32_e32 v39, 0xffff0000, v210
	v_lshlrev_b32_e32 v208, 16, v180
	v_and_b32_e32 v209, 0xffff0000, v180
	v_fma_f32 v208, v208, v216, v200
	v_fma_f32 v209, v209, v216, v201
	v_cvt_pk_bf16_f32 v210, v208, v209
	v_lshlrev_b32_e32 v40, 16, v210
	v_and_b32_e32 v41, 0xffff0000, v210
	v_lshlrev_b32_e32 v208, 16, v181
	v_and_b32_e32 v209, 0xffff0000, v181
	v_fma_f32 v208, v208, v216, v202
	v_fma_f32 v209, v209, v216, v203
	v_cvt_pk_bf16_f32 v210, v208, v209
	v_lshlrev_b32_e32 v42, 16, v210
	v_and_b32_e32 v43, 0xffff0000, v210
	v_lshlrev_b32_e32 v208, 16, v182
	v_and_b32_e32 v209, 0xffff0000, v182
	v_fma_f32 v208, v208, v216, v204
	v_fma_f32 v209, v209, v216, v205
	v_cvt_pk_bf16_f32 v210, v208, v209
	v_lshlrev_b32_e32 v44, 16, v210
	v_and_b32_e32 v45, 0xffff0000, v210
	v_lshlrev_b32_e32 v208, 16, v183
	v_and_b32_e32 v209, 0xffff0000, v183
	v_fma_f32 v208, v208, v216, v206
	v_fma_f32 v209, v209, v216, v207
	v_cvt_pk_bf16_f32 v210, v208, v209
	v_lshlrev_b32_e32 v46, 16, v210
	v_and_b32_e32 v47, 0xffff0000, v210
	v_lshlrev_b32_e32 v208, 16, v184
	v_and_b32_e32 v209, 0xffff0000, v184
	v_fma_f32 v208, v208, v232, v192
	v_fma_f32 v209, v209, v232, v193
	v_cvt_pk_bf16_f32 v210, v208, v209
	v_lshlrev_b32_e32 v48, 16, v210
	v_and_b32_e32 v49, 0xffff0000, v210
	v_lshlrev_b32_e32 v208, 16, v185
	v_and_b32_e32 v209, 0xffff0000, v185
	v_fma_f32 v208, v208, v232, v194
	v_fma_f32 v209, v209, v232, v195
	v_cvt_pk_bf16_f32 v210, v208, v209
	v_lshlrev_b32_e32 v50, 16, v210
	v_and_b32_e32 v51, 0xffff0000, v210
	v_lshlrev_b32_e32 v208, 16, v186
	v_and_b32_e32 v209, 0xffff0000, v186
	v_fma_f32 v208, v208, v232, v196
	v_fma_f32 v209, v209, v232, v197
	v_cvt_pk_bf16_f32 v210, v208, v209
	v_lshlrev_b32_e32 v52, 16, v210
	v_and_b32_e32 v53, 0xffff0000, v210
	v_lshlrev_b32_e32 v208, 16, v187
	v_and_b32_e32 v209, 0xffff0000, v187
	v_fma_f32 v208, v208, v232, v198
	v_fma_f32 v209, v209, v232, v199
	v_cvt_pk_bf16_f32 v210, v208, v209
	v_lshlrev_b32_e32 v54, 16, v210
	v_and_b32_e32 v55, 0xffff0000, v210
	v_lshlrev_b32_e32 v208, 16, v188
	v_and_b32_e32 v209, 0xffff0000, v188
	v_fma_f32 v208, v208, v232, v200
	v_fma_f32 v209, v209, v232, v201
	v_cvt_pk_bf16_f32 v210, v208, v209
	v_lshlrev_b32_e32 v56, 16, v210
	v_and_b32_e32 v57, 0xffff0000, v210
	v_lshlrev_b32_e32 v208, 16, v189
	v_and_b32_e32 v209, 0xffff0000, v189
	v_fma_f32 v208, v208, v232, v202
	v_fma_f32 v209, v209, v232, v203
	v_cvt_pk_bf16_f32 v210, v208, v209
	v_lshlrev_b32_e32 v58, 16, v210
	v_and_b32_e32 v59, 0xffff0000, v210
	v_lshlrev_b32_e32 v208, 16, v190
	v_and_b32_e32 v209, 0xffff0000, v190
	v_fma_f32 v208, v208, v232, v204
	v_fma_f32 v209, v209, v232, v205
	v_cvt_pk_bf16_f32 v210, v208, v209
	v_lshlrev_b32_e32 v60, 16, v210
	v_and_b32_e32 v61, 0xffff0000, v210
	v_lshlrev_b32_e32 v208, 16, v191
	v_and_b32_e32 v209, 0xffff0000, v191
	v_fma_f32 v208, v208, v232, v206
	v_fma_f32 v209, v209, v232, v207
	v_cvt_pk_bf16_f32 v210, v208, v209
	v_lshlrev_b32_e32 v62, 16, v210
	v_and_b32_e32 v63, 0xffff0000, v210
	s_nop 0
	s_add_i32 s0, s77, 6
	s_lshl_b32 s1, s0, 11
	s_add_u32 s78, s12, s1
	s_addc_u32 s79, s13, 0
	global_load_dwordx4 v[176:179], v245, s[78:79]
	global_load_dwordx4 v[180:183], v245, s[78:79] offset:16
	global_load_dwordx4 v[184:187], v245, s[78:79] offset:2048
	global_load_dwordx4 v[188:191], v245, s[78:79] offset:2064
	s_lshl_b32 s1, s0, 6
	s_add_u32 s78, s14, s1
	s_addc_u32 s79, s15, 0
	global_load_dwordx4 v[216:219], v244, s[78:79] offset:0
	global_load_dwordx4 v[220:223], v244, s[78:79] offset:16
	global_load_dwordx4 v[224:227], v244, s[78:79] offset:32
	global_load_dwordx4 v[228:231], v244, s[78:79] offset:48
	global_load_dwordx4 v[232:235], v244, s[78:79] offset:64
	global_load_dwordx4 v[236:239], v244, s[78:79] offset:80
	global_load_dwordx4 v[248:251], v244, s[78:79] offset:96
	global_load_dwordx4 v[252:255], v244, s[78:79] offset:112
	s_waitcnt vmcnt(12)
; __device__ __forceinline__ unsigned pk2(float lo, float hi) { const f32x2 v = {lo, hi}; const bf16x2_t b = __builtin_convertvector(v, bf16x2_t); return __builtin_bit_cast(unsigned, b); }
; __device__ __forceinline__ float bflo(unsigned u) { return __uint_as_float(u << 16); }
; __device__ __forceinline__ float bfhi(unsigned u) { return __uint_as_float(u & 0xffff0000u); }
; __device__ __forceinline__ void peer_tile(const Args& A, LAS unsigned char* lds, int tile) {
;     ...
;         for (int tk = 0; tk < 4; ++tk) { const size_t m = (size_t)tile * 64 + tb + tk;
;             { const u32x4 ra = *(const u32x4*)(A3 + m * 1024 + 16 * lane), rb = *(const u32x4*)(A3 + m * 1024 + 16 * lane + 8);
;               float xr_; { const f32x4 p0 = *(const f32x4*)(RSq + m * 16), p1 = *(const f32x4*)(RSq + m * 16 + 4), p2 = *(const f32x4*)(RSq + m * 16 + 8), p3 = *(const f32x4*)(RSq + m * 16 + 12);
;                 const f32x4 ps = (p0 + p1) + (p2 + p3); xr_ = rsqrtf(((ps[0] + ps[1]) + (ps[2] + ps[3])) * (1.f / 1024.f) + 1e-6f); }
;               const unsigned rr[8] = {ra.x, ra.y, ra.z, ra.w, rb.x, rb.y, rb.z, rb.w}; unsigned hh[8];
;               const float* sp = MOD + (int)(m >> 11) * 6144 + 3072 + 16 * lane;
; #pragma unroll
;               for (int q = 0; q < 8; ++q) { const f32x2 sh = *(const f32x2*)(sp + 2 * q); hh[q] = pk2(bflo(rr[q]) * xr_ + sh[0], bfhi(rr[q]) * xr_ + sh[1]); }
;               xpa[tk] = (u32x4){hh[0], hh[1], hh[2], hh[3]}; xpb[tk] = (u32x4){hh[4], hh[5], hh[6], hh[7]}; }
	v_pk_add_f32 v[144:145], v[144:145], v[148:149]
	v_pk_add_f32 v[146:147], v[146:147], v[150:151]
	v_pk_add_f32 v[152:153], v[152:153], v[156:157]
	v_pk_add_f32 v[154:155], v[154:155], v[158:159]
	v_pk_add_f32 v[144:145], v[144:145], v[152:153]
	v_pk_add_f32 v[146:147], v[146:147], v[154:155]
	v_add_f32_e32 v144, v144, v145
	v_add_f32_e32 v146, v146, v147
	v_add_f32_e32 v144, v144, v146
	v_fmamk_f32 v144, v144, 0x3a800000, v243
	v_rsq_f32_e32 v144, v144
	v_pk_add_f32 v[160:161], v[160:161], v[164:165]
	v_pk_add_f32 v[162:163], v[162:163], v[166:167]
	v_pk_add_f32 v[168:169], v[168:169], v[172:173]
	v_pk_add_f32 v[170:171], v[170:171], v[174:175]
	v_pk_add_f32 v[160:161], v[160:161], v[168:169]
	v_pk_add_f32 v[162:163], v[162:163], v[170:171]
	v_add_f32_e32 v160, v160, v161
	v_add_f32_e32 v162, v162, v163
	v_add_f32_e32 v160, v160, v162
	v_fmamk_f32 v160, v160, 0x3a800000, v243
	v_rsq_f32_e32 v160, v160
	v_lshlrev_b32_e32 v208, 16, v128
	v_and_b32_e32 v209, 0xffff0000, v128
	v_fma_f32 v208, v208, v144, v192
	v_fma_f32 v209, v209, v144, v193
	v_cvt_pk_bf16_f32 v210, v208, v209
	v_lshlrev_b32_e32 v64, 16, v210
	v_and_b32_e32 v65, 0xffff0000, v210
	v_lshlrev_b32_e32 v208, 16, v129
	v_and_b32_e32 v209, 0xffff0000, v129
	v_fma_f32 v208, v208, v144, v194
	v_fma_f32 v209, v209, v144, v195
	v_cvt_pk_bf16_f32 v210, v208, v209
	v_lshlrev_b32_e32 v66, 16, v210
	v_and_b32_e32 v67, 0xffff0000, v210
	v_lshlrev_b32_e32 v208, 16, v130
	v_and_b32_e32 v209, 0xffff0000, v130
	v_fma_f32 v208, v208, v144, v196
	v_fma_f32 v209, v209, v144, v197
	v_cvt_pk_bf16_f32 v210, v208, v209
	v_lshlrev_b32_e32 v68, 16, v210
	v_and_b32_e32 v69, 0xffff0000, v210
	v_lshlrev_b32_e32 v208, 16, v131
	v_and_b32_e32 v209, 0xffff0000, v131
	v_fma_f32 v208, v208, v144, v198
	v_fma_f32 v209, v209, v144, v199
	v_cvt_pk_bf16_f32 v210, v208, v209
	v_lshlrev_b32_e32 v70, 16, v210
	v_and_b32_e32 v71, 0xffff0000, v210
	v_lshlrev_b32_e32 v208, 16, v132
	v_and_b32_e32 v209, 0xffff0000, v132
	v_fma_f32 v208, v208, v144, v200
	v_fma_f32 v209, v209, v144, v201
	v_cvt_pk_bf16_f32 v210, v208, v209
	v_lshlrev_b32_e32 v72, 16, v210
	v_and_b32_e32 v73, 0xffff0000, v210
	v_lshlrev_b32_e32 v208, 16, v133
	v_and_b32_e32 v209, 0xffff0000, v133
	v_fma_f32 v208, v208, v144, v202
	v_fma_f32 v209, v209, v144, v203
	v_cvt_pk_bf16_f32 v210, v208, v209
	v_lshlrev_b32_e32 v74, 16, v210
	v_and_b32_e32 v75, 0xffff0000, v210
	v_lshlrev_b32_e32 v208, 16, v134
	v_and_b32_e32 v209, 0xffff0000, v134
	v_fma_f32 v208, v208, v144, v204
	v_fma_f32 v209, v209, v144, v205
	v_cvt_pk_bf16_f32 v210, v208, v209
	v_lshlrev_b32_e32 v76, 16, v210
	v_and_b32_e32 v77, 0xffff0000, v210
	v_lshlrev_b32_e32 v208, 16, v135
	v_and_b32_e32 v209, 0xffff0000, v135
	v_fma_f32 v208, v208, v144, v206
	v_fma_f32 v209, v209, v144, v207
	v_cvt_pk_bf16_f32 v210, v208, v209
	v_lshlrev_b32_e32 v78, 16, v210
	v_and_b32_e32 v79, 0xffff0000, v210
	v_lshlrev_b32_e32 v208, 16, v136
	v_and_b32_e32 v209, 0xffff0000, v136
	v_fma_f32 v208, v208, v160, v192
	v_fma_f32 v209, v209, v160, v193
	v_cvt_pk_bf16_f32 v210, v208, v209
	v_lshlrev_b32_e32 v80, 16, v210
	v_and_b32_e32 v81, 0xffff0000, v210
	v_lshlrev_b32_e32 v208, 16, v137
	v_and_b32_e32 v209, 0xffff0000, v137
	v_fma_f32 v208, v208, v160, v194
	v_fma_f32 v209, v209, v160, v195
	v_cvt_pk_bf16_f32 v210, v208, v209
	v_lshlrev_b32_e32 v82, 16, v210
	v_and_b32_e32 v83, 0xffff0000, v210
	v_lshlrev_b32_e32 v208, 16, v138
	v_and_b32_e32 v209, 0xffff0000, v138
	v_fma_f32 v208, v208, v160, v196
	v_fma_f32 v209, v209, v160, v197
	v_cvt_pk_bf16_f32 v210, v208, v209
	v_lshlrev_b32_e32 v84, 16, v210
	v_and_b32_e32 v85, 0xffff0000, v210
	v_lshlrev_b32_e32 v208, 16, v139
	v_and_b32_e32 v209, 0xffff0000, v139
	v_fma_f32 v208, v208, v160, v198
	v_fma_f32 v209, v209, v160, v199
	v_cvt_pk_bf16_f32 v210, v208, v209
	v_lshlrev_b32_e32 v86, 16, v210
	v_and_b32_e32 v87, 0xffff0000, v210
	v_lshlrev_b32_e32 v208, 16, v140
	v_and_b32_e32 v209, 0xffff0000, v140
	v_fma_f32 v208, v208, v160, v200
	v_fma_f32 v209, v209, v160, v201
	v_cvt_pk_bf16_f32 v210, v208, v209
	v_lshlrev_b32_e32 v88, 16, v210
	v_and_b32_e32 v89, 0xffff0000, v210
	v_lshlrev_b32_e32 v208, 16, v141
	v_and_b32_e32 v209, 0xffff0000, v141
	v_fma_f32 v208, v208, v160, v202
	v_fma_f32 v209, v209, v160, v203
	v_cvt_pk_bf16_f32 v210, v208, v209
	v_lshlrev_b32_e32 v90, 16, v210
	v_and_b32_e32 v91, 0xffff0000, v210
	v_lshlrev_b32_e32 v208, 16, v142
	v_and_b32_e32 v209, 0xffff0000, v142
	v_fma_f32 v208, v208, v160, v204
	v_fma_f32 v209, v209, v160, v205
	v_cvt_pk_bf16_f32 v210, v208, v209
	v_lshlrev_b32_e32 v92, 16, v210
	v_and_b32_e32 v93, 0xffff0000, v210
	v_lshlrev_b32_e32 v208, 16, v143
	v_and_b32_e32 v209, 0xffff0000, v143
	v_fma_f32 v208, v208, v160, v206
	v_fma_f32 v209, v209, v160, v207
	v_cvt_pk_bf16_f32 v210, v208, v209
	v_lshlrev_b32_e32 v94, 16, v210
	v_and_b32_e32 v95, 0xffff0000, v210
	s_nop 0
	s_waitcnt vmcnt(0)
; __device__ __forceinline__ unsigned pk2(float lo, float hi) { const f32x2 v = {lo, hi}; const bf16x2_t b = __builtin_convertvector(v, bf16x2_t); return __builtin_bit_cast(unsigned, b); }
; __device__ __forceinline__ float bflo(unsigned u) { return __uint_as_float(u << 16); }
; __device__ __forceinline__ void peer_tile(const Args& A, LAS unsigned char* lds, int tile) {
;     ...
;     for (int ti = 0; ti < 8; ++ti) {
;         const int tl = 8 * w + ti;
;         const u32x2 e0 = SEL[tl * 128 + lane], e1 = SEL[tl * 128 + 64 + lane];
;         const int p0 = (int)(e0.x >> 10), p1 = (int)(e1.x >> 10);
;         int off = 0;
;         for (int p = 0; p < 16; ++p) {
;             const unsigned long long m0 = __ballot(p0 == p), m1 = __ballot(p1 == p);
;             const int c0 = __popcll(m0), c1 = __popcll(m1);
;             const int r0 = __builtin_amdgcn_mbcnt_hi((unsigned)(m0 >> 32), __builtin_amdgcn_mbcnt_lo((unsigned)m0, 0u));
;             const int r1 = __builtin_amdgcn_mbcnt_hi((unsigned)(m1 >> 32), __builtin_amdgcn_mbcnt_lo((unsigned)m1, 0u));
;             if (p0 == p) SORT[tl * 128 + off + r0] = e0;
;             if (p1 == p) SORT[tl * 128 + off + c0 + r1] = e1;
;             if (lane == 0) OFFS[tl * 17 + p] = off;
;             off += c0 + c1;
;         }
;         if (lane == 0) OFFS[tl * 17 + 16] = off;
;     }
;     ...
;         for (int tk = 0; tk < 4; ++tk) { const size_t m = (size_t)tile * 64 + tb + tk;
;             { const u32x4 ra = *(const u32x4*)(A3 + m * 1024 + 16 * lane), rb = *(const u32x4*)(A3 + m * 1024 + 16 * lane + 8);
;               float xr_; { const f32x4 p0 = *(const f32x4*)(RSq + m * 16), p1 = *(const f32x4*)(RSq + m * 16 + 4), p2 = *(const f32x4*)(RSq + m * 16 + 8), p3 = *(const f32x4*)(RSq + m * 16 + 12);
;                 const f32x4 ps = (p0 + p1) + (p2 + p3); xr_ = rsqrtf(((ps[0] + ps[1]) + (ps[2] + ps[3])) * (1.f / 1024.f) + 1e-6f); }
;               const unsigned rr[8] = {ra.x, ra.y, ra.z, ra.w, rb.x, rb.y, rb.z, rb.w}; unsigned hh[8];
;               const float* sp = MOD + (int)(m >> 11) * 6144 + 3072 + 16 * lane;
; #pragma unroll
;               for (int q = 0; q < 8; ++q) { const f32x2 sh = *(const f32x2*)(sp + 2 * q); hh[q] = pk2(bflo(rr[q]) * xr_ + sh[0], bfhi(rr[q]) * xr_ + sh[1]); }
;               xpa[tk] = (u32x4){hh[0], hh[1], hh[2], hh[3]}; xpb[tk] = (u32x4){hh[4], hh[5], hh[6], hh[7]}; }
	v_pk_add_f32 v[216:217], v[216:217], v[220:221]
	v_pk_add_f32 v[218:219], v[218:219], v[222:223]
	v_pk_add_f32 v[224:225], v[224:225], v[228:229]
	v_pk_add_f32 v[226:227], v[226:227], v[230:231]
	v_pk_add_f32 v[216:217], v[216:217], v[224:225]
	v_pk_add_f32 v[218:219], v[218:219], v[226:227]
	v_add_f32_e32 v216, v216, v217
	v_add_f32_e32 v218, v218, v219
	v_add_f32_e32 v216, v216, v218
	v_fmamk_f32 v216, v216, 0x3a800000, v243
	v_rsq_f32_e32 v216, v216
	v_pk_add_f32 v[232:233], v[232:233], v[236:237]
	v_pk_add_f32 v[234:235], v[234:235], v[238:239]
	v_pk_add_f32 v[248:249], v[248:249], v[252:253]
	v_pk_add_f32 v[250:251], v[250:251], v[254:255]
	v_pk_add_f32 v[232:233], v[232:233], v[248:249]
	v_pk_add_f32 v[234:235], v[234:235], v[250:251]
	v_add_f32_e32 v232, v232, v233
	v_add_f32_e32 v234, v234, v235
	v_add_f32_e32 v232, v232, v234
	v_fmamk_f32 v232, v232, 0x3a800000, v243
	v_rsq_f32_e32 v232, v232
	v_lshlrev_b32_e32 v208, 16, v176
	v_and_b32_e32 v209, 0xffff0000, v176
	v_fma_f32 v208, v208, v216, v192
	v_fma_f32 v209, v209, v216, v193
	v_cvt_pk_bf16_f32 v210, v208, v209
	v_lshlrev_b32_e32 v96, 16, v210
	v_and_b32_e32 v97, 0xffff0000, v210
	v_lshlrev_b32_e32 v208, 16, v177
	v_and_b32_e32 v209, 0xffff0000, v177
	v_fma_f32 v208, v208, v216, v194
	v_fma_f32 v209, v209, v216, v195
	v_cvt_pk_bf16_f32 v210, v208, v209
	v_lshlrev_b32_e32 v98, 16, v210
	v_and_b32_e32 v99, 0xffff0000, v210
	v_lshlrev_b32_e32 v208, 16, v178
	v_and_b32_e32 v209, 0xffff0000, v178
	v_fma_f32 v208, v208, v216, v196
	v_fma_f32 v209, v209, v216, v197
	v_cvt_pk_bf16_f32 v210, v208, v209
	v_lshlrev_b32_e32 v100, 16, v210
	v_and_b32_e32 v101, 0xffff0000, v210
	v_lshlrev_b32_e32 v208, 16, v179
	v_and_b32_e32 v209, 0xffff0000, v179
	v_fma_f32 v208, v208, v216, v198
	v_fma_f32 v209, v209, v216, v199
	v_cvt_pk_bf16_f32 v210, v208, v209
	v_lshlrev_b32_e32 v102, 16, v210
	v_and_b32_e32 v103, 0xffff0000, v210
	v_lshlrev_b32_e32 v208, 16, v180
	v_and_b32_e32 v209, 0xffff0000, v180
	v_fma_f32 v208, v208, v216, v200
	v_fma_f32 v209, v209, v216, v201
	v_cvt_pk_bf16_f32 v210, v208, v209
	v_lshlrev_b32_e32 v104, 16, v210
	v_and_b32_e32 v105, 0xffff0000, v210
	v_lshlrev_b32_e32 v208, 16, v181
	v_and_b32_e32 v209, 0xffff0000, v181
	v_fma_f32 v208, v208, v216, v202
	v_fma_f32 v209, v209, v216, v203
	v_cvt_pk_bf16_f32 v210, v208, v209
	v_lshlrev_b32_e32 v106, 16, v210
	v_and_b32_e32 v107, 0xffff0000, v210
	v_lshlrev_b32_e32 v208, 16, v182
	v_and_b32_e32 v209, 0xffff0000, v182
	v_fma_f32 v208, v208, v216, v204
	v_fma_f32 v209, v209, v216, v205
	v_cvt_pk_bf16_f32 v210, v208, v209
	v_lshlrev_b32_e32 v108, 16, v210
	v_and_b32_e32 v109, 0xffff0000, v210
	v_lshlrev_b32_e32 v208, 16, v183
	v_and_b32_e32 v209, 0xffff0000, v183
	v_fma_f32 v208, v208, v216, v206
	v_fma_f32 v209, v209, v216, v207
	v_cvt_pk_bf16_f32 v210, v208, v209
	v_lshlrev_b32_e32 v110, 16, v210
	v_and_b32_e32 v111, 0xffff0000, v210
	v_lshlrev_b32_e32 v208, 16, v184
	v_and_b32_e32 v209, 0xffff0000, v184
	v_fma_f32 v208, v208, v232, v192
	v_fma_f32 v209, v209, v232, v193
	v_cvt_pk_bf16_f32 v210, v208, v209
	v_lshlrev_b32_e32 v112, 16, v210
	v_and_b32_e32 v113, 0xffff0000, v210
	v_lshlrev_b32_e32 v208, 16, v185
	v_and_b32_e32 v209, 0xffff0000, v185
	v_fma_f32 v208, v208, v232, v194
	v_fma_f32 v209, v209, v232, v195
	v_cvt_pk_bf16_f32 v210, v208, v209
	v_lshlrev_b32_e32 v114, 16, v210
	v_and_b32_e32 v115, 0xffff0000, v210
	v_lshlrev_b32_e32 v208, 16, v186
	v_and_b32_e32 v209, 0xffff0000, v186
	v_fma_f32 v208, v208, v232, v196
	v_fma_f32 v209, v209, v232, v197
	v_cvt_pk_bf16_f32 v210, v208, v209
	v_lshlrev_b32_e32 v116, 16, v210
	v_and_b32_e32 v117, 0xffff0000, v210
	v_lshlrev_b32_e32 v208, 16, v187
	v_and_b32_e32 v209, 0xffff0000, v187
	v_fma_f32 v208, v208, v232, v198
	v_fma_f32 v209, v209, v232, v199
	v_cvt_pk_bf16_f32 v210, v208, v209
	v_lshlrev_b32_e32 v118, 16, v210
	v_and_b32_e32 v119, 0xffff0000, v210
	v_lshlrev_b32_e32 v208, 16, v188
	v_and_b32_e32 v209, 0xffff0000, v188
	v_fma_f32 v208, v208, v232, v200
	v_fma_f32 v209, v209, v232, v201
	v_cvt_pk_bf16_f32 v210, v208, v209
	v_lshlrev_b32_e32 v120, 16, v210
	v_and_b32_e32 v121, 0xffff0000, v210
	v_lshlrev_b32_e32 v208, 16, v189
	v_and_b32_e32 v209, 0xffff0000, v189
	v_fma_f32 v208, v208, v232, v202
	v_fma_f32 v209, v209, v232, v203
	v_cvt_pk_bf16_f32 v210, v208, v209
	v_lshlrev_b32_e32 v122, 16, v210
	v_and_b32_e32 v123, 0xffff0000, v210
	v_lshlrev_b32_e32 v208, 16, v190
	v_and_b32_e32 v209, 0xffff0000, v190
	v_fma_f32 v208, v208, v232, v204
	v_fma_f32 v209, v209, v232, v205
	v_cvt_pk_bf16_f32 v210, v208, v209
	v_lshlrev_b32_e32 v124, 16, v210
	v_and_b32_e32 v125, 0xffff0000, v210
	v_lshlrev_b32_e32 v208, 16, v191
	v_and_b32_e32 v209, 0xffff0000, v191
	v_fma_f32 v208, v208, v232, v206
	v_fma_f32 v209, v209, v232, v207
	v_cvt_pk_bf16_f32 v210, v208, v209
	v_lshlrev_b32_e32 v126, 16, v210
	v_and_b32_e32 v127, 0xffff0000, v210
	s_nop 0
	s_mov_b32 s24, s8
	s_and_b32 s25, s9, 0xffff
	s_mov_b32 s26, 0x20000
	s_mov_b32 s27, 0x00027000
	s_lshl_b32 s0, s76, 10
	s_add_i32 s0, s0, 0x11000
	s_sub_i32 s85, s0, s22
	v_mov_b32_e32 v224, 0x7fffffff
	v_mov_b32_e32 v225, 0x7fffffff
	v_mov_b32_e32 v226, 0x7fffffff
	v_mov_b32_e32 v227, 0x7fffffff
	v_mov_b32_e32 v228, 0
	v_mov_b32_e32 v229, 0
	v_mov_b32_e32 v230, 0
	v_mov_b32_e32 v231, 0
	v_add_u32_e32 v232, s22, v240
	ds_write_b128 v232, v[224:227] offset:0
	ds_write_b128 v232, v[228:231] offset:4992
	ds_write_b128 v232, v[224:227] offset:1024
	ds_write_b128 v232, v[228:231] offset:6016
	ds_write_b128 v232, v[224:227] offset:2048
	ds_write_b128 v232, v[228:231] offset:7040
	ds_write_b128 v232, v[224:227] offset:3072
	ds_write_b128 v232, v[228:231] offset:8064
	s_mov_b32 exec_hi, 0x00ffffff
	ds_write_b128 v232, v[224:227] offset:4096
	s_mov_b32 exec_hi, 0x000fffff
	ds_write_b128 v232, v[228:231] offset:9088
	s_mov_b64 exec, -1
	v_lshrrev_b32_e32 v221, 2, v240
	v_add_u32_e32 v221, s22, v221
	ds_write_b32 v221, v228 offset:4224
	v_lshrrev_b32_e32 v233, 1, v240
	s_lshl_b32 s0, s76, 10
	s_add_i32 s0, s0, 0x11000
	v_add_u32_e32 v233, s0, v233
	ds_read_b64 v[128:129], v233 offset:0
	ds_read_b64 v[130:131], v233 offset:512
	ds_read_b64 v[132:133], v233 offset:1024
	ds_read_b64 v[134:135], v233 offset:1536
	ds_read_b64 v[136:137], v233 offset:2048
	ds_read_b64 v[138:139], v233 offset:2560
	ds_read_b64 v[140:141], v233 offset:3072
	ds_read_b64 v[142:143], v233 offset:3584
	ds_read_b64 v[144:145], v233 offset:4096
	ds_read_b64 v[146:147], v233 offset:4608
	ds_read_b64 v[148:149], v233 offset:5120
	ds_read_b64 v[150:151], v233 offset:5632
	ds_read_b64 v[152:153], v233 offset:6144
	ds_read_b64 v[154:155], v233 offset:6656
	ds_read_b64 v[156:157], v233 offset:7168
	ds_read_b64 v[158:159], v233 offset:7680
	v_mov_b32_e32 v220, 1
	v_lshrrev_b32_e32 v200, 4, v240
	v_lshrrev_b32_e32 v201, 3, v200
	v_and_b32_e32 v200, 7, v200
	s_add_i32 s3, s22, 4224
	s_and_b32 s1, s32, 7
	s_waitcnt lgkmcnt(0)
; __device__ __forceinline__ void peer_tile(const Args& A, LAS unsigned char* lds, int tile) {
;     ...
;     for (int ti = 0; ti < 8; ++ti) {
;         const int tl = 8 * w + ti;
;         const u32x2 e0 = SEL[tl * 128 + lane], e1 = SEL[tl * 128 + 64 + lane];
;         const int p0 = (int)(e0.x >> 10), p1 = (int)(e1.x >> 10);
;         int off = 0;
;         for (int p = 0; p < 16; ++p) {
;             const unsigned long long m0 = __ballot(p0 == p), m1 = __ballot(p1 == p);
;             const int c0 = __popcll(m0), c1 = __popcll(m1);
;             const int r0 = __builtin_amdgcn_mbcnt_hi((unsigned)(m0 >> 32), __builtin_amdgcn_mbcnt_lo((unsigned)m0, 0u));
;             const int r1 = __builtin_amdgcn_mbcnt_hi((unsigned)(m1 >> 32), __builtin_amdgcn_mbcnt_lo((unsigned)m1, 0u));
;             if (p0 == p) SORT[tl * 128 + off + r0] = e0;
;             if (p1 == p) SORT[tl * 128 + off + c0 + r1] = e1;
;             if (lane == 0) OFFS[tl * 17 + p] = off;
;             off += c0 + c1;
;         }
;         if (lane == 0) OFFS[tl * 17 + 16] = off;
;     }
	v_lshrrev_b32_e32 v160, 11, v128
	v_subrev_u32_e32 v160, s1, v160
	v_and_b32_e32 v160, 7, v160
	v_lshl_add_u32 v176, v160, 2, s3
	v_lshrrev_b32_e32 v161, 11, v130
	v_subrev_u32_e32 v161, s1, v161
	v_and_b32_e32 v161, 7, v161
	v_lshl_add_u32 v177, v161, 2, s3
	v_lshrrev_b32_e32 v162, 11, v132
	v_subrev_u32_e32 v162, s1, v162
	v_and_b32_e32 v162, 7, v162
	v_lshl_add_u32 v178, v162, 2, s3
	v_lshrrev_b32_e32 v163, 11, v134
	v_subrev_u32_e32 v163, s1, v163
	v_and_b32_e32 v163, 7, v163
	v_lshl_add_u32 v179, v163, 2, s3
	v_lshrrev_b32_e32 v164, 11, v136
	v_subrev_u32_e32 v164, s1, v164
	v_and_b32_e32 v164, 7, v164
	v_lshl_add_u32 v180, v164, 2, s3
	v_lshrrev_b32_e32 v165, 11, v138
	v_subrev_u32_e32 v165, s1, v165
	v_and_b32_e32 v165, 7, v165
	v_lshl_add_u32 v181, v165, 2, s3
	v_lshrrev_b32_e32 v166, 11, v140
	v_subrev_u32_e32 v166, s1, v166
	v_and_b32_e32 v166, 7, v166
	v_lshl_add_u32 v182, v166, 2, s3
	v_lshrrev_b32_e32 v167, 11, v142
	v_subrev_u32_e32 v167, s1, v167
	v_and_b32_e32 v167, 7, v167
	v_lshl_add_u32 v183, v167, 2, s3
	v_lshrrev_b32_e32 v168, 11, v144
	v_subrev_u32_e32 v168, s1, v168
	v_and_b32_e32 v168, 7, v168
	v_lshl_add_u32 v184, v168, 2, s3
	v_lshrrev_b32_e32 v169, 11, v146
	v_subrev_u32_e32 v169, s1, v169
	v_and_b32_e32 v169, 7, v169
	v_lshl_add_u32 v185, v169, 2, s3
	v_lshrrev_b32_e32 v170, 11, v148
	v_subrev_u32_e32 v170, s1, v170
	v_and_b32_e32 v170, 7, v170
	v_lshl_add_u32 v186, v170, 2, s3
	v_lshrrev_b32_e32 v171, 11, v150
	v_subrev_u32_e32 v171, s1, v171
	v_and_b32_e32 v171, 7, v171
	v_lshl_add_u32 v187, v171, 2, s3
	v_lshrrev_b32_e32 v172, 11, v152
	v_subrev_u32_e32 v172, s1, v172
	v_and_b32_e32 v172, 7, v172
	v_lshl_add_u32 v188, v172, 2, s3
	v_lshrrev_b32_e32 v173, 11, v154
	v_subrev_u32_e32 v173, s1, v173
	v_and_b32_e32 v173, 7, v173
	v_lshl_add_u32 v189, v173, 2, s3
	v_lshrrev_b32_e32 v174, 11, v156
	v_subrev_u32_e32 v174, s1, v174
	v_and_b32_e32 v174, 7, v174
	v_lshl_add_u32 v190, v174, 2, s3
	v_lshrrev_b32_e32 v175, 11, v158
	v_subrev_u32_e32 v175, s1, v175
	v_and_b32_e32 v175, 7, v175
	v_lshl_add_u32 v191, v175, 2, s3
	v_lshlrev_b32_e32 v206, 3, v128
	buffer_load_dwordx2 v[224:225], v206, s[24:27], 0 offen
	v_lshlrev_b32_e32 v206, 3, v130
	buffer_load_dwordx2 v[226:227], v206, s[24:27], 0 offen
	v_lshlrev_b32_e32 v206, 3, v132
	buffer_load_dwordx2 v[228:229], v206, s[24:27], 0 offen
	v_lshlrev_b32_e32 v206, 3, v134
	buffer_load_dwordx2 v[230:231], v206, s[24:27], 0 offen
	v_lshlrev_b32_e32 v206, 3, v136
	buffer_load_dwordx2 v[232:233], v206, s[24:27], 0 offen
	v_lshlrev_b32_e32 v206, 3, v138
	buffer_load_dwordx2 v[234:235], v206, s[24:27], 0 offen
	v_lshlrev_b32_e32 v206, 3, v140
	buffer_load_dwordx2 v[236:237], v206, s[24:27], 0 offen
	v_lshlrev_b32_e32 v206, 3, v142
	buffer_load_dwordx2 v[238:239], v206, s[24:27], 0 offen
	v_lshlrev_b32_e32 v206, 3, v144
	buffer_load_dwordx2 v[248:249], v206, s[24:27], 0 offen
	v_lshlrev_b32_e32 v206, 3, v146
	buffer_load_dwordx2 v[250:251], v206, s[24:27], 0 offen
	v_lshlrev_b32_e32 v206, 3, v148
	buffer_load_dwordx2 v[252:253], v206, s[24:27], 0 offen
	v_lshlrev_b32_e32 v206, 3, v150
	buffer_load_dwordx2 v[254:255], v206, s[24:27], 0 offen
	ds_add_rtn_u32 v176, v176, v220 offset:0
	ds_add_rtn_u32 v177, v177, v220 offset:0
	ds_add_rtn_u32 v178, v178, v220 offset:32
	ds_add_rtn_u32 v179, v179, v220 offset:32
	ds_add_rtn_u32 v180, v180, v220 offset:64
	ds_add_rtn_u32 v181, v181, v220 offset:64
	ds_add_rtn_u32 v182, v182, v220 offset:96
	ds_add_rtn_u32 v183, v183, v220 offset:96
	ds_add_rtn_u32 v184, v184, v220 offset:128
	ds_add_rtn_u32 v185, v185, v220 offset:128
	ds_add_rtn_u32 v186, v186, v220 offset:160
	ds_add_rtn_u32 v187, v187, v220 offset:160
	ds_add_rtn_u32 v188, v188, v220 offset:192
	ds_add_rtn_u32 v189, v189, v220 offset:192
	ds_add_rtn_u32 v190, v190, v220 offset:224
	ds_add_rtn_u32 v191, v191, v220 offset:224
	v_lshl_add_u32 v207, v201, 5, s3
	ds_read_b32 v203, v221 offset:4224
	ds_read_b128 v[192:195], v207
	ds_read_b128 v[196:199], v207 offset:16
	v_mov_b32_e32 v202, 0
	s_waitcnt lgkmcnt(0)
	v_cmp_lt_u32_e64 s[38:39], 0, v200
	v_cmp_lt_u32_e64 s[40:41], 1, v200
	v_cmp_lt_u32_e64 s[42:43], 2, v200
	v_cmp_lt_u32_e64 s[44:45], 3, v200
	v_cmp_lt_u32_e64 s[64:65], 4, v200
	v_cmp_lt_u32_e64 s[66:67], 5, v200
	v_cmp_lt_u32_e64 s[94:95], 6, v200
	v_cndmask_b32_e64 v206, 0, v192, s[38:39]
	v_add_u32_e32 v202, v202, v206
	v_cndmask_b32_e64 v206, 0, v193, s[40:41]
	v_add_u32_e32 v202, v202, v206
	v_cndmask_b32_e64 v206, 0, v194, s[42:43]
	v_add_u32_e32 v202, v202, v206
	v_cndmask_b32_e64 v206, 0, v195, s[44:45]
	v_add_u32_e32 v202, v202, v206
	v_cndmask_b32_e64 v206, 0, v196, s[64:65]
	v_add_u32_e32 v202, v202, v206
	v_cndmask_b32_e64 v206, 0, v197, s[66:67]
	v_add_u32_e32 v202, v202, v206
	v_cndmask_b32_e64 v206, 0, v198, s[94:95]
	v_add_u32_e32 v202, v202, v206
	v_add_u32_e32 v204, 3, v202
	v_add3_u32 v212, v202, v203, 3
	v_lshrrev_b32_e32 v204, 2, v204
	v_lshrrev_b32_e32 v212, 2, v212
	v_sub_u32_e32 v212, v212, v204
	v_lshl_add_u32 v207, v200, 3, v201
	v_lshl_add_u32 v207, v207, 2, s3
	ds_write_b32 v207, v212 offset:256
	v_lshl_add_u32 v208, v200, 5, s3
	ds_read_b128 v[192:195], v208 offset:256
	ds_read_b128 v[196:199], v208 offset:272
	v_mov_b32_e32 v205, 0
	s_waitcnt lgkmcnt(0)
; __device__ __forceinline__ void peer_tile(const Args& A, LAS unsigned char* lds, int tile) {
;     ...
;     for (int ti = 0; ti < 8; ++ti) {
;         const int tl = 8 * w + ti;
;         const u32x2 e0 = SEL[tl * 128 + lane], e1 = SEL[tl * 128 + 64 + lane];
;         const int p0 = (int)(e0.x >> 10), p1 = (int)(e1.x >> 10);
;         int off = 0;
;         for (int p = 0; p < 16; ++p) {
;             const unsigned long long m0 = __ballot(p0 == p), m1 = __ballot(p1 == p);
;             const int c0 = __popcll(m0), c1 = __popcll(m1);
;             const int r0 = __builtin_amdgcn_mbcnt_hi((unsigned)(m0 >> 32), __builtin_amdgcn_mbcnt_lo((unsigned)m0, 0u));
;             const int r1 = __builtin_amdgcn_mbcnt_hi((unsigned)(m1 >> 32), __builtin_amdgcn_mbcnt_lo((unsigned)m1, 0u));
;             if (p0 == p) SORT[tl * 128 + off + r0] = e0;
;             if (p1 == p) SORT[tl * 128 + off + c0 + r1] = e1;
;             if (lane == 0) OFFS[tl * 17 + p] = off;
;             off += c0 + c1;
;         }
;         if (lane == 0) OFFS[tl * 17 + 16] = off;
;     }
	v_cmp_lt_u32_e64 s[38:39], 0, v201
	v_cmp_lt_u32_e64 s[40:41], 1, v201
	v_cmp_lt_u32_e64 s[42:43], 2, v201
	v_cmp_lt_u32_e64 s[44:45], 3, v201
	v_cmp_lt_u32_e64 s[64:65], 4, v201
	v_cmp_lt_u32_e64 s[66:67], 5, v201
	v_cmp_lt_u32_e64 s[94:95], 6, v201
	v_cndmask_b32_e64 v206, 0, v192, s[38:39]
	v_add_u32_e32 v205, v205, v206
	v_cndmask_b32_e64 v206, 0, v193, s[40:41]
	v_add_u32_e32 v205, v205, v206
	v_cndmask_b32_e64 v206, 0, v194, s[42:43]
	v_add_u32_e32 v205, v205, v206
	v_cndmask_b32_e64 v206, 0, v195, s[44:45]
	v_add_u32_e32 v205, v205, v206
	v_cndmask_b32_e64 v206, 0, v196, s[64:65]
	v_add_u32_e32 v205, v205, v206
	v_cndmask_b32_e64 v206, 0, v197, s[66:67]
	v_add_u32_e32 v205, v205, v206
	v_cndmask_b32_e64 v206, 0, v198, s[94:95]
	v_add_u32_e32 v205, v205, v206
	v_add_u32_e32 v206, v192, v193
	v_add_u32_e32 v206, v206, v194
	v_add_u32_e32 v206, v206, v195
	v_add_u32_e32 v206, v206, v196
	v_add_u32_e32 v206, v206, v197
	v_add_u32_e32 v206, v206, v198
	v_add_u32_e32 v206, v206, v199
	v_lshl_add_u32 v207, v200, 2, s3
	ds_write_b32 v207, v206 offset:512
	v_mov_b32_e32 v207, s3
	ds_read_b128 v[192:195], v207 offset:512
	ds_read_b128 v[196:199], v207 offset:528
	ds_write_b32 v221, v202 offset:4224
	s_waitcnt lgkmcnt(0)
	v_cmp_lt_u32_e64 s[38:39], 0, v200
	v_cmp_lt_u32_e64 s[40:41], 1, v200
	v_cmp_lt_u32_e64 s[42:43], 2, v200
	v_cmp_lt_u32_e64 s[44:45], 3, v200
	v_cmp_lt_u32_e64 s[64:65], 4, v200
	v_cmp_lt_u32_e64 s[66:67], 5, v200
	v_cmp_lt_u32_e64 s[94:95], 6, v200
	v_cndmask_b32_e64 v206, 0, v192, s[38:39]
	v_add_u32_e32 v205, v205, v206
	v_cndmask_b32_e64 v206, 0, v193, s[40:41]
	v_add_u32_e32 v205, v205, v206
	v_cndmask_b32_e64 v206, 0, v194, s[42:43]
	v_add_u32_e32 v205, v205, v206
	v_cndmask_b32_e64 v206, 0, v195, s[44:45]
	v_add_u32_e32 v205, v205, v206
	v_cndmask_b32_e64 v206, 0, v196, s[64:65]
	v_add_u32_e32 v205, v205, v206
	v_cndmask_b32_e64 v206, 0, v197, s[66:67]
	v_add_u32_e32 v205, v205, v206
	v_cndmask_b32_e64 v206, 0, v198, s[94:95]
	v_add_u32_e32 v205, v205, v206
	v_sub_u32_e32 v205, v205, v204
	v_lshrrev_b32_e32 v208, 4, v240
	v_and_b32_e32 v222, 31, v208
	v_lshrrev_b32_e32 v208, 5, v208
	v_add_u32_e32 v207, 0, v208
	v_lshl_add_u32 v206, v207, 5, s3
	ds_read_b128 v[192:195], v206
	ds_read_b128 v[196:199], v206 offset:16
	v_lshlrev_b32_e32 v206, 2, v222
	v_lshlrev_b32_e32 v223, 3, v207
	s_waitcnt lgkmcnt(0)
	v_cmp_le_u32_e64 s[38:39], v193, v206
	v_cmp_le_u32_e64 s[40:41], v194, v206
	v_cmp_le_u32_e64 s[42:43], v195, v206
	v_cmp_le_u32_e64 s[44:45], v196, v206
	v_cmp_le_u32_e64 s[64:65], v197, v206
	v_cmp_le_u32_e64 s[66:67], v198, v206
	v_cmp_le_u32_e64 s[94:95], v199, v206
	v_addc_co_u32_e64 v223, s[92:93], 0, v223, s[38:39]
	v_addc_co_u32_e64 v223, s[92:93], 0, v223, s[40:41]
	v_addc_co_u32_e64 v223, s[92:93], 0, v223, s[42:43]
	v_addc_co_u32_e64 v223, s[92:93], 0, v223, s[44:45]
	v_addc_co_u32_e64 v223, s[92:93], 0, v223, s[64:65]
	v_addc_co_u32_e64 v223, s[92:93], 0, v223, s[66:67]
	v_addc_co_u32_e64 v223, s[92:93], 0, v223, s[94:95]
	v_lshlrev_b32_e32 v223, 2, v223
	ds_bpermute_b32 v216, v223, v205
	v_add_u32_e32 v207, 2, v208
	v_lshl_add_u32 v206, v207, 5, s3
	ds_read_b128 v[192:195], v206
	ds_read_b128 v[196:199], v206 offset:16
	v_lshlrev_b32_e32 v206, 2, v222
	v_lshlrev_b32_e32 v223, 3, v207
	s_waitcnt lgkmcnt(0)
	v_cmp_le_u32_e64 s[38:39], v193, v206
	v_cmp_le_u32_e64 s[40:41], v194, v206
	v_cmp_le_u32_e64 s[42:43], v195, v206
	v_cmp_le_u32_e64 s[44:45], v196, v206
	v_cmp_le_u32_e64 s[64:65], v197, v206
	v_cmp_le_u32_e64 s[66:67], v198, v206
	v_cmp_le_u32_e64 s[94:95], v199, v206
	v_addc_co_u32_e64 v223, s[92:93], 0, v223, s[38:39]
	v_addc_co_u32_e64 v223, s[92:93], 0, v223, s[40:41]
	v_addc_co_u32_e64 v223, s[92:93], 0, v223, s[42:43]
	v_addc_co_u32_e64 v223, s[92:93], 0, v223, s[44:45]
	v_addc_co_u32_e64 v223, s[92:93], 0, v223, s[64:65]
	v_addc_co_u32_e64 v223, s[92:93], 0, v223, s[66:67]
	v_addc_co_u32_e64 v223, s[92:93], 0, v223, s[94:95]
	v_lshlrev_b32_e32 v223, 2, v223
	ds_bpermute_b32 v217, v223, v205
	v_add_u32_e32 v207, 4, v208
	v_lshl_add_u32 v206, v207, 5, s3
	ds_read_b128 v[192:195], v206
	ds_read_b128 v[196:199], v206 offset:16
	v_lshlrev_b32_e32 v206, 2, v222
	v_lshlrev_b32_e32 v223, 3, v207
	s_waitcnt lgkmcnt(0)
	v_cmp_le_u32_e64 s[38:39], v193, v206
	v_cmp_le_u32_e64 s[40:41], v194, v206
	v_cmp_le_u32_e64 s[42:43], v195, v206
	v_cmp_le_u32_e64 s[44:45], v196, v206
	v_cmp_le_u32_e64 s[64:65], v197, v206
	v_cmp_le_u32_e64 s[66:67], v198, v206
	v_cmp_le_u32_e64 s[94:95], v199, v206
	v_addc_co_u32_e64 v223, s[92:93], 0, v223, s[38:39]
	v_addc_co_u32_e64 v223, s[92:93], 0, v223, s[40:41]
	v_addc_co_u32_e64 v223, s[92:93], 0, v223, s[42:43]
	v_addc_co_u32_e64 v223, s[92:93], 0, v223, s[44:45]
	v_addc_co_u32_e64 v223, s[92:93], 0, v223, s[64:65]
	v_addc_co_u32_e64 v223, s[92:93], 0, v223, s[66:67]
	v_addc_co_u32_e64 v223, s[92:93], 0, v223, s[94:95]
	v_lshlrev_b32_e32 v223, 2, v223
	ds_bpermute_b32 v218, v223, v205
	v_add_u32_e32 v207, 6, v208
	v_lshl_add_u32 v206, v207, 5, s3
	ds_read_b128 v[192:195], v206
	ds_read_b128 v[196:199], v206 offset:16
	v_lshlrev_b32_e32 v206, 2, v222
	v_lshlrev_b32_e32 v223, 3, v207
	s_waitcnt lgkmcnt(0)
	v_cmp_le_u32_e64 s[38:39], v193, v206
	v_cmp_le_u32_e64 s[40:41], v194, v206
	v_cmp_le_u32_e64 s[42:43], v195, v206
	v_cmp_le_u32_e64 s[44:45], v196, v206
	v_cmp_le_u32_e64 s[64:65], v197, v206
	v_cmp_le_u32_e64 s[66:67], v198, v206
	v_cmp_le_u32_e64 s[94:95], v199, v206
	v_addc_co_u32_e64 v223, s[92:93], 0, v223, s[38:39]
	v_addc_co_u32_e64 v223, s[92:93], 0, v223, s[40:41]
	v_addc_co_u32_e64 v223, s[92:93], 0, v223, s[42:43]
	v_addc_co_u32_e64 v223, s[92:93], 0, v223, s[44:45]
	v_addc_co_u32_e64 v223, s[92:93], 0, v223, s[64:65]
	v_addc_co_u32_e64 v223, s[92:93], 0, v223, s[66:67]
	v_addc_co_u32_e64 v223, s[92:93], 0, v223, s[94:95]
	v_lshlrev_b32_e32 v223, 2, v223
	ds_bpermute_b32 v219, v223, v205
	s_waitcnt lgkmcnt(0)
; __device__ __forceinline__ void peer_tile(const Args& A, LAS unsigned char* lds, int tile) {
;     ...
;     for (int ti = 0; ti < 8; ++ti) {
;         const int tl = 8 * w + ti;
;         const u32x2 e0 = SEL[tl * 128 + lane], e1 = SEL[tl * 128 + 64 + lane];
;         const int p0 = (int)(e0.x >> 10), p1 = (int)(e1.x >> 10);
;         int off = 0;
;         for (int p = 0; p < 16; ++p) {
;             const unsigned long long m0 = __ballot(p0 == p), m1 = __ballot(p1 == p);
;             const int c0 = __popcll(m0), c1 = __popcll(m1);
;             const int r0 = __builtin_amdgcn_mbcnt_hi((unsigned)(m0 >> 32), __builtin_amdgcn_mbcnt_lo((unsigned)m0, 0u));
;             const int r1 = __builtin_amdgcn_mbcnt_hi((unsigned)(m1 >> 32), __builtin_amdgcn_mbcnt_lo((unsigned)m1, 0u));
;             if (p0 == p) SORT[tl * 128 + off + r0] = e0;
;             if (p1 == p) SORT[tl * 128 + off + c0 + r1] = e1;
;             if (lane == 0) OFFS[tl * 17 + p] = off;
;             off += c0 + c1;
;         }
;         if (lane == 0) OFFS[tl * 17 + 16] = off;
;     }
	v_add_u32_e32 v216, v216, v222
	v_add_u32_e32 v217, v217, v222
	v_add_u32_e32 v218, v218, v222
	v_add_u32_e32 v219, v219, v222
	v_lshlrev_b32_e32 v206, 3, v152
	buffer_load_dwordx2 v[192:193], v206, s[24:27], 0 offen
	v_lshlrev_b32_e32 v206, 3, v154
	buffer_load_dwordx2 v[194:195], v206, s[24:27], 0 offen
	v_lshlrev_b32_e32 v206, 3, v156
	buffer_load_dwordx2 v[196:197], v206, s[24:27], 0 offen
	v_lshlrev_b32_e32 v206, 3, v158
	buffer_load_dwordx2 v[198:199], v206, s[24:27], 0 offen
	v_lshlrev_b32_e32 v160, 2, v160
	ds_bpermute_b32 v160, v160, v202
	v_lshlrev_b32_e32 v161, 2, v161
	ds_bpermute_b32 v161, v161, v202
	v_lshlrev_b32_e32 v162, 2, v162
	v_add_u32_e32 v162, 32, v162
	ds_bpermute_b32 v162, v162, v202
	v_lshlrev_b32_e32 v163, 2, v163
	v_add_u32_e32 v163, 32, v163
	ds_bpermute_b32 v163, v163, v202
	v_lshlrev_b32_e32 v164, 2, v164
	v_add_u32_e32 v164, 64, v164
	ds_bpermute_b32 v164, v164, v202
	v_lshlrev_b32_e32 v165, 2, v165
	v_add_u32_e32 v165, 64, v165
	ds_bpermute_b32 v165, v165, v202
	v_lshlrev_b32_e32 v166, 2, v166
	v_add_u32_e32 v166, 96, v166
	ds_bpermute_b32 v166, v166, v202
	v_lshlrev_b32_e32 v167, 2, v167
	v_add_u32_e32 v167, 96, v167
	ds_bpermute_b32 v167, v167, v202
	v_lshlrev_b32_e32 v168, 2, v168
	v_add_u32_e32 v168, 128, v168
	ds_bpermute_b32 v168, v168, v202
	v_lshlrev_b32_e32 v169, 2, v169
	v_add_u32_e32 v169, 128, v169
	ds_bpermute_b32 v169, v169, v202
	v_lshlrev_b32_e32 v170, 2, v170
	v_add_u32_e32 v170, 160, v170
	ds_bpermute_b32 v170, v170, v202
	v_lshlrev_b32_e32 v171, 2, v171
	v_add_u32_e32 v171, 160, v171
	ds_bpermute_b32 v171, v171, v202
	v_lshlrev_b32_e32 v172, 2, v172
	v_add_u32_e32 v172, 192, v172
	ds_bpermute_b32 v172, v172, v202
	v_lshlrev_b32_e32 v173, 2, v173
	v_add_u32_e32 v173, 192, v173
	ds_bpermute_b32 v173, v173, v202
	v_lshlrev_b32_e32 v174, 2, v174
	v_add_u32_e32 v174, 224, v174
	ds_bpermute_b32 v174, v174, v202
	v_lshlrev_b32_e32 v175, 2, v175
	v_add_u32_e32 v175, 224, v175
	ds_bpermute_b32 v175, v175, v202
	s_waitcnt lgkmcnt(0)
	v_add_u32_e32 v176, v176, v160
	v_lshrrev_b32_e32 v160, 2, v176
	v_and_b32_e32 v176, 3, v176
	v_lshlrev_b32_e32 v160, 2, v160
	ds_bpermute_b32 v160, v160, v216
	v_add_u32_e32 v177, v177, v161
	v_lshrrev_b32_e32 v161, 2, v177
	v_and_b32_e32 v177, 3, v177
	v_lshlrev_b32_e32 v161, 2, v161
	ds_bpermute_b32 v161, v161, v216
	v_add_u32_e32 v178, v178, v162
	v_lshrrev_b32_e32 v162, 2, v178
	v_and_b32_e32 v178, 3, v178
	v_lshlrev_b32_e32 v162, 2, v162
	v_add_u32_e32 v162, 128, v162
	ds_bpermute_b32 v162, v162, v216
	v_add_u32_e32 v179, v179, v163
	v_lshrrev_b32_e32 v163, 2, v179
	v_and_b32_e32 v179, 3, v179
	v_lshlrev_b32_e32 v163, 2, v163
	v_add_u32_e32 v163, 128, v163
	ds_bpermute_b32 v163, v163, v216
	v_add_u32_e32 v180, v180, v164
	v_lshrrev_b32_e32 v164, 2, v180
	v_and_b32_e32 v180, 3, v180
	v_lshlrev_b32_e32 v164, 2, v164
	ds_bpermute_b32 v164, v164, v217
	v_add_u32_e32 v181, v181, v165
	v_lshrrev_b32_e32 v165, 2, v181
	v_and_b32_e32 v181, 3, v181
	v_lshlrev_b32_e32 v165, 2, v165
	ds_bpermute_b32 v165, v165, v217
	v_add_u32_e32 v182, v182, v166
	v_lshrrev_b32_e32 v166, 2, v182
	v_and_b32_e32 v182, 3, v182
	v_lshlrev_b32_e32 v166, 2, v166
	v_add_u32_e32 v166, 128, v166
	ds_bpermute_b32 v166, v166, v217
	v_add_u32_e32 v183, v183, v167
	v_lshrrev_b32_e32 v167, 2, v183
	v_and_b32_e32 v183, 3, v183
	v_lshlrev_b32_e32 v167, 2, v167
	v_add_u32_e32 v167, 128, v167
	ds_bpermute_b32 v167, v167, v217
	v_add_u32_e32 v184, v184, v168
	v_lshrrev_b32_e32 v168, 2, v184
	v_and_b32_e32 v184, 3, v184
	v_lshlrev_b32_e32 v168, 2, v168
	ds_bpermute_b32 v168, v168, v218
	v_add_u32_e32 v185, v185, v169
	v_lshrrev_b32_e32 v169, 2, v185
	v_and_b32_e32 v185, 3, v185
	v_lshlrev_b32_e32 v169, 2, v169
	ds_bpermute_b32 v169, v169, v218
	v_add_u32_e32 v186, v186, v170
	v_lshrrev_b32_e32 v170, 2, v186
	v_and_b32_e32 v186, 3, v186
	v_lshlrev_b32_e32 v170, 2, v170
	v_add_u32_e32 v170, 128, v170
	ds_bpermute_b32 v170, v170, v218
	v_add_u32_e32 v187, v187, v171
	v_lshrrev_b32_e32 v171, 2, v187
	v_and_b32_e32 v187, 3, v187
	v_lshlrev_b32_e32 v171, 2, v171
	v_add_u32_e32 v171, 128, v171
	ds_bpermute_b32 v171, v171, v218
	v_add_u32_e32 v188, v188, v172
	v_lshrrev_b32_e32 v172, 2, v188
	v_and_b32_e32 v188, 3, v188
	v_lshlrev_b32_e32 v172, 2, v172
	ds_bpermute_b32 v172, v172, v219
	v_add_u32_e32 v189, v189, v173
	v_lshrrev_b32_e32 v173, 2, v189
	v_and_b32_e32 v189, 3, v189
	v_lshlrev_b32_e32 v173, 2, v173
	ds_bpermute_b32 v173, v173, v219
	v_add_u32_e32 v190, v190, v174
	v_lshrrev_b32_e32 v174, 2, v190
	v_and_b32_e32 v190, 3, v190
	v_lshlrev_b32_e32 v174, 2, v174
	v_add_u32_e32 v174, 128, v174
	ds_bpermute_b32 v174, v174, v219
	v_add_u32_e32 v191, v191, v175
	v_lshrrev_b32_e32 v175, 2, v191
	v_and_b32_e32 v191, 3, v191
	v_lshlrev_b32_e32 v175, 2, v175
	v_add_u32_e32 v175, 128, v175
	ds_bpermute_b32 v175, v175, v219
	s_waitcnt lgkmcnt(0)
; #define LDS_WAIT() asm volatile("s_waitcnt lgkmcnt(0)" ::: "memory")
; #define IT_ADVANCE() do { it_j += 4; while (it_j >= it_end) { if (it_done) break; ++it_tk; if (it_tk == 4) { it_tk = 0; ++it_p; if (it_p == 16) { it_done = true; it_p = 15; it_j = 0; it_end = 1; break; } } \
;             it_j = __builtin_amdgcn_readfirstlane(OFFS[(tb + it_tk) * 17 + it_p]); it_end = __builtin_amdgcn_readfirstlane(OFFS[(tb + it_tk) * 17 + it_p + 1]); } } while (0)
; __device__ __forceinline__ void peer_tile(const Args& A, LAS unsigned char* lds, int tile) {
;     ...
;     for (int ti = 0; ti < 8; ++ti) {
;         const int tl = 8 * w + ti;
;         const u32x2 e0 = SEL[tl * 128 + lane], e1 = SEL[tl * 128 + 64 + lane];
;         const int p0 = (int)(e0.x >> 10), p1 = (int)(e1.x >> 10);
;         int off = 0;
;         for (int p = 0; p < 16; ++p) {
;             const unsigned long long m0 = __ballot(p0 == p), m1 = __ballot(p1 == p);
;             const int c0 = __popcll(m0), c1 = __popcll(m1);
;             const int r0 = __builtin_amdgcn_mbcnt_hi((unsigned)(m0 >> 32), __builtin_amdgcn_mbcnt_lo((unsigned)m0, 0u));
;             const int r1 = __builtin_amdgcn_mbcnt_hi((unsigned)(m1 >> 32), __builtin_amdgcn_mbcnt_lo((unsigned)m1, 0u));
;             if (p0 == p) SORT[tl * 128 + off + r0] = e0;
;             if (p1 == p) SORT[tl * 128 + off + c0 + r1] = e1;
;             if (lane == 0) OFFS[tl * 17 + p] = off;
;             off += c0 + c1;
;         }
;         if (lane == 0) OFFS[tl * 17 + 16] = off;
;     }
;     LDS_WAIT(); __builtin_amdgcn_wave_barrier();
;     ...
;         int it_p = 0, it_tk = -1, it_j = 0, it_end = 0; bool it_done = false;
;     ...
;         u32x4 uA[4], vA[4], uB[4], vB[4]; float cgA = 0.f, suA = 0.f, svA = 0.f, cgB = 0.f, suB = 0.f, svB = 0.f;
; #pragma unroll
;         for (int k = 0; k < 4; ++k) { uA[k] = (u32x4){0u, 0u, 0u, 0u}; vA[k] = uA[k]; uB[k] = uA[k]; vB[k] = uA[k]; }
;         IT_ADVANCE();
;         LOAD_SET(uA, vA, cgA, suA, svA);
	v_lshl_add_u32 v160, v160, 4, s22
	v_lshl_add_u32 v160, v176, 2, v160
	ds_write_b32 v160, v128
	ds_write_b32 v160, v129 offset:4992
	v_lshl_add_u32 v161, v161, 4, s22
	v_lshl_add_u32 v161, v177, 2, v161
	ds_write_b32 v161, v130
	ds_write_b32 v161, v131 offset:4992
	v_lshl_add_u32 v162, v162, 4, s22
	v_lshl_add_u32 v162, v178, 2, v162
	ds_write_b32 v162, v132
	ds_write_b32 v162, v133 offset:4992
	v_lshl_add_u32 v163, v163, 4, s22
	v_lshl_add_u32 v163, v179, 2, v163
	ds_write_b32 v163, v134
	ds_write_b32 v163, v135 offset:4992
	v_lshl_add_u32 v164, v164, 4, s22
	v_lshl_add_u32 v164, v180, 2, v164
	ds_write_b32 v164, v136
	ds_write_b32 v164, v137 offset:4992
	v_lshl_add_u32 v165, v165, 4, s22
	v_lshl_add_u32 v165, v181, 2, v165
	ds_write_b32 v165, v138
	ds_write_b32 v165, v139 offset:4992
	v_lshl_add_u32 v166, v166, 4, s22
	v_lshl_add_u32 v166, v182, 2, v166
	ds_write_b32 v166, v140
	ds_write_b32 v166, v141 offset:4992
	v_lshl_add_u32 v167, v167, 4, s22
	v_lshl_add_u32 v167, v183, 2, v167
	ds_write_b32 v167, v142
	ds_write_b32 v167, v143 offset:4992
	v_lshl_add_u32 v168, v168, 4, s22
	v_lshl_add_u32 v168, v184, 2, v168
	ds_write_b32 v168, v144
	ds_write_b32 v168, v145 offset:4992
	v_lshl_add_u32 v169, v169, 4, s22
	v_lshl_add_u32 v169, v185, 2, v169
	ds_write_b32 v169, v146
	ds_write_b32 v169, v147 offset:4992
	v_lshl_add_u32 v170, v170, 4, s22
	v_lshl_add_u32 v170, v186, 2, v170
	ds_write_b32 v170, v148
	ds_write_b32 v170, v149 offset:4992
	v_lshl_add_u32 v171, v171, 4, s22
	v_lshl_add_u32 v171, v187, 2, v171
	ds_write_b32 v171, v150
	ds_write_b32 v171, v151 offset:4992
	v_lshl_add_u32 v172, v172, 4, s22
	v_lshl_add_u32 v172, v188, 2, v172
	ds_write_b32 v172, v152
	ds_write_b32 v172, v153 offset:4992
	v_lshl_add_u32 v173, v173, 4, s22
	v_lshl_add_u32 v173, v189, 2, v173
	ds_write_b32 v173, v154
	ds_write_b32 v173, v155 offset:4992
	v_lshl_add_u32 v174, v174, 4, s22
	v_lshl_add_u32 v174, v190, 2, v174
	ds_write_b32 v174, v156
	ds_write_b32 v174, v157 offset:4992
	v_lshl_add_u32 v175, v175, 4, s22
	v_lshl_add_u32 v175, v191, 2, v175
	ds_write_b32 v175, v158
	ds_write_b32 v175, v159 offset:4992
	s_waitcnt vmcnt(0)
	v_add_u32_e32 v160, s85, v160
	ds_write_b32 v160, v224
	ds_write_b32 v160, v225 offset:4096
	v_add_u32_e32 v161, s85, v161
	ds_write_b32 v161, v226
	ds_write_b32 v161, v227 offset:4096
	v_add_u32_e32 v162, s85, v162
	ds_write_b32 v162, v228
	ds_write_b32 v162, v229 offset:4096
	v_add_u32_e32 v163, s85, v163
	ds_write_b32 v163, v230
	ds_write_b32 v163, v231 offset:4096
	v_add_u32_e32 v164, s85, v164
	ds_write_b32 v164, v232
	ds_write_b32 v164, v233 offset:4096
	v_add_u32_e32 v165, s85, v165
	ds_write_b32 v165, v234
	ds_write_b32 v165, v235 offset:4096
	v_add_u32_e32 v166, s85, v166
	ds_write_b32 v166, v236
	ds_write_b32 v166, v237 offset:4096
	v_add_u32_e32 v167, s85, v167
	ds_write_b32 v167, v238
	ds_write_b32 v167, v239 offset:4096
	v_add_u32_e32 v168, s85, v168
	ds_write_b32 v168, v248
	ds_write_b32 v168, v249 offset:4096
	v_add_u32_e32 v169, s85, v169
	ds_write_b32 v169, v250
	ds_write_b32 v169, v251 offset:4096
	v_add_u32_e32 v170, s85, v170
	ds_write_b32 v170, v252
	ds_write_b32 v170, v253 offset:4096
	v_add_u32_e32 v171, s85, v171
	ds_write_b32 v171, v254
	ds_write_b32 v171, v255 offset:4096
	v_add_u32_e32 v172, s85, v172
	ds_write_b32 v172, v192
	ds_write_b32 v172, v193 offset:4096
	v_add_u32_e32 v173, s85, v173
	ds_write_b32 v173, v194
	ds_write_b32 v173, v195 offset:4096
	v_add_u32_e32 v174, s85, v174
	ds_write_b32 v174, v196
	ds_write_b32 v174, v197 offset:4096
	v_add_u32_e32 v175, s85, v175
	ds_write_b32 v175, v198
	ds_write_b32 v175, v199 offset:4096
	v_mov_b32_e32 v206, 0x7fffffff
	ds_write_b32 v221, v206 offset:4224
	ds_write_b32 v221, v206 offset:4480
	ds_write_b32 v221, v206 offset:4736
	s_mov_b32 s91, 256
	s_add_i32 s20, s91, 3
	s_and_b32 s20, s20, -4
	s_mov_b32 s24, s8
	s_and_b32 s25, s9, 0xffff
	s_mov_b32 s26, 0x20000
	s_mov_b32 s27, 0x00027000
	s_mov_b32 s28, s52
	s_and_b32 s29, s53, 0xffff
	s_mov_b32 s30, 0x20000
	s_mov_b32 s31, 0x00027000
	s_waitcnt vmcnt(0) lgkmcnt(0)
	v_mov_b32_e32 v213, s22
	v_mov_b32_e32 v233, v240
	v_mov_b32_e32 v235, v240
	v_mov_b32_e32 v237, v240
	v_mov_b32_e32 v239, v240
	ds_read_b32 v232, v213 offset:0
	ds_read_b32 v234, v213 offset:4
	ds_read_b32 v236, v213 offset:8
	ds_read_b32 v238, v213 offset:12
	s_waitcnt lgkmcnt(0)
	buffer_load_dwordx4 v[128:131], v[232:233], s[56:59], 0 idxen offen
	buffer_load_dwordx4 v[132:135], v[234:235], s[56:59], 0 idxen offen
	buffer_load_dwordx4 v[136:139], v[236:237], s[56:59], 0 idxen offen
	buffer_load_dwordx4 v[140:143], v[238:239], s[56:59], 0 idxen offen
	ds_read_b32 v232, v213 offset:16
	ds_read_b32 v234, v213 offset:20
	ds_read_b32 v236, v213 offset:24
	ds_read_b32 v238, v213 offset:28
	s_waitcnt lgkmcnt(0)
	buffer_load_dwordx4 v[144:147], v[232:233], s[56:59], 0 idxen offen
	buffer_load_dwordx4 v[148:151], v[234:235], s[56:59], 0 idxen offen
	buffer_load_dwordx4 v[152:155], v[236:237], s[56:59], 0 idxen offen
	buffer_load_dwordx4 v[156:159], v[238:239], s[56:59], 0 idxen offen
	ds_read_b32 v232, v213 offset:32
	ds_read_b32 v234, v213 offset:36
	ds_read_b32 v236, v213 offset:40
	ds_read_b32 v238, v213 offset:44
	s_waitcnt lgkmcnt(0)
	buffer_load_dwordx4 v[160:163], v[232:233], s[56:59], 0 idxen offen
	buffer_load_dwordx4 v[164:167], v[234:235], s[56:59], 0 idxen offen
	buffer_load_dwordx4 v[168:171], v[236:237], s[56:59], 0 idxen offen
	buffer_load_dwordx4 v[172:175], v[238:239], s[56:59], 0 idxen offen
	ds_read_b32 v232, v213 offset:48
	ds_read_b32 v234, v213 offset:52
	ds_read_b32 v236, v213 offset:56
	ds_read_b32 v238, v213 offset:60
	s_mov_b32 s21, 0
	s_mov_b32 s89, -1
	s_mov_b32 s86, 0
	v_lshrrev_b32_e32 v208, 6, v240
	v_and_b32_e32 v208, 3, v208
	v_lshrrev_b32_e32 v209, 1, v208
	v_lshlrev_b32_e32 v208, 1, v208
	v_and_b32_e32 v208, 2, v208
	v_or_b32_e32 v208, v208, v209
	v_lshlrev_b32_e32 v208, 2, v208
	v_add3_u32 v211, v208, v247, s22
	v_add_u32_e32 v250, s85, v211
	ds_read_b32 v252, v250
	ds_read_b32 v253, v250 offset:4096
	ds_read_b32 v249, v211 offset:4992
	s_branch .LU_sw0

; #define IT_ADVANCE() do { it_j += 4; while (it_j >= it_end) { if (it_done) break; ++it_tk; if (it_tk == 4) { it_tk = 0; ++it_p; if (it_p == 16) { it_done = true; it_p = 15; it_j = 0; it_end = 1; break; } } \
;             it_j = __builtin_amdgcn_readfirstlane(OFFS[(tb + it_tk) * 17 + it_p]); it_end = __builtin_amdgcn_readfirstlane(OFFS[(tb + it_tk) * 17 + it_p + 1]); } } while (0)
; __device__ __forceinline__ void peer_tile(const Args& A, LAS unsigned char* lds, int tile) {
;     ...
; #pragma unroll
;             for (int q = 0; q < 8; ++q) oacc[tk][q] = (f32x2){0.f, 0.f}; }
;         int it_p = 0, it_tk = -1, it_j = 0, it_end = 0; bool it_done = false;
;     ...
;         u32x4 uA[4], vA[4], uB[4], vB[4]; float cgA = 0.f, suA = 0.f, svA = 0.f, cgB = 0.f, suB = 0.f, svB = 0.f;
; #pragma unroll
;         for (int k = 0; k < 4; ++k) { uA[k] = (u32x4){0u, 0u, 0u, 0u}; vA[k] = uA[k]; uB[k] = uA[k]; vB[k] = uA[k]; }
;         IT_ADVANCE();
;         LOAD_SET(uA, vA, cgA, suA, svA);
.LU_done:
	s_waitcnt vmcnt(0) lgkmcnt(0)
	s_add_i32 s20, s91, 3
	s_and_b32 s20, s20, -4
	s_waitcnt vmcnt(0) lgkmcnt(0)
	v_mov_b32_e32 v213, s22
	v_mov_b32_e32 v233, v240
	v_mov_b32_e32 v235, v240
	v_mov_b32_e32 v237, v240
	v_mov_b32_e32 v239, v240
	ds_read_b32 v232, v213 offset:0
	ds_read_b32 v234, v213 offset:4
	ds_read_b32 v236, v213 offset:8
	ds_read_b32 v238, v213 offset:12
	s_waitcnt lgkmcnt(0)
	buffer_load_dwordx4 v[128:131], v[232:233], s[60:63], 0 idxen offen
	buffer_load_dwordx4 v[132:135], v[234:235], s[60:63], 0 idxen offen
	buffer_load_dwordx4 v[136:139], v[236:237], s[60:63], 0 idxen offen
	buffer_load_dwordx4 v[140:143], v[238:239], s[60:63], 0 idxen offen
	ds_read_b32 v232, v213 offset:16
	ds_read_b32 v234, v213 offset:20
	ds_read_b32 v236, v213 offset:24
	ds_read_b32 v238, v213 offset:28
	s_waitcnt lgkmcnt(0)
	buffer_load_dwordx4 v[144:147], v[232:233], s[60:63], 0 idxen offen
	buffer_load_dwordx4 v[148:151], v[234:235], s[60:63], 0 idxen offen
	buffer_load_dwordx4 v[152:155], v[236:237], s[60:63], 0 idxen offen
	buffer_load_dwordx4 v[156:159], v[238:239], s[60:63], 0 idxen offen
	ds_read_b32 v232, v213 offset:32
	ds_read_b32 v234, v213 offset:36
	ds_read_b32 v236, v213 offset:40
	ds_read_b32 v238, v213 offset:44
	s_waitcnt lgkmcnt(0)
	buffer_load_dwordx4 v[160:163], v[232:233], s[60:63], 0 idxen offen
	buffer_load_dwordx4 v[164:167], v[234:235], s[60:63], 0 idxen offen
	buffer_load_dwordx4 v[168:171], v[236:237], s[60:63], 0 idxen offen
	buffer_load_dwordx4 v[172:175], v[238:239], s[60:63], 0 idxen offen
	ds_read_b32 v232, v213 offset:48
	ds_read_b32 v234, v213 offset:52
	ds_read_b32 v236, v213 offset:56
	ds_read_b32 v238, v213 offset:60
	s_waitcnt lgkmcnt(0)
	buffer_load_dwordx4 v[176:179], v[232:233], s[60:63], 0 idxen offen
	buffer_load_dwordx4 v[180:183], v[234:235], s[60:63], 0 idxen offen
	buffer_load_dwordx4 v[184:187], v[236:237], s[60:63], 0 idxen offen
	buffer_load_dwordx4 v[188:191], v[238:239], s[60:63], 0 idxen offen
	ds_read_b128 v[248:251], v213 offset:4992
	ds_read_b32 v232, v213 offset:64
	ds_read_b32 v234, v213 offset:68
	ds_read_b32 v236, v213 offset:72
	ds_read_b32 v238, v213 offset:76
	s_mov_b32 s21, 0
	s_mov_b32 s89, -1
	s_mov_b32 s86, 0
	s_mov_b32 s20, 260
	v_mov_b64_e32 v[0:1], 0
	v_mov_b64_e32 v[2:3], 0
	v_mov_b64_e32 v[4:5], 0
	v_mov_b64_e32 v[6:7], 0
	v_mov_b64_e32 v[8:9], 0
	v_mov_b64_e32 v[10:11], 0
	v_mov_b64_e32 v[12:13], 0
	v_mov_b64_e32 v[14:15], 0
	v_mov_b64_e32 v[16:17], 0
	v_mov_b64_e32 v[18:19], 0
	v_mov_b64_e32 v[20:21], 0
	v_mov_b64_e32 v[22:23], 0
	v_mov_b64_e32 v[24:25], 0
	v_mov_b64_e32 v[26:27], 0
	v_mov_b64_e32 v[28:29], 0
	v_mov_b64_e32 v[30:31], 0
	v_mov_b64_e32 v[32:33], 0
	v_mov_b64_e32 v[34:35], 0
	v_mov_b64_e32 v[36:37], 0
	v_mov_b64_e32 v[38:39], 0
	v_mov_b64_e32 v[40:41], 0
	v_mov_b64_e32 v[42:43], 0
	v_mov_b64_e32 v[44:45], 0
	v_mov_b64_e32 v[46:47], 0
	v_mov_b64_e32 v[48:49], 0
	v_mov_b64_e32 v[50:51], 0
	v_mov_b64_e32 v[52:53], 0
	v_mov_b64_e32 v[54:55], 0
	v_mov_b64_e32 v[56:57], 0
	v_mov_b64_e32 v[58:59], 0
	v_mov_b64_e32 v[60:61], 0
	v_mov_b64_e32 v[62:63], 0
	v_mov_b64_e32 v[64:65], 0
	v_mov_b64_e32 v[66:67], 0
	v_mov_b64_e32 v[68:69], 0
	v_mov_b64_e32 v[70:71], 0
	v_mov_b64_e32 v[72:73], 0
	v_mov_b64_e32 v[74:75], 0
	v_mov_b64_e32 v[76:77], 0
	v_mov_b64_e32 v[78:79], 0
	v_mov_b64_e32 v[80:81], 0
	v_mov_b64_e32 v[82:83], 0
	v_mov_b64_e32 v[84:85], 0
	v_mov_b64_e32 v[86:87], 0
	v_mov_b64_e32 v[88:89], 0
	v_mov_b64_e32 v[90:91], 0
	v_mov_b64_e32 v[92:93], 0
	v_mov_b64_e32 v[94:95], 0
	v_mov_b64_e32 v[96:97], 0
	v_mov_b64_e32 v[98:99], 0
	v_mov_b64_e32 v[100:101], 0
	v_mov_b64_e32 v[102:103], 0
	v_mov_b64_e32 v[104:105], 0
	v_mov_b64_e32 v[106:107], 0
	v_mov_b64_e32 v[108:109], 0
	v_mov_b64_e32 v[110:111], 0
	v_mov_b64_e32 v[112:113], 0
	v_mov_b64_e32 v[114:115], 0
	v_mov_b64_e32 v[116:117], 0
	v_mov_b64_e32 v[118:119], 0
	v_mov_b64_e32 v[120:121], 0
	v_mov_b64_e32 v[122:123], 0
	v_mov_b64_e32 v[124:125], 0
	v_mov_b64_e32 v[126:127], 0
	s_branch .LV_sw0

; __device__ __forceinline__ void peer_tile(const Args& A, LAS unsigned char* lds, int tile) {
;     ...
;         for (int tk = 0; tk < 4; ++tk) {
;             const size_t m = (size_t)tile * 64 + tb + tk; const int b = (int)(m >> 11);
;             float* orow = A.out + m * 1024 + 16 * lane;
;             const float* g2 = MOD + b * 6144 + 5120 + 16 * lane;
;             f32x4 xv[4]; float ss = 0.f;
; #pragma unroll
;             for (int j = 0; j < 4; ++j) { const f32x4 x1 = *(const f32x4*)(orow + 4 * j), gg = *(const f32x4*)(g2 + 4 * j);
;                 const f32x4 pe = (f32x4){oacc[tk][2 * j][0], oacc[tk][2 * j][1], oacc[tk][2 * j + 1][0], oacc[tk][2 * j + 1][1]};
;                 xv[j] = x1 + gg * pe; ss += (xv[j][0] * xv[j][0] + xv[j][1] * xv[j][1]) + (xv[j][2] * xv[j][2] + xv[j][3] * xv[j][3]); }
;             const float rstd = rsqrtf(wave_sum(ss) * (1.f / 1024.f) + 1e-6f);
.LV_done:
	s_waitcnt lgkmcnt(0)
	global_load_dwordx4 v[192:195], v246, s[82:83]
	global_load_dwordx4 v[196:199], v246, s[82:83] offset:16
	global_load_dwordx4 v[200:203], v246, s[82:83] offset:32
	global_load_dwordx4 v[204:207], v246, s[82:83] offset:48
	global_load_dwordx4 v[216:219], v246, s[46:47]
	global_load_dwordx4 v[220:223], v246, s[46:47] offset:16
	global_load_dwordx4 v[224:227], v246, s[46:47] offset:32
	global_load_dwordx4 v[228:231], v246, s[46:47] offset:48
	s_add_i32 s0, s77, 0
	s_lshl_b32 s0, s0, 12
	s_add_u32 s24, s48, s0
	s_addc_u32 s25, s49, 0
	s_add_i32 s0, s77, 1
	s_lshl_b32 s0, s0, 12
	s_add_u32 s26, s48, s0
	s_addc_u32 s27, s49, 0
	s_add_i32 s0, s77, 2
	s_lshl_b32 s0, s0, 12
	s_add_u32 s28, s48, s0
	s_addc_u32 s29, s49, 0
	s_add_i32 s0, s77, 3
	s_lshl_b32 s0, s0, 12
	s_add_u32 s30, s48, s0
	s_addc_u32 s31, s49, 0
	global_load_dwordx4 v[128:131], v246, s[24:25]
	global_load_dwordx4 v[132:135], v246, s[24:25] offset:16
	global_load_dwordx4 v[136:139], v246, s[24:25] offset:32
	global_load_dwordx4 v[140:143], v246, s[24:25] offset:48
	global_load_dwordx4 v[144:147], v246, s[26:27]
	global_load_dwordx4 v[148:151], v246, s[26:27] offset:16
	global_load_dwordx4 v[152:155], v246, s[26:27] offset:32
	global_load_dwordx4 v[156:159], v246, s[26:27] offset:48
	global_load_dwordx4 v[160:163], v246, s[28:29]
	global_load_dwordx4 v[164:167], v246, s[28:29] offset:16
	global_load_dwordx4 v[168:171], v246, s[28:29] offset:32
	global_load_dwordx4 v[172:175], v246, s[28:29] offset:48
	global_load_dwordx4 v[176:179], v246, s[30:31]
	global_load_dwordx4 v[180:183], v246, s[30:31] offset:16
	global_load_dwordx4 v[184:187], v246, s[30:31] offset:32
	global_load_dwordx4 v[188:191], v246, s[30:31] offset:48
	s_waitcnt vmcnt(0)
	v_pk_fma_f32 v[128:129], v[0:1], v[192:193], v[128:129]
	v_pk_fma_f32 v[130:131], v[2:3], v[194:195], v[130:131]
	v_pk_fma_f32 v[132:133], v[4:5], v[196:197], v[132:133]
	v_pk_fma_f32 v[134:135], v[6:7], v[198:199], v[134:135]
	v_pk_fma_f32 v[136:137], v[8:9], v[200:201], v[136:137]
	v_pk_fma_f32 v[138:139], v[10:11], v[202:203], v[138:139]
	v_pk_fma_f32 v[140:141], v[12:13], v[204:205], v[140:141]
	v_pk_fma_f32 v[142:143], v[14:15], v[206:207], v[142:143]
	v_pk_mul_f32 v[248:249], v[128:129], v[128:129]
	v_pk_fma_f32 v[248:249], v[130:131], v[130:131], v[248:249]
	v_pk_fma_f32 v[248:249], v[132:133], v[132:133], v[248:249]
	v_pk_fma_f32 v[248:249], v[134:135], v[134:135], v[248:249]
	v_pk_fma_f32 v[248:249], v[136:137], v[136:137], v[248:249]
	v_pk_fma_f32 v[248:249], v[138:139], v[138:139], v[248:249]
	v_pk_fma_f32 v[248:249], v[140:141], v[140:141], v[248:249]
	v_pk_fma_f32 v[248:249], v[142:143], v[142:143], v[248:249]
	v_pk_fma_f32 v[144:145], v[16:17], v[192:193], v[144:145]
	v_pk_fma_f32 v[146:147], v[18:19], v[194:195], v[146:147]
	v_pk_fma_f32 v[148:149], v[20:21], v[196:197], v[148:149]
	v_pk_fma_f32 v[150:151], v[22:23], v[198:199], v[150:151]
	v_pk_fma_f32 v[152:153], v[24:25], v[200:201], v[152:153]
	v_pk_fma_f32 v[154:155], v[26:27], v[202:203], v[154:155]
	v_pk_fma_f32 v[156:157], v[28:29], v[204:205], v[156:157]
	v_pk_fma_f32 v[158:159], v[30:31], v[206:207], v[158:159]
	v_pk_mul_f32 v[250:251], v[144:145], v[144:145]
	v_pk_fma_f32 v[250:251], v[146:147], v[146:147], v[250:251]
	v_pk_fma_f32 v[250:251], v[148:149], v[148:149], v[250:251]
	v_pk_fma_f32 v[250:251], v[150:151], v[150:151], v[250:251]
	v_pk_fma_f32 v[250:251], v[152:153], v[152:153], v[250:251]
	v_pk_fma_f32 v[250:251], v[154:155], v[154:155], v[250:251]
	v_pk_fma_f32 v[250:251], v[156:157], v[156:157], v[250:251]
	v_pk_fma_f32 v[250:251], v[158:159], v[158:159], v[250:251]
	v_pk_fma_f32 v[160:161], v[32:33], v[192:193], v[160:161]
	v_pk_fma_f32 v[162:163], v[34:35], v[194:195], v[162:163]
	v_pk_fma_f32 v[164:165], v[36:37], v[196:197], v[164:165]
	v_pk_fma_f32 v[166:167], v[38:39], v[198:199], v[166:167]
	v_pk_fma_f32 v[168:169], v[40:41], v[200:201], v[168:169]
	v_pk_fma_f32 v[170:171], v[42:43], v[202:203], v[170:171]
	v_pk_fma_f32 v[172:173], v[44:45], v[204:205], v[172:173]
	v_pk_fma_f32 v[174:175], v[46:47], v[206:207], v[174:175]
	v_pk_mul_f32 v[252:253], v[160:161], v[160:161]
	v_pk_fma_f32 v[252:253], v[162:163], v[162:163], v[252:253]
	v_pk_fma_f32 v[252:253], v[164:165], v[164:165], v[252:253]
	v_pk_fma_f32 v[252:253], v[166:167], v[166:167], v[252:253]
	v_pk_fma_f32 v[252:253], v[168:169], v[168:169], v[252:253]
	v_pk_fma_f32 v[252:253], v[170:171], v[170:171], v[252:253]
	v_pk_fma_f32 v[252:253], v[172:173], v[172:173], v[252:253]
	v_pk_fma_f32 v[252:253], v[174:175], v[174:175], v[252:253]
	v_pk_fma_f32 v[176:177], v[48:49], v[192:193], v[176:177]
	v_pk_fma_f32 v[178:179], v[50:51], v[194:195], v[178:179]
	v_pk_fma_f32 v[180:181], v[52:53], v[196:197], v[180:181]
	v_pk_fma_f32 v[182:183], v[54:55], v[198:199], v[182:183]
	v_pk_fma_f32 v[184:185], v[56:57], v[200:201], v[184:185]
	v_pk_fma_f32 v[186:187], v[58:59], v[202:203], v[186:187]
	v_pk_fma_f32 v[188:189], v[60:61], v[204:205], v[188:189]
	v_pk_fma_f32 v[190:191], v[62:63], v[206:207], v[190:191]
	v_pk_mul_f32 v[254:255], v[176:177], v[176:177]
	v_pk_fma_f32 v[254:255], v[178:179], v[178:179], v[254:255]
	v_pk_fma_f32 v[254:255], v[180:181], v[180:181], v[254:255]
	v_pk_fma_f32 v[254:255], v[182:183], v[182:183], v[254:255]
	v_pk_fma_f32 v[254:255], v[184:185], v[184:185], v[254:255]
	v_pk_fma_f32 v[254:255], v[186:187], v[186:187], v[254:255]
	v_pk_fma_f32 v[254:255], v[188:189], v[188:189], v[254:255]
	v_pk_fma_f32 v[254:255], v[190:191], v[190:191], v[254:255]
	v_add_f32_e32 v248, v248, v249
	v_add_f32_e32 v250, v250, v251
	v_add_f32_e32 v252, v252, v253
; __device__ __forceinline__ void peer_tile(const Args& A, LAS unsigned char* lds, int tile) {
;     ...
;             for (int j = 0; j < 4; ++j) { const f32x4 x1 = *(const f32x4*)(orow + 4 * j), gg = *(const f32x4*)(g2 + 4 * j);
;                 const f32x4 pe = (f32x4){oacc[tk][2 * j][0], oacc[tk][2 * j][1], oacc[tk][2 * j + 1][0], oacc[tk][2 * j + 1][1]};
;                 xv[j] = x1 + gg * pe; ss += (xv[j][0] * xv[j][0] + xv[j][1] * xv[j][1]) + (xv[j][2] * xv[j][2] + xv[j][3] * xv[j][3]); }
;             const float rstd = rsqrtf(wave_sum(ss) * (1.f / 1024.f) + 1e-6f);
; #pragma unroll
;             for (int j = 0; j < 4; ++j) { const f32x4 fg = *(const f32x4*)(A.final_g + 16 * lane + 4 * j); *(f32x4*)(orow + 4 * j) = xv[j] * rstd * fg; }
	v_add_f32_e32 v254, v254, v255
	v_mov_b32_e32 v249, v248
	v_mov_b32_e32 v251, v250
	v_mov_b32_e32 v253, v252
	v_mov_b32_e32 v255, v254
	v_permlane32_swap_b32_e32 v248, v249
	v_permlane32_swap_b32_e32 v250, v251
	v_permlane32_swap_b32_e32 v252, v253
	v_permlane32_swap_b32_e32 v254, v255
	v_add_f32_e32 v248, v248, v249
	v_add_f32_e32 v250, v250, v251
	v_add_f32_e32 v252, v252, v253
	v_add_f32_e32 v254, v254, v255
	v_mov_b32_e32 v249, v248
	v_mov_b32_e32 v251, v250
	v_mov_b32_e32 v253, v252
	v_mov_b32_e32 v255, v254
	v_permlane16_swap_b32_e32 v248, v249
	v_permlane16_swap_b32_e32 v250, v251
	v_permlane16_swap_b32_e32 v252, v253
	v_permlane16_swap_b32_e32 v254, v255
	v_add_f32_e32 v248, v248, v249
	v_add_f32_e32 v250, v250, v251
	v_add_f32_e32 v252, v252, v253
	v_add_f32_e32 v254, v254, v255
	v_add_f32_dpp v248, v248, v248 quad_perm:[1,0,3,2] row_mask:0xf bank_mask:0xf bound_ctrl:1
	v_add_f32_dpp v250, v250, v250 quad_perm:[1,0,3,2] row_mask:0xf bank_mask:0xf bound_ctrl:1
	v_add_f32_dpp v252, v252, v252 quad_perm:[1,0,3,2] row_mask:0xf bank_mask:0xf bound_ctrl:1
	v_add_f32_dpp v254, v254, v254 quad_perm:[1,0,3,2] row_mask:0xf bank_mask:0xf bound_ctrl:1
	v_add_f32_dpp v248, v248, v248 quad_perm:[2,3,0,1] row_mask:0xf bank_mask:0xf bound_ctrl:1
	v_add_f32_dpp v250, v250, v250 quad_perm:[2,3,0,1] row_mask:0xf bank_mask:0xf bound_ctrl:1
	v_add_f32_dpp v252, v252, v252 quad_perm:[2,3,0,1] row_mask:0xf bank_mask:0xf bound_ctrl:1
	v_add_f32_dpp v254, v254, v254 quad_perm:[2,3,0,1] row_mask:0xf bank_mask:0xf bound_ctrl:1
	v_add_f32_dpp v248, v248, v248 row_half_mirror row_mask:0xf bank_mask:0xf bound_ctrl:1
	v_add_f32_dpp v250, v250, v250 row_half_mirror row_mask:0xf bank_mask:0xf bound_ctrl:1
	v_add_f32_dpp v252, v252, v252 row_half_mirror row_mask:0xf bank_mask:0xf bound_ctrl:1
	v_add_f32_dpp v254, v254, v254 row_half_mirror row_mask:0xf bank_mask:0xf bound_ctrl:1
	v_add_f32_dpp v248, v248, v248 row_mirror row_mask:0xf bank_mask:0xf bound_ctrl:1
	v_add_f32_dpp v250, v250, v250 row_mirror row_mask:0xf bank_mask:0xf bound_ctrl:1
	v_add_f32_dpp v252, v252, v252 row_mirror row_mask:0xf bank_mask:0xf bound_ctrl:1
	v_add_f32_dpp v254, v254, v254 row_mirror row_mask:0xf bank_mask:0xf bound_ctrl:1
	v_fmamk_f32 v248, v248, 0x3a800000, v243
	v_fmamk_f32 v250, v250, 0x3a800000, v243
	v_fmamk_f32 v252, v252, 0x3a800000, v243
	v_fmamk_f32 v254, v254, 0x3a800000, v243
	v_rsq_f32_e32 v248, v248
	v_rsq_f32_e32 v250, v250
	v_rsq_f32_e32 v252, v252
	v_rsq_f32_e32 v254, v254
	s_nop 0
	v_pk_mul_f32 v[128:129], v[128:129], v[248:249] op_sel_hi:[1,0]
	v_pk_mul_f32 v[130:131], v[130:131], v[248:249] op_sel_hi:[1,0]
	v_pk_mul_f32 v[132:133], v[132:133], v[248:249] op_sel_hi:[1,0]
	v_pk_mul_f32 v[134:135], v[134:135], v[248:249] op_sel_hi:[1,0]
	v_pk_mul_f32 v[136:137], v[136:137], v[248:249] op_sel_hi:[1,0]
	v_pk_mul_f32 v[138:139], v[138:139], v[248:249] op_sel_hi:[1,0]
	v_pk_mul_f32 v[140:141], v[140:141], v[248:249] op_sel_hi:[1,0]
	v_pk_mul_f32 v[142:143], v[142:143], v[248:249] op_sel_hi:[1,0]
	v_pk_mul_f32 v[128:129], v[216:217], v[128:129]
	v_pk_mul_f32 v[130:131], v[218:219], v[130:131]
	v_pk_mul_f32 v[132:133], v[220:221], v[132:133]
	v_pk_mul_f32 v[134:135], v[222:223], v[134:135]
	v_pk_mul_f32 v[136:137], v[224:225], v[136:137]
	v_pk_mul_f32 v[138:139], v[226:227], v[138:139]
	v_pk_mul_f32 v[140:141], v[228:229], v[140:141]
	v_pk_mul_f32 v[142:143], v[230:231], v[142:143]
	global_store_dwordx4 v246, v[128:131], s[24:25]
	global_store_dwordx4 v246, v[132:135], s[24:25] offset:16
	global_store_dwordx4 v246, v[136:139], s[24:25] offset:32
	global_store_dwordx4 v246, v[140:143], s[24:25] offset:48
	v_pk_mul_f32 v[144:145], v[144:145], v[250:251] op_sel_hi:[1,0]
	v_pk_mul_f32 v[146:147], v[146:147], v[250:251] op_sel_hi:[1,0]
	v_pk_mul_f32 v[148:149], v[148:149], v[250:251] op_sel_hi:[1,0]
	v_pk_mul_f32 v[150:151], v[150:151], v[250:251] op_sel_hi:[1,0]
	v_pk_mul_f32 v[152:153], v[152:153], v[250:251] op_sel_hi:[1,0]
	v_pk_mul_f32 v[154:155], v[154:155], v[250:251] op_sel_hi:[1,0]
	v_pk_mul_f32 v[156:157], v[156:157], v[250:251] op_sel_hi:[1,0]
	v_pk_mul_f32 v[158:159], v[158:159], v[250:251] op_sel_hi:[1,0]
	v_pk_mul_f32 v[144:145], v[216:217], v[144:145]
	v_pk_mul_f32 v[146:147], v[218:219], v[146:147]
	v_pk_mul_f32 v[148:149], v[220:221], v[148:149]
	v_pk_mul_f32 v[150:151], v[222:223], v[150:151]
	v_pk_mul_f32 v[152:153], v[224:225], v[152:153]
	v_pk_mul_f32 v[154:155], v[226:227], v[154:155]
	v_pk_mul_f32 v[156:157], v[228:229], v[156:157]
	v_pk_mul_f32 v[158:159], v[230:231], v[158:159]
	global_store_dwordx4 v246, v[144:147], s[26:27]
	global_store_dwordx4 v246, v[148:151], s[26:27] offset:16
	global_store_dwordx4 v246, v[152:155], s[26:27] offset:32
	global_store_dwordx4 v246, v[156:159], s[26:27] offset:48
	v_pk_mul_f32 v[160:161], v[160:161], v[252:253] op_sel_hi:[1,0]
	v_pk_mul_f32 v[162:163], v[162:163], v[252:253] op_sel_hi:[1,0]
	v_pk_mul_f32 v[164:165], v[164:165], v[252:253] op_sel_hi:[1,0]
	v_pk_mul_f32 v[166:167], v[166:167], v[252:253] op_sel_hi:[1,0]
	v_pk_mul_f32 v[168:169], v[168:169], v[252:253] op_sel_hi:[1,0]
	v_pk_mul_f32 v[170:171], v[170:171], v[252:253] op_sel_hi:[1,0]
	v_pk_mul_f32 v[172:173], v[172:173], v[252:253] op_sel_hi:[1,0]
	v_pk_mul_f32 v[174:175], v[174:175], v[252:253] op_sel_hi:[1,0]
	v_pk_mul_f32 v[160:161], v[216:217], v[160:161]
	v_pk_mul_f32 v[162:163], v[218:219], v[162:163]
	v_pk_mul_f32 v[164:165], v[220:221], v[164:165]
	v_pk_mul_f32 v[166:167], v[222:223], v[166:167]
	v_pk_mul_f32 v[168:169], v[224:225], v[168:169]
	v_pk_mul_f32 v[170:171], v[226:227], v[170:171]
	v_pk_mul_f32 v[172:173], v[228:229], v[172:173]
; __device__ __forceinline__ void peer_tile(const Args& A, LAS unsigned char* lds, int tile) {
;     ...
;         for (int tk = 0; tk < 4; ++tk) {
;             const size_t m = (size_t)tile * 64 + tb + tk; const int b = (int)(m >> 11);
;             float* orow = A.out + m * 1024 + 16 * lane;
;             const float* g2 = MOD + b * 6144 + 5120 + 16 * lane;
;             f32x4 xv[4]; float ss = 0.f;
; #pragma unroll
;             for (int j = 0; j < 4; ++j) { const f32x4 x1 = *(const f32x4*)(orow + 4 * j), gg = *(const f32x4*)(g2 + 4 * j);
;                 const f32x4 pe = (f32x4){oacc[tk][2 * j][0], oacc[tk][2 * j][1], oacc[tk][2 * j + 1][0], oacc[tk][2 * j + 1][1]};
;                 xv[j] = x1 + gg * pe; ss += (xv[j][0] * xv[j][0] + xv[j][1] * xv[j][1]) + (xv[j][2] * xv[j][2] + xv[j][3] * xv[j][3]); }
	v_pk_mul_f32 v[174:175], v[230:231], v[174:175]
	global_store_dwordx4 v246, v[160:163], s[28:29]
	global_store_dwordx4 v246, v[164:167], s[28:29] offset:16
	global_store_dwordx4 v246, v[168:171], s[28:29] offset:32
	global_store_dwordx4 v246, v[172:175], s[28:29] offset:48
	v_pk_mul_f32 v[176:177], v[176:177], v[254:255] op_sel_hi:[1,0]
	v_pk_mul_f32 v[178:179], v[178:179], v[254:255] op_sel_hi:[1,0]
	v_pk_mul_f32 v[180:181], v[180:181], v[254:255] op_sel_hi:[1,0]
	v_pk_mul_f32 v[182:183], v[182:183], v[254:255] op_sel_hi:[1,0]
	v_pk_mul_f32 v[184:185], v[184:185], v[254:255] op_sel_hi:[1,0]
	v_pk_mul_f32 v[186:187], v[186:187], v[254:255] op_sel_hi:[1,0]
	v_pk_mul_f32 v[188:189], v[188:189], v[254:255] op_sel_hi:[1,0]
	v_pk_mul_f32 v[190:191], v[190:191], v[254:255] op_sel_hi:[1,0]
	v_pk_mul_f32 v[176:177], v[216:217], v[176:177]
	v_pk_mul_f32 v[178:179], v[218:219], v[178:179]
	v_pk_mul_f32 v[180:181], v[220:221], v[180:181]
	v_pk_mul_f32 v[182:183], v[222:223], v[182:183]
	v_pk_mul_f32 v[184:185], v[224:225], v[184:185]
	v_pk_mul_f32 v[186:187], v[226:227], v[186:187]
	v_pk_mul_f32 v[188:189], v[228:229], v[188:189]
	v_pk_mul_f32 v[190:191], v[230:231], v[190:191]
	global_store_dwordx4 v246, v[176:179], s[30:31]
	global_store_dwordx4 v246, v[180:183], s[30:31] offset:16
	global_store_dwordx4 v246, v[184:187], s[30:31] offset:32
	global_store_dwordx4 v246, v[188:191], s[30:31] offset:48
	s_nop 1
	s_add_i32 s0, s77, 4
	s_lshl_b32 s0, s0, 12
	s_add_u32 s24, s48, s0
	s_addc_u32 s25, s49, 0
	s_add_i32 s0, s77, 5
	s_lshl_b32 s0, s0, 12
	s_add_u32 s26, s48, s0
	s_addc_u32 s27, s49, 0
	s_add_i32 s0, s77, 6
	s_lshl_b32 s0, s0, 12
	s_add_u32 s28, s48, s0
	s_addc_u32 s29, s49, 0
	s_add_i32 s0, s77, 7
	s_lshl_b32 s0, s0, 12
	s_add_u32 s30, s48, s0
	s_addc_u32 s31, s49, 0
	global_load_dwordx4 v[128:131], v246, s[24:25]
	global_load_dwordx4 v[132:135], v246, s[24:25] offset:16
	global_load_dwordx4 v[136:139], v246, s[24:25] offset:32
	global_load_dwordx4 v[140:143], v246, s[24:25] offset:48
	global_load_dwordx4 v[144:147], v246, s[26:27]
	global_load_dwordx4 v[148:151], v246, s[26:27] offset:16
	global_load_dwordx4 v[152:155], v246, s[26:27] offset:32
	global_load_dwordx4 v[156:159], v246, s[26:27] offset:48
	global_load_dwordx4 v[160:163], v246, s[28:29]
	global_load_dwordx4 v[164:167], v246, s[28:29] offset:16
	global_load_dwordx4 v[168:171], v246, s[28:29] offset:32
	global_load_dwordx4 v[172:175], v246, s[28:29] offset:48
	global_load_dwordx4 v[176:179], v246, s[30:31]
	global_load_dwordx4 v[180:183], v246, s[30:31] offset:16
	global_load_dwordx4 v[184:187], v246, s[30:31] offset:32
	global_load_dwordx4 v[188:191], v246, s[30:31] offset:48
	s_waitcnt vmcnt(0)
	v_pk_fma_f32 v[128:129], v[64:65], v[192:193], v[128:129]
	v_pk_fma_f32 v[130:131], v[66:67], v[194:195], v[130:131]
	v_pk_fma_f32 v[132:133], v[68:69], v[196:197], v[132:133]
	v_pk_fma_f32 v[134:135], v[70:71], v[198:199], v[134:135]
	v_pk_fma_f32 v[136:137], v[72:73], v[200:201], v[136:137]
	v_pk_fma_f32 v[138:139], v[74:75], v[202:203], v[138:139]
	v_pk_fma_f32 v[140:141], v[76:77], v[204:205], v[140:141]
	v_pk_fma_f32 v[142:143], v[78:79], v[206:207], v[142:143]
	v_pk_mul_f32 v[248:249], v[128:129], v[128:129]
	v_pk_fma_f32 v[248:249], v[130:131], v[130:131], v[248:249]
	v_pk_fma_f32 v[248:249], v[132:133], v[132:133], v[248:249]
	v_pk_fma_f32 v[248:249], v[134:135], v[134:135], v[248:249]
	v_pk_fma_f32 v[248:249], v[136:137], v[136:137], v[248:249]
	v_pk_fma_f32 v[248:249], v[138:139], v[138:139], v[248:249]
	v_pk_fma_f32 v[248:249], v[140:141], v[140:141], v[248:249]
	v_pk_fma_f32 v[248:249], v[142:143], v[142:143], v[248:249]
	v_pk_fma_f32 v[144:145], v[80:81], v[192:193], v[144:145]
	v_pk_fma_f32 v[146:147], v[82:83], v[194:195], v[146:147]
	v_pk_fma_f32 v[148:149], v[84:85], v[196:197], v[148:149]
	v_pk_fma_f32 v[150:151], v[86:87], v[198:199], v[150:151]
	v_pk_fma_f32 v[152:153], v[88:89], v[200:201], v[152:153]
	v_pk_fma_f32 v[154:155], v[90:91], v[202:203], v[154:155]
	v_pk_fma_f32 v[156:157], v[92:93], v[204:205], v[156:157]
	v_pk_fma_f32 v[158:159], v[94:95], v[206:207], v[158:159]
	v_pk_mul_f32 v[250:251], v[144:145], v[144:145]
	v_pk_fma_f32 v[250:251], v[146:147], v[146:147], v[250:251]
	v_pk_fma_f32 v[250:251], v[148:149], v[148:149], v[250:251]
	v_pk_fma_f32 v[250:251], v[150:151], v[150:151], v[250:251]
	v_pk_fma_f32 v[250:251], v[152:153], v[152:153], v[250:251]
	v_pk_fma_f32 v[250:251], v[154:155], v[154:155], v[250:251]
	v_pk_fma_f32 v[250:251], v[156:157], v[156:157], v[250:251]
	v_pk_fma_f32 v[250:251], v[158:159], v[158:159], v[250:251]
	v_pk_fma_f32 v[160:161], v[96:97], v[192:193], v[160:161]
	v_pk_fma_f32 v[162:163], v[98:99], v[194:195], v[162:163]
	v_pk_fma_f32 v[164:165], v[100:101], v[196:197], v[164:165]
	v_pk_fma_f32 v[166:167], v[102:103], v[198:199], v[166:167]
	v_pk_fma_f32 v[168:169], v[104:105], v[200:201], v[168:169]
	v_pk_fma_f32 v[170:171], v[106:107], v[202:203], v[170:171]
	v_pk_fma_f32 v[172:173], v[108:109], v[204:205], v[172:173]
	v_pk_fma_f32 v[174:175], v[110:111], v[206:207], v[174:175]
	v_pk_mul_f32 v[252:253], v[160:161], v[160:161]
	v_pk_fma_f32 v[252:253], v[162:163], v[162:163], v[252:253]
	v_pk_fma_f32 v[252:253], v[164:165], v[164:165], v[252:253]
	v_pk_fma_f32 v[252:253], v[166:167], v[166:167], v[252:253]
	v_pk_fma_f32 v[252:253], v[168:169], v[168:169], v[252:253]
	v_pk_fma_f32 v[252:253], v[170:171], v[170:171], v[252:253]
	v_pk_fma_f32 v[252:253], v[172:173], v[172:173], v[252:253]
	v_pk_fma_f32 v[252:253], v[174:175], v[174:175], v[252:253]
	v_pk_fma_f32 v[176:177], v[112:113], v[192:193], v[176:177]
; __device__ __forceinline__ void peer_tile(const Args& A, LAS unsigned char* lds, int tile) {
;     ...
;                 xv[j] = x1 + gg * pe; ss += (xv[j][0] * xv[j][0] + xv[j][1] * xv[j][1]) + (xv[j][2] * xv[j][2] + xv[j][3] * xv[j][3]); }
;             const float rstd = rsqrtf(wave_sum(ss) * (1.f / 1024.f) + 1e-6f);
; #pragma unroll
;             for (int j = 0; j < 4; ++j) { const f32x4 fg = *(const f32x4*)(A.final_g + 16 * lane + 4 * j); *(f32x4*)(orow + 4 * j) = xv[j] * rstd * fg; }
	v_pk_fma_f32 v[178:179], v[114:115], v[194:195], v[178:179]
	v_pk_fma_f32 v[180:181], v[116:117], v[196:197], v[180:181]
	v_pk_fma_f32 v[182:183], v[118:119], v[198:199], v[182:183]
	v_pk_fma_f32 v[184:185], v[120:121], v[200:201], v[184:185]
	v_pk_fma_f32 v[186:187], v[122:123], v[202:203], v[186:187]
	v_pk_fma_f32 v[188:189], v[124:125], v[204:205], v[188:189]
	v_pk_fma_f32 v[190:191], v[126:127], v[206:207], v[190:191]
	v_pk_mul_f32 v[254:255], v[176:177], v[176:177]
	v_pk_fma_f32 v[254:255], v[178:179], v[178:179], v[254:255]
	v_pk_fma_f32 v[254:255], v[180:181], v[180:181], v[254:255]
	v_pk_fma_f32 v[254:255], v[182:183], v[182:183], v[254:255]
	v_pk_fma_f32 v[254:255], v[184:185], v[184:185], v[254:255]
	v_pk_fma_f32 v[254:255], v[186:187], v[186:187], v[254:255]
	v_pk_fma_f32 v[254:255], v[188:189], v[188:189], v[254:255]
	v_pk_fma_f32 v[254:255], v[190:191], v[190:191], v[254:255]
	v_add_f32_e32 v248, v248, v249
	v_add_f32_e32 v250, v250, v251
	v_add_f32_e32 v252, v252, v253
	v_add_f32_e32 v254, v254, v255
	v_mov_b32_e32 v249, v248
	v_mov_b32_e32 v251, v250
	v_mov_b32_e32 v253, v252
	v_mov_b32_e32 v255, v254
	v_permlane32_swap_b32_e32 v248, v249
	v_permlane32_swap_b32_e32 v250, v251
	v_permlane32_swap_b32_e32 v252, v253
	v_permlane32_swap_b32_e32 v254, v255
	v_add_f32_e32 v248, v248, v249
	v_add_f32_e32 v250, v250, v251
	v_add_f32_e32 v252, v252, v253
	v_add_f32_e32 v254, v254, v255
	v_mov_b32_e32 v249, v248
	v_mov_b32_e32 v251, v250
	v_mov_b32_e32 v253, v252
	v_mov_b32_e32 v255, v254
	v_permlane16_swap_b32_e32 v248, v249
	v_permlane16_swap_b32_e32 v250, v251
	v_permlane16_swap_b32_e32 v252, v253
	v_permlane16_swap_b32_e32 v254, v255
	v_add_f32_e32 v248, v248, v249
	v_add_f32_e32 v250, v250, v251
	v_add_f32_e32 v252, v252, v253
	v_add_f32_e32 v254, v254, v255
	v_add_f32_dpp v248, v248, v248 quad_perm:[1,0,3,2] row_mask:0xf bank_mask:0xf bound_ctrl:1
	v_add_f32_dpp v250, v250, v250 quad_perm:[1,0,3,2] row_mask:0xf bank_mask:0xf bound_ctrl:1
	v_add_f32_dpp v252, v252, v252 quad_perm:[1,0,3,2] row_mask:0xf bank_mask:0xf bound_ctrl:1
	v_add_f32_dpp v254, v254, v254 quad_perm:[1,0,3,2] row_mask:0xf bank_mask:0xf bound_ctrl:1
	v_add_f32_dpp v248, v248, v248 quad_perm:[2,3,0,1] row_mask:0xf bank_mask:0xf bound_ctrl:1
	v_add_f32_dpp v250, v250, v250 quad_perm:[2,3,0,1] row_mask:0xf bank_mask:0xf bound_ctrl:1
	v_add_f32_dpp v252, v252, v252 quad_perm:[2,3,0,1] row_mask:0xf bank_mask:0xf bound_ctrl:1
	v_add_f32_dpp v254, v254, v254 quad_perm:[2,3,0,1] row_mask:0xf bank_mask:0xf bound_ctrl:1
	v_add_f32_dpp v248, v248, v248 row_half_mirror row_mask:0xf bank_mask:0xf bound_ctrl:1
	v_add_f32_dpp v250, v250, v250 row_half_mirror row_mask:0xf bank_mask:0xf bound_ctrl:1
	v_add_f32_dpp v252, v252, v252 row_half_mirror row_mask:0xf bank_mask:0xf bound_ctrl:1
	v_add_f32_dpp v254, v254, v254 row_half_mirror row_mask:0xf bank_mask:0xf bound_ctrl:1
	v_add_f32_dpp v248, v248, v248 row_mirror row_mask:0xf bank_mask:0xf bound_ctrl:1
	v_add_f32_dpp v250, v250, v250 row_mirror row_mask:0xf bank_mask:0xf bound_ctrl:1
	v_add_f32_dpp v252, v252, v252 row_mirror row_mask:0xf bank_mask:0xf bound_ctrl:1
	v_add_f32_dpp v254, v254, v254 row_mirror row_mask:0xf bank_mask:0xf bound_ctrl:1
	v_fmamk_f32 v248, v248, 0x3a800000, v243
	v_fmamk_f32 v250, v250, 0x3a800000, v243
	v_fmamk_f32 v252, v252, 0x3a800000, v243
	v_fmamk_f32 v254, v254, 0x3a800000, v243
	v_rsq_f32_e32 v248, v248
	v_rsq_f32_e32 v250, v250
	v_rsq_f32_e32 v252, v252
	v_rsq_f32_e32 v254, v254
	s_nop 0
	v_pk_mul_f32 v[128:129], v[128:129], v[248:249] op_sel_hi:[1,0]
	v_pk_mul_f32 v[130:131], v[130:131], v[248:249] op_sel_hi:[1,0]
	v_pk_mul_f32 v[132:133], v[132:133], v[248:249] op_sel_hi:[1,0]
	v_pk_mul_f32 v[134:135], v[134:135], v[248:249] op_sel_hi:[1,0]
	v_pk_mul_f32 v[136:137], v[136:137], v[248:249] op_sel_hi:[1,0]
	v_pk_mul_f32 v[138:139], v[138:139], v[248:249] op_sel_hi:[1,0]
	v_pk_mul_f32 v[140:141], v[140:141], v[248:249] op_sel_hi:[1,0]
	v_pk_mul_f32 v[142:143], v[142:143], v[248:249] op_sel_hi:[1,0]
	v_pk_mul_f32 v[128:129], v[216:217], v[128:129]
	v_pk_mul_f32 v[130:131], v[218:219], v[130:131]
	v_pk_mul_f32 v[132:133], v[220:221], v[132:133]
; __device__ __forceinline__ void peer_tile(const Args& A, LAS unsigned char* lds, int tile) {
;     ...
;             const float rstd = rsqrtf(wave_sum(ss) * (1.f / 1024.f) + 1e-6f);
; #pragma unroll
;             for (int j = 0; j < 4; ++j) { const f32x4 fg = *(const f32x4*)(A.final_g + 16 * lane + 4 * j); *(f32x4*)(orow + 4 * j) = xv[j] * rstd * fg; }
;         }
;     }
	v_pk_mul_f32 v[134:135], v[222:223], v[134:135]
	v_pk_mul_f32 v[136:137], v[224:225], v[136:137]
	v_pk_mul_f32 v[138:139], v[226:227], v[138:139]
	v_pk_mul_f32 v[140:141], v[228:229], v[140:141]
	v_pk_mul_f32 v[142:143], v[230:231], v[142:143]
	global_store_dwordx4 v246, v[128:131], s[24:25]
	global_store_dwordx4 v246, v[132:135], s[24:25] offset:16
	global_store_dwordx4 v246, v[136:139], s[24:25] offset:32
	global_store_dwordx4 v246, v[140:143], s[24:25] offset:48
	v_pk_mul_f32 v[144:145], v[144:145], v[250:251] op_sel_hi:[1,0]
	v_pk_mul_f32 v[146:147], v[146:147], v[250:251] op_sel_hi:[1,0]
	v_pk_mul_f32 v[148:149], v[148:149], v[250:251] op_sel_hi:[1,0]
	v_pk_mul_f32 v[150:151], v[150:151], v[250:251] op_sel_hi:[1,0]
	v_pk_mul_f32 v[152:153], v[152:153], v[250:251] op_sel_hi:[1,0]
	v_pk_mul_f32 v[154:155], v[154:155], v[250:251] op_sel_hi:[1,0]
	v_pk_mul_f32 v[156:157], v[156:157], v[250:251] op_sel_hi:[1,0]
	v_pk_mul_f32 v[158:159], v[158:159], v[250:251] op_sel_hi:[1,0]
	v_pk_mul_f32 v[144:145], v[216:217], v[144:145]
	v_pk_mul_f32 v[146:147], v[218:219], v[146:147]
	v_pk_mul_f32 v[148:149], v[220:221], v[148:149]
	v_pk_mul_f32 v[150:151], v[222:223], v[150:151]
	v_pk_mul_f32 v[152:153], v[224:225], v[152:153]
	v_pk_mul_f32 v[154:155], v[226:227], v[154:155]
	v_pk_mul_f32 v[156:157], v[228:229], v[156:157]
	v_pk_mul_f32 v[158:159], v[230:231], v[158:159]
	global_store_dwordx4 v246, v[144:147], s[26:27]
	global_store_dwordx4 v246, v[148:151], s[26:27] offset:16
	global_store_dwordx4 v246, v[152:155], s[26:27] offset:32
	global_store_dwordx4 v246, v[156:159], s[26:27] offset:48
	v_pk_mul_f32 v[160:161], v[160:161], v[252:253] op_sel_hi:[1,0]
	v_pk_mul_f32 v[162:163], v[162:163], v[252:253] op_sel_hi:[1,0]
	v_pk_mul_f32 v[164:165], v[164:165], v[252:253] op_sel_hi:[1,0]
	v_pk_mul_f32 v[166:167], v[166:167], v[252:253] op_sel_hi:[1,0]
	v_pk_mul_f32 v[168:169], v[168:169], v[252:253] op_sel_hi:[1,0]
	v_pk_mul_f32 v[170:171], v[170:171], v[252:253] op_sel_hi:[1,0]
	v_pk_mul_f32 v[172:173], v[172:173], v[252:253] op_sel_hi:[1,0]
	v_pk_mul_f32 v[174:175], v[174:175], v[252:253] op_sel_hi:[1,0]
	v_pk_mul_f32 v[160:161], v[216:217], v[160:161]
	v_pk_mul_f32 v[162:163], v[218:219], v[162:163]
	v_pk_mul_f32 v[164:165], v[220:221], v[164:165]
	v_pk_mul_f32 v[166:167], v[222:223], v[166:167]
	v_pk_mul_f32 v[168:169], v[224:225], v[168:169]
	v_pk_mul_f32 v[170:171], v[226:227], v[170:171]
	v_pk_mul_f32 v[172:173], v[228:229], v[172:173]
	v_pk_mul_f32 v[174:175], v[230:231], v[174:175]
	global_store_dwordx4 v246, v[160:163], s[28:29]
	global_store_dwordx4 v246, v[164:167], s[28:29] offset:16
	global_store_dwordx4 v246, v[168:171], s[28:29] offset:32
	global_store_dwordx4 v246, v[172:175], s[28:29] offset:48
	v_pk_mul_f32 v[176:177], v[176:177], v[254:255] op_sel_hi:[1,0]
	v_pk_mul_f32 v[178:179], v[178:179], v[254:255] op_sel_hi:[1,0]
	v_pk_mul_f32 v[180:181], v[180:181], v[254:255] op_sel_hi:[1,0]
	v_pk_mul_f32 v[182:183], v[182:183], v[254:255] op_sel_hi:[1,0]
	v_pk_mul_f32 v[184:185], v[184:185], v[254:255] op_sel_hi:[1,0]
	v_pk_mul_f32 v[186:187], v[186:187], v[254:255] op_sel_hi:[1,0]
	v_pk_mul_f32 v[188:189], v[188:189], v[254:255] op_sel_hi:[1,0]
	v_pk_mul_f32 v[190:191], v[190:191], v[254:255] op_sel_hi:[1,0]
	v_pk_mul_f32 v[176:177], v[216:217], v[176:177]
	v_pk_mul_f32 v[178:179], v[218:219], v[178:179]
	v_pk_mul_f32 v[180:181], v[220:221], v[180:181]
	v_pk_mul_f32 v[182:183], v[222:223], v[182:183]
	v_pk_mul_f32 v[184:185], v[224:225], v[184:185]
	v_pk_mul_f32 v[186:187], v[226:227], v[186:187]
	v_pk_mul_f32 v[188:189], v[228:229], v[188:189]
	v_pk_mul_f32 v[190:191], v[230:231], v[190:191]
	global_store_dwordx4 v246, v[176:179], s[30:31]
	global_store_dwordx4 v246, v[180:183], s[30:31] offset:16
	global_store_dwordx4 v246, v[184:187], s[30:31] offset:32
	global_store_dwordx4 v246, v[188:191], s[30:31] offset:48
	s_nop 1
	v_mov_b32_e32 v113, 0
	v_mbcnt_lo_u32_b32 v215, -1, 0
	v_mbcnt_hi_u32_b32 v215, -1, v215
	v_and_b32_e32 v216, 64, v215
	v_add_u32_e32 v216, 64, v216
	v_xor_b32_e32 v217, 16, v215
	v_xor_b32_e32 v218, 32, v215
	s_branch .LBB0_698

